# v41 + loop-edge edit: K-loop pointer/counter SALU updates and the loop test hoisted above the closing s_barrier (into the last MFMAs' shadow) in 15 of 16 GEMM loops
# baseline (speedup 1.0000x reference)
; #define PG8_STAGE(bufoff, gbase, voff) do { _Pragma("unroll") for (int _i = 0; _i < 2; ++_i) \
;         __builtin_amdgcn_global_load_lds((const unsigned*)((const char*)(gbase) + (voff)[_i]), (LAS unsigned*)(lds + (bufoff) + ldsw + _i * 8192), 16, 0, 0); } while (0)
; #define PG8_LDA(dst, b, h) do { _Pragma("unroll") for (int m = 0; m < 4; ++m) _Pragma("unroll") for (int k = 0; k < 2; ++k) dst[m][k] = *(const LAS bf16x8*)(lds + PG8_SA(b, h) + aoff + m * 2048 + k * 1024); } while (0)
; #define PG8_LDB(dst, b, h) do { _Pragma("unroll") for (int n = 0; n < 2; ++n) _Pragma("unroll") for (int k = 0; k < 2; ++k) dst[n][k] = *(const LAS bf16x8*)(lds + PG8_SB(b, h) + boff + n * 2048 + k * 1024); } while (0)
; #define PG8_MMA(ai, bj, At, Bt) do { __builtin_amdgcn_s_setprio(1); _Pragma("unroll") for (int m = 0; m < 4; ++m) _Pragma("unroll") for (int n = 0; n < 2; ++n) _Pragma("unroll") for (int k = 0; k < 2; ++k) \
;         acc[ai][bj][m][n] = __builtin_amdgcn_mfma_f32_16x16x32_bf16(Bt[n][k], At[m][k], acc[ai][bj][m][n], 0, 0, 0); __builtin_amdgcn_s_setprio(0); } while (0)
; #define PG8_WAIT_V(n) asm volatile("s_waitcnt vmcnt(" #n ")" ::: "memory")
; #define PG8_WAIT_L(n) asm volatile("s_waitcnt lgkmcnt(" #n ")" ::: "memory")
; #define PG8_BAR __builtin_amdgcn_s_barrier()
; #define PG8_SCHED __builtin_amdgcn_sched_barrier(0)
; template <class Epi>
; __device__ __forceinline__ void gemm_phase(LAS unsigned char* lds, const Gemm g, const Order& S, const Epi& E, const int wid) {
;     ...
;             const bool last = (t == nt - 2);
;             const char* a1 = cA + (size_t)(t + 1) * kstep;
;             const char* a2 = last ? nA : cA + (size_t)(t + 2) * kstep; const char* b2 = last ? nB : cB + (size_t)(t + 2) * kstep;
;             const char* a3 = a2 + kstep; const char* b3 = b2 + kstep;
;     ...
;             PG8_LDB(B0, 0, 0); PG8_LDB(B1, 0, 1); PG8_SCHED; PG8_LDA(At, 0, 0); PG8_STAGE(PG8_SA(1, 1), a1 + hA, voffA);
;             PG8_WAIT_V(8); PG8_WAIT_L(0); PG8_BAR; PG8_MMA(0, 0, At, B0); PG8_MMA(0, 1, At, B1); PG8_BAR; PG8_SCHED;
;             PG8_LDA(At, 0, 1); PG8_STAGE(PG8_SB(0, 0), b2, voffB); PG8_STAGE(PG8_SB(0, 1), b2 + hB, voffB); PG8_STAGE(PG8_SA(0, 0), a2, voffA);
;             PG8_WAIT_V(8); PG8_WAIT_L(0); PG8_BAR; PG8_MMA(1, 0, At, B0); PG8_MMA(1, 1, At, B1); PG8_BAR; PG8_SCHED;
.LBB0_225:
	ds_read_b128 v[144:147], v142
	ds_read_b128 v[148:151], v142 offset:1024
	ds_read_b128 v[158:161], v142 offset:2048
	ds_read_b128 v[162:165], v142 offset:3072
	ds_read_b128 v[166:169], v143
	ds_read_b128 v[170:173], v143 offset:1024
	ds_read_b128 v[174:177], v143 offset:2048
	ds_read_b128 v[178:181], v143 offset:3072
	s_add_u32 s26, s58, 0xfff00080
	s_addc_u32 s27, s59, -1
	s_cmp_eq_u32 s25, 60
	s_cselect_b32 s65, s0, s27
	s_cselect_b32 s64, s1, s26
	s_cselect_b32 s63, s6, s24
	s_cselect_b32 s62, s22, s23
	v_lshl_add_u64 v[214:215], s[58:59], 0, v[132:133]
	s_add_i32 m0, s70, 0xc000
	ds_read_b128 v[182:185], v141
	ds_read_b128 v[186:189], v141 offset:1024
	ds_read_b128 v[190:193], v141 offset:2048
	ds_read_b128 v[194:197], v141 offset:3072
	ds_read_b128 v[198:201], v141 offset:4096
	ds_read_b128 v[202:205], v141 offset:5120
	ds_read_b128 v[206:209], v141 offset:6144
	ds_read_b128 v[210:213], v141 offset:7168
	global_load_lds_dwordx4 v[214:215], off
	v_lshl_add_u64 v[214:215], s[58:59], 0, v[138:139]
	s_add_i32 m0, s70, 0xe000
	s_nop 0
	global_load_lds_dwordx4 v[214:215], off
	s_waitcnt vmcnt(8)
	s_waitcnt lgkmcnt(0)
	s_barrier
	s_waitcnt lgkmcnt(0)
	v_mfma_f32_16x16x32_bf16 v[124:127], v[144:147], v[182:185], v[124:127]
	v_mfma_f32_16x16x32_bf16 v[124:127], v[148:151], v[186:189], v[124:127]
	v_mfma_f32_16x16x32_bf16 v[120:123], v[158:161], v[182:185], v[120:123]
	v_mfma_f32_16x16x32_bf16 v[120:123], v[162:165], v[186:189], v[120:123]
	v_mfma_f32_16x16x32_bf16 v[108:111], v[144:147], v[190:193], v[108:111]
	v_mfma_f32_16x16x32_bf16 v[108:111], v[148:151], v[194:197], v[108:111]
	v_mfma_f32_16x16x32_bf16 v[104:107], v[158:161], v[190:193], v[104:107]
	v_mfma_f32_16x16x32_bf16 v[104:107], v[162:165], v[194:197], v[104:107]
	v_mfma_f32_16x16x32_bf16 v[92:95], v[144:147], v[198:201], v[92:95]
	v_mfma_f32_16x16x32_bf16 v[92:95], v[148:151], v[202:205], v[92:95]
	v_mfma_f32_16x16x32_bf16 v[88:91], v[158:161], v[198:201], v[88:91]
	v_mfma_f32_16x16x32_bf16 v[88:91], v[162:165], v[202:205], v[88:91]
	v_mfma_f32_16x16x32_bf16 v[76:79], v[144:147], v[206:209], v[76:79]
	v_mfma_f32_16x16x32_bf16 v[76:79], v[148:151], v[210:213], v[76:79]
	v_mfma_f32_16x16x32_bf16 v[72:75], v[158:161], v[206:209], v[72:75]
	v_mfma_f32_16x16x32_bf16 v[72:75], v[162:165], v[210:213], v[72:75]
	v_mfma_f32_16x16x32_bf16 v[116:119], v[166:169], v[182:185], v[116:119]
	v_mfma_f32_16x16x32_bf16 v[116:119], v[170:173], v[186:189], v[116:119]
	v_mfma_f32_16x16x32_bf16 v[112:115], v[174:177], v[182:185], v[112:115]
	v_mfma_f32_16x16x32_bf16 v[112:115], v[178:181], v[186:189], v[112:115]
	v_mfma_f32_16x16x32_bf16 v[100:103], v[166:169], v[190:193], v[100:103]
	v_mfma_f32_16x16x32_bf16 v[100:103], v[170:173], v[194:197], v[100:103]
	v_mfma_f32_16x16x32_bf16 v[96:99], v[174:177], v[190:193], v[96:99]
	v_mfma_f32_16x16x32_bf16 v[96:99], v[178:181], v[194:197], v[96:99]
	v_mfma_f32_16x16x32_bf16 v[84:87], v[166:169], v[198:201], v[84:87]
	v_mfma_f32_16x16x32_bf16 v[84:87], v[170:173], v[202:205], v[84:87]
	v_mfma_f32_16x16x32_bf16 v[80:83], v[174:177], v[198:201], v[80:83]
	v_mfma_f32_16x16x32_bf16 v[80:83], v[178:181], v[202:205], v[80:83]
	v_mfma_f32_16x16x32_bf16 v[68:71], v[166:169], v[206:209], v[68:71]
	v_mfma_f32_16x16x32_bf16 v[68:71], v[170:173], v[210:213], v[68:71]
	v_mfma_f32_16x16x32_bf16 v[64:67], v[174:177], v[206:209], v[64:67]
	v_mfma_f32_16x16x32_bf16 v[64:67], v[178:181], v[210:213], v[64:67]
	s_barrier
	s_add_i32 s26, s12, s69
	v_lshl_add_u64 v[214:215], s[62:63], 0, v[128:129]
	s_mov_b32 m0, s26
	ds_read_b128 v[182:185], v141 offset:16384
	ds_read_b128 v[186:189], v141 offset:17408
	ds_read_b128 v[190:193], v141 offset:18432
	ds_read_b128 v[194:197], v141 offset:19456
	ds_read_b128 v[198:201], v141 offset:20480
	ds_read_b128 v[202:205], v141 offset:21504
	ds_read_b128 v[206:209], v141 offset:22528
	ds_read_b128 v[210:213], v141 offset:23552
	global_load_lds_dwordx4 v[214:215], off
	s_add_i32 m0, s26, 0x2000
	s_add_u32 s26, s62, 0x100000
	v_lshl_add_u64 v[216:217], s[62:63], 0, v[130:131]
	s_addc_u32 s27, s63, 0
	s_add_i32 s28, s13, s69
	global_load_lds_dwordx4 v[216:217], off
	v_lshl_add_u64 v[218:219], s[26:27], 0, v[128:129]
	s_mov_b32 m0, s28
	v_lshl_add_u64 v[220:221], s[64:65], 0, v[138:139]
	global_load_lds_dwordx4 v[218:219], off
	v_lshl_add_u64 v[218:219], s[26:27], 0, v[130:131]
	s_add_i32 m0, s28, 0x2000
	s_nop 0
	global_load_lds_dwordx4 v[218:219], off
	v_lshl_add_u64 v[218:219], s[64:65], 0, v[132:133]
	s_mov_b32 m0, s70
	s_nop 0
	global_load_lds_dwordx4 v[218:219], off
	s_mov_b32 m0, s71
	s_nop 0
	global_load_lds_dwordx4 v[220:221], off
	s_waitcnt vmcnt(8)
	s_waitcnt lgkmcnt(0)
	s_barrier
; #define PG8_STAGE(bufoff, gbase, voff) do { _Pragma("unroll") for (int _i = 0; _i < 2; ++_i) \
;         __builtin_amdgcn_global_load_lds((const unsigned*)((const char*)(gbase) + (voff)[_i]), (LAS unsigned*)(lds + (bufoff) + ldsw + _i * 8192), 16, 0, 0); } while (0)
; #define PG8_LDA(dst, b, h) do { _Pragma("unroll") for (int m = 0; m < 4; ++m) _Pragma("unroll") for (int k = 0; k < 2; ++k) dst[m][k] = *(const LAS bf16x8*)(lds + PG8_SA(b, h) + aoff + m * 2048 + k * 1024); } while (0)
; #define PG8_LDB(dst, b, h) do { _Pragma("unroll") for (int n = 0; n < 2; ++n) _Pragma("unroll") for (int k = 0; k < 2; ++k) dst[n][k] = *(const LAS bf16x8*)(lds + PG8_SB(b, h) + boff + n * 2048 + k * 1024); } while (0)
; #define PG8_MMA(ai, bj, At, Bt) do { __builtin_amdgcn_s_setprio(1); _Pragma("unroll") for (int m = 0; m < 4; ++m) _Pragma("unroll") for (int n = 0; n < 2; ++n) _Pragma("unroll") for (int k = 0; k < 2; ++k) \
;         acc[ai][bj][m][n] = __builtin_amdgcn_mfma_f32_16x16x32_bf16(Bt[n][k], At[m][k], acc[ai][bj][m][n], 0, 0, 0); __builtin_amdgcn_s_setprio(0); } while (0)
; #define PG8_WAIT_V(n) asm volatile("s_waitcnt vmcnt(" #n ")" ::: "memory")
; #define PG8_WAIT_L(n) asm volatile("s_waitcnt lgkmcnt(" #n ")" ::: "memory")
; #define PG8_BAR __builtin_amdgcn_s_barrier()
; #define PG8_SCHED __builtin_amdgcn_sched_barrier(0)
; template <class Epi>
; __device__ __forceinline__ void gemm_phase(LAS unsigned char* lds, const Gemm g, const Order& S, const Epi& E, const int wid) {
;     ...
;             PG8_WAIT_V(8); PG8_WAIT_L(0); PG8_BAR; PG8_MMA(1, 0, At, B0); PG8_MMA(1, 1, At, B1); PG8_BAR; PG8_SCHED;
;             PG8_LDB(B0, 1, 0); PG8_LDB(B1, 1, 1); PG8_SCHED; PG8_LDA(At, 1, 0); PG8_STAGE(PG8_SA(0, 1), a2 + hA, voffA);
;             PG8_WAIT_V(8); PG8_WAIT_L(0); PG8_BAR; PG8_MMA(0, 0, At, B0); PG8_MMA(0, 1, At, B1); PG8_BAR; PG8_SCHED;
;             PG8_LDA(At, 1, 1); PG8_STAGE(PG8_SB(1, 0), b3, voffB); PG8_STAGE(PG8_SB(1, 1), b3 + hB, voffB); PG8_STAGE(PG8_SA(1, 0), a3, voffA);
	s_waitcnt lgkmcnt(0)
	v_mfma_f32_16x16x32_bf16 v[60:63], v[144:147], v[182:185], v[60:63]
	v_mfma_f32_16x16x32_bf16 v[60:63], v[148:151], v[186:189], v[60:63]
	v_mfma_f32_16x16x32_bf16 v[56:59], v[158:161], v[182:185], v[56:59]
	v_mfma_f32_16x16x32_bf16 v[56:59], v[162:165], v[186:189], v[56:59]
	v_mfma_f32_16x16x32_bf16 v[44:47], v[144:147], v[190:193], v[44:47]
	v_mfma_f32_16x16x32_bf16 v[44:47], v[148:151], v[194:197], v[44:47]
	v_mfma_f32_16x16x32_bf16 v[40:43], v[158:161], v[190:193], v[40:43]
	v_mfma_f32_16x16x32_bf16 v[40:43], v[162:165], v[194:197], v[40:43]
	v_mfma_f32_16x16x32_bf16 v[28:31], v[144:147], v[198:201], v[28:31]
	v_mfma_f32_16x16x32_bf16 v[28:31], v[148:151], v[202:205], v[28:31]
	v_mfma_f32_16x16x32_bf16 v[24:27], v[158:161], v[198:201], v[24:27]
	v_mfma_f32_16x16x32_bf16 v[24:27], v[162:165], v[202:205], v[24:27]
	v_mfma_f32_16x16x32_bf16 v[12:15], v[144:147], v[206:209], v[12:15]
	v_mfma_f32_16x16x32_bf16 v[12:15], v[148:151], v[210:213], v[12:15]
	v_mfma_f32_16x16x32_bf16 v[8:11], v[158:161], v[206:209], v[8:11]
	v_mfma_f32_16x16x32_bf16 v[8:11], v[162:165], v[210:213], v[8:11]
	v_mfma_f32_16x16x32_bf16 v[52:55], v[166:169], v[182:185], v[52:55]
	v_mfma_f32_16x16x32_bf16 v[52:55], v[170:173], v[186:189], v[52:55]
	v_mfma_f32_16x16x32_bf16 v[48:51], v[174:177], v[182:185], v[48:51]
	v_mfma_f32_16x16x32_bf16 v[48:51], v[178:181], v[186:189], v[48:51]
	v_mfma_f32_16x16x32_bf16 v[36:39], v[166:169], v[190:193], v[36:39]
	v_mfma_f32_16x16x32_bf16 v[36:39], v[170:173], v[194:197], v[36:39]
	v_mfma_f32_16x16x32_bf16 v[32:35], v[174:177], v[190:193], v[32:35]
	v_mfma_f32_16x16x32_bf16 v[32:35], v[178:181], v[194:197], v[32:35]
	v_mfma_f32_16x16x32_bf16 v[20:23], v[166:169], v[198:201], v[20:23]
	v_mfma_f32_16x16x32_bf16 v[20:23], v[170:173], v[202:205], v[20:23]
	v_mfma_f32_16x16x32_bf16 v[16:19], v[174:177], v[198:201], v[16:19]
	v_mfma_f32_16x16x32_bf16 v[16:19], v[178:181], v[202:205], v[16:19]
	v_mfma_f32_16x16x32_bf16 v[4:7], v[166:169], v[206:209], v[4:7]
	v_mfma_f32_16x16x32_bf16 v[4:7], v[170:173], v[210:213], v[4:7]
	v_mfma_f32_16x16x32_bf16 v[0:3], v[174:177], v[206:209], v[0:3]
	v_mfma_f32_16x16x32_bf16 v[0:3], v[178:181], v[210:213], v[0:3]
	s_barrier
	s_add_i32 s28, 0, 0x18000
	v_add_u32_e32 v157, s28, v140
	s_add_i32 s29, 0, 0x1c000
	ds_read_b128 v[144:147], v157
	ds_read_b128 v[148:151], v157 offset:1024
	ds_read_b128 v[158:161], v157 offset:2048
	ds_read_b128 v[162:165], v157 offset:3072
	v_add_u32_e32 v157, s29, v140
	ds_read_b128 v[166:169], v157
	ds_read_b128 v[170:173], v157 offset:1024
	ds_read_b128 v[174:177], v157 offset:2048
	ds_read_b128 v[178:181], v157 offset:3072
	s_add_u32 s26, s64, 0x100000
	s_addc_u32 s27, s65, 0
	s_mov_b32 m0, s76
	v_lshl_add_u64 v[222:223], s[26:27], 0, v[132:133]
	ds_read_b128 v[182:185], v141 offset:32768
	ds_read_b128 v[186:189], v141 offset:33792
	ds_read_b128 v[190:193], v141 offset:34816
	ds_read_b128 v[194:197], v141 offset:35840
	ds_read_b128 v[198:201], v141 offset:36864
	ds_read_b128 v[202:205], v141 offset:37888
	ds_read_b128 v[206:209], v141 offset:38912
	ds_read_b128 v[210:213], v141 offset:39936
	global_load_lds_dwordx4 v[222:223], off
	v_lshl_add_u64 v[222:223], s[26:27], 0, v[138:139]
	s_mov_b32 m0, s77
	s_nop 0
	global_load_lds_dwordx4 v[222:223], off
	s_waitcnt vmcnt(8)
	s_waitcnt lgkmcnt(0)
	s_barrier
	s_waitcnt lgkmcnt(0)
	v_mfma_f32_16x16x32_bf16 v[124:127], v[144:147], v[182:185], v[124:127]
	v_mfma_f32_16x16x32_bf16 v[124:127], v[148:151], v[186:189], v[124:127]
	v_mfma_f32_16x16x32_bf16 v[120:123], v[158:161], v[182:185], v[120:123]
	v_mfma_f32_16x16x32_bf16 v[120:123], v[162:165], v[186:189], v[120:123]
	v_mfma_f32_16x16x32_bf16 v[108:111], v[144:147], v[190:193], v[108:111]
	v_mfma_f32_16x16x32_bf16 v[108:111], v[148:151], v[194:197], v[108:111]
	v_mfma_f32_16x16x32_bf16 v[104:107], v[158:161], v[190:193], v[104:107]
	v_mfma_f32_16x16x32_bf16 v[104:107], v[162:165], v[194:197], v[104:107]
	v_mfma_f32_16x16x32_bf16 v[92:95], v[144:147], v[198:201], v[92:95]
	v_mfma_f32_16x16x32_bf16 v[92:95], v[148:151], v[202:205], v[92:95]
	v_mfma_f32_16x16x32_bf16 v[88:91], v[158:161], v[198:201], v[88:91]
	v_mfma_f32_16x16x32_bf16 v[88:91], v[162:165], v[202:205], v[88:91]
	v_mfma_f32_16x16x32_bf16 v[76:79], v[144:147], v[206:209], v[76:79]
	v_mfma_f32_16x16x32_bf16 v[76:79], v[148:151], v[210:213], v[76:79]
	v_mfma_f32_16x16x32_bf16 v[72:75], v[158:161], v[206:209], v[72:75]
	v_mfma_f32_16x16x32_bf16 v[72:75], v[162:165], v[210:213], v[72:75]
	v_mfma_f32_16x16x32_bf16 v[116:119], v[166:169], v[182:185], v[116:119]
	v_mfma_f32_16x16x32_bf16 v[116:119], v[170:173], v[186:189], v[116:119]
	v_mfma_f32_16x16x32_bf16 v[112:115], v[174:177], v[182:185], v[112:115]
	v_mfma_f32_16x16x32_bf16 v[112:115], v[178:181], v[186:189], v[112:115]
	v_mfma_f32_16x16x32_bf16 v[100:103], v[166:169], v[190:193], v[100:103]
	v_mfma_f32_16x16x32_bf16 v[100:103], v[170:173], v[194:197], v[100:103]
	v_mfma_f32_16x16x32_bf16 v[96:99], v[174:177], v[190:193], v[96:99]
	v_mfma_f32_16x16x32_bf16 v[96:99], v[178:181], v[194:197], v[96:99]
	v_mfma_f32_16x16x32_bf16 v[84:87], v[166:169], v[198:201], v[84:87]
	v_mfma_f32_16x16x32_bf16 v[84:87], v[170:173], v[202:205], v[84:87]
	v_mfma_f32_16x16x32_bf16 v[80:83], v[174:177], v[198:201], v[80:83]
	v_mfma_f32_16x16x32_bf16 v[80:83], v[178:181], v[202:205], v[80:83]
	v_mfma_f32_16x16x32_bf16 v[68:71], v[166:169], v[206:209], v[68:71]
	v_mfma_f32_16x16x32_bf16 v[68:71], v[170:173], v[210:213], v[68:71]
	v_mfma_f32_16x16x32_bf16 v[64:67], v[174:177], v[206:209], v[64:67]
	v_mfma_f32_16x16x32_bf16 v[64:67], v[178:181], v[210:213], v[64:67]
	s_barrier
; #define PG8_STAGE(bufoff, gbase, voff) do { _Pragma("unroll") for (int _i = 0; _i < 2; ++_i) \
;         __builtin_amdgcn_global_load_lds((const unsigned*)((const char*)(gbase) + (voff)[_i]), (LAS unsigned*)(lds + (bufoff) + ldsw + _i * 8192), 16, 0, 0); } while (0)
; #define PG8_LDA(dst, b, h) do { _Pragma("unroll") for (int m = 0; m < 4; ++m) _Pragma("unroll") for (int k = 0; k < 2; ++k) dst[m][k] = *(const LAS bf16x8*)(lds + PG8_SA(b, h) + aoff + m * 2048 + k * 1024); } while (0)
; #define PG8_MMA(ai, bj, At, Bt) do { __builtin_amdgcn_s_setprio(1); _Pragma("unroll") for (int m = 0; m < 4; ++m) _Pragma("unroll") for (int n = 0; n < 2; ++n) _Pragma("unroll") for (int k = 0; k < 2; ++k) \
;         acc[ai][bj][m][n] = __builtin_amdgcn_mfma_f32_16x16x32_bf16(Bt[n][k], At[m][k], acc[ai][bj][m][n], 0, 0, 0); __builtin_amdgcn_s_setprio(0); } while (0)
; #define PG8_WAIT_V(n) asm volatile("s_waitcnt vmcnt(" #n ")" ::: "memory")
; #define PG8_WAIT_L(n) asm volatile("s_waitcnt lgkmcnt(" #n ")" ::: "memory")
; #define PG8_BAR __builtin_amdgcn_s_barrier()
; #define PG8_SCHED __builtin_amdgcn_sched_barrier(0)
; template <class Epi>
; __device__ __forceinline__ void gemm_phase(LAS unsigned char* lds, const Gemm g, const Order& S, const Epi& E, const int wid) {
;     ...
;         for (int t = 0; t < nt; t += 2) {
;     ...
;             PG8_LDA(At, 1, 1); PG8_STAGE(PG8_SB(1, 0), b3, voffB); PG8_STAGE(PG8_SB(1, 1), b3 + hB, voffB); PG8_STAGE(PG8_SA(1, 0), a3, voffA);
;             PG8_WAIT_V(8); PG8_WAIT_L(0); PG8_BAR; PG8_MMA(1, 0, At, B0); PG8_MMA(1, 1, At, B1); PG8_BAR; PG8_SCHED;
	s_add_i32 s26, s28, s69
	v_lshl_add_u64 v[214:215], v[214:215], 0, s[36:37]
	s_mov_b32 m0, s26
	ds_read_b128 v[182:185], v141 offset:49152
	ds_read_b128 v[186:189], v141 offset:50176
	ds_read_b128 v[190:193], v141 offset:51200
	ds_read_b128 v[194:197], v141 offset:52224
	ds_read_b128 v[198:201], v141 offset:53248
	ds_read_b128 v[202:205], v141 offset:54272
	ds_read_b128 v[206:209], v141 offset:55296
	ds_read_b128 v[210:213], v141 offset:56320
	global_load_lds_dwordx4 v[214:215], off
	s_add_i32 m0, s26, 0x2000
	s_add_u32 s26, s62, 0x100080
	v_lshl_add_u64 v[214:215], v[216:217], 0, s[36:37]
	s_addc_u32 s27, s63, 0
	s_add_i32 s28, s29, s69
	global_load_lds_dwordx4 v[214:215], off
	v_lshl_add_u64 v[214:215], s[26:27], 0, v[128:129]
	s_mov_b32 m0, s28
	s_nop 0
	global_load_lds_dwordx4 v[214:215], off
	v_lshl_add_u64 v[214:215], s[26:27], 0, v[130:131]
	s_add_i32 m0, s28, 0x2000
	s_nop 0
	global_load_lds_dwordx4 v[214:215], off
	v_lshl_add_u64 v[214:215], v[218:219], 0, s[36:37]
	s_mov_b32 m0, s75
	s_nop 0
	global_load_lds_dwordx4 v[214:215], off
	v_lshl_add_u64 v[214:215], v[220:221], 0, s[36:37]
	s_mov_b32 m0, s79
	s_nop 0
	global_load_lds_dwordx4 v[214:215], off
	s_waitcnt vmcnt(8)
	s_waitcnt lgkmcnt(0)
	s_barrier
	s_waitcnt lgkmcnt(0)
	v_mfma_f32_16x16x32_bf16 v[60:63], v[144:147], v[182:185], v[60:63]
	v_mfma_f32_16x16x32_bf16 v[60:63], v[148:151], v[186:189], v[60:63]
	v_mfma_f32_16x16x32_bf16 v[56:59], v[158:161], v[182:185], v[56:59]
	v_mfma_f32_16x16x32_bf16 v[56:59], v[162:165], v[186:189], v[56:59]
	v_mfma_f32_16x16x32_bf16 v[44:47], v[144:147], v[190:193], v[44:47]
	v_mfma_f32_16x16x32_bf16 v[44:47], v[148:151], v[194:197], v[44:47]
	v_mfma_f32_16x16x32_bf16 v[40:43], v[158:161], v[190:193], v[40:43]
	v_mfma_f32_16x16x32_bf16 v[40:43], v[162:165], v[194:197], v[40:43]
	v_mfma_f32_16x16x32_bf16 v[28:31], v[144:147], v[198:201], v[28:31]
	v_mfma_f32_16x16x32_bf16 v[28:31], v[148:151], v[202:205], v[28:31]
	v_mfma_f32_16x16x32_bf16 v[24:27], v[158:161], v[198:201], v[24:27]
	v_mfma_f32_16x16x32_bf16 v[24:27], v[162:165], v[202:205], v[24:27]
	v_mfma_f32_16x16x32_bf16 v[12:15], v[144:147], v[206:209], v[12:15]
	v_mfma_f32_16x16x32_bf16 v[12:15], v[148:151], v[210:213], v[12:15]
	v_mfma_f32_16x16x32_bf16 v[8:11], v[158:161], v[206:209], v[8:11]
	v_mfma_f32_16x16x32_bf16 v[8:11], v[162:165], v[210:213], v[8:11]
	v_mfma_f32_16x16x32_bf16 v[52:55], v[166:169], v[182:185], v[52:55]
	v_mfma_f32_16x16x32_bf16 v[52:55], v[170:173], v[186:189], v[52:55]
	v_mfma_f32_16x16x32_bf16 v[48:51], v[174:177], v[182:185], v[48:51]
	v_mfma_f32_16x16x32_bf16 v[48:51], v[178:181], v[186:189], v[48:51]
	v_mfma_f32_16x16x32_bf16 v[36:39], v[166:169], v[190:193], v[36:39]
	v_mfma_f32_16x16x32_bf16 v[36:39], v[170:173], v[194:197], v[36:39]
	v_mfma_f32_16x16x32_bf16 v[32:35], v[174:177], v[190:193], v[32:35]
	v_mfma_f32_16x16x32_bf16 v[32:35], v[178:181], v[194:197], v[32:35]
	v_mfma_f32_16x16x32_bf16 v[20:23], v[166:169], v[198:201], v[20:23]
	v_mfma_f32_16x16x32_bf16 v[20:23], v[170:173], v[202:205], v[20:23]
	v_mfma_f32_16x16x32_bf16 v[16:19], v[174:177], v[198:201], v[16:19]
	v_mfma_f32_16x16x32_bf16 v[16:19], v[178:181], v[202:205], v[16:19]
	v_mfma_f32_16x16x32_bf16 v[4:7], v[166:169], v[206:209], v[4:7]
	v_mfma_f32_16x16x32_bf16 v[4:7], v[170:173], v[210:213], v[4:7]
	v_mfma_f32_16x16x32_bf16 v[0:3], v[174:177], v[206:209], v[0:3]
	v_mfma_f32_16x16x32_bf16 v[0:3], v[178:181], v[210:213], v[0:3]
	s_add_i32 s25, s25, 2
	s_add_u32 s58, s58, 0x100
	s_addc_u32 s59, s59, 0
	s_add_u32 s23, s23, 0x100
	s_addc_u32 s24, s24, 0
	s_cmp_gt_u32 s25, 61
	s_barrier
	s_cbranch_scc0 .LBB0_225
	s_and_b64 vcc, exec, s[14:15]
	s_cbranch_vccz .LBB0_228
	s_barrier

; #define PG8_STAGE(bufoff, gbase, voff) do { _Pragma("unroll") for (int _i = 0; _i < 2; ++_i) \
;         __builtin_amdgcn_global_load_lds((const unsigned*)((const char*)(gbase) + (voff)[_i]), (LAS unsigned*)(lds + (bufoff) + ldsw + _i * 8192), 16, 0, 0); } while (0)
; #define PG8_LDA(dst, b, h) do { _Pragma("unroll") for (int m = 0; m < 4; ++m) _Pragma("unroll") for (int k = 0; k < 2; ++k) dst[m][k] = *(const LAS bf16x8*)(lds + PG8_SA(b, h) + aoff + m * 2048 + k * 1024); } while (0)
; #define PG8_LDB(dst, b, h) do { _Pragma("unroll") for (int n = 0; n < 2; ++n) _Pragma("unroll") for (int k = 0; k < 2; ++k) dst[n][k] = *(const LAS bf16x8*)(lds + PG8_SB(b, h) + boff + n * 2048 + k * 1024); } while (0)
; #define PG8_MMA(ai, bj, At, Bt) do { __builtin_amdgcn_s_setprio(1); _Pragma("unroll") for (int m = 0; m < 4; ++m) _Pragma("unroll") for (int n = 0; n < 2; ++n) _Pragma("unroll") for (int k = 0; k < 2; ++k) \
;         acc[ai][bj][m][n] = __builtin_amdgcn_mfma_f32_16x16x32_bf16(Bt[n][k], At[m][k], acc[ai][bj][m][n], 0, 0, 0); __builtin_amdgcn_s_setprio(0); } while (0)
; #define PG8_WAIT_V(n) asm volatile("s_waitcnt vmcnt(" #n ")" ::: "memory")
; #define PG8_WAIT_L(n) asm volatile("s_waitcnt lgkmcnt(" #n ")" ::: "memory")
; #define PG8_BAR __builtin_amdgcn_s_barrier()
; #define PG8_SCHED __builtin_amdgcn_sched_barrier(0)
; template <class Epi>
; __device__ __forceinline__ void gemm_phase(LAS unsigned char* lds, const Gemm g, const Order& S, const Epi& E, const int wid) {
;     ...
;             const bool last = (t == nt - 2);
;             const char* a1 = cA + (size_t)(t + 1) * kstep;
;             const char* a2 = last ? nA : cA + (size_t)(t + 2) * kstep; const char* b2 = last ? nB : cB + (size_t)(t + 2) * kstep;
;             const char* a3 = a2 + kstep; const char* b3 = b2 + kstep;
;     ...
;             PG8_LDB(B0, 0, 0); PG8_LDB(B1, 0, 1); PG8_SCHED; PG8_LDA(At, 0, 0); PG8_STAGE(PG8_SA(1, 1), a1 + hA, voffA);
;             PG8_WAIT_V(8); PG8_WAIT_L(0); PG8_BAR; PG8_MMA(0, 0, At, B0); PG8_MMA(0, 1, At, B1); PG8_BAR; PG8_SCHED;
;             PG8_LDA(At, 0, 1); PG8_STAGE(PG8_SB(0, 0), b2, voffB); PG8_STAGE(PG8_SB(0, 1), b2 + hB, voffB); PG8_STAGE(PG8_SA(0, 0), a2, voffA);
;             PG8_WAIT_V(8); PG8_WAIT_L(0); PG8_BAR; PG8_MMA(1, 0, At, B0); PG8_MMA(1, 1, At, B1); PG8_BAR; PG8_SCHED;
.LBB0_344:
	ds_read_b128 v[144:147], v141
	ds_read_b128 v[152:155], v141 offset:1024
	ds_read_b128 v[156:159], v141 offset:2048
	ds_read_b128 v[160:163], v141 offset:3072
	ds_read_b128 v[164:167], v142
	ds_read_b128 v[168:171], v142 offset:1024
	ds_read_b128 v[172:175], v142 offset:2048
	ds_read_b128 v[176:179], v142 offset:3072
	s_add_u32 s10, s8, 0xfffc0080
	s_addc_u32 s11, s9, -1
	s_cmp_eq_u32 s75, 12
	s_cselect_b32 s13, s7, s11
	s_cselect_b32 s12, s40, s10
	s_cselect_b32 s11, s47, s74
	s_cselect_b32 s10, s55, s73
	v_lshl_add_u64 v[212:213], s[8:9], 0, v[128:129]
	s_add_i32 m0, s29, 0xc000
	ds_read_b128 v[180:183], v143
	ds_read_b128 v[184:187], v143 offset:1024
	ds_read_b128 v[188:191], v143 offset:2048
	ds_read_b128 v[192:195], v143 offset:3072
	ds_read_b128 v[196:199], v143 offset:4096
	ds_read_b128 v[200:203], v143 offset:5120
	ds_read_b128 v[204:207], v143 offset:6144
	ds_read_b128 v[208:211], v143 offset:7168
	global_load_lds_dwordx4 v[212:213], off
	v_lshl_add_u64 v[212:213], s[8:9], 0, v[138:139]
	s_add_i32 m0, s29, 0xe000
	s_nop 0
	global_load_lds_dwordx4 v[212:213], off
	s_waitcnt vmcnt(8)
	s_waitcnt lgkmcnt(0)
	s_barrier
	s_waitcnt lgkmcnt(0)
	v_mfma_f32_16x16x32_bf16 v[124:127], v[144:147], v[180:183], v[124:127]
	v_mfma_f32_16x16x32_bf16 v[124:127], v[152:155], v[184:187], v[124:127]
	v_mfma_f32_16x16x32_bf16 v[120:123], v[156:159], v[180:183], v[120:123]
	v_mfma_f32_16x16x32_bf16 v[120:123], v[160:163], v[184:187], v[120:123]
	v_mfma_f32_16x16x32_bf16 v[112:115], v[144:147], v[188:191], v[112:115]
	v_mfma_f32_16x16x32_bf16 v[112:115], v[152:155], v[192:195], v[112:115]
	v_mfma_f32_16x16x32_bf16 v[104:107], v[156:159], v[188:191], v[104:107]
	v_mfma_f32_16x16x32_bf16 v[104:107], v[160:163], v[192:195], v[104:107]
	v_mfma_f32_16x16x32_bf16 v[96:99], v[144:147], v[196:199], v[96:99]
	v_mfma_f32_16x16x32_bf16 v[96:99], v[152:155], v[200:203], v[96:99]
	v_mfma_f32_16x16x32_bf16 v[88:91], v[156:159], v[196:199], v[88:91]
	v_mfma_f32_16x16x32_bf16 v[88:91], v[160:163], v[200:203], v[88:91]
	v_mfma_f32_16x16x32_bf16 v[80:83], v[144:147], v[204:207], v[80:83]
	v_mfma_f32_16x16x32_bf16 v[80:83], v[152:155], v[208:211], v[80:83]
	v_mfma_f32_16x16x32_bf16 v[72:75], v[156:159], v[204:207], v[72:75]
	v_mfma_f32_16x16x32_bf16 v[72:75], v[160:163], v[208:211], v[72:75]
	v_mfma_f32_16x16x32_bf16 v[116:119], v[164:167], v[180:183], v[116:119]
	v_mfma_f32_16x16x32_bf16 v[116:119], v[168:171], v[184:187], v[116:119]
	v_mfma_f32_16x16x32_bf16 v[108:111], v[172:175], v[180:183], v[108:111]
	v_mfma_f32_16x16x32_bf16 v[108:111], v[176:179], v[184:187], v[108:111]
	v_mfma_f32_16x16x32_bf16 v[100:103], v[164:167], v[188:191], v[100:103]
	v_mfma_f32_16x16x32_bf16 v[100:103], v[168:171], v[192:195], v[100:103]
	v_mfma_f32_16x16x32_bf16 v[92:95], v[172:175], v[188:191], v[92:95]
	v_mfma_f32_16x16x32_bf16 v[92:95], v[176:179], v[192:195], v[92:95]
	v_mfma_f32_16x16x32_bf16 v[84:87], v[164:167], v[196:199], v[84:87]
	v_mfma_f32_16x16x32_bf16 v[84:87], v[168:171], v[200:203], v[84:87]
	v_mfma_f32_16x16x32_bf16 v[76:79], v[172:175], v[196:199], v[76:79]
	v_mfma_f32_16x16x32_bf16 v[76:79], v[176:179], v[200:203], v[76:79]
	v_mfma_f32_16x16x32_bf16 v[68:71], v[164:167], v[204:207], v[68:71]
	v_mfma_f32_16x16x32_bf16 v[68:71], v[168:171], v[208:211], v[68:71]
	v_mfma_f32_16x16x32_bf16 v[64:67], v[172:175], v[204:207], v[64:67]
	v_mfma_f32_16x16x32_bf16 v[64:67], v[176:179], v[208:211], v[64:67]
	s_barrier
	s_add_i32 s76, s65, s0
	v_lshl_add_u64 v[212:213], s[10:11], 0, v[134:135]
	s_mov_b32 m0, s76
	ds_read_b128 v[180:183], v143 offset:16384
	ds_read_b128 v[184:187], v143 offset:17408
	ds_read_b128 v[188:191], v143 offset:18432
	ds_read_b128 v[192:195], v143 offset:19456
	ds_read_b128 v[196:199], v143 offset:20480
	ds_read_b128 v[200:203], v143 offset:21504
	ds_read_b128 v[204:207], v143 offset:22528
	ds_read_b128 v[208:211], v143 offset:23552
	global_load_lds_dwordx4 v[212:213], off
	s_add_i32 m0, s76, 0x2000
	s_add_u32 s76, s10, 0x40000
	v_lshl_add_u64 v[214:215], s[10:11], 0, v[136:137]
	s_addc_u32 s77, s11, 0
	s_add_i32 s78, s66, s0
	global_load_lds_dwordx4 v[214:215], off
	v_lshl_add_u64 v[216:217], s[76:77], 0, v[134:135]
	s_mov_b32 m0, s78
	v_lshl_add_u64 v[218:219], s[12:13], 0, v[138:139]
	global_load_lds_dwordx4 v[216:217], off
	v_lshl_add_u64 v[216:217], s[76:77], 0, v[136:137]
	s_add_i32 m0, s78, 0x2000
	s_nop 0
	global_load_lds_dwordx4 v[216:217], off
	v_lshl_add_u64 v[216:217], s[12:13], 0, v[128:129]
	s_mov_b32 m0, s29
	s_nop 0
	global_load_lds_dwordx4 v[216:217], off
	s_mov_b32 m0, s30
	s_nop 0
	global_load_lds_dwordx4 v[218:219], off
	s_waitcnt vmcnt(8)
	s_waitcnt lgkmcnt(0)
	s_barrier
; #define PG8_STAGE(bufoff, gbase, voff) do { _Pragma("unroll") for (int _i = 0; _i < 2; ++_i) \
;         __builtin_amdgcn_global_load_lds((const unsigned*)((const char*)(gbase) + (voff)[_i]), (LAS unsigned*)(lds + (bufoff) + ldsw + _i * 8192), 16, 0, 0); } while (0)
; #define PG8_LDA(dst, b, h) do { _Pragma("unroll") for (int m = 0; m < 4; ++m) _Pragma("unroll") for (int k = 0; k < 2; ++k) dst[m][k] = *(const LAS bf16x8*)(lds + PG8_SA(b, h) + aoff + m * 2048 + k * 1024); } while (0)
; #define PG8_LDB(dst, b, h) do { _Pragma("unroll") for (int n = 0; n < 2; ++n) _Pragma("unroll") for (int k = 0; k < 2; ++k) dst[n][k] = *(const LAS bf16x8*)(lds + PG8_SB(b, h) + boff + n * 2048 + k * 1024); } while (0)
; #define PG8_MMA(ai, bj, At, Bt) do { __builtin_amdgcn_s_setprio(1); _Pragma("unroll") for (int m = 0; m < 4; ++m) _Pragma("unroll") for (int n = 0; n < 2; ++n) _Pragma("unroll") for (int k = 0; k < 2; ++k) \
;         acc[ai][bj][m][n] = __builtin_amdgcn_mfma_f32_16x16x32_bf16(Bt[n][k], At[m][k], acc[ai][bj][m][n], 0, 0, 0); __builtin_amdgcn_s_setprio(0); } while (0)
; #define PG8_WAIT_V(n) asm volatile("s_waitcnt vmcnt(" #n ")" ::: "memory")
; #define PG8_WAIT_L(n) asm volatile("s_waitcnt lgkmcnt(" #n ")" ::: "memory")
; #define PG8_BAR __builtin_amdgcn_s_barrier()
; #define PG8_SCHED __builtin_amdgcn_sched_barrier(0)
; template <class Epi>
; __device__ __forceinline__ void gemm_phase(LAS unsigned char* lds, const Gemm g, const Order& S, const Epi& E, const int wid) {
;     ...
;             PG8_WAIT_V(8); PG8_WAIT_L(0); PG8_BAR; PG8_MMA(1, 0, At, B0); PG8_MMA(1, 1, At, B1); PG8_BAR; PG8_SCHED;
;             PG8_LDB(B0, 1, 0); PG8_LDB(B1, 1, 1); PG8_SCHED; PG8_LDA(At, 1, 0); PG8_STAGE(PG8_SA(0, 1), a2 + hA, voffA);
;             PG8_WAIT_V(8); PG8_WAIT_L(0); PG8_BAR; PG8_MMA(0, 0, At, B0); PG8_MMA(0, 1, At, B1); PG8_BAR; PG8_SCHED;
;             PG8_LDA(At, 1, 1); PG8_STAGE(PG8_SB(1, 0), b3, voffB); PG8_STAGE(PG8_SB(1, 1), b3 + hB, voffB); PG8_STAGE(PG8_SA(1, 0), a3, voffA);
	s_waitcnt lgkmcnt(0)
	v_mfma_f32_16x16x32_bf16 v[60:63], v[144:147], v[180:183], v[60:63]
	v_mfma_f32_16x16x32_bf16 v[60:63], v[152:155], v[184:187], v[60:63]
	v_mfma_f32_16x16x32_bf16 v[56:59], v[156:159], v[180:183], v[56:59]
	v_mfma_f32_16x16x32_bf16 v[56:59], v[160:163], v[184:187], v[56:59]
	v_mfma_f32_16x16x32_bf16 v[48:51], v[144:147], v[188:191], v[48:51]
	v_mfma_f32_16x16x32_bf16 v[48:51], v[152:155], v[192:195], v[48:51]
	v_mfma_f32_16x16x32_bf16 v[40:43], v[156:159], v[188:191], v[40:43]
	v_mfma_f32_16x16x32_bf16 v[40:43], v[160:163], v[192:195], v[40:43]
	v_mfma_f32_16x16x32_bf16 v[32:35], v[144:147], v[196:199], v[32:35]
	v_mfma_f32_16x16x32_bf16 v[32:35], v[152:155], v[200:203], v[32:35]
	v_mfma_f32_16x16x32_bf16 v[24:27], v[156:159], v[196:199], v[24:27]
	v_mfma_f32_16x16x32_bf16 v[24:27], v[160:163], v[200:203], v[24:27]
	v_mfma_f32_16x16x32_bf16 v[16:19], v[144:147], v[204:207], v[16:19]
	v_mfma_f32_16x16x32_bf16 v[16:19], v[152:155], v[208:211], v[16:19]
	v_mfma_f32_16x16x32_bf16 v[8:11], v[156:159], v[204:207], v[8:11]
	v_mfma_f32_16x16x32_bf16 v[8:11], v[160:163], v[208:211], v[8:11]
	v_mfma_f32_16x16x32_bf16 v[52:55], v[164:167], v[180:183], v[52:55]
	v_mfma_f32_16x16x32_bf16 v[52:55], v[168:171], v[184:187], v[52:55]
	v_mfma_f32_16x16x32_bf16 v[44:47], v[172:175], v[180:183], v[44:47]
	v_mfma_f32_16x16x32_bf16 v[44:47], v[176:179], v[184:187], v[44:47]
	v_mfma_f32_16x16x32_bf16 v[36:39], v[164:167], v[188:191], v[36:39]
	v_mfma_f32_16x16x32_bf16 v[36:39], v[168:171], v[192:195], v[36:39]
	v_mfma_f32_16x16x32_bf16 v[28:31], v[172:175], v[188:191], v[28:31]
	v_mfma_f32_16x16x32_bf16 v[28:31], v[176:179], v[192:195], v[28:31]
	v_mfma_f32_16x16x32_bf16 v[20:23], v[164:167], v[196:199], v[20:23]
	v_mfma_f32_16x16x32_bf16 v[20:23], v[168:171], v[200:203], v[20:23]
	v_mfma_f32_16x16x32_bf16 v[12:15], v[172:175], v[196:199], v[12:15]
	v_mfma_f32_16x16x32_bf16 v[12:15], v[176:179], v[200:203], v[12:15]
	v_mfma_f32_16x16x32_bf16 v[4:7], v[164:167], v[204:207], v[4:7]
	v_mfma_f32_16x16x32_bf16 v[4:7], v[168:171], v[208:211], v[4:7]
	v_mfma_f32_16x16x32_bf16 v[0:3], v[172:175], v[204:207], v[0:3]
	v_mfma_f32_16x16x32_bf16 v[0:3], v[176:179], v[208:211], v[0:3]
	s_barrier
	s_add_i32 s76, 0, 0x18000
	s_add_i32 s77, 0, 0x1c000
	v_add_u32_e32 v160, s76, v140
	v_add_u32_e32 v176, s77, v140
	ds_read_b128 v[144:147], v160
	ds_read_b128 v[152:155], v160 offset:1024
	ds_read_b128 v[156:159], v160 offset:2048
	ds_read_b128 v[160:163], v160 offset:3072
	ds_read_b128 v[164:167], v176
	ds_read_b128 v[168:171], v176 offset:1024
	ds_read_b128 v[172:175], v176 offset:2048
	ds_read_b128 v[176:179], v176 offset:3072
	s_add_u32 s12, s12, 0x40000
	s_addc_u32 s13, s13, 0
	s_mov_b32 m0, s31
	v_lshl_add_u64 v[220:221], s[12:13], 0, v[128:129]
	ds_read_b128 v[180:183], v143 offset:32768
	ds_read_b128 v[184:187], v143 offset:33792
	ds_read_b128 v[188:191], v143 offset:34816
	ds_read_b128 v[192:195], v143 offset:35840
	ds_read_b128 v[196:199], v143 offset:36864
	ds_read_b128 v[200:203], v143 offset:37888
	ds_read_b128 v[204:207], v143 offset:38912
	ds_read_b128 v[208:211], v143 offset:39936
	global_load_lds_dwordx4 v[220:221], off
	v_lshl_add_u64 v[220:221], s[12:13], 0, v[138:139]
	s_mov_b32 m0, s33
	s_nop 0
	global_load_lds_dwordx4 v[220:221], off
	s_waitcnt vmcnt(8)
	s_waitcnt lgkmcnt(0)
	s_barrier
	s_waitcnt lgkmcnt(0)
	v_mfma_f32_16x16x32_bf16 v[124:127], v[144:147], v[180:183], v[124:127]
	v_mfma_f32_16x16x32_bf16 v[124:127], v[152:155], v[184:187], v[124:127]
	v_mfma_f32_16x16x32_bf16 v[120:123], v[156:159], v[180:183], v[120:123]
	v_mfma_f32_16x16x32_bf16 v[120:123], v[160:163], v[184:187], v[120:123]
	v_mfma_f32_16x16x32_bf16 v[112:115], v[144:147], v[188:191], v[112:115]
	v_mfma_f32_16x16x32_bf16 v[112:115], v[152:155], v[192:195], v[112:115]
	v_mfma_f32_16x16x32_bf16 v[104:107], v[156:159], v[188:191], v[104:107]
	v_mfma_f32_16x16x32_bf16 v[104:107], v[160:163], v[192:195], v[104:107]
	v_mfma_f32_16x16x32_bf16 v[96:99], v[144:147], v[196:199], v[96:99]
	v_mfma_f32_16x16x32_bf16 v[96:99], v[152:155], v[200:203], v[96:99]
	v_mfma_f32_16x16x32_bf16 v[88:91], v[156:159], v[196:199], v[88:91]
	v_mfma_f32_16x16x32_bf16 v[88:91], v[160:163], v[200:203], v[88:91]
	v_mfma_f32_16x16x32_bf16 v[80:83], v[144:147], v[204:207], v[80:83]
	v_mfma_f32_16x16x32_bf16 v[80:83], v[152:155], v[208:211], v[80:83]
	v_mfma_f32_16x16x32_bf16 v[72:75], v[156:159], v[204:207], v[72:75]
	v_mfma_f32_16x16x32_bf16 v[72:75], v[160:163], v[208:211], v[72:75]
	v_mfma_f32_16x16x32_bf16 v[116:119], v[164:167], v[180:183], v[116:119]
	v_mfma_f32_16x16x32_bf16 v[116:119], v[168:171], v[184:187], v[116:119]
	v_mfma_f32_16x16x32_bf16 v[108:111], v[172:175], v[180:183], v[108:111]
	v_mfma_f32_16x16x32_bf16 v[108:111], v[176:179], v[184:187], v[108:111]
	v_mfma_f32_16x16x32_bf16 v[100:103], v[164:167], v[188:191], v[100:103]
	v_mfma_f32_16x16x32_bf16 v[100:103], v[168:171], v[192:195], v[100:103]
	v_mfma_f32_16x16x32_bf16 v[92:95], v[172:175], v[188:191], v[92:95]
	v_mfma_f32_16x16x32_bf16 v[92:95], v[176:179], v[192:195], v[92:95]
	v_mfma_f32_16x16x32_bf16 v[84:87], v[164:167], v[196:199], v[84:87]
	v_mfma_f32_16x16x32_bf16 v[84:87], v[168:171], v[200:203], v[84:87]
	v_mfma_f32_16x16x32_bf16 v[76:79], v[172:175], v[196:199], v[76:79]
	v_mfma_f32_16x16x32_bf16 v[76:79], v[176:179], v[200:203], v[76:79]
	v_mfma_f32_16x16x32_bf16 v[68:71], v[164:167], v[204:207], v[68:71]
	v_mfma_f32_16x16x32_bf16 v[68:71], v[168:171], v[208:211], v[68:71]
	v_mfma_f32_16x16x32_bf16 v[64:67], v[172:175], v[204:207], v[64:67]
	v_mfma_f32_16x16x32_bf16 v[64:67], v[176:179], v[208:211], v[64:67]
	s_barrier
; #define PG8_STAGE(bufoff, gbase, voff) do { _Pragma("unroll") for (int _i = 0; _i < 2; ++_i) \
;         __builtin_amdgcn_global_load_lds((const unsigned*)((const char*)(gbase) + (voff)[_i]), (LAS unsigned*)(lds + (bufoff) + ldsw + _i * 8192), 16, 0, 0); } while (0)
; #define PG8_LDA(dst, b, h) do { _Pragma("unroll") for (int m = 0; m < 4; ++m) _Pragma("unroll") for (int k = 0; k < 2; ++k) dst[m][k] = *(const LAS bf16x8*)(lds + PG8_SA(b, h) + aoff + m * 2048 + k * 1024); } while (0)
; #define PG8_MMA(ai, bj, At, Bt) do { __builtin_amdgcn_s_setprio(1); _Pragma("unroll") for (int m = 0; m < 4; ++m) _Pragma("unroll") for (int n = 0; n < 2; ++n) _Pragma("unroll") for (int k = 0; k < 2; ++k) \
;         acc[ai][bj][m][n] = __builtin_amdgcn_mfma_f32_16x16x32_bf16(Bt[n][k], At[m][k], acc[ai][bj][m][n], 0, 0, 0); __builtin_amdgcn_s_setprio(0); } while (0)
; #define PG8_WAIT_V(n) asm volatile("s_waitcnt vmcnt(" #n ")" ::: "memory")
; #define PG8_WAIT_L(n) asm volatile("s_waitcnt lgkmcnt(" #n ")" ::: "memory")
; #define PG8_BAR __builtin_amdgcn_s_barrier()
; #define PG8_SCHED __builtin_amdgcn_sched_barrier(0)
; template <class Epi>
; __device__ __forceinline__ void gemm_phase(LAS unsigned char* lds, const Gemm g, const Order& S, const Epi& E, const int wid) {
;     ...
;         for (int t = 0; t < nt; t += 2) {
;     ...
;             PG8_LDA(At, 1, 1); PG8_STAGE(PG8_SB(1, 0), b3, voffB); PG8_STAGE(PG8_SB(1, 1), b3 + hB, voffB); PG8_STAGE(PG8_SA(1, 0), a3, voffA);
;             PG8_WAIT_V(8); PG8_WAIT_L(0); PG8_BAR; PG8_MMA(1, 0, At, B0); PG8_MMA(1, 1, At, B1); PG8_BAR; PG8_SCHED;
	s_add_i32 s12, s76, s0
	v_lshl_add_u64 v[212:213], v[212:213], 0, s[44:45]
	s_mov_b32 m0, s12
	ds_read_b128 v[180:183], v143 offset:49152
	ds_read_b128 v[184:187], v143 offset:50176
	ds_read_b128 v[188:191], v143 offset:51200
	ds_read_b128 v[192:195], v143 offset:52224
	ds_read_b128 v[196:199], v143 offset:53248
	ds_read_b128 v[200:203], v143 offset:54272
	ds_read_b128 v[204:207], v143 offset:55296
	ds_read_b128 v[208:211], v143 offset:56320
	global_load_lds_dwordx4 v[212:213], off
	s_add_i32 m0, s12, 0x2000
	s_add_u32 s10, s10, 0x40080
	v_lshl_add_u64 v[212:213], v[214:215], 0, s[44:45]
	s_addc_u32 s11, s11, 0
	s_add_i32 s12, s77, s0
	global_load_lds_dwordx4 v[212:213], off
	v_lshl_add_u64 v[212:213], s[10:11], 0, v[134:135]
	s_mov_b32 m0, s12
	s_nop 0
	global_load_lds_dwordx4 v[212:213], off
	v_lshl_add_u64 v[212:213], s[10:11], 0, v[136:137]
	s_add_i32 m0, s12, 0x2000
	s_nop 0
	global_load_lds_dwordx4 v[212:213], off
	v_lshl_add_u64 v[212:213], v[216:217], 0, s[44:45]
	s_mov_b32 m0, s63
	s_nop 0
	global_load_lds_dwordx4 v[212:213], off
	v_lshl_add_u64 v[212:213], v[218:219], 0, s[44:45]
	s_mov_b32 m0, s64
	s_nop 0
	global_load_lds_dwordx4 v[212:213], off
	s_waitcnt vmcnt(8)
	s_waitcnt lgkmcnt(0)
	s_barrier
	s_waitcnt lgkmcnt(0)
	v_mfma_f32_16x16x32_bf16 v[60:63], v[144:147], v[180:183], v[60:63]
	v_mfma_f32_16x16x32_bf16 v[60:63], v[152:155], v[184:187], v[60:63]
	v_mfma_f32_16x16x32_bf16 v[56:59], v[156:159], v[180:183], v[56:59]
	v_mfma_f32_16x16x32_bf16 v[56:59], v[160:163], v[184:187], v[56:59]
	v_mfma_f32_16x16x32_bf16 v[48:51], v[144:147], v[188:191], v[48:51]
	v_mfma_f32_16x16x32_bf16 v[48:51], v[152:155], v[192:195], v[48:51]
	v_mfma_f32_16x16x32_bf16 v[40:43], v[156:159], v[188:191], v[40:43]
	v_mfma_f32_16x16x32_bf16 v[40:43], v[160:163], v[192:195], v[40:43]
	v_mfma_f32_16x16x32_bf16 v[32:35], v[144:147], v[196:199], v[32:35]
	v_mfma_f32_16x16x32_bf16 v[32:35], v[152:155], v[200:203], v[32:35]
	v_mfma_f32_16x16x32_bf16 v[24:27], v[156:159], v[196:199], v[24:27]
	v_mfma_f32_16x16x32_bf16 v[24:27], v[160:163], v[200:203], v[24:27]
	v_mfma_f32_16x16x32_bf16 v[16:19], v[144:147], v[204:207], v[16:19]
	v_mfma_f32_16x16x32_bf16 v[16:19], v[152:155], v[208:211], v[16:19]
	v_mfma_f32_16x16x32_bf16 v[8:11], v[156:159], v[204:207], v[8:11]
	v_mfma_f32_16x16x32_bf16 v[8:11], v[160:163], v[208:211], v[8:11]
	v_mfma_f32_16x16x32_bf16 v[52:55], v[164:167], v[180:183], v[52:55]
	v_mfma_f32_16x16x32_bf16 v[52:55], v[168:171], v[184:187], v[52:55]
	v_mfma_f32_16x16x32_bf16 v[44:47], v[172:175], v[180:183], v[44:47]
	v_mfma_f32_16x16x32_bf16 v[44:47], v[176:179], v[184:187], v[44:47]
	v_mfma_f32_16x16x32_bf16 v[36:39], v[164:167], v[188:191], v[36:39]
	v_mfma_f32_16x16x32_bf16 v[36:39], v[168:171], v[192:195], v[36:39]
	v_mfma_f32_16x16x32_bf16 v[28:31], v[172:175], v[188:191], v[28:31]
	v_mfma_f32_16x16x32_bf16 v[28:31], v[176:179], v[192:195], v[28:31]
	v_mfma_f32_16x16x32_bf16 v[20:23], v[164:167], v[196:199], v[20:23]
	v_mfma_f32_16x16x32_bf16 v[20:23], v[168:171], v[200:203], v[20:23]
	v_mfma_f32_16x16x32_bf16 v[12:15], v[172:175], v[196:199], v[12:15]
	v_mfma_f32_16x16x32_bf16 v[12:15], v[176:179], v[200:203], v[12:15]
	v_mfma_f32_16x16x32_bf16 v[4:7], v[164:167], v[204:207], v[4:7]
	v_mfma_f32_16x16x32_bf16 v[4:7], v[168:171], v[208:211], v[4:7]
	v_mfma_f32_16x16x32_bf16 v[0:3], v[172:175], v[204:207], v[0:3]
	v_mfma_f32_16x16x32_bf16 v[0:3], v[176:179], v[208:211], v[0:3]
	s_add_i32 s75, s75, 2
	s_add_u32 s8, s8, 0x100
	s_addc_u32 s9, s9, 0
	s_add_u32 s73, s73, 0x100
	s_addc_u32 s74, s74, 0
	s_cmp_gt_u32 s75, 13
	s_barrier
	s_cbranch_scc0 .LBB0_344
	s_and_b64 vcc, exec, s[94:95]
	s_cbranch_vccz .LBB0_347
	s_barrier

; #define PG8_STAGE(bufoff, gbase, voff) do { _Pragma("unroll") for (int _i = 0; _i < 2; ++_i) \
;         __builtin_amdgcn_global_load_lds((const unsigned*)((const char*)(gbase) + (voff)[_i]), (LAS unsigned*)(lds + (bufoff) + ldsw + _i * 8192), 16, 0, 0); } while (0)
; #define PG8_LDA(dst, b, h) do { _Pragma("unroll") for (int m = 0; m < 4; ++m) _Pragma("unroll") for (int k = 0; k < 2; ++k) dst[m][k] = *(const LAS bf16x8*)(lds + PG8_SA(b, h) + aoff + m * 2048 + k * 1024); } while (0)
; #define PG8_LDB(dst, b, h) do { _Pragma("unroll") for (int n = 0; n < 2; ++n) _Pragma("unroll") for (int k = 0; k < 2; ++k) dst[n][k] = *(const LAS bf16x8*)(lds + PG8_SB(b, h) + boff + n * 2048 + k * 1024); } while (0)
; #define PG8_MMA(ai, bj, At, Bt) do { __builtin_amdgcn_s_setprio(1); _Pragma("unroll") for (int m = 0; m < 4; ++m) _Pragma("unroll") for (int n = 0; n < 2; ++n) _Pragma("unroll") for (int k = 0; k < 2; ++k) \
;         acc[ai][bj][m][n] = __builtin_amdgcn_mfma_f32_16x16x32_bf16(Bt[n][k], At[m][k], acc[ai][bj][m][n], 0, 0, 0); __builtin_amdgcn_s_setprio(0); } while (0)
; #define PG8_WAIT_V(n) asm volatile("s_waitcnt vmcnt(" #n ")" ::: "memory")
; #define PG8_WAIT_L(n) asm volatile("s_waitcnt lgkmcnt(" #n ")" ::: "memory")
; #define PG8_BAR __builtin_amdgcn_s_barrier()
; #define PG8_SCHED __builtin_amdgcn_sched_barrier(0)
; template <class Epi>
; __device__ __forceinline__ void gemm_phase(LAS unsigned char* lds, const Gemm g, const Order& S, const Epi& E, const int wid) {
;     ...
;             const bool last = (t == nt - 2);
;             const char* a1 = cA + (size_t)(t + 1) * kstep;
;             const char* a2 = last ? nA : cA + (size_t)(t + 2) * kstep; const char* b2 = last ? nB : cB + (size_t)(t + 2) * kstep;
;             const char* a3 = a2 + kstep; const char* b3 = b2 + kstep;
;     ...
;             PG8_LDB(B0, 0, 0); PG8_LDB(B1, 0, 1); PG8_SCHED; PG8_LDA(At, 0, 0); PG8_STAGE(PG8_SA(1, 1), a1 + hA, voffA);
;             PG8_WAIT_V(8); PG8_WAIT_L(0); PG8_BAR; PG8_MMA(0, 0, At, B0); PG8_MMA(0, 1, At, B1); PG8_BAR; PG8_SCHED;
;             PG8_LDA(At, 0, 1); PG8_STAGE(PG8_SB(0, 0), b2, voffB); PG8_STAGE(PG8_SB(0, 1), b2 + hB, voffB); PG8_STAGE(PG8_SA(0, 0), a2, voffA);
;             PG8_WAIT_V(8); PG8_WAIT_L(0); PG8_BAR; PG8_MMA(1, 0, At, B0); PG8_MMA(1, 1, At, B1); PG8_BAR; PG8_SCHED;
.LBB0_379:
	ds_read_b128 v[146:149], v141
	ds_read_b128 v[150:153], v141 offset:1024
	ds_read_b128 v[154:157], v141 offset:2048
	ds_read_b128 v[158:161], v141 offset:3072
	ds_read_b128 v[162:165], v144
	ds_read_b128 v[166:169], v144 offset:1024
	ds_read_b128 v[170:173], v144 offset:2048
	ds_read_b128 v[174:177], v144 offset:3072
	s_add_u32 s44, s42, 0xfffe0080
	s_addc_u32 s45, s43, -1
	s_cmp_eq_u32 s63, 4
	s_cselect_b32 s47, s13, s45
	s_cselect_b32 s46, s59, s44
	s_cselect_b32 s45, s21, s62
	s_cselect_b32 s44, s60, s61
	v_lshl_add_u64 v[210:211], s[42:43], 0, v[128:129]
	s_add_i32 m0, s22, 0xc000
	ds_read_b128 v[178:181], v145
	ds_read_b128 v[182:185], v145 offset:1024
	ds_read_b128 v[186:189], v145 offset:2048
	ds_read_b128 v[190:193], v145 offset:3072
	ds_read_b128 v[194:197], v145 offset:4096
	ds_read_b128 v[198:201], v145 offset:5120
	ds_read_b128 v[202:205], v145 offset:6144
	ds_read_b128 v[206:209], v145 offset:7168
	global_load_lds_dwordx4 v[210:211], off
	v_lshl_add_u64 v[210:211], s[42:43], 0, v[138:139]
	s_add_i32 m0, s22, 0xe000
	s_nop 0
	global_load_lds_dwordx4 v[210:211], off
	s_waitcnt vmcnt(8)
	s_waitcnt lgkmcnt(0)
	s_barrier
	s_waitcnt lgkmcnt(0)
	v_mfma_f32_16x16x32_bf16 v[124:127], v[146:149], v[178:181], v[124:127]
	v_mfma_f32_16x16x32_bf16 v[124:127], v[150:153], v[182:185], v[124:127]
	v_mfma_f32_16x16x32_bf16 v[120:123], v[154:157], v[178:181], v[120:123]
	v_mfma_f32_16x16x32_bf16 v[120:123], v[158:161], v[182:185], v[120:123]
	v_mfma_f32_16x16x32_bf16 v[108:111], v[146:149], v[186:189], v[108:111]
	v_mfma_f32_16x16x32_bf16 v[108:111], v[150:153], v[190:193], v[108:111]
	v_mfma_f32_16x16x32_bf16 v[104:107], v[154:157], v[186:189], v[104:107]
	v_mfma_f32_16x16x32_bf16 v[104:107], v[158:161], v[190:193], v[104:107]
	v_mfma_f32_16x16x32_bf16 v[92:95], v[146:149], v[194:197], v[92:95]
	v_mfma_f32_16x16x32_bf16 v[92:95], v[150:153], v[198:201], v[92:95]
	v_mfma_f32_16x16x32_bf16 v[88:91], v[154:157], v[194:197], v[88:91]
	v_mfma_f32_16x16x32_bf16 v[88:91], v[158:161], v[198:201], v[88:91]
	v_mfma_f32_16x16x32_bf16 v[76:79], v[146:149], v[202:205], v[76:79]
	v_mfma_f32_16x16x32_bf16 v[76:79], v[150:153], v[206:209], v[76:79]
	v_mfma_f32_16x16x32_bf16 v[72:75], v[154:157], v[202:205], v[72:75]
	v_mfma_f32_16x16x32_bf16 v[72:75], v[158:161], v[206:209], v[72:75]
	v_mfma_f32_16x16x32_bf16 v[116:119], v[162:165], v[178:181], v[116:119]
	v_mfma_f32_16x16x32_bf16 v[116:119], v[166:169], v[182:185], v[116:119]
	v_mfma_f32_16x16x32_bf16 v[112:115], v[170:173], v[178:181], v[112:115]
	v_mfma_f32_16x16x32_bf16 v[112:115], v[174:177], v[182:185], v[112:115]
	v_mfma_f32_16x16x32_bf16 v[100:103], v[162:165], v[186:189], v[100:103]
	v_mfma_f32_16x16x32_bf16 v[100:103], v[166:169], v[190:193], v[100:103]
	v_mfma_f32_16x16x32_bf16 v[96:99], v[170:173], v[186:189], v[96:99]
	v_mfma_f32_16x16x32_bf16 v[96:99], v[174:177], v[190:193], v[96:99]
	v_mfma_f32_16x16x32_bf16 v[84:87], v[162:165], v[194:197], v[84:87]
	v_mfma_f32_16x16x32_bf16 v[84:87], v[166:169], v[198:201], v[84:87]
	v_mfma_f32_16x16x32_bf16 v[80:83], v[170:173], v[194:197], v[80:83]
	v_mfma_f32_16x16x32_bf16 v[80:83], v[174:177], v[198:201], v[80:83]
	v_mfma_f32_16x16x32_bf16 v[68:71], v[162:165], v[202:205], v[68:71]
	v_mfma_f32_16x16x32_bf16 v[68:71], v[166:169], v[206:209], v[68:71]
	v_mfma_f32_16x16x32_bf16 v[64:67], v[170:173], v[202:205], v[64:67]
	v_mfma_f32_16x16x32_bf16 v[64:67], v[174:177], v[206:209], v[64:67]
	s_barrier
	s_add_i32 s64, s56, s0
	v_lshl_add_u64 v[210:211], s[44:45], 0, v[134:135]
	s_mov_b32 m0, s64
	ds_read_b128 v[178:181], v145 offset:16384
	ds_read_b128 v[182:185], v145 offset:17408
	ds_read_b128 v[186:189], v145 offset:18432
	ds_read_b128 v[190:193], v145 offset:19456
	ds_read_b128 v[194:197], v145 offset:20480
	ds_read_b128 v[198:201], v145 offset:21504
	ds_read_b128 v[202:205], v145 offset:22528
	ds_read_b128 v[206:209], v145 offset:23552
	global_load_lds_dwordx4 v[210:211], off
	s_add_i32 m0, s64, 0x2000
	s_add_u32 s64, s44, 0x20000
	v_lshl_add_u64 v[212:213], s[44:45], 0, v[136:137]
	s_addc_u32 s65, s45, 0
	s_add_i32 s66, s57, s0
	global_load_lds_dwordx4 v[212:213], off
	v_lshl_add_u64 v[214:215], s[64:65], 0, v[134:135]
	s_mov_b32 m0, s66
	v_lshl_add_u64 v[216:217], s[46:47], 0, v[138:139]
	global_load_lds_dwordx4 v[214:215], off
	v_lshl_add_u64 v[214:215], s[64:65], 0, v[136:137]
	s_add_i32 m0, s66, 0x2000
	s_nop 0
	global_load_lds_dwordx4 v[214:215], off
	v_lshl_add_u64 v[214:215], s[46:47], 0, v[128:129]
	s_mov_b32 m0, s22
	s_nop 0
	global_load_lds_dwordx4 v[214:215], off
	s_mov_b32 m0, s23
	s_nop 0
	global_load_lds_dwordx4 v[216:217], off
	s_waitcnt vmcnt(8)
	s_waitcnt lgkmcnt(0)
	s_barrier
; #define PG8_STAGE(bufoff, gbase, voff) do { _Pragma("unroll") for (int _i = 0; _i < 2; ++_i) \
;         __builtin_amdgcn_global_load_lds((const unsigned*)((const char*)(gbase) + (voff)[_i]), (LAS unsigned*)(lds + (bufoff) + ldsw + _i * 8192), 16, 0, 0); } while (0)
; #define PG8_LDA(dst, b, h) do { _Pragma("unroll") for (int m = 0; m < 4; ++m) _Pragma("unroll") for (int k = 0; k < 2; ++k) dst[m][k] = *(const LAS bf16x8*)(lds + PG8_SA(b, h) + aoff + m * 2048 + k * 1024); } while (0)
; #define PG8_LDB(dst, b, h) do { _Pragma("unroll") for (int n = 0; n < 2; ++n) _Pragma("unroll") for (int k = 0; k < 2; ++k) dst[n][k] = *(const LAS bf16x8*)(lds + PG8_SB(b, h) + boff + n * 2048 + k * 1024); } while (0)
; #define PG8_MMA(ai, bj, At, Bt) do { __builtin_amdgcn_s_setprio(1); _Pragma("unroll") for (int m = 0; m < 4; ++m) _Pragma("unroll") for (int n = 0; n < 2; ++n) _Pragma("unroll") for (int k = 0; k < 2; ++k) \
;         acc[ai][bj][m][n] = __builtin_amdgcn_mfma_f32_16x16x32_bf16(Bt[n][k], At[m][k], acc[ai][bj][m][n], 0, 0, 0); __builtin_amdgcn_s_setprio(0); } while (0)
; #define PG8_WAIT_V(n) asm volatile("s_waitcnt vmcnt(" #n ")" ::: "memory")
; #define PG8_WAIT_L(n) asm volatile("s_waitcnt lgkmcnt(" #n ")" ::: "memory")
; #define PG8_BAR __builtin_amdgcn_s_barrier()
; #define PG8_SCHED __builtin_amdgcn_sched_barrier(0)
; template <class Epi>
; __device__ __forceinline__ void gemm_phase(LAS unsigned char* lds, const Gemm g, const Order& S, const Epi& E, const int wid) {
;     ...
;             PG8_WAIT_V(8); PG8_WAIT_L(0); PG8_BAR; PG8_MMA(1, 0, At, B0); PG8_MMA(1, 1, At, B1); PG8_BAR; PG8_SCHED;
;             PG8_LDB(B0, 1, 0); PG8_LDB(B1, 1, 1); PG8_SCHED; PG8_LDA(At, 1, 0); PG8_STAGE(PG8_SA(0, 1), a2 + hA, voffA);
;             PG8_WAIT_V(8); PG8_WAIT_L(0); PG8_BAR; PG8_MMA(0, 0, At, B0); PG8_MMA(0, 1, At, B1); PG8_BAR; PG8_SCHED;
;             PG8_LDA(At, 1, 1); PG8_STAGE(PG8_SB(1, 0), b3, voffB); PG8_STAGE(PG8_SB(1, 1), b3 + hB, voffB); PG8_STAGE(PG8_SA(1, 0), a3, voffA);
	s_waitcnt lgkmcnt(0)
	v_mfma_f32_16x16x32_bf16 v[60:63], v[146:149], v[178:181], v[60:63]
	v_mfma_f32_16x16x32_bf16 v[60:63], v[150:153], v[182:185], v[60:63]
	v_mfma_f32_16x16x32_bf16 v[56:59], v[154:157], v[178:181], v[56:59]
	v_mfma_f32_16x16x32_bf16 v[56:59], v[158:161], v[182:185], v[56:59]
	v_mfma_f32_16x16x32_bf16 v[44:47], v[146:149], v[186:189], v[44:47]
	v_mfma_f32_16x16x32_bf16 v[44:47], v[150:153], v[190:193], v[44:47]
	v_mfma_f32_16x16x32_bf16 v[40:43], v[154:157], v[186:189], v[40:43]
	v_mfma_f32_16x16x32_bf16 v[40:43], v[158:161], v[190:193], v[40:43]
	v_mfma_f32_16x16x32_bf16 v[28:31], v[146:149], v[194:197], v[28:31]
	v_mfma_f32_16x16x32_bf16 v[28:31], v[150:153], v[198:201], v[28:31]
	v_mfma_f32_16x16x32_bf16 v[24:27], v[154:157], v[194:197], v[24:27]
	v_mfma_f32_16x16x32_bf16 v[24:27], v[158:161], v[198:201], v[24:27]
	v_mfma_f32_16x16x32_bf16 v[12:15], v[146:149], v[202:205], v[12:15]
	v_mfma_f32_16x16x32_bf16 v[12:15], v[150:153], v[206:209], v[12:15]
	v_mfma_f32_16x16x32_bf16 v[8:11], v[154:157], v[202:205], v[8:11]
	v_mfma_f32_16x16x32_bf16 v[8:11], v[158:161], v[206:209], v[8:11]
	v_mfma_f32_16x16x32_bf16 v[52:55], v[162:165], v[178:181], v[52:55]
	v_mfma_f32_16x16x32_bf16 v[52:55], v[166:169], v[182:185], v[52:55]
	v_mfma_f32_16x16x32_bf16 v[48:51], v[170:173], v[178:181], v[48:51]
	v_mfma_f32_16x16x32_bf16 v[48:51], v[174:177], v[182:185], v[48:51]
	v_mfma_f32_16x16x32_bf16 v[36:39], v[162:165], v[186:189], v[36:39]
	v_mfma_f32_16x16x32_bf16 v[36:39], v[166:169], v[190:193], v[36:39]
	v_mfma_f32_16x16x32_bf16 v[32:35], v[170:173], v[186:189], v[32:35]
	v_mfma_f32_16x16x32_bf16 v[32:35], v[174:177], v[190:193], v[32:35]
	v_mfma_f32_16x16x32_bf16 v[20:23], v[162:165], v[194:197], v[20:23]
	v_mfma_f32_16x16x32_bf16 v[20:23], v[166:169], v[198:201], v[20:23]
	v_mfma_f32_16x16x32_bf16 v[16:19], v[170:173], v[194:197], v[16:19]
	v_mfma_f32_16x16x32_bf16 v[16:19], v[174:177], v[198:201], v[16:19]
	v_mfma_f32_16x16x32_bf16 v[4:7], v[162:165], v[202:205], v[4:7]
	v_mfma_f32_16x16x32_bf16 v[4:7], v[166:169], v[206:209], v[4:7]
	v_mfma_f32_16x16x32_bf16 v[0:3], v[170:173], v[202:205], v[0:3]
	v_mfma_f32_16x16x32_bf16 v[0:3], v[174:177], v[206:209], v[0:3]
	s_barrier
	s_add_i32 s64, 0, 0x18000
	s_add_i32 s65, 0, 0x1c000
	v_add_u32_e32 v158, s64, v140
	v_add_u32_e32 v174, s65, v140
	ds_read_b128 v[146:149], v158
	ds_read_b128 v[150:153], v158 offset:1024
	ds_read_b128 v[154:157], v158 offset:2048
	ds_read_b128 v[158:161], v158 offset:3072
	ds_read_b128 v[162:165], v174
	ds_read_b128 v[166:169], v174 offset:1024
	ds_read_b128 v[170:173], v174 offset:2048
	ds_read_b128 v[174:177], v174 offset:3072
	s_add_u32 s46, s46, 0x20000
	s_addc_u32 s47, s47, 0
	s_mov_b32 m0, s29
	v_lshl_add_u64 v[218:219], s[46:47], 0, v[128:129]
	ds_read_b128 v[178:181], v145 offset:32768
	ds_read_b128 v[182:185], v145 offset:33792
	ds_read_b128 v[186:189], v145 offset:34816
	ds_read_b128 v[190:193], v145 offset:35840
	ds_read_b128 v[194:197], v145 offset:36864
	ds_read_b128 v[198:201], v145 offset:37888
	ds_read_b128 v[202:205], v145 offset:38912
	ds_read_b128 v[206:209], v145 offset:39936
	global_load_lds_dwordx4 v[218:219], off
	v_lshl_add_u64 v[218:219], s[46:47], 0, v[138:139]
	s_mov_b32 m0, s30
	s_nop 0
	global_load_lds_dwordx4 v[218:219], off
	s_waitcnt vmcnt(8)
	s_waitcnt lgkmcnt(0)
	s_barrier
	s_waitcnt lgkmcnt(0)
	v_mfma_f32_16x16x32_bf16 v[124:127], v[146:149], v[178:181], v[124:127]
	v_mfma_f32_16x16x32_bf16 v[124:127], v[150:153], v[182:185], v[124:127]
	v_mfma_f32_16x16x32_bf16 v[120:123], v[154:157], v[178:181], v[120:123]
	v_mfma_f32_16x16x32_bf16 v[120:123], v[158:161], v[182:185], v[120:123]
	v_mfma_f32_16x16x32_bf16 v[108:111], v[146:149], v[186:189], v[108:111]
	v_mfma_f32_16x16x32_bf16 v[108:111], v[150:153], v[190:193], v[108:111]
	v_mfma_f32_16x16x32_bf16 v[104:107], v[154:157], v[186:189], v[104:107]
	v_mfma_f32_16x16x32_bf16 v[104:107], v[158:161], v[190:193], v[104:107]
	v_mfma_f32_16x16x32_bf16 v[92:95], v[146:149], v[194:197], v[92:95]
	v_mfma_f32_16x16x32_bf16 v[92:95], v[150:153], v[198:201], v[92:95]
	v_mfma_f32_16x16x32_bf16 v[88:91], v[154:157], v[194:197], v[88:91]
	v_mfma_f32_16x16x32_bf16 v[88:91], v[158:161], v[198:201], v[88:91]
	v_mfma_f32_16x16x32_bf16 v[76:79], v[146:149], v[202:205], v[76:79]
	v_mfma_f32_16x16x32_bf16 v[76:79], v[150:153], v[206:209], v[76:79]
	v_mfma_f32_16x16x32_bf16 v[72:75], v[154:157], v[202:205], v[72:75]
	v_mfma_f32_16x16x32_bf16 v[72:75], v[158:161], v[206:209], v[72:75]
	v_mfma_f32_16x16x32_bf16 v[116:119], v[162:165], v[178:181], v[116:119]
	v_mfma_f32_16x16x32_bf16 v[116:119], v[166:169], v[182:185], v[116:119]
	v_mfma_f32_16x16x32_bf16 v[112:115], v[170:173], v[178:181], v[112:115]
	v_mfma_f32_16x16x32_bf16 v[112:115], v[174:177], v[182:185], v[112:115]
	v_mfma_f32_16x16x32_bf16 v[100:103], v[162:165], v[186:189], v[100:103]
	v_mfma_f32_16x16x32_bf16 v[100:103], v[166:169], v[190:193], v[100:103]
	v_mfma_f32_16x16x32_bf16 v[96:99], v[170:173], v[186:189], v[96:99]
	v_mfma_f32_16x16x32_bf16 v[96:99], v[174:177], v[190:193], v[96:99]
	v_mfma_f32_16x16x32_bf16 v[84:87], v[162:165], v[194:197], v[84:87]
	v_mfma_f32_16x16x32_bf16 v[84:87], v[166:169], v[198:201], v[84:87]
	v_mfma_f32_16x16x32_bf16 v[80:83], v[170:173], v[194:197], v[80:83]
	v_mfma_f32_16x16x32_bf16 v[80:83], v[174:177], v[198:201], v[80:83]
	v_mfma_f32_16x16x32_bf16 v[68:71], v[162:165], v[202:205], v[68:71]
	v_mfma_f32_16x16x32_bf16 v[68:71], v[166:169], v[206:209], v[68:71]
	v_mfma_f32_16x16x32_bf16 v[64:67], v[170:173], v[202:205], v[64:67]
	v_mfma_f32_16x16x32_bf16 v[64:67], v[174:177], v[206:209], v[64:67]
	s_barrier
; #define PG8_STAGE(bufoff, gbase, voff) do { _Pragma("unroll") for (int _i = 0; _i < 2; ++_i) \
;         __builtin_amdgcn_global_load_lds((const unsigned*)((const char*)(gbase) + (voff)[_i]), (LAS unsigned*)(lds + (bufoff) + ldsw + _i * 8192), 16, 0, 0); } while (0)
; #define PG8_LDA(dst, b, h) do { _Pragma("unroll") for (int m = 0; m < 4; ++m) _Pragma("unroll") for (int k = 0; k < 2; ++k) dst[m][k] = *(const LAS bf16x8*)(lds + PG8_SA(b, h) + aoff + m * 2048 + k * 1024); } while (0)
; #define PG8_MMA(ai, bj, At, Bt) do { __builtin_amdgcn_s_setprio(1); _Pragma("unroll") for (int m = 0; m < 4; ++m) _Pragma("unroll") for (int n = 0; n < 2; ++n) _Pragma("unroll") for (int k = 0; k < 2; ++k) \
;         acc[ai][bj][m][n] = __builtin_amdgcn_mfma_f32_16x16x32_bf16(Bt[n][k], At[m][k], acc[ai][bj][m][n], 0, 0, 0); __builtin_amdgcn_s_setprio(0); } while (0)
; #define PG8_WAIT_V(n) asm volatile("s_waitcnt vmcnt(" #n ")" ::: "memory")
; #define PG8_WAIT_L(n) asm volatile("s_waitcnt lgkmcnt(" #n ")" ::: "memory")
; #define PG8_BAR __builtin_amdgcn_s_barrier()
; #define PG8_SCHED __builtin_amdgcn_sched_barrier(0)
; template <class Epi>
; __device__ __forceinline__ void gemm_phase(LAS unsigned char* lds, const Gemm g, const Order& S, const Epi& E, const int wid) {
;     ...
;         for (int t = 0; t < nt; t += 2) {
;     ...
;             PG8_LDA(At, 1, 1); PG8_STAGE(PG8_SB(1, 0), b3, voffB); PG8_STAGE(PG8_SB(1, 1), b3 + hB, voffB); PG8_STAGE(PG8_SA(1, 0), a3, voffA);
;             PG8_WAIT_V(8); PG8_WAIT_L(0); PG8_BAR; PG8_MMA(1, 0, At, B0); PG8_MMA(1, 1, At, B1); PG8_BAR; PG8_SCHED;
	s_add_i32 s46, s64, s0
	v_lshl_add_u64 v[210:211], v[210:211], 0, s[10:11]
	s_mov_b32 m0, s46
	ds_read_b128 v[178:181], v145 offset:49152
	ds_read_b128 v[182:185], v145 offset:50176
	ds_read_b128 v[186:189], v145 offset:51200
	ds_read_b128 v[190:193], v145 offset:52224
	ds_read_b128 v[194:197], v145 offset:53248
	ds_read_b128 v[198:201], v145 offset:54272
	ds_read_b128 v[202:205], v145 offset:55296
	ds_read_b128 v[206:209], v145 offset:56320
	global_load_lds_dwordx4 v[210:211], off
	s_add_i32 m0, s46, 0x2000
	s_add_u32 s44, s44, 0x20080
	v_lshl_add_u64 v[210:211], v[212:213], 0, s[10:11]
	s_addc_u32 s45, s45, 0
	s_add_i32 s46, s65, s0
	global_load_lds_dwordx4 v[210:211], off
	v_lshl_add_u64 v[210:211], s[44:45], 0, v[134:135]
	s_mov_b32 m0, s46
	s_nop 0
	global_load_lds_dwordx4 v[210:211], off
	v_lshl_add_u64 v[210:211], s[44:45], 0, v[136:137]
	s_add_i32 m0, s46, 0x2000
	s_nop 0
	global_load_lds_dwordx4 v[210:211], off
	v_lshl_add_u64 v[210:211], v[214:215], 0, s[10:11]
	s_mov_b32 m0, s51
	s_nop 0
	global_load_lds_dwordx4 v[210:211], off
	v_lshl_add_u64 v[210:211], v[216:217], 0, s[10:11]
	s_mov_b32 m0, s54
	s_nop 0
	global_load_lds_dwordx4 v[210:211], off
	s_waitcnt vmcnt(8)
	s_waitcnt lgkmcnt(0)
	s_barrier
	s_waitcnt lgkmcnt(0)
	v_mfma_f32_16x16x32_bf16 v[60:63], v[146:149], v[178:181], v[60:63]
	v_mfma_f32_16x16x32_bf16 v[60:63], v[150:153], v[182:185], v[60:63]
	v_mfma_f32_16x16x32_bf16 v[56:59], v[154:157], v[178:181], v[56:59]
	v_mfma_f32_16x16x32_bf16 v[56:59], v[158:161], v[182:185], v[56:59]
	v_mfma_f32_16x16x32_bf16 v[44:47], v[146:149], v[186:189], v[44:47]
	v_mfma_f32_16x16x32_bf16 v[44:47], v[150:153], v[190:193], v[44:47]
	v_mfma_f32_16x16x32_bf16 v[40:43], v[154:157], v[186:189], v[40:43]
	v_mfma_f32_16x16x32_bf16 v[40:43], v[158:161], v[190:193], v[40:43]
	v_mfma_f32_16x16x32_bf16 v[28:31], v[146:149], v[194:197], v[28:31]
	v_mfma_f32_16x16x32_bf16 v[28:31], v[150:153], v[198:201], v[28:31]
	v_mfma_f32_16x16x32_bf16 v[24:27], v[154:157], v[194:197], v[24:27]
	v_mfma_f32_16x16x32_bf16 v[24:27], v[158:161], v[198:201], v[24:27]
	v_mfma_f32_16x16x32_bf16 v[12:15], v[146:149], v[202:205], v[12:15]
	v_mfma_f32_16x16x32_bf16 v[12:15], v[150:153], v[206:209], v[12:15]
	v_mfma_f32_16x16x32_bf16 v[8:11], v[154:157], v[202:205], v[8:11]
	v_mfma_f32_16x16x32_bf16 v[8:11], v[158:161], v[206:209], v[8:11]
	v_mfma_f32_16x16x32_bf16 v[52:55], v[162:165], v[178:181], v[52:55]
	v_mfma_f32_16x16x32_bf16 v[52:55], v[166:169], v[182:185], v[52:55]
	v_mfma_f32_16x16x32_bf16 v[48:51], v[170:173], v[178:181], v[48:51]
	v_mfma_f32_16x16x32_bf16 v[48:51], v[174:177], v[182:185], v[48:51]
	v_mfma_f32_16x16x32_bf16 v[36:39], v[162:165], v[186:189], v[36:39]
	v_mfma_f32_16x16x32_bf16 v[36:39], v[166:169], v[190:193], v[36:39]
	v_mfma_f32_16x16x32_bf16 v[32:35], v[170:173], v[186:189], v[32:35]
	v_mfma_f32_16x16x32_bf16 v[32:35], v[174:177], v[190:193], v[32:35]
	v_mfma_f32_16x16x32_bf16 v[20:23], v[162:165], v[194:197], v[20:23]
	v_mfma_f32_16x16x32_bf16 v[20:23], v[166:169], v[198:201], v[20:23]
	v_mfma_f32_16x16x32_bf16 v[16:19], v[170:173], v[194:197], v[16:19]
	v_mfma_f32_16x16x32_bf16 v[16:19], v[174:177], v[198:201], v[16:19]
	v_mfma_f32_16x16x32_bf16 v[4:7], v[162:165], v[202:205], v[4:7]
	v_mfma_f32_16x16x32_bf16 v[4:7], v[166:169], v[206:209], v[4:7]
	v_mfma_f32_16x16x32_bf16 v[0:3], v[170:173], v[202:205], v[0:3]
	v_mfma_f32_16x16x32_bf16 v[0:3], v[174:177], v[206:209], v[0:3]
	s_add_i32 s63, s63, 2
	s_add_u32 s42, s42, 0x100
	s_addc_u32 s43, s43, 0
	s_add_u32 s61, s61, 0x100
	s_addc_u32 s62, s62, 0
	s_cmp_gt_u32 s63, 5
	s_barrier
	s_cbranch_scc0 .LBB0_379
	s_and_b64 vcc, exec, s[94:95]
	s_cbranch_vccz .LBB0_382
	s_barrier

; #define PG8_STAGE(bufoff, gbase, voff) do { _Pragma("unroll") for (int _i = 0; _i < 2; ++_i) \
;         __builtin_amdgcn_global_load_lds((const unsigned*)((const char*)(gbase) + (voff)[_i]), (LAS unsigned*)(lds + (bufoff) + ldsw + _i * 8192), 16, 0, 0); } while (0)
; #define PG8_LDA(dst, b, h) do { _Pragma("unroll") for (int m = 0; m < 4; ++m) _Pragma("unroll") for (int k = 0; k < 2; ++k) dst[m][k] = *(const LAS bf16x8*)(lds + PG8_SA(b, h) + aoff + m * 2048 + k * 1024); } while (0)
; #define PG8_LDB(dst, b, h) do { _Pragma("unroll") for (int n = 0; n < 2; ++n) _Pragma("unroll") for (int k = 0; k < 2; ++k) dst[n][k] = *(const LAS bf16x8*)(lds + PG8_SB(b, h) + boff + n * 2048 + k * 1024); } while (0)
; #define PG8_MMA(ai, bj, At, Bt) do { __builtin_amdgcn_s_setprio(1); _Pragma("unroll") for (int m = 0; m < 4; ++m) _Pragma("unroll") for (int n = 0; n < 2; ++n) _Pragma("unroll") for (int k = 0; k < 2; ++k) \
;         acc[ai][bj][m][n] = __builtin_amdgcn_mfma_f32_16x16x32_bf16(Bt[n][k], At[m][k], acc[ai][bj][m][n], 0, 0, 0); __builtin_amdgcn_s_setprio(0); } while (0)
; #define PG8_WAIT_V(n) asm volatile("s_waitcnt vmcnt(" #n ")" ::: "memory")
; #define PG8_WAIT_L(n) asm volatile("s_waitcnt lgkmcnt(" #n ")" ::: "memory")
; #define PG8_BAR __builtin_amdgcn_s_barrier()
; #define PG8_SCHED __builtin_amdgcn_sched_barrier(0)
; template <class Epi>
; __device__ __forceinline__ void gemm_phase(LAS unsigned char* lds, const Gemm g, const Order& S, const Epi& E, const int wid) {
;     ...
;             const bool last = (t == nt - 2);
;             const char* a1 = cA + (size_t)(t + 1) * kstep;
;             const char* a2 = last ? nA : cA + (size_t)(t + 2) * kstep; const char* b2 = last ? nB : cB + (size_t)(t + 2) * kstep;
;             const char* a3 = a2 + kstep; const char* b3 = b2 + kstep;
;     ...
;             PG8_LDB(B0, 0, 0); PG8_LDB(B1, 0, 1); PG8_SCHED; PG8_LDA(At, 0, 0); PG8_STAGE(PG8_SA(1, 1), a1 + hA, voffA);
;             PG8_WAIT_V(8); PG8_WAIT_L(0); PG8_BAR; PG8_MMA(0, 0, At, B0); PG8_MMA(0, 1, At, B1); PG8_BAR; PG8_SCHED;
;             PG8_LDA(At, 0, 1); PG8_STAGE(PG8_SB(0, 0), b2, voffB); PG8_STAGE(PG8_SB(0, 1), b2 + hB, voffB); PG8_STAGE(PG8_SA(0, 0), a2, voffA);
;             PG8_WAIT_V(8); PG8_WAIT_L(0); PG8_BAR; PG8_MMA(1, 0, At, B0); PG8_MMA(1, 1, At, B1); PG8_BAR; PG8_SCHED;
.LBB0_581:
	ds_read_b128 v[146:149], v142
	ds_read_b128 v[150:153], v142 offset:1024
	ds_read_b128 v[154:157], v142 offset:2048
	ds_read_b128 v[158:161], v142 offset:3072
	ds_read_b128 v[162:165], v143
	ds_read_b128 v[166:169], v143 offset:1024
	ds_read_b128 v[170:173], v143 offset:2048
	ds_read_b128 v[174:177], v143 offset:3072
	s_add_u32 s38, s36, 0xfff80080
	s_addc_u32 s39, s37, -1
	s_cmp_eq_u32 s58, 28
	s_cselect_b32 s41, s5, s39
	s_cselect_b32 s40, s4, s38
	s_cselect_b32 s39, s21, s19
	s_cselect_b32 s38, s20, s17
	v_lshl_add_u64 v[210:211], s[36:37], 0, v[128:129]
	s_add_i32 m0, s26, 0xc000
	ds_read_b128 v[178:181], v144
	ds_read_b128 v[182:185], v144 offset:1024
	ds_read_b128 v[186:189], v144 offset:2048
	ds_read_b128 v[190:193], v144 offset:3072
	ds_read_b128 v[194:197], v144 offset:4096
	ds_read_b128 v[198:201], v144 offset:5120
	ds_read_b128 v[202:205], v144 offset:6144
	ds_read_b128 v[206:209], v144 offset:7168
	global_load_lds_dwordx4 v[210:211], off
	v_lshl_add_u64 v[210:211], s[36:37], 0, v[138:139]
	s_add_i32 m0, s26, 0xe000
	s_nop 0
	global_load_lds_dwordx4 v[210:211], off
	s_waitcnt vmcnt(8)
	s_waitcnt lgkmcnt(0)
	s_barrier
	s_waitcnt lgkmcnt(0)
	v_mfma_f32_16x16x32_bf16 v[124:127], v[146:149], v[178:181], v[124:127]
	v_mfma_f32_16x16x32_bf16 v[124:127], v[150:153], v[182:185], v[124:127]
	v_mfma_f32_16x16x32_bf16 v[120:123], v[154:157], v[178:181], v[120:123]
	v_mfma_f32_16x16x32_bf16 v[120:123], v[158:161], v[182:185], v[120:123]
	v_mfma_f32_16x16x32_bf16 v[116:119], v[146:149], v[186:189], v[116:119]
	v_mfma_f32_16x16x32_bf16 v[116:119], v[150:153], v[190:193], v[116:119]
	v_mfma_f32_16x16x32_bf16 v[112:115], v[154:157], v[186:189], v[112:115]
	v_mfma_f32_16x16x32_bf16 v[112:115], v[158:161], v[190:193], v[112:115]
	v_mfma_f32_16x16x32_bf16 v[100:103], v[146:149], v[194:197], v[100:103]
	v_mfma_f32_16x16x32_bf16 v[100:103], v[150:153], v[198:201], v[100:103]
	v_mfma_f32_16x16x32_bf16 v[96:99], v[154:157], v[194:197], v[96:99]
	v_mfma_f32_16x16x32_bf16 v[96:99], v[158:161], v[198:201], v[96:99]
	v_mfma_f32_16x16x32_bf16 v[84:87], v[146:149], v[202:205], v[84:87]
	v_mfma_f32_16x16x32_bf16 v[84:87], v[150:153], v[206:209], v[84:87]
	v_mfma_f32_16x16x32_bf16 v[80:83], v[154:157], v[202:205], v[80:83]
	v_mfma_f32_16x16x32_bf16 v[80:83], v[158:161], v[206:209], v[80:83]
	v_mfma_f32_16x16x32_bf16 v[108:111], v[162:165], v[178:181], v[108:111]
	v_mfma_f32_16x16x32_bf16 v[108:111], v[166:169], v[182:185], v[108:111]
	v_mfma_f32_16x16x32_bf16 v[104:107], v[170:173], v[178:181], v[104:107]
	v_mfma_f32_16x16x32_bf16 v[104:107], v[174:177], v[182:185], v[104:107]
	v_mfma_f32_16x16x32_bf16 v[92:95], v[162:165], v[186:189], v[92:95]
	v_mfma_f32_16x16x32_bf16 v[92:95], v[166:169], v[190:193], v[92:95]
	v_mfma_f32_16x16x32_bf16 v[88:91], v[170:173], v[186:189], v[88:91]
	v_mfma_f32_16x16x32_bf16 v[88:91], v[174:177], v[190:193], v[88:91]
	v_mfma_f32_16x16x32_bf16 v[76:79], v[162:165], v[194:197], v[76:79]
	v_mfma_f32_16x16x32_bf16 v[76:79], v[166:169], v[198:201], v[76:79]
	v_mfma_f32_16x16x32_bf16 v[72:75], v[170:173], v[194:197], v[72:75]
	v_mfma_f32_16x16x32_bf16 v[72:75], v[174:177], v[198:201], v[72:75]
	v_mfma_f32_16x16x32_bf16 v[68:71], v[162:165], v[202:205], v[68:71]
	v_mfma_f32_16x16x32_bf16 v[68:71], v[166:169], v[206:209], v[68:71]
	v_mfma_f32_16x16x32_bf16 v[64:67], v[170:173], v[202:205], v[64:67]
	v_mfma_f32_16x16x32_bf16 v[64:67], v[174:177], v[206:209], v[64:67]
	s_barrier
	s_add_i32 s59, s50, s24
	v_lshl_add_u64 v[210:211], s[38:39], 0, v[134:135]
	s_mov_b32 m0, s59
	ds_read_b128 v[178:181], v144 offset:16384
	ds_read_b128 v[182:185], v144 offset:17408
	ds_read_b128 v[186:189], v144 offset:18432
	ds_read_b128 v[190:193], v144 offset:19456
	ds_read_b128 v[194:197], v144 offset:20480
	ds_read_b128 v[198:201], v144 offset:21504
	ds_read_b128 v[202:205], v144 offset:22528
	ds_read_b128 v[206:209], v144 offset:23552
	global_load_lds_dwordx4 v[210:211], off
	s_add_i32 m0, s59, 0x2000
	s_add_u32 s60, s38, 0x80000
	v_lshl_add_u64 v[212:213], s[38:39], 0, v[136:137]
	s_addc_u32 s61, s39, 0
	s_add_i32 s59, s51, s24
	global_load_lds_dwordx4 v[212:213], off
	v_lshl_add_u64 v[214:215], s[60:61], 0, v[134:135]
	s_mov_b32 m0, s59
	v_lshl_add_u64 v[216:217], s[40:41], 0, v[138:139]
	global_load_lds_dwordx4 v[214:215], off
	v_lshl_add_u64 v[214:215], s[60:61], 0, v[136:137]
	s_add_i32 m0, s59, 0x2000
	s_nop 0
	global_load_lds_dwordx4 v[214:215], off
	v_lshl_add_u64 v[214:215], s[40:41], 0, v[128:129]
	s_mov_b32 m0, s26
	s_nop 0
	global_load_lds_dwordx4 v[214:215], off
	s_mov_b32 m0, s27
	s_nop 0
	global_load_lds_dwordx4 v[216:217], off
	s_waitcnt vmcnt(8)
	s_waitcnt lgkmcnt(0)
	s_barrier
; #define PG8_STAGE(bufoff, gbase, voff) do { _Pragma("unroll") for (int _i = 0; _i < 2; ++_i) \
;         __builtin_amdgcn_global_load_lds((const unsigned*)((const char*)(gbase) + (voff)[_i]), (LAS unsigned*)(lds + (bufoff) + ldsw + _i * 8192), 16, 0, 0); } while (0)
; #define PG8_LDA(dst, b, h) do { _Pragma("unroll") for (int m = 0; m < 4; ++m) _Pragma("unroll") for (int k = 0; k < 2; ++k) dst[m][k] = *(const LAS bf16x8*)(lds + PG8_SA(b, h) + aoff + m * 2048 + k * 1024); } while (0)
; #define PG8_LDB(dst, b, h) do { _Pragma("unroll") for (int n = 0; n < 2; ++n) _Pragma("unroll") for (int k = 0; k < 2; ++k) dst[n][k] = *(const LAS bf16x8*)(lds + PG8_SB(b, h) + boff + n * 2048 + k * 1024); } while (0)
; #define PG8_MMA(ai, bj, At, Bt) do { __builtin_amdgcn_s_setprio(1); _Pragma("unroll") for (int m = 0; m < 4; ++m) _Pragma("unroll") for (int n = 0; n < 2; ++n) _Pragma("unroll") for (int k = 0; k < 2; ++k) \
;         acc[ai][bj][m][n] = __builtin_amdgcn_mfma_f32_16x16x32_bf16(Bt[n][k], At[m][k], acc[ai][bj][m][n], 0, 0, 0); __builtin_amdgcn_s_setprio(0); } while (0)
; #define PG8_WAIT_V(n) asm volatile("s_waitcnt vmcnt(" #n ")" ::: "memory")
; #define PG8_WAIT_L(n) asm volatile("s_waitcnt lgkmcnt(" #n ")" ::: "memory")
; #define PG8_BAR __builtin_amdgcn_s_barrier()
; #define PG8_SCHED __builtin_amdgcn_sched_barrier(0)
; template <class Epi>
; __device__ __forceinline__ void gemm_phase(LAS unsigned char* lds, const Gemm g, const Order& S, const Epi& E, const int wid) {
;     ...
;             PG8_WAIT_V(8); PG8_WAIT_L(0); PG8_BAR; PG8_MMA(1, 0, At, B0); PG8_MMA(1, 1, At, B1); PG8_BAR; PG8_SCHED;
;             PG8_LDB(B0, 1, 0); PG8_LDB(B1, 1, 1); PG8_SCHED; PG8_LDA(At, 1, 0); PG8_STAGE(PG8_SA(0, 1), a2 + hA, voffA);
;             PG8_WAIT_V(8); PG8_WAIT_L(0); PG8_BAR; PG8_MMA(0, 0, At, B0); PG8_MMA(0, 1, At, B1); PG8_BAR; PG8_SCHED;
;             PG8_LDA(At, 1, 1); PG8_STAGE(PG8_SB(1, 0), b3, voffB); PG8_STAGE(PG8_SB(1, 1), b3 + hB, voffB); PG8_STAGE(PG8_SA(1, 0), a3, voffA);
	s_waitcnt lgkmcnt(0)
	v_mfma_f32_16x16x32_bf16 v[60:63], v[146:149], v[178:181], v[60:63]
	v_mfma_f32_16x16x32_bf16 v[60:63], v[150:153], v[182:185], v[60:63]
	v_mfma_f32_16x16x32_bf16 v[56:59], v[154:157], v[178:181], v[56:59]
	v_mfma_f32_16x16x32_bf16 v[56:59], v[158:161], v[182:185], v[56:59]
	v_mfma_f32_16x16x32_bf16 v[52:55], v[146:149], v[186:189], v[52:55]
	v_mfma_f32_16x16x32_bf16 v[52:55], v[150:153], v[190:193], v[52:55]
	v_mfma_f32_16x16x32_bf16 v[48:51], v[154:157], v[186:189], v[48:51]
	v_mfma_f32_16x16x32_bf16 v[48:51], v[158:161], v[190:193], v[48:51]
	v_mfma_f32_16x16x32_bf16 v[36:39], v[146:149], v[194:197], v[36:39]
	v_mfma_f32_16x16x32_bf16 v[36:39], v[150:153], v[198:201], v[36:39]
	v_mfma_f32_16x16x32_bf16 v[32:35], v[154:157], v[194:197], v[32:35]
	v_mfma_f32_16x16x32_bf16 v[32:35], v[158:161], v[198:201], v[32:35]
	v_mfma_f32_16x16x32_bf16 v[20:23], v[146:149], v[202:205], v[20:23]
	v_mfma_f32_16x16x32_bf16 v[20:23], v[150:153], v[206:209], v[20:23]
	v_mfma_f32_16x16x32_bf16 v[16:19], v[154:157], v[202:205], v[16:19]
	v_mfma_f32_16x16x32_bf16 v[16:19], v[158:161], v[206:209], v[16:19]
	v_mfma_f32_16x16x32_bf16 v[44:47], v[162:165], v[178:181], v[44:47]
	v_mfma_f32_16x16x32_bf16 v[44:47], v[166:169], v[182:185], v[44:47]
	v_mfma_f32_16x16x32_bf16 v[40:43], v[170:173], v[178:181], v[40:43]
	v_mfma_f32_16x16x32_bf16 v[40:43], v[174:177], v[182:185], v[40:43]
	v_mfma_f32_16x16x32_bf16 v[28:31], v[162:165], v[186:189], v[28:31]
	v_mfma_f32_16x16x32_bf16 v[28:31], v[166:169], v[190:193], v[28:31]
	v_mfma_f32_16x16x32_bf16 v[24:27], v[170:173], v[186:189], v[24:27]
	v_mfma_f32_16x16x32_bf16 v[24:27], v[174:177], v[190:193], v[24:27]
	v_mfma_f32_16x16x32_bf16 v[12:15], v[162:165], v[194:197], v[12:15]
	v_mfma_f32_16x16x32_bf16 v[12:15], v[166:169], v[198:201], v[12:15]
	v_mfma_f32_16x16x32_bf16 v[8:11], v[170:173], v[194:197], v[8:11]
	v_mfma_f32_16x16x32_bf16 v[8:11], v[174:177], v[198:201], v[8:11]
	v_mfma_f32_16x16x32_bf16 v[4:7], v[162:165], v[202:205], v[4:7]
	v_mfma_f32_16x16x32_bf16 v[4:7], v[166:169], v[206:209], v[4:7]
	v_mfma_f32_16x16x32_bf16 v[0:3], v[170:173], v[202:205], v[0:3]
	v_mfma_f32_16x16x32_bf16 v[0:3], v[174:177], v[206:209], v[0:3]
	s_barrier
	s_add_i32 s59, 0, 0x18000
	v_add_u32_e32 v145, s59, v141
	s_add_i32 s60, 0, 0x1c000
	ds_read_b128 v[146:149], v145
	ds_read_b128 v[150:153], v145 offset:1024
	ds_read_b128 v[154:157], v145 offset:2048
	ds_read_b128 v[158:161], v145 offset:3072
	v_add_u32_e32 v145, s60, v141
	ds_read_b128 v[162:165], v145
	ds_read_b128 v[166:169], v145 offset:1024
	ds_read_b128 v[170:173], v145 offset:2048
	ds_read_b128 v[174:177], v145 offset:3072
	s_add_u32 s40, s40, 0x80000
	s_addc_u32 s41, s41, 0
	s_mov_b32 m0, s28
	v_lshl_add_u64 v[218:219], s[40:41], 0, v[128:129]
	ds_read_b128 v[178:181], v144 offset:32768
	ds_read_b128 v[182:185], v144 offset:33792
	ds_read_b128 v[186:189], v144 offset:34816
	ds_read_b128 v[190:193], v144 offset:35840
	ds_read_b128 v[194:197], v144 offset:36864
	ds_read_b128 v[198:201], v144 offset:37888
	ds_read_b128 v[202:205], v144 offset:38912
	ds_read_b128 v[206:209], v144 offset:39936
	global_load_lds_dwordx4 v[218:219], off
	v_lshl_add_u64 v[218:219], s[40:41], 0, v[138:139]
	s_mov_b32 m0, s29
	s_nop 0
	global_load_lds_dwordx4 v[218:219], off
	s_waitcnt vmcnt(8)
	s_waitcnt lgkmcnt(0)
	s_barrier
	s_waitcnt lgkmcnt(0)
	v_mfma_f32_16x16x32_bf16 v[124:127], v[146:149], v[178:181], v[124:127]
	v_mfma_f32_16x16x32_bf16 v[124:127], v[150:153], v[182:185], v[124:127]
	v_mfma_f32_16x16x32_bf16 v[120:123], v[154:157], v[178:181], v[120:123]
	v_mfma_f32_16x16x32_bf16 v[120:123], v[158:161], v[182:185], v[120:123]
	v_mfma_f32_16x16x32_bf16 v[116:119], v[146:149], v[186:189], v[116:119]
	v_mfma_f32_16x16x32_bf16 v[116:119], v[150:153], v[190:193], v[116:119]
	v_mfma_f32_16x16x32_bf16 v[112:115], v[154:157], v[186:189], v[112:115]
	v_mfma_f32_16x16x32_bf16 v[112:115], v[158:161], v[190:193], v[112:115]
	v_mfma_f32_16x16x32_bf16 v[100:103], v[146:149], v[194:197], v[100:103]
	v_mfma_f32_16x16x32_bf16 v[100:103], v[150:153], v[198:201], v[100:103]
	v_mfma_f32_16x16x32_bf16 v[96:99], v[154:157], v[194:197], v[96:99]
	v_mfma_f32_16x16x32_bf16 v[96:99], v[158:161], v[198:201], v[96:99]
	v_mfma_f32_16x16x32_bf16 v[84:87], v[146:149], v[202:205], v[84:87]
	v_mfma_f32_16x16x32_bf16 v[84:87], v[150:153], v[206:209], v[84:87]
	v_mfma_f32_16x16x32_bf16 v[80:83], v[154:157], v[202:205], v[80:83]
	v_mfma_f32_16x16x32_bf16 v[80:83], v[158:161], v[206:209], v[80:83]
	v_mfma_f32_16x16x32_bf16 v[108:111], v[162:165], v[178:181], v[108:111]
	v_mfma_f32_16x16x32_bf16 v[108:111], v[166:169], v[182:185], v[108:111]
	v_mfma_f32_16x16x32_bf16 v[104:107], v[170:173], v[178:181], v[104:107]
	v_mfma_f32_16x16x32_bf16 v[104:107], v[174:177], v[182:185], v[104:107]
	v_mfma_f32_16x16x32_bf16 v[92:95], v[162:165], v[186:189], v[92:95]
	v_mfma_f32_16x16x32_bf16 v[92:95], v[166:169], v[190:193], v[92:95]
	v_mfma_f32_16x16x32_bf16 v[88:91], v[170:173], v[186:189], v[88:91]
	v_mfma_f32_16x16x32_bf16 v[88:91], v[174:177], v[190:193], v[88:91]
	v_mfma_f32_16x16x32_bf16 v[76:79], v[162:165], v[194:197], v[76:79]
	v_mfma_f32_16x16x32_bf16 v[76:79], v[166:169], v[198:201], v[76:79]
	v_mfma_f32_16x16x32_bf16 v[72:75], v[170:173], v[194:197], v[72:75]
	v_mfma_f32_16x16x32_bf16 v[72:75], v[174:177], v[198:201], v[72:75]
	v_mfma_f32_16x16x32_bf16 v[68:71], v[162:165], v[202:205], v[68:71]
	v_mfma_f32_16x16x32_bf16 v[68:71], v[166:169], v[206:209], v[68:71]
	v_mfma_f32_16x16x32_bf16 v[64:67], v[170:173], v[202:205], v[64:67]
	v_mfma_f32_16x16x32_bf16 v[64:67], v[174:177], v[206:209], v[64:67]
	s_barrier
; #define PG8_STAGE(bufoff, gbase, voff) do { _Pragma("unroll") for (int _i = 0; _i < 2; ++_i) \
;         __builtin_amdgcn_global_load_lds((const unsigned*)((const char*)(gbase) + (voff)[_i]), (LAS unsigned*)(lds + (bufoff) + ldsw + _i * 8192), 16, 0, 0); } while (0)
; #define PG8_LDA(dst, b, h) do { _Pragma("unroll") for (int m = 0; m < 4; ++m) _Pragma("unroll") for (int k = 0; k < 2; ++k) dst[m][k] = *(const LAS bf16x8*)(lds + PG8_SA(b, h) + aoff + m * 2048 + k * 1024); } while (0)
; #define PG8_MMA(ai, bj, At, Bt) do { __builtin_amdgcn_s_setprio(1); _Pragma("unroll") for (int m = 0; m < 4; ++m) _Pragma("unroll") for (int n = 0; n < 2; ++n) _Pragma("unroll") for (int k = 0; k < 2; ++k) \
;         acc[ai][bj][m][n] = __builtin_amdgcn_mfma_f32_16x16x32_bf16(Bt[n][k], At[m][k], acc[ai][bj][m][n], 0, 0, 0); __builtin_amdgcn_s_setprio(0); } while (0)
; #define PG8_WAIT_V(n) asm volatile("s_waitcnt vmcnt(" #n ")" ::: "memory")
; #define PG8_WAIT_L(n) asm volatile("s_waitcnt lgkmcnt(" #n ")" ::: "memory")
; #define PG8_BAR __builtin_amdgcn_s_barrier()
; #define PG8_SCHED __builtin_amdgcn_sched_barrier(0)
; template <class Epi>
; __device__ __forceinline__ void gemm_phase(LAS unsigned char* lds, const Gemm g, const Order& S, const Epi& E, const int wid) {
;     ...
;         for (int t = 0; t < nt; t += 2) {
;     ...
;             PG8_LDA(At, 1, 1); PG8_STAGE(PG8_SB(1, 0), b3, voffB); PG8_STAGE(PG8_SB(1, 1), b3 + hB, voffB); PG8_STAGE(PG8_SA(1, 0), a3, voffA);
;             PG8_WAIT_V(8); PG8_WAIT_L(0); PG8_BAR; PG8_MMA(1, 0, At, B0); PG8_MMA(1, 1, At, B1); PG8_BAR; PG8_SCHED;
	s_add_i32 s40, s59, s24
	v_lshl_add_u64 v[210:211], v[210:211], 0, s[12:13]
	s_mov_b32 m0, s40
	ds_read_b128 v[178:181], v144 offset:49152
	ds_read_b128 v[182:185], v144 offset:50176
	ds_read_b128 v[186:189], v144 offset:51200
	ds_read_b128 v[190:193], v144 offset:52224
	ds_read_b128 v[194:197], v144 offset:53248
	ds_read_b128 v[198:201], v144 offset:54272
	ds_read_b128 v[202:205], v144 offset:55296
	ds_read_b128 v[206:209], v144 offset:56320
	global_load_lds_dwordx4 v[210:211], off
	s_add_i32 m0, s40, 0x2000
	s_add_u32 s38, s38, 0x80080
	v_lshl_add_u64 v[210:211], v[212:213], 0, s[12:13]
	s_addc_u32 s39, s39, 0
	s_add_i32 s40, s60, s24
	global_load_lds_dwordx4 v[210:211], off
	v_lshl_add_u64 v[210:211], s[38:39], 0, v[134:135]
	s_mov_b32 m0, s40
	s_nop 0
	global_load_lds_dwordx4 v[210:211], off
	v_lshl_add_u64 v[210:211], s[38:39], 0, v[136:137]
	s_add_i32 m0, s40, 0x2000
	s_nop 0
	global_load_lds_dwordx4 v[210:211], off
	v_lshl_add_u64 v[210:211], v[214:215], 0, s[12:13]
	s_mov_b32 m0, s47
	s_nop 0
	global_load_lds_dwordx4 v[210:211], off
	v_lshl_add_u64 v[210:211], v[216:217], 0, s[12:13]
	s_mov_b32 m0, s48
	s_nop 0
	global_load_lds_dwordx4 v[210:211], off
	s_waitcnt vmcnt(8)
	s_waitcnt lgkmcnt(0)
	s_barrier
	s_waitcnt lgkmcnt(0)
	v_mfma_f32_16x16x32_bf16 v[60:63], v[146:149], v[178:181], v[60:63]
	v_mfma_f32_16x16x32_bf16 v[60:63], v[150:153], v[182:185], v[60:63]
	v_mfma_f32_16x16x32_bf16 v[56:59], v[154:157], v[178:181], v[56:59]
	v_mfma_f32_16x16x32_bf16 v[56:59], v[158:161], v[182:185], v[56:59]
	v_mfma_f32_16x16x32_bf16 v[52:55], v[146:149], v[186:189], v[52:55]
	v_mfma_f32_16x16x32_bf16 v[52:55], v[150:153], v[190:193], v[52:55]
	v_mfma_f32_16x16x32_bf16 v[48:51], v[154:157], v[186:189], v[48:51]
	v_mfma_f32_16x16x32_bf16 v[48:51], v[158:161], v[190:193], v[48:51]
	v_mfma_f32_16x16x32_bf16 v[36:39], v[146:149], v[194:197], v[36:39]
	v_mfma_f32_16x16x32_bf16 v[36:39], v[150:153], v[198:201], v[36:39]
	v_mfma_f32_16x16x32_bf16 v[32:35], v[154:157], v[194:197], v[32:35]
	v_mfma_f32_16x16x32_bf16 v[32:35], v[158:161], v[198:201], v[32:35]
	v_mfma_f32_16x16x32_bf16 v[20:23], v[146:149], v[202:205], v[20:23]
	v_mfma_f32_16x16x32_bf16 v[20:23], v[150:153], v[206:209], v[20:23]
	v_mfma_f32_16x16x32_bf16 v[16:19], v[154:157], v[202:205], v[16:19]
	v_mfma_f32_16x16x32_bf16 v[16:19], v[158:161], v[206:209], v[16:19]
	v_mfma_f32_16x16x32_bf16 v[44:47], v[162:165], v[178:181], v[44:47]
	v_mfma_f32_16x16x32_bf16 v[44:47], v[166:169], v[182:185], v[44:47]
	v_mfma_f32_16x16x32_bf16 v[40:43], v[170:173], v[178:181], v[40:43]
	v_mfma_f32_16x16x32_bf16 v[40:43], v[174:177], v[182:185], v[40:43]
	v_mfma_f32_16x16x32_bf16 v[28:31], v[162:165], v[186:189], v[28:31]
	v_mfma_f32_16x16x32_bf16 v[28:31], v[166:169], v[190:193], v[28:31]
	v_mfma_f32_16x16x32_bf16 v[24:27], v[170:173], v[186:189], v[24:27]
	v_mfma_f32_16x16x32_bf16 v[24:27], v[174:177], v[190:193], v[24:27]
	v_mfma_f32_16x16x32_bf16 v[12:15], v[162:165], v[194:197], v[12:15]
	v_mfma_f32_16x16x32_bf16 v[12:15], v[166:169], v[198:201], v[12:15]
	v_mfma_f32_16x16x32_bf16 v[8:11], v[170:173], v[194:197], v[8:11]
	v_mfma_f32_16x16x32_bf16 v[8:11], v[174:177], v[198:201], v[8:11]
	v_mfma_f32_16x16x32_bf16 v[4:7], v[162:165], v[202:205], v[4:7]
	v_mfma_f32_16x16x32_bf16 v[4:7], v[166:169], v[206:209], v[4:7]
	v_mfma_f32_16x16x32_bf16 v[0:3], v[170:173], v[202:205], v[0:3]
	v_mfma_f32_16x16x32_bf16 v[0:3], v[174:177], v[206:209], v[0:3]
	s_add_i32 s58, s58, 2
	s_add_u32 s36, s36, 0x100
	s_addc_u32 s37, s37, 0
	s_add_u32 s17, s17, 0x100
	s_addc_u32 s19, s19, 0
	s_cmp_gt_u32 s58, 29
	s_barrier
	s_cbranch_scc0 .LBB0_581
	s_and_b64 vcc, exec, s[10:11]
	s_cbranch_vccz .LBB0_584
	s_barrier

; #define PG8_STAGE(bufoff, gbase, voff) do { _Pragma("unroll") for (int _i = 0; _i < 2; ++_i) \
;         __builtin_amdgcn_global_load_lds((const unsigned*)((const char*)(gbase) + (voff)[_i]), (LAS unsigned*)(lds + (bufoff) + ldsw + _i * 8192), 16, 0, 0); } while (0)
; #define PG8_LDA(dst, b, h) do { _Pragma("unroll") for (int m = 0; m < 4; ++m) _Pragma("unroll") for (int k = 0; k < 2; ++k) dst[m][k] = *(const LAS bf16x8*)(lds + PG8_SA(b, h) + aoff + m * 2048 + k * 1024); } while (0)
; #define PG8_LDB(dst, b, h) do { _Pragma("unroll") for (int n = 0; n < 2; ++n) _Pragma("unroll") for (int k = 0; k < 2; ++k) dst[n][k] = *(const LAS bf16x8*)(lds + PG8_SB(b, h) + boff + n * 2048 + k * 1024); } while (0)
; #define PG8_MMA(ai, bj, At, Bt) do { __builtin_amdgcn_s_setprio(1); _Pragma("unroll") for (int m = 0; m < 4; ++m) _Pragma("unroll") for (int n = 0; n < 2; ++n) _Pragma("unroll") for (int k = 0; k < 2; ++k) \
;         acc[ai][bj][m][n] = __builtin_amdgcn_mfma_f32_16x16x32_bf16(Bt[n][k], At[m][k], acc[ai][bj][m][n], 0, 0, 0); __builtin_amdgcn_s_setprio(0); } while (0)
; #define PG8_WAIT_V(n) asm volatile("s_waitcnt vmcnt(" #n ")" ::: "memory")
; #define PG8_WAIT_L(n) asm volatile("s_waitcnt lgkmcnt(" #n ")" ::: "memory")
; #define PG8_BAR __builtin_amdgcn_s_barrier()
; #define PG8_SCHED __builtin_amdgcn_sched_barrier(0)
; template <class Epi>
; __device__ __forceinline__ void gemm_phase(LAS unsigned char* lds, const Gemm g, const Order& S, const Epi& E, const int wid) {
;     ...
;         for (int t = 0; t < nt; t += 2) {
;             const bool last = (t == nt - 2);
;             const char* a1 = cA + (size_t)(t + 1) * kstep;
;             const char* a2 = last ? nA : cA + (size_t)(t + 2) * kstep; const char* b2 = last ? nB : cB + (size_t)(t + 2) * kstep;
;             const char* a3 = a2 + kstep; const char* b3 = b2 + kstep;
;     ...
;             PG8_LDB(B0, 0, 0); PG8_LDB(B1, 0, 1); PG8_SCHED; PG8_LDA(At, 0, 0); PG8_STAGE(PG8_SA(1, 1), a1 + hA, voffA);
;             PG8_WAIT_V(8); PG8_WAIT_L(0); PG8_BAR; PG8_MMA(0, 0, At, B0); PG8_MMA(0, 1, At, B1); PG8_BAR; PG8_SCHED;
;             PG8_LDA(At, 0, 1); PG8_STAGE(PG8_SB(0, 0), b2, voffB); PG8_STAGE(PG8_SB(0, 1), b2 + hB, voffB); PG8_STAGE(PG8_SA(0, 0), a2, voffA);
.LBB0_665:
	ds_read_b128 v[146:149], v142
	ds_read_b128 v[150:153], v142 offset:1024
	ds_read_b128 v[154:157], v142 offset:2048
	ds_read_b128 v[158:161], v142 offset:3072
	ds_read_b128 v[162:165], v143
	ds_read_b128 v[166:169], v143 offset:1024
	ds_read_b128 v[170:173], v143 offset:2048
	ds_read_b128 v[174:177], v143 offset:3072
	s_add_u32 s42, s40, 0xfff80080
	s_addc_u32 s43, s41, -1
	s_cmp_eq_u32 s60, 28
	s_cselect_b32 s45, s17, s43
	s_cselect_b32 s44, s56, s42
	s_cselect_b32 s43, s19, s59
	s_cselect_b32 s42, s57, s58
	v_lshl_add_u64 v[210:211], s[40:41], 0, v[128:129]
	s_add_i32 m0, s21, 0xc000
	ds_read_b128 v[178:181], v144
	ds_read_b128 v[182:185], v144 offset:1024
	ds_read_b128 v[186:189], v144 offset:2048
	ds_read_b128 v[190:193], v144 offset:3072
	ds_read_b128 v[194:197], v144 offset:4096
	ds_read_b128 v[198:201], v144 offset:5120
	ds_read_b128 v[202:205], v144 offset:6144
	ds_read_b128 v[206:209], v144 offset:7168
	global_load_lds_dwordx4 v[210:211], off
	v_lshl_add_u64 v[210:211], s[40:41], 0, v[138:139]
	s_add_i32 m0, s21, 0xe000
	s_nop 0
	global_load_lds_dwordx4 v[210:211], off
	s_waitcnt vmcnt(8)
	s_waitcnt lgkmcnt(0)
	s_barrier
	s_waitcnt lgkmcnt(0)
	v_mfma_f32_16x16x32_bf16 v[124:127], v[146:149], v[178:181], v[124:127]
	v_mfma_f32_16x16x32_bf16 v[124:127], v[150:153], v[182:185], v[124:127]
	v_mfma_f32_16x16x32_bf16 v[120:123], v[154:157], v[178:181], v[120:123]
	v_mfma_f32_16x16x32_bf16 v[120:123], v[158:161], v[182:185], v[120:123]
	v_mfma_f32_16x16x32_bf16 v[116:119], v[146:149], v[186:189], v[116:119]
	v_mfma_f32_16x16x32_bf16 v[116:119], v[150:153], v[190:193], v[116:119]
	v_mfma_f32_16x16x32_bf16 v[112:115], v[154:157], v[186:189], v[112:115]
	v_mfma_f32_16x16x32_bf16 v[112:115], v[158:161], v[190:193], v[112:115]
	v_mfma_f32_16x16x32_bf16 v[100:103], v[146:149], v[194:197], v[100:103]
	v_mfma_f32_16x16x32_bf16 v[100:103], v[150:153], v[198:201], v[100:103]
	v_mfma_f32_16x16x32_bf16 v[96:99], v[154:157], v[194:197], v[96:99]
	v_mfma_f32_16x16x32_bf16 v[96:99], v[158:161], v[198:201], v[96:99]
	v_mfma_f32_16x16x32_bf16 v[84:87], v[146:149], v[202:205], v[84:87]
	v_mfma_f32_16x16x32_bf16 v[84:87], v[150:153], v[206:209], v[84:87]
	v_mfma_f32_16x16x32_bf16 v[80:83], v[154:157], v[202:205], v[80:83]
	v_mfma_f32_16x16x32_bf16 v[80:83], v[158:161], v[206:209], v[80:83]
	v_mfma_f32_16x16x32_bf16 v[108:111], v[162:165], v[178:181], v[108:111]
	v_mfma_f32_16x16x32_bf16 v[108:111], v[166:169], v[182:185], v[108:111]
	v_mfma_f32_16x16x32_bf16 v[104:107], v[170:173], v[178:181], v[104:107]
	v_mfma_f32_16x16x32_bf16 v[104:107], v[174:177], v[182:185], v[104:107]
	v_mfma_f32_16x16x32_bf16 v[92:95], v[162:165], v[186:189], v[92:95]
	v_mfma_f32_16x16x32_bf16 v[92:95], v[166:169], v[190:193], v[92:95]
	v_mfma_f32_16x16x32_bf16 v[88:91], v[170:173], v[186:189], v[88:91]
	v_mfma_f32_16x16x32_bf16 v[88:91], v[174:177], v[190:193], v[88:91]
	v_mfma_f32_16x16x32_bf16 v[76:79], v[162:165], v[194:197], v[76:79]
	v_mfma_f32_16x16x32_bf16 v[76:79], v[166:169], v[198:201], v[76:79]
	v_mfma_f32_16x16x32_bf16 v[72:75], v[170:173], v[194:197], v[72:75]
	v_mfma_f32_16x16x32_bf16 v[72:75], v[174:177], v[198:201], v[72:75]
	v_mfma_f32_16x16x32_bf16 v[68:71], v[162:165], v[202:205], v[68:71]
	v_mfma_f32_16x16x32_bf16 v[68:71], v[166:169], v[206:209], v[68:71]
	v_mfma_f32_16x16x32_bf16 v[64:67], v[170:173], v[202:205], v[64:67]
	v_mfma_f32_16x16x32_bf16 v[64:67], v[174:177], v[206:209], v[64:67]
	s_barrier
	s_add_i32 s61, s51, s24
	v_lshl_add_u64 v[210:211], s[42:43], 0, v[134:135]
	s_mov_b32 m0, s61
	ds_read_b128 v[178:181], v144 offset:16384
	ds_read_b128 v[182:185], v144 offset:17408
	ds_read_b128 v[186:189], v144 offset:18432
	ds_read_b128 v[190:193], v144 offset:19456
	ds_read_b128 v[194:197], v144 offset:20480
	ds_read_b128 v[198:201], v144 offset:21504
	ds_read_b128 v[202:205], v144 offset:22528
	ds_read_b128 v[206:209], v144 offset:23552
	global_load_lds_dwordx4 v[210:211], off
	s_add_i32 m0, s61, 0x2000
	s_add_u32 s62, s42, 0x80000
	v_lshl_add_u64 v[212:213], s[42:43], 0, v[136:137]
	s_addc_u32 s63, s43, 0
	s_add_i32 s61, s54, s24
	global_load_lds_dwordx4 v[212:213], off
	v_lshl_add_u64 v[214:215], s[62:63], 0, v[134:135]
	s_mov_b32 m0, s61
	v_lshl_add_u64 v[216:217], s[44:45], 0, v[138:139]
	global_load_lds_dwordx4 v[214:215], off
	v_lshl_add_u64 v[214:215], s[62:63], 0, v[136:137]
	s_add_i32 m0, s61, 0x2000
	s_nop 0
	global_load_lds_dwordx4 v[214:215], off
	v_lshl_add_u64 v[214:215], s[44:45], 0, v[128:129]
	s_mov_b32 m0, s21
	s_nop 0
	global_load_lds_dwordx4 v[214:215], off
	s_mov_b32 m0, s26
	s_nop 0
	global_load_lds_dwordx4 v[216:217], off
	s_waitcnt vmcnt(8)
	s_waitcnt lgkmcnt(0)
	s_barrier
; #define PG8_STAGE(bufoff, gbase, voff) do { _Pragma("unroll") for (int _i = 0; _i < 2; ++_i) \
;         __builtin_amdgcn_global_load_lds((const unsigned*)((const char*)(gbase) + (voff)[_i]), (LAS unsigned*)(lds + (bufoff) + ldsw + _i * 8192), 16, 0, 0); } while (0)
; #define PG8_LDA(dst, b, h) do { _Pragma("unroll") for (int m = 0; m < 4; ++m) _Pragma("unroll") for (int k = 0; k < 2; ++k) dst[m][k] = *(const LAS bf16x8*)(lds + PG8_SA(b, h) + aoff + m * 2048 + k * 1024); } while (0)
; #define PG8_LDB(dst, b, h) do { _Pragma("unroll") for (int n = 0; n < 2; ++n) _Pragma("unroll") for (int k = 0; k < 2; ++k) dst[n][k] = *(const LAS bf16x8*)(lds + PG8_SB(b, h) + boff + n * 2048 + k * 1024); } while (0)
; #define PG8_MMA(ai, bj, At, Bt) do { __builtin_amdgcn_s_setprio(1); _Pragma("unroll") for (int m = 0; m < 4; ++m) _Pragma("unroll") for (int n = 0; n < 2; ++n) _Pragma("unroll") for (int k = 0; k < 2; ++k) \
;         acc[ai][bj][m][n] = __builtin_amdgcn_mfma_f32_16x16x32_bf16(Bt[n][k], At[m][k], acc[ai][bj][m][n], 0, 0, 0); __builtin_amdgcn_s_setprio(0); } while (0)
; #define PG8_WAIT_V(n) asm volatile("s_waitcnt vmcnt(" #n ")" ::: "memory")
; #define PG8_WAIT_L(n) asm volatile("s_waitcnt lgkmcnt(" #n ")" ::: "memory")
; #define PG8_BAR __builtin_amdgcn_s_barrier()
; #define PG8_SCHED __builtin_amdgcn_sched_barrier(0)
; template <class Epi>
; __device__ __forceinline__ void gemm_phase(LAS unsigned char* lds, const Gemm g, const Order& S, const Epi& E, const int wid) {
;     ...
;             PG8_WAIT_V(8); PG8_WAIT_L(0); PG8_BAR; PG8_MMA(1, 0, At, B0); PG8_MMA(1, 1, At, B1); PG8_BAR; PG8_SCHED;
;             PG8_LDB(B0, 1, 0); PG8_LDB(B1, 1, 1); PG8_SCHED; PG8_LDA(At, 1, 0); PG8_STAGE(PG8_SA(0, 1), a2 + hA, voffA);
;             PG8_WAIT_V(8); PG8_WAIT_L(0); PG8_BAR; PG8_MMA(0, 0, At, B0); PG8_MMA(0, 1, At, B1); PG8_BAR; PG8_SCHED;
	s_waitcnt lgkmcnt(0)
	v_mfma_f32_16x16x32_bf16 v[60:63], v[146:149], v[178:181], v[60:63]
	v_mfma_f32_16x16x32_bf16 v[60:63], v[150:153], v[182:185], v[60:63]
	v_mfma_f32_16x16x32_bf16 v[56:59], v[154:157], v[178:181], v[56:59]
	v_mfma_f32_16x16x32_bf16 v[56:59], v[158:161], v[182:185], v[56:59]
	v_mfma_f32_16x16x32_bf16 v[52:55], v[146:149], v[186:189], v[52:55]
	v_mfma_f32_16x16x32_bf16 v[52:55], v[150:153], v[190:193], v[52:55]
	v_mfma_f32_16x16x32_bf16 v[48:51], v[154:157], v[186:189], v[48:51]
	v_mfma_f32_16x16x32_bf16 v[48:51], v[158:161], v[190:193], v[48:51]
	v_mfma_f32_16x16x32_bf16 v[36:39], v[146:149], v[194:197], v[36:39]
	v_mfma_f32_16x16x32_bf16 v[36:39], v[150:153], v[198:201], v[36:39]
	v_mfma_f32_16x16x32_bf16 v[32:35], v[154:157], v[194:197], v[32:35]
	v_mfma_f32_16x16x32_bf16 v[32:35], v[158:161], v[198:201], v[32:35]
	v_mfma_f32_16x16x32_bf16 v[20:23], v[146:149], v[202:205], v[20:23]
	v_mfma_f32_16x16x32_bf16 v[20:23], v[150:153], v[206:209], v[20:23]
	v_mfma_f32_16x16x32_bf16 v[16:19], v[154:157], v[202:205], v[16:19]
	v_mfma_f32_16x16x32_bf16 v[16:19], v[158:161], v[206:209], v[16:19]
	v_mfma_f32_16x16x32_bf16 v[44:47], v[162:165], v[178:181], v[44:47]
	v_mfma_f32_16x16x32_bf16 v[44:47], v[166:169], v[182:185], v[44:47]
	v_mfma_f32_16x16x32_bf16 v[40:43], v[170:173], v[178:181], v[40:43]
	v_mfma_f32_16x16x32_bf16 v[40:43], v[174:177], v[182:185], v[40:43]
	v_mfma_f32_16x16x32_bf16 v[28:31], v[162:165], v[186:189], v[28:31]
	v_mfma_f32_16x16x32_bf16 v[28:31], v[166:169], v[190:193], v[28:31]
	v_mfma_f32_16x16x32_bf16 v[24:27], v[170:173], v[186:189], v[24:27]
	v_mfma_f32_16x16x32_bf16 v[24:27], v[174:177], v[190:193], v[24:27]
	v_mfma_f32_16x16x32_bf16 v[12:15], v[162:165], v[194:197], v[12:15]
	v_mfma_f32_16x16x32_bf16 v[12:15], v[166:169], v[198:201], v[12:15]
	v_mfma_f32_16x16x32_bf16 v[8:11], v[170:173], v[194:197], v[8:11]
	v_mfma_f32_16x16x32_bf16 v[8:11], v[174:177], v[198:201], v[8:11]
	v_mfma_f32_16x16x32_bf16 v[4:7], v[162:165], v[202:205], v[4:7]
	v_mfma_f32_16x16x32_bf16 v[4:7], v[166:169], v[206:209], v[4:7]
	v_mfma_f32_16x16x32_bf16 v[0:3], v[170:173], v[202:205], v[0:3]
	v_mfma_f32_16x16x32_bf16 v[0:3], v[174:177], v[206:209], v[0:3]
	s_barrier
	s_add_i32 s61, 0, 0x18000
	v_add_u32_e32 v145, s61, v141
	s_add_i32 s62, 0, 0x1c000
	ds_read_b128 v[146:149], v145
	ds_read_b128 v[150:153], v145 offset:1024
	ds_read_b128 v[154:157], v145 offset:2048
	ds_read_b128 v[158:161], v145 offset:3072
	v_add_u32_e32 v145, s62, v141
	ds_read_b128 v[162:165], v145
	ds_read_b128 v[166:169], v145 offset:1024
	ds_read_b128 v[170:173], v145 offset:2048
	ds_read_b128 v[174:177], v145 offset:3072
	s_add_u32 s44, s44, 0x80000
	s_addc_u32 s45, s45, 0
	s_mov_b32 m0, s27
	v_lshl_add_u64 v[218:219], s[44:45], 0, v[128:129]
	ds_read_b128 v[178:181], v144 offset:32768
	ds_read_b128 v[182:185], v144 offset:33792
	ds_read_b128 v[186:189], v144 offset:34816
	ds_read_b128 v[190:193], v144 offset:35840
	ds_read_b128 v[194:197], v144 offset:36864
	ds_read_b128 v[198:201], v144 offset:37888
	ds_read_b128 v[202:205], v144 offset:38912
	ds_read_b128 v[206:209], v144 offset:39936
	global_load_lds_dwordx4 v[218:219], off
	v_lshl_add_u64 v[218:219], s[44:45], 0, v[138:139]
	s_mov_b32 m0, s28
	s_nop 0
	global_load_lds_dwordx4 v[218:219], off
	s_waitcnt vmcnt(8)
	s_waitcnt lgkmcnt(0)
	s_barrier
	s_waitcnt lgkmcnt(0)
	v_mfma_f32_16x16x32_bf16 v[124:127], v[146:149], v[178:181], v[124:127]
	v_mfma_f32_16x16x32_bf16 v[124:127], v[150:153], v[182:185], v[124:127]
	v_mfma_f32_16x16x32_bf16 v[120:123], v[154:157], v[178:181], v[120:123]
	v_mfma_f32_16x16x32_bf16 v[120:123], v[158:161], v[182:185], v[120:123]
	v_mfma_f32_16x16x32_bf16 v[116:119], v[146:149], v[186:189], v[116:119]
	v_mfma_f32_16x16x32_bf16 v[116:119], v[150:153], v[190:193], v[116:119]
	v_mfma_f32_16x16x32_bf16 v[112:115], v[154:157], v[186:189], v[112:115]
	v_mfma_f32_16x16x32_bf16 v[112:115], v[158:161], v[190:193], v[112:115]
	v_mfma_f32_16x16x32_bf16 v[100:103], v[146:149], v[194:197], v[100:103]
	v_mfma_f32_16x16x32_bf16 v[100:103], v[150:153], v[198:201], v[100:103]
	v_mfma_f32_16x16x32_bf16 v[96:99], v[154:157], v[194:197], v[96:99]
	v_mfma_f32_16x16x32_bf16 v[96:99], v[158:161], v[198:201], v[96:99]
	v_mfma_f32_16x16x32_bf16 v[84:87], v[146:149], v[202:205], v[84:87]
	v_mfma_f32_16x16x32_bf16 v[84:87], v[150:153], v[206:209], v[84:87]
	v_mfma_f32_16x16x32_bf16 v[80:83], v[154:157], v[202:205], v[80:83]
	v_mfma_f32_16x16x32_bf16 v[80:83], v[158:161], v[206:209], v[80:83]
	v_mfma_f32_16x16x32_bf16 v[108:111], v[162:165], v[178:181], v[108:111]
	v_mfma_f32_16x16x32_bf16 v[108:111], v[166:169], v[182:185], v[108:111]
	v_mfma_f32_16x16x32_bf16 v[104:107], v[170:173], v[178:181], v[104:107]
	v_mfma_f32_16x16x32_bf16 v[104:107], v[174:177], v[182:185], v[104:107]
	v_mfma_f32_16x16x32_bf16 v[92:95], v[162:165], v[186:189], v[92:95]
	v_mfma_f32_16x16x32_bf16 v[92:95], v[166:169], v[190:193], v[92:95]
	v_mfma_f32_16x16x32_bf16 v[88:91], v[170:173], v[186:189], v[88:91]
	v_mfma_f32_16x16x32_bf16 v[88:91], v[174:177], v[190:193], v[88:91]
	v_mfma_f32_16x16x32_bf16 v[76:79], v[162:165], v[194:197], v[76:79]
	v_mfma_f32_16x16x32_bf16 v[76:79], v[166:169], v[198:201], v[76:79]
	v_mfma_f32_16x16x32_bf16 v[72:75], v[170:173], v[194:197], v[72:75]
	v_mfma_f32_16x16x32_bf16 v[72:75], v[174:177], v[198:201], v[72:75]
	v_mfma_f32_16x16x32_bf16 v[68:71], v[162:165], v[202:205], v[68:71]
	v_mfma_f32_16x16x32_bf16 v[68:71], v[166:169], v[206:209], v[68:71]
	v_mfma_f32_16x16x32_bf16 v[64:67], v[170:173], v[202:205], v[64:67]
	v_mfma_f32_16x16x32_bf16 v[64:67], v[174:177], v[206:209], v[64:67]
	s_barrier
; #define PG8_STAGE(bufoff, gbase, voff) do { _Pragma("unroll") for (int _i = 0; _i < 2; ++_i) \
;         __builtin_amdgcn_global_load_lds((const unsigned*)((const char*)(gbase) + (voff)[_i]), (LAS unsigned*)(lds + (bufoff) + ldsw + _i * 8192), 16, 0, 0); } while (0)
; #define PG8_LDA(dst, b, h) do { _Pragma("unroll") for (int m = 0; m < 4; ++m) _Pragma("unroll") for (int k = 0; k < 2; ++k) dst[m][k] = *(const LAS bf16x8*)(lds + PG8_SA(b, h) + aoff + m * 2048 + k * 1024); } while (0)
; #define PG8_MMA(ai, bj, At, Bt) do { __builtin_amdgcn_s_setprio(1); _Pragma("unroll") for (int m = 0; m < 4; ++m) _Pragma("unroll") for (int n = 0; n < 2; ++n) _Pragma("unroll") for (int k = 0; k < 2; ++k) \
;         acc[ai][bj][m][n] = __builtin_amdgcn_mfma_f32_16x16x32_bf16(Bt[n][k], At[m][k], acc[ai][bj][m][n], 0, 0, 0); __builtin_amdgcn_s_setprio(0); } while (0)
; #define PG8_WAIT_V(n) asm volatile("s_waitcnt vmcnt(" #n ")" ::: "memory")
; #define PG8_WAIT_L(n) asm volatile("s_waitcnt lgkmcnt(" #n ")" ::: "memory")
; #define PG8_BAR __builtin_amdgcn_s_barrier()
; #define PG8_SCHED __builtin_amdgcn_sched_barrier(0)
; template <class Epi>
; __device__ __forceinline__ void gemm_phase(LAS unsigned char* lds, const Gemm g, const Order& S, const Epi& E, const int wid) {
;     ...
;         for (int t = 0; t < nt; t += 2) {
;     ...
;             PG8_LDA(At, 1, 1); PG8_STAGE(PG8_SB(1, 0), b3, voffB); PG8_STAGE(PG8_SB(1, 1), b3 + hB, voffB); PG8_STAGE(PG8_SA(1, 0), a3, voffA);
;             PG8_WAIT_V(8); PG8_WAIT_L(0); PG8_BAR; PG8_MMA(1, 0, At, B0); PG8_MMA(1, 1, At, B1); PG8_BAR; PG8_SCHED;
	s_add_i32 s44, s61, s24
	v_lshl_add_u64 v[210:211], v[210:211], 0, s[12:13]
	s_mov_b32 m0, s44
	ds_read_b128 v[178:181], v144 offset:49152
	ds_read_b128 v[182:185], v144 offset:50176
	ds_read_b128 v[186:189], v144 offset:51200
	ds_read_b128 v[190:193], v144 offset:52224
	ds_read_b128 v[194:197], v144 offset:53248
	ds_read_b128 v[198:201], v144 offset:54272
	ds_read_b128 v[202:205], v144 offset:55296
	ds_read_b128 v[206:209], v144 offset:56320
	global_load_lds_dwordx4 v[210:211], off
	s_add_i32 m0, s44, 0x2000
	s_add_u32 s42, s42, 0x80080
	v_lshl_add_u64 v[210:211], v[212:213], 0, s[12:13]
	s_addc_u32 s43, s43, 0
	s_add_i32 s44, s62, s24
	global_load_lds_dwordx4 v[210:211], off
	v_lshl_add_u64 v[210:211], s[42:43], 0, v[134:135]
	s_mov_b32 m0, s44
	s_nop 0
	global_load_lds_dwordx4 v[210:211], off
	v_lshl_add_u64 v[210:211], s[42:43], 0, v[136:137]
	s_add_i32 m0, s44, 0x2000
	s_nop 0
	global_load_lds_dwordx4 v[210:211], off
	v_lshl_add_u64 v[210:211], v[214:215], 0, s[12:13]
	s_mov_b32 m0, s48
	s_nop 0
	global_load_lds_dwordx4 v[210:211], off
	v_lshl_add_u64 v[210:211], v[216:217], 0, s[12:13]
	s_mov_b32 m0, s49
	s_nop 0
	global_load_lds_dwordx4 v[210:211], off
	s_waitcnt vmcnt(8)
	s_waitcnt lgkmcnt(0)
	s_barrier
	s_waitcnt lgkmcnt(0)
	v_mfma_f32_16x16x32_bf16 v[60:63], v[146:149], v[178:181], v[60:63]
	v_mfma_f32_16x16x32_bf16 v[60:63], v[150:153], v[182:185], v[60:63]
	v_mfma_f32_16x16x32_bf16 v[56:59], v[154:157], v[178:181], v[56:59]
	v_mfma_f32_16x16x32_bf16 v[56:59], v[158:161], v[182:185], v[56:59]
	v_mfma_f32_16x16x32_bf16 v[52:55], v[146:149], v[186:189], v[52:55]
	v_mfma_f32_16x16x32_bf16 v[52:55], v[150:153], v[190:193], v[52:55]
	v_mfma_f32_16x16x32_bf16 v[48:51], v[154:157], v[186:189], v[48:51]
	v_mfma_f32_16x16x32_bf16 v[48:51], v[158:161], v[190:193], v[48:51]
	v_mfma_f32_16x16x32_bf16 v[36:39], v[146:149], v[194:197], v[36:39]
	v_mfma_f32_16x16x32_bf16 v[36:39], v[150:153], v[198:201], v[36:39]
	v_mfma_f32_16x16x32_bf16 v[32:35], v[154:157], v[194:197], v[32:35]
	v_mfma_f32_16x16x32_bf16 v[32:35], v[158:161], v[198:201], v[32:35]
	v_mfma_f32_16x16x32_bf16 v[20:23], v[146:149], v[202:205], v[20:23]
	v_mfma_f32_16x16x32_bf16 v[20:23], v[150:153], v[206:209], v[20:23]
	v_mfma_f32_16x16x32_bf16 v[16:19], v[154:157], v[202:205], v[16:19]
	v_mfma_f32_16x16x32_bf16 v[16:19], v[158:161], v[206:209], v[16:19]
	v_mfma_f32_16x16x32_bf16 v[44:47], v[162:165], v[178:181], v[44:47]
	v_mfma_f32_16x16x32_bf16 v[44:47], v[166:169], v[182:185], v[44:47]
	v_mfma_f32_16x16x32_bf16 v[40:43], v[170:173], v[178:181], v[40:43]
	v_mfma_f32_16x16x32_bf16 v[40:43], v[174:177], v[182:185], v[40:43]
	v_mfma_f32_16x16x32_bf16 v[28:31], v[162:165], v[186:189], v[28:31]
	v_mfma_f32_16x16x32_bf16 v[28:31], v[166:169], v[190:193], v[28:31]
	v_mfma_f32_16x16x32_bf16 v[24:27], v[170:173], v[186:189], v[24:27]
	v_mfma_f32_16x16x32_bf16 v[24:27], v[174:177], v[190:193], v[24:27]
	v_mfma_f32_16x16x32_bf16 v[12:15], v[162:165], v[194:197], v[12:15]
	v_mfma_f32_16x16x32_bf16 v[12:15], v[166:169], v[198:201], v[12:15]
	v_mfma_f32_16x16x32_bf16 v[8:11], v[170:173], v[194:197], v[8:11]
	v_mfma_f32_16x16x32_bf16 v[8:11], v[174:177], v[198:201], v[8:11]
	v_mfma_f32_16x16x32_bf16 v[4:7], v[162:165], v[202:205], v[4:7]
	v_mfma_f32_16x16x32_bf16 v[4:7], v[166:169], v[206:209], v[4:7]
	v_mfma_f32_16x16x32_bf16 v[0:3], v[170:173], v[202:205], v[0:3]
	v_mfma_f32_16x16x32_bf16 v[0:3], v[174:177], v[206:209], v[0:3]
	s_add_i32 s60, s60, 2
	s_add_u32 s40, s40, 0x100
	s_addc_u32 s41, s41, 0
	s_add_u32 s58, s58, 0x100
	s_addc_u32 s59, s59, 0
	s_cmp_gt_u32 s60, 29
	s_barrier
	s_cbranch_scc0 .LBB0_665
	s_and_b64 vcc, exec, s[10:11]
	s_cbranch_vccz .LBB0_668
	s_barrier

; #define PG8_STAGE(bufoff, gbase, voff) do { _Pragma("unroll") for (int _i = 0; _i < 2; ++_i) \
;         __builtin_amdgcn_global_load_lds((const unsigned*)((const char*)(gbase) + (voff)[_i]), (LAS unsigned*)(lds + (bufoff) + ldsw + _i * 8192), 16, 0, 0); } while (0)
; #define PG8_LDA(dst, b, h) do { _Pragma("unroll") for (int m = 0; m < 4; ++m) _Pragma("unroll") for (int k = 0; k < 2; ++k) dst[m][k] = *(const LAS bf16x8*)(lds + PG8_SA(b, h) + aoff + m * 2048 + k * 1024); } while (0)
; #define PG8_LDB(dst, b, h) do { _Pragma("unroll") for (int n = 0; n < 2; ++n) _Pragma("unroll") for (int k = 0; k < 2; ++k) dst[n][k] = *(const LAS bf16x8*)(lds + PG8_SB(b, h) + boff + n * 2048 + k * 1024); } while (0)
; #define PG8_MMA(ai, bj, At, Bt) do { __builtin_amdgcn_s_setprio(1); _Pragma("unroll") for (int m = 0; m < 4; ++m) _Pragma("unroll") for (int n = 0; n < 2; ++n) _Pragma("unroll") for (int k = 0; k < 2; ++k) \
;         acc[ai][bj][m][n] = __builtin_amdgcn_mfma_f32_16x16x32_bf16(Bt[n][k], At[m][k], acc[ai][bj][m][n], 0, 0, 0); __builtin_amdgcn_s_setprio(0); } while (0)
; #define PG8_WAIT_V(n) asm volatile("s_waitcnt vmcnt(" #n ")" ::: "memory")
; #define PG8_WAIT_L(n) asm volatile("s_waitcnt lgkmcnt(" #n ")" ::: "memory")
; #define PG8_BAR __builtin_amdgcn_s_barrier()
; #define PG8_SCHED __builtin_amdgcn_sched_barrier(0)
; template <class Epi>
; __device__ __forceinline__ void gemm_phase(LAS unsigned char* lds, const Gemm g, const Order& S, const Epi& E, const int wid) {
;     ...
;         for (int t = 0; t < nt; t += 2) {
;             const bool last = (t == nt - 2);
;             const char* a1 = cA + (size_t)(t + 1) * kstep;
;             const char* a2 = last ? nA : cA + (size_t)(t + 2) * kstep; const char* b2 = last ? nB : cB + (size_t)(t + 2) * kstep;
;             const char* a3 = a2 + kstep; const char* b3 = b2 + kstep;
;     ...
;             PG8_LDB(B0, 0, 0); PG8_LDB(B1, 0, 1); PG8_SCHED; PG8_LDA(At, 0, 0); PG8_STAGE(PG8_SA(1, 1), a1 + hA, voffA);
;             PG8_WAIT_V(8); PG8_WAIT_L(0); PG8_BAR; PG8_MMA(0, 0, At, B0); PG8_MMA(0, 1, At, B1); PG8_BAR; PG8_SCHED;
;             PG8_LDA(At, 0, 1); PG8_STAGE(PG8_SB(0, 0), b2, voffB); PG8_STAGE(PG8_SB(0, 1), b2 + hB, voffB); PG8_STAGE(PG8_SA(0, 0), a2, voffA);
.LBB0_742:
	ds_read_b128 v[138:141], v135
	ds_read_b128 v[142:145], v135 offset:1024
	ds_read_b128 v[146:149], v135 offset:2048
	ds_read_b128 v[150:153], v135 offset:3072
	ds_read_b128 v[154:157], v136
	ds_read_b128 v[158:161], v136 offset:1024
	ds_read_b128 v[170:173], v136 offset:2048
	ds_read_b128 v[174:177], v136 offset:3072
	s_add_u32 s54, s46, 0xfff00080
	s_addc_u32 s55, s47, -1
	s_cmp_eq_u32 s68, 60
	s_cselect_b32 s57, s37, s55
	s_cselect_b32 s56, s64, s54
	s_cselect_b32 s55, s39, s67
	s_cselect_b32 s54, s65, s66
	v_lshl_add_u64 v[162:163], s[46:47], 0, v[164:165]
	s_add_i32 m0, s26, 0xc000
	ds_read_b128 v[178:181], v137
	ds_read_b128 v[184:187], v137 offset:1024
	ds_read_b128 v[188:191], v137 offset:2048
	ds_read_b128 v[192:195], v137 offset:3072
	ds_read_b128 v[196:199], v137 offset:4096
	ds_read_b128 v[200:203], v137 offset:5120
	ds_read_b128 v[204:207], v137 offset:6144
	ds_read_b128 v[208:211], v137 offset:7168
	global_load_lds_dwordx4 v[162:163], off
	v_lshl_add_u64 v[162:163], s[46:47], 0, v[132:133]
	s_add_i32 m0, s26, 0xe000
	s_nop 0
	global_load_lds_dwordx4 v[162:163], off
	s_waitcnt vmcnt(8)
	s_waitcnt lgkmcnt(0)
	s_barrier
	s_waitcnt lgkmcnt(0)
	v_mfma_f32_16x16x32_bf16 v[124:127], v[138:141], v[178:181], v[124:127]
	v_mfma_f32_16x16x32_bf16 v[124:127], v[142:145], v[184:187], v[124:127]
	v_mfma_f32_16x16x32_bf16 v[120:123], v[146:149], v[178:181], v[120:123]
	v_mfma_f32_16x16x32_bf16 v[120:123], v[150:153], v[184:187], v[120:123]
	v_mfma_f32_16x16x32_bf16 v[108:111], v[138:141], v[188:191], v[108:111]
	v_mfma_f32_16x16x32_bf16 v[108:111], v[142:145], v[192:195], v[108:111]
	v_mfma_f32_16x16x32_bf16 v[104:107], v[146:149], v[188:191], v[104:107]
	v_mfma_f32_16x16x32_bf16 v[104:107], v[150:153], v[192:195], v[104:107]
	v_mfma_f32_16x16x32_bf16 v[92:95], v[138:141], v[196:199], v[92:95]
	v_mfma_f32_16x16x32_bf16 v[92:95], v[142:145], v[200:203], v[92:95]
	v_mfma_f32_16x16x32_bf16 v[88:91], v[146:149], v[196:199], v[88:91]
	v_mfma_f32_16x16x32_bf16 v[88:91], v[150:153], v[200:203], v[88:91]
	v_mfma_f32_16x16x32_bf16 v[76:79], v[138:141], v[204:207], v[76:79]
	v_mfma_f32_16x16x32_bf16 v[76:79], v[142:145], v[208:211], v[76:79]
	v_mfma_f32_16x16x32_bf16 v[72:75], v[146:149], v[204:207], v[72:75]
	v_mfma_f32_16x16x32_bf16 v[72:75], v[150:153], v[208:211], v[72:75]
	v_mfma_f32_16x16x32_bf16 v[116:119], v[154:157], v[178:181], v[116:119]
	v_mfma_f32_16x16x32_bf16 v[116:119], v[158:161], v[184:187], v[116:119]
	v_mfma_f32_16x16x32_bf16 v[112:115], v[170:173], v[178:181], v[112:115]
	v_mfma_f32_16x16x32_bf16 v[112:115], v[174:177], v[184:187], v[112:115]
	v_mfma_f32_16x16x32_bf16 v[100:103], v[154:157], v[188:191], v[100:103]
	v_mfma_f32_16x16x32_bf16 v[100:103], v[158:161], v[192:195], v[100:103]
	v_mfma_f32_16x16x32_bf16 v[96:99], v[170:173], v[188:191], v[96:99]
	v_mfma_f32_16x16x32_bf16 v[96:99], v[174:177], v[192:195], v[96:99]
	v_mfma_f32_16x16x32_bf16 v[84:87], v[154:157], v[196:199], v[84:87]
	v_mfma_f32_16x16x32_bf16 v[84:87], v[158:161], v[200:203], v[84:87]
	v_mfma_f32_16x16x32_bf16 v[80:83], v[170:173], v[196:199], v[80:83]
	v_mfma_f32_16x16x32_bf16 v[80:83], v[174:177], v[200:203], v[80:83]
	v_mfma_f32_16x16x32_bf16 v[68:71], v[154:157], v[204:207], v[68:71]
	v_mfma_f32_16x16x32_bf16 v[68:71], v[158:161], v[208:211], v[68:71]
	v_mfma_f32_16x16x32_bf16 v[64:67], v[170:173], v[204:207], v[64:67]
	v_mfma_f32_16x16x32_bf16 v[64:67], v[174:177], v[208:211], v[64:67]
	s_barrier
	s_add_i32 s69, s61, s24
	v_lshl_add_u64 v[162:163], s[54:55], 0, v[128:129]
	s_mov_b32 m0, s69
	ds_read_b128 v[178:181], v137 offset:16384
	ds_read_b128 v[184:187], v137 offset:17408
	ds_read_b128 v[188:191], v137 offset:18432
	ds_read_b128 v[192:195], v137 offset:19456
	ds_read_b128 v[196:199], v137 offset:20480
	ds_read_b128 v[200:203], v137 offset:21504
	ds_read_b128 v[204:207], v137 offset:22528
	ds_read_b128 v[208:211], v137 offset:23552
	global_load_lds_dwordx4 v[162:163], off
	s_add_i32 m0, s69, 0x2000
	s_add_u32 s70, s54, 0x100000
	v_lshl_add_u64 v[212:213], s[54:55], 0, v[130:131]
	s_addc_u32 s71, s55, 0
	s_add_i32 s69, s62, s24
	global_load_lds_dwordx4 v[212:213], off
	v_lshl_add_u64 v[214:215], s[70:71], 0, v[128:129]
	s_mov_b32 m0, s69
	v_lshl_add_u64 v[216:217], s[56:57], 0, v[132:133]
	global_load_lds_dwordx4 v[214:215], off
	v_lshl_add_u64 v[214:215], s[70:71], 0, v[130:131]
	s_add_i32 m0, s69, 0x2000
	s_nop 0
	global_load_lds_dwordx4 v[214:215], off
	v_lshl_add_u64 v[214:215], s[56:57], 0, v[164:165]
	s_mov_b32 m0, s26
	s_nop 0
	global_load_lds_dwordx4 v[214:215], off
	s_mov_b32 m0, s27
	s_nop 0
	global_load_lds_dwordx4 v[216:217], off
	s_waitcnt vmcnt(8)
	s_waitcnt lgkmcnt(0)
	s_barrier
; #define PG8_STAGE(bufoff, gbase, voff) do { _Pragma("unroll") for (int _i = 0; _i < 2; ++_i) \
;         __builtin_amdgcn_global_load_lds((const unsigned*)((const char*)(gbase) + (voff)[_i]), (LAS unsigned*)(lds + (bufoff) + ldsw + _i * 8192), 16, 0, 0); } while (0)
; #define PG8_LDA(dst, b, h) do { _Pragma("unroll") for (int m = 0; m < 4; ++m) _Pragma("unroll") for (int k = 0; k < 2; ++k) dst[m][k] = *(const LAS bf16x8*)(lds + PG8_SA(b, h) + aoff + m * 2048 + k * 1024); } while (0)
; #define PG8_LDB(dst, b, h) do { _Pragma("unroll") for (int n = 0; n < 2; ++n) _Pragma("unroll") for (int k = 0; k < 2; ++k) dst[n][k] = *(const LAS bf16x8*)(lds + PG8_SB(b, h) + boff + n * 2048 + k * 1024); } while (0)
; #define PG8_MMA(ai, bj, At, Bt) do { __builtin_amdgcn_s_setprio(1); _Pragma("unroll") for (int m = 0; m < 4; ++m) _Pragma("unroll") for (int n = 0; n < 2; ++n) _Pragma("unroll") for (int k = 0; k < 2; ++k) \
;         acc[ai][bj][m][n] = __builtin_amdgcn_mfma_f32_16x16x32_bf16(Bt[n][k], At[m][k], acc[ai][bj][m][n], 0, 0, 0); __builtin_amdgcn_s_setprio(0); } while (0)
; #define PG8_WAIT_V(n) asm volatile("s_waitcnt vmcnt(" #n ")" ::: "memory")
; #define PG8_WAIT_L(n) asm volatile("s_waitcnt lgkmcnt(" #n ")" ::: "memory")
; #define PG8_BAR __builtin_amdgcn_s_barrier()
; #define PG8_SCHED __builtin_amdgcn_sched_barrier(0)
; template <class Epi>
; __device__ __forceinline__ void gemm_phase(LAS unsigned char* lds, const Gemm g, const Order& S, const Epi& E, const int wid) {
;     ...
;             PG8_WAIT_V(8); PG8_WAIT_L(0); PG8_BAR; PG8_MMA(1, 0, At, B0); PG8_MMA(1, 1, At, B1); PG8_BAR; PG8_SCHED;
;             PG8_LDB(B0, 1, 0); PG8_LDB(B1, 1, 1); PG8_SCHED; PG8_LDA(At, 1, 0); PG8_STAGE(PG8_SA(0, 1), a2 + hA, voffA);
;             PG8_WAIT_V(8); PG8_WAIT_L(0); PG8_BAR; PG8_MMA(0, 0, At, B0); PG8_MMA(0, 1, At, B1); PG8_BAR; PG8_SCHED;
	s_waitcnt lgkmcnt(0)
	v_mfma_f32_16x16x32_bf16 v[60:63], v[138:141], v[178:181], v[60:63]
	v_mfma_f32_16x16x32_bf16 v[60:63], v[142:145], v[184:187], v[60:63]
	v_mfma_f32_16x16x32_bf16 v[56:59], v[146:149], v[178:181], v[56:59]
	v_mfma_f32_16x16x32_bf16 v[56:59], v[150:153], v[184:187], v[56:59]
	v_mfma_f32_16x16x32_bf16 v[44:47], v[138:141], v[188:191], v[44:47]
	v_mfma_f32_16x16x32_bf16 v[44:47], v[142:145], v[192:195], v[44:47]
	v_mfma_f32_16x16x32_bf16 v[40:43], v[146:149], v[188:191], v[40:43]
	v_mfma_f32_16x16x32_bf16 v[40:43], v[150:153], v[192:195], v[40:43]
	v_mfma_f32_16x16x32_bf16 v[28:31], v[138:141], v[196:199], v[28:31]
	v_mfma_f32_16x16x32_bf16 v[28:31], v[142:145], v[200:203], v[28:31]
	v_mfma_f32_16x16x32_bf16 v[24:27], v[146:149], v[196:199], v[24:27]
	v_mfma_f32_16x16x32_bf16 v[24:27], v[150:153], v[200:203], v[24:27]
	v_mfma_f32_16x16x32_bf16 v[12:15], v[138:141], v[204:207], v[12:15]
	v_mfma_f32_16x16x32_bf16 v[12:15], v[142:145], v[208:211], v[12:15]
	v_mfma_f32_16x16x32_bf16 v[8:11], v[146:149], v[204:207], v[8:11]
	v_mfma_f32_16x16x32_bf16 v[8:11], v[150:153], v[208:211], v[8:11]
	v_mfma_f32_16x16x32_bf16 v[52:55], v[154:157], v[178:181], v[52:55]
	v_mfma_f32_16x16x32_bf16 v[52:55], v[158:161], v[184:187], v[52:55]
	v_mfma_f32_16x16x32_bf16 v[48:51], v[170:173], v[178:181], v[48:51]
	v_mfma_f32_16x16x32_bf16 v[48:51], v[174:177], v[184:187], v[48:51]
	v_mfma_f32_16x16x32_bf16 v[36:39], v[154:157], v[188:191], v[36:39]
	v_mfma_f32_16x16x32_bf16 v[36:39], v[158:161], v[192:195], v[36:39]
	v_mfma_f32_16x16x32_bf16 v[32:35], v[170:173], v[188:191], v[32:35]
	v_mfma_f32_16x16x32_bf16 v[32:35], v[174:177], v[192:195], v[32:35]
	v_mfma_f32_16x16x32_bf16 v[20:23], v[154:157], v[196:199], v[20:23]
	v_mfma_f32_16x16x32_bf16 v[20:23], v[158:161], v[200:203], v[20:23]
	v_mfma_f32_16x16x32_bf16 v[16:19], v[170:173], v[196:199], v[16:19]
	v_mfma_f32_16x16x32_bf16 v[16:19], v[174:177], v[200:203], v[16:19]
	v_mfma_f32_16x16x32_bf16 v[4:7], v[154:157], v[204:207], v[4:7]
	v_mfma_f32_16x16x32_bf16 v[4:7], v[158:161], v[208:211], v[4:7]
	v_mfma_f32_16x16x32_bf16 v[0:3], v[170:173], v[204:207], v[0:3]
	v_mfma_f32_16x16x32_bf16 v[0:3], v[174:177], v[208:211], v[0:3]
	s_barrier
	s_add_i32 s69, 0, 0x18000
	s_add_i32 s70, 0, 0x1c000
	v_add_u32_e32 v150, s69, v134
	v_add_u32_e32 v174, s70, v134
	ds_read_b128 v[138:141], v150
	ds_read_b128 v[142:145], v150 offset:1024
	ds_read_b128 v[146:149], v150 offset:2048
	ds_read_b128 v[150:153], v150 offset:3072
	ds_read_b128 v[154:157], v174
	ds_read_b128 v[158:161], v174 offset:1024
	ds_read_b128 v[170:173], v174 offset:2048
	ds_read_b128 v[174:177], v174 offset:3072
	s_add_u32 s56, s56, 0x100000
	s_addc_u32 s57, s57, 0
	s_mov_b32 m0, s28
	v_lshl_add_u64 v[218:219], s[56:57], 0, v[164:165]
	ds_read_b128 v[178:181], v137 offset:32768
	ds_read_b128 v[184:187], v137 offset:33792
	ds_read_b128 v[188:191], v137 offset:34816
	ds_read_b128 v[192:195], v137 offset:35840
	ds_read_b128 v[196:199], v137 offset:36864
	ds_read_b128 v[200:203], v137 offset:37888
	ds_read_b128 v[204:207], v137 offset:38912
	ds_read_b128 v[208:211], v137 offset:39936
	global_load_lds_dwordx4 v[218:219], off
	v_lshl_add_u64 v[218:219], s[56:57], 0, v[132:133]
	s_mov_b32 m0, s29
	s_nop 0
	global_load_lds_dwordx4 v[218:219], off
	s_waitcnt vmcnt(8)
	s_waitcnt lgkmcnt(0)
	s_barrier
	s_waitcnt lgkmcnt(0)
	v_mfma_f32_16x16x32_bf16 v[124:127], v[138:141], v[178:181], v[124:127]
	v_mfma_f32_16x16x32_bf16 v[124:127], v[142:145], v[184:187], v[124:127]
	v_mfma_f32_16x16x32_bf16 v[120:123], v[146:149], v[178:181], v[120:123]
	v_mfma_f32_16x16x32_bf16 v[120:123], v[150:153], v[184:187], v[120:123]
	v_mfma_f32_16x16x32_bf16 v[108:111], v[138:141], v[188:191], v[108:111]
	v_mfma_f32_16x16x32_bf16 v[108:111], v[142:145], v[192:195], v[108:111]
	v_mfma_f32_16x16x32_bf16 v[104:107], v[146:149], v[188:191], v[104:107]
	v_mfma_f32_16x16x32_bf16 v[104:107], v[150:153], v[192:195], v[104:107]
	v_mfma_f32_16x16x32_bf16 v[92:95], v[138:141], v[196:199], v[92:95]
	v_mfma_f32_16x16x32_bf16 v[92:95], v[142:145], v[200:203], v[92:95]
	v_mfma_f32_16x16x32_bf16 v[88:91], v[146:149], v[196:199], v[88:91]
	v_mfma_f32_16x16x32_bf16 v[88:91], v[150:153], v[200:203], v[88:91]
	v_mfma_f32_16x16x32_bf16 v[76:79], v[138:141], v[204:207], v[76:79]
	v_mfma_f32_16x16x32_bf16 v[76:79], v[142:145], v[208:211], v[76:79]
	v_mfma_f32_16x16x32_bf16 v[72:75], v[146:149], v[204:207], v[72:75]
	v_mfma_f32_16x16x32_bf16 v[72:75], v[150:153], v[208:211], v[72:75]
	v_mfma_f32_16x16x32_bf16 v[116:119], v[154:157], v[178:181], v[116:119]
	v_mfma_f32_16x16x32_bf16 v[116:119], v[158:161], v[184:187], v[116:119]
	v_mfma_f32_16x16x32_bf16 v[112:115], v[170:173], v[178:181], v[112:115]
	v_mfma_f32_16x16x32_bf16 v[112:115], v[174:177], v[184:187], v[112:115]
	v_mfma_f32_16x16x32_bf16 v[100:103], v[154:157], v[188:191], v[100:103]
	v_mfma_f32_16x16x32_bf16 v[100:103], v[158:161], v[192:195], v[100:103]
	v_mfma_f32_16x16x32_bf16 v[96:99], v[170:173], v[188:191], v[96:99]
	v_mfma_f32_16x16x32_bf16 v[96:99], v[174:177], v[192:195], v[96:99]
	v_mfma_f32_16x16x32_bf16 v[84:87], v[154:157], v[196:199], v[84:87]
	v_mfma_f32_16x16x32_bf16 v[84:87], v[158:161], v[200:203], v[84:87]
	v_mfma_f32_16x16x32_bf16 v[80:83], v[170:173], v[196:199], v[80:83]
	v_mfma_f32_16x16x32_bf16 v[80:83], v[174:177], v[200:203], v[80:83]
	v_mfma_f32_16x16x32_bf16 v[68:71], v[154:157], v[204:207], v[68:71]
	v_mfma_f32_16x16x32_bf16 v[68:71], v[158:161], v[208:211], v[68:71]
	v_mfma_f32_16x16x32_bf16 v[64:67], v[170:173], v[204:207], v[64:67]
	v_mfma_f32_16x16x32_bf16 v[64:67], v[174:177], v[208:211], v[64:67]
	s_barrier
; #define PG8_STAGE(bufoff, gbase, voff) do { _Pragma("unroll") for (int _i = 0; _i < 2; ++_i) \
;         __builtin_amdgcn_global_load_lds((const unsigned*)((const char*)(gbase) + (voff)[_i]), (LAS unsigned*)(lds + (bufoff) + ldsw + _i * 8192), 16, 0, 0); } while (0)
; #define PG8_LDA(dst, b, h) do { _Pragma("unroll") for (int m = 0; m < 4; ++m) _Pragma("unroll") for (int k = 0; k < 2; ++k) dst[m][k] = *(const LAS bf16x8*)(lds + PG8_SA(b, h) + aoff + m * 2048 + k * 1024); } while (0)
; #define PG8_MMA(ai, bj, At, Bt) do { __builtin_amdgcn_s_setprio(1); _Pragma("unroll") for (int m = 0; m < 4; ++m) _Pragma("unroll") for (int n = 0; n < 2; ++n) _Pragma("unroll") for (int k = 0; k < 2; ++k) \
;         acc[ai][bj][m][n] = __builtin_amdgcn_mfma_f32_16x16x32_bf16(Bt[n][k], At[m][k], acc[ai][bj][m][n], 0, 0, 0); __builtin_amdgcn_s_setprio(0); } while (0)
; #define PG8_WAIT_V(n) asm volatile("s_waitcnt vmcnt(" #n ")" ::: "memory")
; #define PG8_WAIT_L(n) asm volatile("s_waitcnt lgkmcnt(" #n ")" ::: "memory")
; #define PG8_BAR __builtin_amdgcn_s_barrier()
; #define PG8_SCHED __builtin_amdgcn_sched_barrier(0)
; template <class Epi>
; __device__ __forceinline__ void gemm_phase(LAS unsigned char* lds, const Gemm g, const Order& S, const Epi& E, const int wid) {
;     ...
;         for (int t = 0; t < nt; t += 2) {
;     ...
;             PG8_LDA(At, 1, 1); PG8_STAGE(PG8_SB(1, 0), b3, voffB); PG8_STAGE(PG8_SB(1, 1), b3 + hB, voffB); PG8_STAGE(PG8_SA(1, 0), a3, voffA);
;             PG8_WAIT_V(8); PG8_WAIT_L(0); PG8_BAR; PG8_MMA(1, 0, At, B0); PG8_MMA(1, 1, At, B1); PG8_BAR; PG8_SCHED;
	s_add_i32 s56, s69, s24
	v_lshl_add_u64 v[162:163], v[162:163], 0, s[18:19]
	s_mov_b32 m0, s56
	ds_read_b128 v[178:181], v137 offset:49152
	ds_read_b128 v[184:187], v137 offset:50176
	ds_read_b128 v[188:191], v137 offset:51200
	ds_read_b128 v[192:195], v137 offset:52224
	ds_read_b128 v[196:199], v137 offset:53248
	ds_read_b128 v[200:203], v137 offset:54272
	ds_read_b128 v[204:207], v137 offset:55296
	ds_read_b128 v[208:211], v137 offset:56320
	global_load_lds_dwordx4 v[162:163], off
	s_add_i32 m0, s56, 0x2000
	s_add_u32 s54, s54, 0x100080
	v_lshl_add_u64 v[162:163], v[212:213], 0, s[18:19]
	s_addc_u32 s55, s55, 0
	s_add_i32 s56, s70, s24
	global_load_lds_dwordx4 v[162:163], off
	v_lshl_add_u64 v[162:163], s[54:55], 0, v[128:129]
	s_mov_b32 m0, s56
	s_nop 0
	global_load_lds_dwordx4 v[162:163], off
	v_lshl_add_u64 v[162:163], s[54:55], 0, v[130:131]
	s_add_i32 m0, s56, 0x2000
	s_nop 0
	global_load_lds_dwordx4 v[162:163], off
	v_lshl_add_u64 v[162:163], v[214:215], 0, s[18:19]
	s_mov_b32 m0, s58
	s_nop 0
	global_load_lds_dwordx4 v[162:163], off
	v_lshl_add_u64 v[162:163], v[216:217], 0, s[18:19]
	s_mov_b32 m0, s59
	s_nop 0
	global_load_lds_dwordx4 v[162:163], off
	s_waitcnt vmcnt(8)
	s_waitcnt lgkmcnt(0)
	s_barrier
	s_waitcnt lgkmcnt(0)
	v_mfma_f32_16x16x32_bf16 v[60:63], v[138:141], v[178:181], v[60:63]
	v_mfma_f32_16x16x32_bf16 v[60:63], v[142:145], v[184:187], v[60:63]
	v_mfma_f32_16x16x32_bf16 v[56:59], v[146:149], v[178:181], v[56:59]
	v_mfma_f32_16x16x32_bf16 v[56:59], v[150:153], v[184:187], v[56:59]
	v_mfma_f32_16x16x32_bf16 v[44:47], v[138:141], v[188:191], v[44:47]
	v_mfma_f32_16x16x32_bf16 v[44:47], v[142:145], v[192:195], v[44:47]
	v_mfma_f32_16x16x32_bf16 v[40:43], v[146:149], v[188:191], v[40:43]
	v_mfma_f32_16x16x32_bf16 v[40:43], v[150:153], v[192:195], v[40:43]
	v_mfma_f32_16x16x32_bf16 v[28:31], v[138:141], v[196:199], v[28:31]
	v_mfma_f32_16x16x32_bf16 v[28:31], v[142:145], v[200:203], v[28:31]
	v_mfma_f32_16x16x32_bf16 v[24:27], v[146:149], v[196:199], v[24:27]
	v_mfma_f32_16x16x32_bf16 v[24:27], v[150:153], v[200:203], v[24:27]
	v_mfma_f32_16x16x32_bf16 v[12:15], v[138:141], v[204:207], v[12:15]
	v_mfma_f32_16x16x32_bf16 v[12:15], v[142:145], v[208:211], v[12:15]
	v_mfma_f32_16x16x32_bf16 v[8:11], v[146:149], v[204:207], v[8:11]
	v_mfma_f32_16x16x32_bf16 v[8:11], v[150:153], v[208:211], v[8:11]
	v_mfma_f32_16x16x32_bf16 v[52:55], v[154:157], v[178:181], v[52:55]
	v_mfma_f32_16x16x32_bf16 v[52:55], v[158:161], v[184:187], v[52:55]
	v_mfma_f32_16x16x32_bf16 v[48:51], v[170:173], v[178:181], v[48:51]
	v_mfma_f32_16x16x32_bf16 v[48:51], v[174:177], v[184:187], v[48:51]
	v_mfma_f32_16x16x32_bf16 v[36:39], v[154:157], v[188:191], v[36:39]
	v_mfma_f32_16x16x32_bf16 v[36:39], v[158:161], v[192:195], v[36:39]
	v_mfma_f32_16x16x32_bf16 v[32:35], v[170:173], v[188:191], v[32:35]
	v_mfma_f32_16x16x32_bf16 v[32:35], v[174:177], v[192:195], v[32:35]
	v_mfma_f32_16x16x32_bf16 v[20:23], v[154:157], v[196:199], v[20:23]
	v_mfma_f32_16x16x32_bf16 v[20:23], v[158:161], v[200:203], v[20:23]
	v_mfma_f32_16x16x32_bf16 v[16:19], v[170:173], v[196:199], v[16:19]
	v_mfma_f32_16x16x32_bf16 v[16:19], v[174:177], v[200:203], v[16:19]
	v_mfma_f32_16x16x32_bf16 v[4:7], v[154:157], v[204:207], v[4:7]
	v_mfma_f32_16x16x32_bf16 v[4:7], v[158:161], v[208:211], v[4:7]
	v_mfma_f32_16x16x32_bf16 v[0:3], v[170:173], v[204:207], v[0:3]
	v_mfma_f32_16x16x32_bf16 v[0:3], v[174:177], v[208:211], v[0:3]
	s_add_i32 s68, s68, 2
	s_add_u32 s46, s46, 0x100
	s_addc_u32 s47, s47, 0
	s_add_u32 s66, s66, 0x100
	s_addc_u32 s67, s67, 0
	s_cmp_gt_u32 s68, 61
	s_barrier
	s_cbranch_scc0 .LBB0_742
	s_and_b64 vcc, exec, s[16:17]
	s_cbranch_vccz .LBB0_745
	s_barrier

; #define PG8_STAGE(bufoff, gbase, voff) do { _Pragma("unroll") for (int _i = 0; _i < 2; ++_i) \
;         __builtin_amdgcn_global_load_lds((const unsigned*)((const char*)(gbase) + (voff)[_i]), (LAS unsigned*)(lds + (bufoff) + ldsw + _i * 8192), 16, 0, 0); } while (0)
; #define PG8_LDA(dst, b, h) do { _Pragma("unroll") for (int m = 0; m < 4; ++m) _Pragma("unroll") for (int k = 0; k < 2; ++k) dst[m][k] = *(const LAS bf16x8*)(lds + PG8_SA(b, h) + aoff + m * 2048 + k * 1024); } while (0)
; #define PG8_LDB(dst, b, h) do { _Pragma("unroll") for (int n = 0; n < 2; ++n) _Pragma("unroll") for (int k = 0; k < 2; ++k) dst[n][k] = *(const LAS bf16x8*)(lds + PG8_SB(b, h) + boff + n * 2048 + k * 1024); } while (0)
; #define PG8_MMA(ai, bj, At, Bt) do { __builtin_amdgcn_s_setprio(1); _Pragma("unroll") for (int m = 0; m < 4; ++m) _Pragma("unroll") for (int n = 0; n < 2; ++n) _Pragma("unroll") for (int k = 0; k < 2; ++k) \
;         acc[ai][bj][m][n] = __builtin_amdgcn_mfma_f32_16x16x32_bf16(Bt[n][k], At[m][k], acc[ai][bj][m][n], 0, 0, 0); __builtin_amdgcn_s_setprio(0); } while (0)
; #define PG8_WAIT_V(n) asm volatile("s_waitcnt vmcnt(" #n ")" ::: "memory")
; #define PG8_WAIT_L(n) asm volatile("s_waitcnt lgkmcnt(" #n ")" ::: "memory")
; #define PG8_BAR __builtin_amdgcn_s_barrier()
; #define PG8_SCHED __builtin_amdgcn_sched_barrier(0)
; template <class Epi>
; __device__ __forceinline__ void gemm_phase(LAS unsigned char* lds, const Gemm g, const Order& S, const Epi& E, const int wid) {
;     ...
;         for (int t = 0; t < nt; t += 2) {
;             const bool last = (t == nt - 2);
;             const char* a1 = cA + (size_t)(t + 1) * kstep;
;             const char* a2 = last ? nA : cA + (size_t)(t + 2) * kstep; const char* b2 = last ? nB : cB + (size_t)(t + 2) * kstep;
;             const char* a3 = a2 + kstep; const char* b3 = b2 + kstep;
;     ...
;             PG8_LDB(B0, 0, 0); PG8_LDB(B1, 0, 1); PG8_SCHED; PG8_LDA(At, 0, 0); PG8_STAGE(PG8_SA(1, 1), a1 + hA, voffA);
;             PG8_WAIT_V(8); PG8_WAIT_L(0); PG8_BAR; PG8_MMA(0, 0, At, B0); PG8_MMA(0, 1, At, B1); PG8_BAR; PG8_SCHED;
;             PG8_LDA(At, 0, 1); PG8_STAGE(PG8_SB(0, 0), b2, voffB); PG8_STAGE(PG8_SB(0, 1), b2 + hB, voffB); PG8_STAGE(PG8_SA(0, 0), a2, voffA);
.LBB0_821:
	ds_read_b128 v[138:141], v135
	ds_read_b128 v[150:153], v135 offset:1024
	ds_read_b128 v[154:157], v135 offset:2048
	ds_read_b128 v[162:165], v135 offset:3072
	ds_read_b128 v[166:169], v136
	ds_read_b128 v[170:173], v136 offset:1024
	ds_read_b128 v[174:177], v136 offset:2048
	ds_read_b128 v[178:181], v136 offset:3072
	s_add_u32 s54, s46, 0xfff00080
	s_addc_u32 s55, s47, -1
	s_cmp_eq_u32 s63, 60
	s_cselect_b32 s57, s5, s55
	s_cselect_b32 s56, s7, s54
	s_cselect_b32 s55, s39, s62
	s_cselect_b32 s54, s41, s61
	v_lshl_add_u64 v[142:143], s[46:47], 0, v[144:145]
	s_add_i32 m0, s25, 0xc000
	ds_read_b128 v[182:185], v137
	ds_read_b128 v[186:189], v137 offset:1024
	ds_read_b128 v[190:193], v137 offset:2048
	ds_read_b128 v[194:197], v137 offset:3072
	ds_read_b128 v[198:201], v137 offset:4096
	ds_read_b128 v[202:205], v137 offset:5120
	ds_read_b128 v[206:209], v137 offset:6144
	ds_read_b128 v[210:213], v137 offset:7168
	global_load_lds_dwordx4 v[142:143], off
	v_lshl_add_u64 v[142:143], s[46:47], 0, v[132:133]
	s_add_i32 m0, s25, 0xe000
	s_nop 0
	global_load_lds_dwordx4 v[142:143], off
	s_waitcnt vmcnt(8)
	s_waitcnt lgkmcnt(0)
	s_barrier
	s_waitcnt lgkmcnt(0)
	v_mfma_f32_16x16x32_bf16 v[124:127], v[138:141], v[182:185], v[124:127]
	v_mfma_f32_16x16x32_bf16 v[124:127], v[150:153], v[186:189], v[124:127]
	v_mfma_f32_16x16x32_bf16 v[120:123], v[154:157], v[182:185], v[120:123]
	v_mfma_f32_16x16x32_bf16 v[120:123], v[162:165], v[186:189], v[120:123]
	v_mfma_f32_16x16x32_bf16 v[108:111], v[138:141], v[190:193], v[108:111]
	v_mfma_f32_16x16x32_bf16 v[108:111], v[150:153], v[194:197], v[108:111]
	v_mfma_f32_16x16x32_bf16 v[104:107], v[154:157], v[190:193], v[104:107]
	v_mfma_f32_16x16x32_bf16 v[104:107], v[162:165], v[194:197], v[104:107]
	v_mfma_f32_16x16x32_bf16 v[92:95], v[138:141], v[198:201], v[92:95]
	v_mfma_f32_16x16x32_bf16 v[92:95], v[150:153], v[202:205], v[92:95]
	v_mfma_f32_16x16x32_bf16 v[88:91], v[154:157], v[198:201], v[88:91]
	v_mfma_f32_16x16x32_bf16 v[88:91], v[162:165], v[202:205], v[88:91]
	v_mfma_f32_16x16x32_bf16 v[76:79], v[138:141], v[206:209], v[76:79]
	v_mfma_f32_16x16x32_bf16 v[76:79], v[150:153], v[210:213], v[76:79]
	v_mfma_f32_16x16x32_bf16 v[72:75], v[154:157], v[206:209], v[72:75]
	v_mfma_f32_16x16x32_bf16 v[72:75], v[162:165], v[210:213], v[72:75]
	v_mfma_f32_16x16x32_bf16 v[116:119], v[166:169], v[182:185], v[116:119]
	v_mfma_f32_16x16x32_bf16 v[116:119], v[170:173], v[186:189], v[116:119]
	v_mfma_f32_16x16x32_bf16 v[112:115], v[174:177], v[182:185], v[112:115]
	v_mfma_f32_16x16x32_bf16 v[112:115], v[178:181], v[186:189], v[112:115]
	v_mfma_f32_16x16x32_bf16 v[100:103], v[166:169], v[190:193], v[100:103]
	v_mfma_f32_16x16x32_bf16 v[100:103], v[170:173], v[194:197], v[100:103]
	v_mfma_f32_16x16x32_bf16 v[96:99], v[174:177], v[190:193], v[96:99]
	v_mfma_f32_16x16x32_bf16 v[96:99], v[178:181], v[194:197], v[96:99]
	v_mfma_f32_16x16x32_bf16 v[84:87], v[166:169], v[198:201], v[84:87]
	v_mfma_f32_16x16x32_bf16 v[84:87], v[170:173], v[202:205], v[84:87]
	v_mfma_f32_16x16x32_bf16 v[80:83], v[174:177], v[198:201], v[80:83]
	v_mfma_f32_16x16x32_bf16 v[80:83], v[178:181], v[202:205], v[80:83]
	v_mfma_f32_16x16x32_bf16 v[68:71], v[166:169], v[206:209], v[68:71]
	v_mfma_f32_16x16x32_bf16 v[68:71], v[170:173], v[210:213], v[68:71]
	v_mfma_f32_16x16x32_bf16 v[64:67], v[174:177], v[206:209], v[64:67]
	v_mfma_f32_16x16x32_bf16 v[64:67], v[178:181], v[210:213], v[64:67]
	s_barrier
	s_add_i32 s64, s59, s24
	v_lshl_add_u64 v[142:143], s[54:55], 0, v[128:129]
	s_mov_b32 m0, s64
	ds_read_b128 v[182:185], v137 offset:16384
	ds_read_b128 v[186:189], v137 offset:17408
	ds_read_b128 v[190:193], v137 offset:18432
	ds_read_b128 v[194:197], v137 offset:19456
	ds_read_b128 v[198:201], v137 offset:20480
	ds_read_b128 v[202:205], v137 offset:21504
	ds_read_b128 v[206:209], v137 offset:22528
	ds_read_b128 v[210:213], v137 offset:23552
	global_load_lds_dwordx4 v[142:143], off
	s_add_i32 m0, s64, 0x2000
	s_add_u32 s64, s54, 0x100000
	v_lshl_add_u64 v[158:159], s[54:55], 0, v[130:131]
	s_addc_u32 s65, s55, 0
	s_add_i32 s66, s60, s24
	global_load_lds_dwordx4 v[158:159], off
	v_lshl_add_u64 v[214:215], s[64:65], 0, v[128:129]
	s_mov_b32 m0, s66
	v_lshl_add_u64 v[216:217], s[56:57], 0, v[132:133]
	global_load_lds_dwordx4 v[214:215], off
	v_lshl_add_u64 v[214:215], s[64:65], 0, v[130:131]
	s_add_i32 m0, s66, 0x2000
	s_nop 0
	global_load_lds_dwordx4 v[214:215], off
	v_lshl_add_u64 v[214:215], s[56:57], 0, v[144:145]
	s_mov_b32 m0, s25
	s_nop 0
	global_load_lds_dwordx4 v[214:215], off
	s_mov_b32 m0, s26
	s_nop 0
	global_load_lds_dwordx4 v[216:217], off
	s_waitcnt vmcnt(8)
	s_waitcnt lgkmcnt(0)
	s_barrier
; #define PG8_STAGE(bufoff, gbase, voff) do { _Pragma("unroll") for (int _i = 0; _i < 2; ++_i) \
;         __builtin_amdgcn_global_load_lds((const unsigned*)((const char*)(gbase) + (voff)[_i]), (LAS unsigned*)(lds + (bufoff) + ldsw + _i * 8192), 16, 0, 0); } while (0)
; #define PG8_LDA(dst, b, h) do { _Pragma("unroll") for (int m = 0; m < 4; ++m) _Pragma("unroll") for (int k = 0; k < 2; ++k) dst[m][k] = *(const LAS bf16x8*)(lds + PG8_SA(b, h) + aoff + m * 2048 + k * 1024); } while (0)
; #define PG8_LDB(dst, b, h) do { _Pragma("unroll") for (int n = 0; n < 2; ++n) _Pragma("unroll") for (int k = 0; k < 2; ++k) dst[n][k] = *(const LAS bf16x8*)(lds + PG8_SB(b, h) + boff + n * 2048 + k * 1024); } while (0)
; #define PG8_MMA(ai, bj, At, Bt) do { __builtin_amdgcn_s_setprio(1); _Pragma("unroll") for (int m = 0; m < 4; ++m) _Pragma("unroll") for (int n = 0; n < 2; ++n) _Pragma("unroll") for (int k = 0; k < 2; ++k) \
;         acc[ai][bj][m][n] = __builtin_amdgcn_mfma_f32_16x16x32_bf16(Bt[n][k], At[m][k], acc[ai][bj][m][n], 0, 0, 0); __builtin_amdgcn_s_setprio(0); } while (0)
; #define PG8_WAIT_V(n) asm volatile("s_waitcnt vmcnt(" #n ")" ::: "memory")
; #define PG8_WAIT_L(n) asm volatile("s_waitcnt lgkmcnt(" #n ")" ::: "memory")
; #define PG8_BAR __builtin_amdgcn_s_barrier()
; #define PG8_SCHED __builtin_amdgcn_sched_barrier(0)
; template <class Epi>
; __device__ __forceinline__ void gemm_phase(LAS unsigned char* lds, const Gemm g, const Order& S, const Epi& E, const int wid) {
;     ...
;             PG8_WAIT_V(8); PG8_WAIT_L(0); PG8_BAR; PG8_MMA(1, 0, At, B0); PG8_MMA(1, 1, At, B1); PG8_BAR; PG8_SCHED;
;             PG8_LDB(B0, 1, 0); PG8_LDB(B1, 1, 1); PG8_SCHED; PG8_LDA(At, 1, 0); PG8_STAGE(PG8_SA(0, 1), a2 + hA, voffA);
;             PG8_WAIT_V(8); PG8_WAIT_L(0); PG8_BAR; PG8_MMA(0, 0, At, B0); PG8_MMA(0, 1, At, B1); PG8_BAR; PG8_SCHED;
	s_waitcnt lgkmcnt(0)
	v_mfma_f32_16x16x32_bf16 v[60:63], v[138:141], v[182:185], v[60:63]
	v_mfma_f32_16x16x32_bf16 v[60:63], v[150:153], v[186:189], v[60:63]
	v_mfma_f32_16x16x32_bf16 v[56:59], v[154:157], v[182:185], v[56:59]
	v_mfma_f32_16x16x32_bf16 v[56:59], v[162:165], v[186:189], v[56:59]
	v_mfma_f32_16x16x32_bf16 v[44:47], v[138:141], v[190:193], v[44:47]
	v_mfma_f32_16x16x32_bf16 v[44:47], v[150:153], v[194:197], v[44:47]
	v_mfma_f32_16x16x32_bf16 v[40:43], v[154:157], v[190:193], v[40:43]
	v_mfma_f32_16x16x32_bf16 v[40:43], v[162:165], v[194:197], v[40:43]
	v_mfma_f32_16x16x32_bf16 v[28:31], v[138:141], v[198:201], v[28:31]
	v_mfma_f32_16x16x32_bf16 v[28:31], v[150:153], v[202:205], v[28:31]
	v_mfma_f32_16x16x32_bf16 v[24:27], v[154:157], v[198:201], v[24:27]
	v_mfma_f32_16x16x32_bf16 v[24:27], v[162:165], v[202:205], v[24:27]
	v_mfma_f32_16x16x32_bf16 v[12:15], v[138:141], v[206:209], v[12:15]
	v_mfma_f32_16x16x32_bf16 v[12:15], v[150:153], v[210:213], v[12:15]
	v_mfma_f32_16x16x32_bf16 v[8:11], v[154:157], v[206:209], v[8:11]
	v_mfma_f32_16x16x32_bf16 v[8:11], v[162:165], v[210:213], v[8:11]
	v_mfma_f32_16x16x32_bf16 v[52:55], v[166:169], v[182:185], v[52:55]
	v_mfma_f32_16x16x32_bf16 v[52:55], v[170:173], v[186:189], v[52:55]
	v_mfma_f32_16x16x32_bf16 v[48:51], v[174:177], v[182:185], v[48:51]
	v_mfma_f32_16x16x32_bf16 v[48:51], v[178:181], v[186:189], v[48:51]
	v_mfma_f32_16x16x32_bf16 v[36:39], v[166:169], v[190:193], v[36:39]
	v_mfma_f32_16x16x32_bf16 v[36:39], v[170:173], v[194:197], v[36:39]
	v_mfma_f32_16x16x32_bf16 v[32:35], v[174:177], v[190:193], v[32:35]
	v_mfma_f32_16x16x32_bf16 v[32:35], v[178:181], v[194:197], v[32:35]
	v_mfma_f32_16x16x32_bf16 v[20:23], v[166:169], v[198:201], v[20:23]
	v_mfma_f32_16x16x32_bf16 v[20:23], v[170:173], v[202:205], v[20:23]
	v_mfma_f32_16x16x32_bf16 v[16:19], v[174:177], v[198:201], v[16:19]
	v_mfma_f32_16x16x32_bf16 v[16:19], v[178:181], v[202:205], v[16:19]
	v_mfma_f32_16x16x32_bf16 v[4:7], v[166:169], v[206:209], v[4:7]
	v_mfma_f32_16x16x32_bf16 v[4:7], v[170:173], v[210:213], v[4:7]
	v_mfma_f32_16x16x32_bf16 v[0:3], v[174:177], v[206:209], v[0:3]
	v_mfma_f32_16x16x32_bf16 v[0:3], v[178:181], v[210:213], v[0:3]
	s_barrier
	s_add_i32 s64, 0, 0x18000
	s_add_i32 s65, 0, 0x1c000
	v_add_u32_e32 v162, s64, v134
	v_add_u32_e32 v178, s65, v134
	ds_read_b128 v[138:141], v162
	ds_read_b128 v[150:153], v162 offset:1024
	ds_read_b128 v[154:157], v162 offset:2048
	ds_read_b128 v[162:165], v162 offset:3072
	ds_read_b128 v[166:169], v178
	ds_read_b128 v[170:173], v178 offset:1024
	ds_read_b128 v[174:177], v178 offset:2048
	ds_read_b128 v[178:181], v178 offset:3072
	s_add_u32 s56, s56, 0x100000
	s_addc_u32 s57, s57, 0
	s_mov_b32 m0, s27
	v_lshl_add_u64 v[218:219], s[56:57], 0, v[144:145]
	ds_read_b128 v[182:185], v137 offset:32768
	ds_read_b128 v[186:189], v137 offset:33792
	ds_read_b128 v[190:193], v137 offset:34816
	ds_read_b128 v[194:197], v137 offset:35840
	ds_read_b128 v[198:201], v137 offset:36864
	ds_read_b128 v[202:205], v137 offset:37888
	ds_read_b128 v[206:209], v137 offset:38912
	ds_read_b128 v[210:213], v137 offset:39936
	global_load_lds_dwordx4 v[218:219], off
	v_lshl_add_u64 v[218:219], s[56:57], 0, v[132:133]
	s_mov_b32 m0, s28
	s_nop 0
	global_load_lds_dwordx4 v[218:219], off
	s_waitcnt vmcnt(8)
	s_waitcnt lgkmcnt(0)
	s_barrier
	s_waitcnt lgkmcnt(0)
	v_mfma_f32_16x16x32_bf16 v[124:127], v[138:141], v[182:185], v[124:127]
	v_mfma_f32_16x16x32_bf16 v[124:127], v[150:153], v[186:189], v[124:127]
	v_mfma_f32_16x16x32_bf16 v[120:123], v[154:157], v[182:185], v[120:123]
	v_mfma_f32_16x16x32_bf16 v[120:123], v[162:165], v[186:189], v[120:123]
	v_mfma_f32_16x16x32_bf16 v[108:111], v[138:141], v[190:193], v[108:111]
	v_mfma_f32_16x16x32_bf16 v[108:111], v[150:153], v[194:197], v[108:111]
	v_mfma_f32_16x16x32_bf16 v[104:107], v[154:157], v[190:193], v[104:107]
	v_mfma_f32_16x16x32_bf16 v[104:107], v[162:165], v[194:197], v[104:107]
	v_mfma_f32_16x16x32_bf16 v[92:95], v[138:141], v[198:201], v[92:95]
	v_mfma_f32_16x16x32_bf16 v[92:95], v[150:153], v[202:205], v[92:95]
	v_mfma_f32_16x16x32_bf16 v[88:91], v[154:157], v[198:201], v[88:91]
	v_mfma_f32_16x16x32_bf16 v[88:91], v[162:165], v[202:205], v[88:91]
	v_mfma_f32_16x16x32_bf16 v[76:79], v[138:141], v[206:209], v[76:79]
	v_mfma_f32_16x16x32_bf16 v[76:79], v[150:153], v[210:213], v[76:79]
	v_mfma_f32_16x16x32_bf16 v[72:75], v[154:157], v[206:209], v[72:75]
	v_mfma_f32_16x16x32_bf16 v[72:75], v[162:165], v[210:213], v[72:75]
	v_mfma_f32_16x16x32_bf16 v[116:119], v[166:169], v[182:185], v[116:119]
	v_mfma_f32_16x16x32_bf16 v[116:119], v[170:173], v[186:189], v[116:119]
	v_mfma_f32_16x16x32_bf16 v[112:115], v[174:177], v[182:185], v[112:115]
	v_mfma_f32_16x16x32_bf16 v[112:115], v[178:181], v[186:189], v[112:115]
	v_mfma_f32_16x16x32_bf16 v[100:103], v[166:169], v[190:193], v[100:103]
	v_mfma_f32_16x16x32_bf16 v[100:103], v[170:173], v[194:197], v[100:103]
	v_mfma_f32_16x16x32_bf16 v[96:99], v[174:177], v[190:193], v[96:99]
	v_mfma_f32_16x16x32_bf16 v[96:99], v[178:181], v[194:197], v[96:99]
	v_mfma_f32_16x16x32_bf16 v[84:87], v[166:169], v[198:201], v[84:87]
	v_mfma_f32_16x16x32_bf16 v[84:87], v[170:173], v[202:205], v[84:87]
	v_mfma_f32_16x16x32_bf16 v[80:83], v[174:177], v[198:201], v[80:83]
	v_mfma_f32_16x16x32_bf16 v[80:83], v[178:181], v[202:205], v[80:83]
	v_mfma_f32_16x16x32_bf16 v[68:71], v[166:169], v[206:209], v[68:71]
	v_mfma_f32_16x16x32_bf16 v[68:71], v[170:173], v[210:213], v[68:71]
	v_mfma_f32_16x16x32_bf16 v[64:67], v[174:177], v[206:209], v[64:67]
	v_mfma_f32_16x16x32_bf16 v[64:67], v[178:181], v[210:213], v[64:67]
	s_barrier
; #define PG8_STAGE(bufoff, gbase, voff) do { _Pragma("unroll") for (int _i = 0; _i < 2; ++_i) \
;         __builtin_amdgcn_global_load_lds((const unsigned*)((const char*)(gbase) + (voff)[_i]), (LAS unsigned*)(lds + (bufoff) + ldsw + _i * 8192), 16, 0, 0); } while (0)
; #define PG8_LDA(dst, b, h) do { _Pragma("unroll") for (int m = 0; m < 4; ++m) _Pragma("unroll") for (int k = 0; k < 2; ++k) dst[m][k] = *(const LAS bf16x8*)(lds + PG8_SA(b, h) + aoff + m * 2048 + k * 1024); } while (0)
; #define PG8_MMA(ai, bj, At, Bt) do { __builtin_amdgcn_s_setprio(1); _Pragma("unroll") for (int m = 0; m < 4; ++m) _Pragma("unroll") for (int n = 0; n < 2; ++n) _Pragma("unroll") for (int k = 0; k < 2; ++k) \
;         acc[ai][bj][m][n] = __builtin_amdgcn_mfma_f32_16x16x32_bf16(Bt[n][k], At[m][k], acc[ai][bj][m][n], 0, 0, 0); __builtin_amdgcn_s_setprio(0); } while (0)
; #define PG8_WAIT_V(n) asm volatile("s_waitcnt vmcnt(" #n ")" ::: "memory")
; #define PG8_WAIT_L(n) asm volatile("s_waitcnt lgkmcnt(" #n ")" ::: "memory")
; #define PG8_BAR __builtin_amdgcn_s_barrier()
; #define PG8_SCHED __builtin_amdgcn_sched_barrier(0)
; template <class Epi>
; __device__ __forceinline__ void gemm_phase(LAS unsigned char* lds, const Gemm g, const Order& S, const Epi& E, const int wid) {
;     ...
;         for (int t = 0; t < nt; t += 2) {
;     ...
;             PG8_LDA(At, 1, 1); PG8_STAGE(PG8_SB(1, 0), b3, voffB); PG8_STAGE(PG8_SB(1, 1), b3 + hB, voffB); PG8_STAGE(PG8_SA(1, 0), a3, voffA);
;             PG8_WAIT_V(8); PG8_WAIT_L(0); PG8_BAR; PG8_MMA(1, 0, At, B0); PG8_MMA(1, 1, At, B1); PG8_BAR; PG8_SCHED;
	s_add_i32 s56, s64, s24
	v_lshl_add_u64 v[142:143], v[142:143], 0, s[20:21]
	s_mov_b32 m0, s56
	ds_read_b128 v[182:185], v137 offset:49152
	ds_read_b128 v[186:189], v137 offset:50176
	ds_read_b128 v[190:193], v137 offset:51200
	ds_read_b128 v[194:197], v137 offset:52224
	ds_read_b128 v[198:201], v137 offset:53248
	ds_read_b128 v[202:205], v137 offset:54272
	ds_read_b128 v[206:209], v137 offset:55296
	ds_read_b128 v[210:213], v137 offset:56320
	global_load_lds_dwordx4 v[142:143], off
	s_add_i32 m0, s56, 0x2000
	s_add_u32 s54, s54, 0x100080
	v_lshl_add_u64 v[142:143], v[158:159], 0, s[20:21]
	s_addc_u32 s55, s55, 0
	s_add_i32 s56, s65, s24
	global_load_lds_dwordx4 v[142:143], off
	v_lshl_add_u64 v[142:143], s[54:55], 0, v[128:129]
	s_mov_b32 m0, s56
	s_nop 0
	global_load_lds_dwordx4 v[142:143], off
	v_lshl_add_u64 v[142:143], s[54:55], 0, v[130:131]
	s_add_i32 m0, s56, 0x2000
	s_nop 0
	global_load_lds_dwordx4 v[142:143], off
	v_lshl_add_u64 v[142:143], v[214:215], 0, s[20:21]
	s_mov_b32 m0, s50
	s_nop 0
	global_load_lds_dwordx4 v[142:143], off
	v_lshl_add_u64 v[142:143], v[216:217], 0, s[20:21]
	s_mov_b32 m0, s51
	s_nop 0
	global_load_lds_dwordx4 v[142:143], off
	s_waitcnt vmcnt(8)
	s_waitcnt lgkmcnt(0)
	s_barrier
	s_waitcnt lgkmcnt(0)
	v_mfma_f32_16x16x32_bf16 v[60:63], v[138:141], v[182:185], v[60:63]
	v_mfma_f32_16x16x32_bf16 v[60:63], v[150:153], v[186:189], v[60:63]
	v_mfma_f32_16x16x32_bf16 v[56:59], v[154:157], v[182:185], v[56:59]
	v_mfma_f32_16x16x32_bf16 v[56:59], v[162:165], v[186:189], v[56:59]
	v_mfma_f32_16x16x32_bf16 v[44:47], v[138:141], v[190:193], v[44:47]
	v_mfma_f32_16x16x32_bf16 v[44:47], v[150:153], v[194:197], v[44:47]
	v_mfma_f32_16x16x32_bf16 v[40:43], v[154:157], v[190:193], v[40:43]
	v_mfma_f32_16x16x32_bf16 v[40:43], v[162:165], v[194:197], v[40:43]
	v_mfma_f32_16x16x32_bf16 v[28:31], v[138:141], v[198:201], v[28:31]
	v_mfma_f32_16x16x32_bf16 v[28:31], v[150:153], v[202:205], v[28:31]
	v_mfma_f32_16x16x32_bf16 v[24:27], v[154:157], v[198:201], v[24:27]
	v_mfma_f32_16x16x32_bf16 v[24:27], v[162:165], v[202:205], v[24:27]
	v_mfma_f32_16x16x32_bf16 v[12:15], v[138:141], v[206:209], v[12:15]
	v_mfma_f32_16x16x32_bf16 v[12:15], v[150:153], v[210:213], v[12:15]
	v_mfma_f32_16x16x32_bf16 v[8:11], v[154:157], v[206:209], v[8:11]
	v_mfma_f32_16x16x32_bf16 v[8:11], v[162:165], v[210:213], v[8:11]
	v_mfma_f32_16x16x32_bf16 v[52:55], v[166:169], v[182:185], v[52:55]
	v_mfma_f32_16x16x32_bf16 v[52:55], v[170:173], v[186:189], v[52:55]
	v_mfma_f32_16x16x32_bf16 v[48:51], v[174:177], v[182:185], v[48:51]
	v_mfma_f32_16x16x32_bf16 v[48:51], v[178:181], v[186:189], v[48:51]
	v_mfma_f32_16x16x32_bf16 v[36:39], v[166:169], v[190:193], v[36:39]
	v_mfma_f32_16x16x32_bf16 v[36:39], v[170:173], v[194:197], v[36:39]
	v_mfma_f32_16x16x32_bf16 v[32:35], v[174:177], v[190:193], v[32:35]
	v_mfma_f32_16x16x32_bf16 v[32:35], v[178:181], v[194:197], v[32:35]
	v_mfma_f32_16x16x32_bf16 v[20:23], v[166:169], v[198:201], v[20:23]
	v_mfma_f32_16x16x32_bf16 v[20:23], v[170:173], v[202:205], v[20:23]
	v_mfma_f32_16x16x32_bf16 v[16:19], v[174:177], v[198:201], v[16:19]
	v_mfma_f32_16x16x32_bf16 v[16:19], v[178:181], v[202:205], v[16:19]
	v_mfma_f32_16x16x32_bf16 v[4:7], v[166:169], v[206:209], v[4:7]
	v_mfma_f32_16x16x32_bf16 v[4:7], v[170:173], v[210:213], v[4:7]
	v_mfma_f32_16x16x32_bf16 v[0:3], v[174:177], v[206:209], v[0:3]
	v_mfma_f32_16x16x32_bf16 v[0:3], v[178:181], v[210:213], v[0:3]
	s_add_i32 s63, s63, 2
	s_add_u32 s46, s46, 0x100
	s_addc_u32 s47, s47, 0
	s_add_u32 s61, s61, 0x100
	s_addc_u32 s62, s62, 0
	s_cmp_gt_u32 s63, 61
	s_barrier
	s_cbranch_scc0 .LBB0_821
	s_and_b64 vcc, exec, s[12:13]
	s_cbranch_vccz .LBB0_824
	s_barrier

; #define PG8_STAGE(bufoff, gbase, voff) do { _Pragma("unroll") for (int _i = 0; _i < 2; ++_i) \
;         __builtin_amdgcn_global_load_lds((const unsigned*)((const char*)(gbase) + (voff)[_i]), (LAS unsigned*)(lds + (bufoff) + ldsw + _i * 8192), 16, 0, 0); } while (0)
; #define PG8_LDA(dst, b, h) do { _Pragma("unroll") for (int m = 0; m < 4; ++m) _Pragma("unroll") for (int k = 0; k < 2; ++k) dst[m][k] = *(const LAS bf16x8*)(lds + PG8_SA(b, h) + aoff + m * 2048 + k * 1024); } while (0)
; #define PG8_LDB(dst, b, h) do { _Pragma("unroll") for (int n = 0; n < 2; ++n) _Pragma("unroll") for (int k = 0; k < 2; ++k) dst[n][k] = *(const LAS bf16x8*)(lds + PG8_SB(b, h) + boff + n * 2048 + k * 1024); } while (0)
; #define PG8_MMA(ai, bj, At, Bt) do { __builtin_amdgcn_s_setprio(1); _Pragma("unroll") for (int m = 0; m < 4; ++m) _Pragma("unroll") for (int n = 0; n < 2; ++n) _Pragma("unroll") for (int k = 0; k < 2; ++k) \
;         acc[ai][bj][m][n] = __builtin_amdgcn_mfma_f32_16x16x32_bf16(Bt[n][k], At[m][k], acc[ai][bj][m][n], 0, 0, 0); __builtin_amdgcn_s_setprio(0); } while (0)
; #define PG8_WAIT_V(n) asm volatile("s_waitcnt vmcnt(" #n ")" ::: "memory")
; #define PG8_WAIT_L(n) asm volatile("s_waitcnt lgkmcnt(" #n ")" ::: "memory")
; #define PG8_BAR __builtin_amdgcn_s_barrier()
; #define PG8_SCHED __builtin_amdgcn_sched_barrier(0)
; template <class Epi>
; __device__ __forceinline__ void gemm_phase(LAS unsigned char* lds, const Gemm g, const Order& S, const Epi& E, const int wid) {
;     ...
;         for (int t = 0; t < nt; t += 2) {
;             const bool last = (t == nt - 2);
;             const char* a1 = cA + (size_t)(t + 1) * kstep;
;             const char* a2 = last ? nA : cA + (size_t)(t + 2) * kstep; const char* b2 = last ? nB : cB + (size_t)(t + 2) * kstep;
;             const char* a3 = a2 + kstep; const char* b3 = b2 + kstep;
;     ...
;             PG8_LDB(B0, 0, 0); PG8_LDB(B1, 0, 1); PG8_SCHED; PG8_LDA(At, 0, 0); PG8_STAGE(PG8_SA(1, 1), a1 + hA, voffA);
;             PG8_WAIT_V(8); PG8_WAIT_L(0); PG8_BAR; PG8_MMA(0, 0, At, B0); PG8_MMA(0, 1, At, B1); PG8_BAR; PG8_SCHED;
;             PG8_LDA(At, 0, 1); PG8_STAGE(PG8_SB(0, 0), b2, voffB); PG8_STAGE(PG8_SB(0, 1), b2 + hB, voffB); PG8_STAGE(PG8_SA(0, 0), a2, voffA);
.LBB0_915:
	ds_read_b128 v[142:145], v139
	ds_read_b128 v[146:149], v139 offset:1024
	ds_read_b128 v[150:153], v139 offset:2048
	ds_read_b128 v[154:157], v139 offset:3072
	ds_read_b128 v[158:161], v140
	ds_read_b128 v[162:165], v140 offset:1024
	ds_read_b128 v[166:169], v140 offset:2048
	ds_read_b128 v[170:173], v140 offset:3072
	s_add_u32 s44, s42, 0xfff00080
	s_addc_u32 s45, s43, -1
	s_cmp_eq_u32 s62, 60
	s_cselect_b32 s47, s11, s45
	s_cselect_b32 s46, s58, s44
	s_cselect_b32 s45, s21, s61
	s_cselect_b32 s44, s59, s60
	v_lshl_add_u64 v[206:207], s[42:43], 0, v[128:129]
	s_add_i32 m0, s33, 0xc000
	ds_read_b128 v[174:177], v141
	ds_read_b128 v[178:181], v141 offset:1024
	ds_read_b128 v[182:185], v141 offset:2048
	ds_read_b128 v[186:189], v141 offset:3072
	ds_read_b128 v[190:193], v141 offset:4096
	ds_read_b128 v[194:197], v141 offset:5120
	ds_read_b128 v[198:201], v141 offset:6144
	ds_read_b128 v[202:205], v141 offset:7168
	global_load_lds_dwordx4 v[206:207], off
	v_lshl_add_u64 v[206:207], s[42:43], 0, v[134:135]
	s_add_i32 m0, s33, 0xe000
	s_nop 0
	global_load_lds_dwordx4 v[206:207], off
	s_waitcnt vmcnt(8)
	s_waitcnt lgkmcnt(0)
	s_barrier
	s_waitcnt lgkmcnt(0)
	v_mfma_f32_16x16x32_bf16 v[124:127], v[142:145], v[174:177], v[124:127]
	v_mfma_f32_16x16x32_bf16 v[124:127], v[146:149], v[178:181], v[124:127]
	v_mfma_f32_16x16x32_bf16 v[120:123], v[150:153], v[174:177], v[120:123]
	v_mfma_f32_16x16x32_bf16 v[120:123], v[154:157], v[178:181], v[120:123]
	v_mfma_f32_16x16x32_bf16 v[116:119], v[142:145], v[182:185], v[116:119]
	v_mfma_f32_16x16x32_bf16 v[116:119], v[146:149], v[186:189], v[116:119]
	v_mfma_f32_16x16x32_bf16 v[112:115], v[150:153], v[182:185], v[112:115]
	v_mfma_f32_16x16x32_bf16 v[112:115], v[154:157], v[186:189], v[112:115]
	v_mfma_f32_16x16x32_bf16 v[100:103], v[142:145], v[190:193], v[100:103]
	v_mfma_f32_16x16x32_bf16 v[100:103], v[146:149], v[194:197], v[100:103]
	v_mfma_f32_16x16x32_bf16 v[96:99], v[150:153], v[190:193], v[96:99]
	v_mfma_f32_16x16x32_bf16 v[96:99], v[154:157], v[194:197], v[96:99]
	v_mfma_f32_16x16x32_bf16 v[84:87], v[142:145], v[198:201], v[84:87]
	v_mfma_f32_16x16x32_bf16 v[84:87], v[146:149], v[202:205], v[84:87]
	v_mfma_f32_16x16x32_bf16 v[80:83], v[150:153], v[198:201], v[80:83]
	v_mfma_f32_16x16x32_bf16 v[80:83], v[154:157], v[202:205], v[80:83]
	v_mfma_f32_16x16x32_bf16 v[108:111], v[158:161], v[174:177], v[108:111]
	v_mfma_f32_16x16x32_bf16 v[108:111], v[162:165], v[178:181], v[108:111]
	v_mfma_f32_16x16x32_bf16 v[104:107], v[166:169], v[174:177], v[104:107]
	v_mfma_f32_16x16x32_bf16 v[104:107], v[170:173], v[178:181], v[104:107]
	v_mfma_f32_16x16x32_bf16 v[92:95], v[158:161], v[182:185], v[92:95]
	v_mfma_f32_16x16x32_bf16 v[92:95], v[162:165], v[186:189], v[92:95]
	v_mfma_f32_16x16x32_bf16 v[88:91], v[166:169], v[182:185], v[88:91]
	v_mfma_f32_16x16x32_bf16 v[88:91], v[170:173], v[186:189], v[88:91]
	v_mfma_f32_16x16x32_bf16 v[76:79], v[158:161], v[190:193], v[76:79]
	v_mfma_f32_16x16x32_bf16 v[76:79], v[162:165], v[194:197], v[76:79]
	v_mfma_f32_16x16x32_bf16 v[72:75], v[166:169], v[190:193], v[72:75]
	v_mfma_f32_16x16x32_bf16 v[72:75], v[170:173], v[194:197], v[72:75]
	v_mfma_f32_16x16x32_bf16 v[68:71], v[158:161], v[198:201], v[68:71]
	v_mfma_f32_16x16x32_bf16 v[68:71], v[162:165], v[202:205], v[68:71]
	v_mfma_f32_16x16x32_bf16 v[64:67], v[166:169], v[198:201], v[64:67]
	v_mfma_f32_16x16x32_bf16 v[64:67], v[170:173], v[202:205], v[64:67]
	s_barrier
	s_add_i32 s63, s54, s24
	v_lshl_add_u64 v[206:207], s[44:45], 0, v[130:131]
	s_mov_b32 m0, s63
	ds_read_b128 v[174:177], v141 offset:16384
	ds_read_b128 v[178:181], v141 offset:17408
	ds_read_b128 v[182:185], v141 offset:18432
	ds_read_b128 v[186:189], v141 offset:19456
	ds_read_b128 v[190:193], v141 offset:20480
	ds_read_b128 v[194:197], v141 offset:21504
	ds_read_b128 v[198:201], v141 offset:22528
	ds_read_b128 v[202:205], v141 offset:23552
	global_load_lds_dwordx4 v[206:207], off
	s_add_i32 m0, s63, 0x2000
	s_add_u32 s64, s44, 0x100000
	v_lshl_add_u64 v[208:209], s[44:45], 0, v[132:133]
	s_addc_u32 s65, s45, 0
	s_add_i32 s63, s55, s24
	global_load_lds_dwordx4 v[208:209], off
	v_lshl_add_u64 v[210:211], s[64:65], 0, v[130:131]
	s_mov_b32 m0, s63
	v_lshl_add_u64 v[212:213], s[46:47], 0, v[134:135]
	global_load_lds_dwordx4 v[210:211], off
	v_lshl_add_u64 v[210:211], s[64:65], 0, v[132:133]
	s_add_i32 m0, s63, 0x2000
	s_nop 0
	global_load_lds_dwordx4 v[210:211], off
	v_lshl_add_u64 v[210:211], s[46:47], 0, v[128:129]
	s_mov_b32 m0, s33
	s_nop 0
	global_load_lds_dwordx4 v[210:211], off
	s_mov_b32 m0, s35
	s_nop 0
	global_load_lds_dwordx4 v[212:213], off
	s_waitcnt vmcnt(8)
	s_waitcnt lgkmcnt(0)
	s_barrier
; #define PG8_STAGE(bufoff, gbase, voff) do { _Pragma("unroll") for (int _i = 0; _i < 2; ++_i) \
;         __builtin_amdgcn_global_load_lds((const unsigned*)((const char*)(gbase) + (voff)[_i]), (LAS unsigned*)(lds + (bufoff) + ldsw + _i * 8192), 16, 0, 0); } while (0)
; #define PG8_LDA(dst, b, h) do { _Pragma("unroll") for (int m = 0; m < 4; ++m) _Pragma("unroll") for (int k = 0; k < 2; ++k) dst[m][k] = *(const LAS bf16x8*)(lds + PG8_SA(b, h) + aoff + m * 2048 + k * 1024); } while (0)
; #define PG8_LDB(dst, b, h) do { _Pragma("unroll") for (int n = 0; n < 2; ++n) _Pragma("unroll") for (int k = 0; k < 2; ++k) dst[n][k] = *(const LAS bf16x8*)(lds + PG8_SB(b, h) + boff + n * 2048 + k * 1024); } while (0)
; #define PG8_MMA(ai, bj, At, Bt) do { __builtin_amdgcn_s_setprio(1); _Pragma("unroll") for (int m = 0; m < 4; ++m) _Pragma("unroll") for (int n = 0; n < 2; ++n) _Pragma("unroll") for (int k = 0; k < 2; ++k) \
;         acc[ai][bj][m][n] = __builtin_amdgcn_mfma_f32_16x16x32_bf16(Bt[n][k], At[m][k], acc[ai][bj][m][n], 0, 0, 0); __builtin_amdgcn_s_setprio(0); } while (0)
; #define PG8_WAIT_V(n) asm volatile("s_waitcnt vmcnt(" #n ")" ::: "memory")
; #define PG8_WAIT_L(n) asm volatile("s_waitcnt lgkmcnt(" #n ")" ::: "memory")
; #define PG8_BAR __builtin_amdgcn_s_barrier()
; #define PG8_SCHED __builtin_amdgcn_sched_barrier(0)
; template <class Epi>
; __device__ __forceinline__ void gemm_phase(LAS unsigned char* lds, const Gemm g, const Order& S, const Epi& E, const int wid) {
;     ...
;             PG8_WAIT_V(8); PG8_WAIT_L(0); PG8_BAR; PG8_MMA(1, 0, At, B0); PG8_MMA(1, 1, At, B1); PG8_BAR; PG8_SCHED;
;             PG8_LDB(B0, 1, 0); PG8_LDB(B1, 1, 1); PG8_SCHED; PG8_LDA(At, 1, 0); PG8_STAGE(PG8_SA(0, 1), a2 + hA, voffA);
;             PG8_WAIT_V(8); PG8_WAIT_L(0); PG8_BAR; PG8_MMA(0, 0, At, B0); PG8_MMA(0, 1, At, B1); PG8_BAR; PG8_SCHED;
	s_waitcnt lgkmcnt(0)
	v_mfma_f32_16x16x32_bf16 v[60:63], v[142:145], v[174:177], v[60:63]
	v_mfma_f32_16x16x32_bf16 v[60:63], v[146:149], v[178:181], v[60:63]
	v_mfma_f32_16x16x32_bf16 v[56:59], v[150:153], v[174:177], v[56:59]
	v_mfma_f32_16x16x32_bf16 v[56:59], v[154:157], v[178:181], v[56:59]
	v_mfma_f32_16x16x32_bf16 v[52:55], v[142:145], v[182:185], v[52:55]
	v_mfma_f32_16x16x32_bf16 v[52:55], v[146:149], v[186:189], v[52:55]
	v_mfma_f32_16x16x32_bf16 v[48:51], v[150:153], v[182:185], v[48:51]
	v_mfma_f32_16x16x32_bf16 v[48:51], v[154:157], v[186:189], v[48:51]
	v_mfma_f32_16x16x32_bf16 v[36:39], v[142:145], v[190:193], v[36:39]
	v_mfma_f32_16x16x32_bf16 v[36:39], v[146:149], v[194:197], v[36:39]
	v_mfma_f32_16x16x32_bf16 v[32:35], v[150:153], v[190:193], v[32:35]
	v_mfma_f32_16x16x32_bf16 v[32:35], v[154:157], v[194:197], v[32:35]
	v_mfma_f32_16x16x32_bf16 v[20:23], v[142:145], v[198:201], v[20:23]
	v_mfma_f32_16x16x32_bf16 v[20:23], v[146:149], v[202:205], v[20:23]
	v_mfma_f32_16x16x32_bf16 v[16:19], v[150:153], v[198:201], v[16:19]
	v_mfma_f32_16x16x32_bf16 v[16:19], v[154:157], v[202:205], v[16:19]
	v_mfma_f32_16x16x32_bf16 v[44:47], v[158:161], v[174:177], v[44:47]
	v_mfma_f32_16x16x32_bf16 v[44:47], v[162:165], v[178:181], v[44:47]
	v_mfma_f32_16x16x32_bf16 v[40:43], v[166:169], v[174:177], v[40:43]
	v_mfma_f32_16x16x32_bf16 v[40:43], v[170:173], v[178:181], v[40:43]
	v_mfma_f32_16x16x32_bf16 v[28:31], v[158:161], v[182:185], v[28:31]
	v_mfma_f32_16x16x32_bf16 v[28:31], v[162:165], v[186:189], v[28:31]
	v_mfma_f32_16x16x32_bf16 v[24:27], v[166:169], v[182:185], v[24:27]
	v_mfma_f32_16x16x32_bf16 v[24:27], v[170:173], v[186:189], v[24:27]
	v_mfma_f32_16x16x32_bf16 v[12:15], v[158:161], v[190:193], v[12:15]
	v_mfma_f32_16x16x32_bf16 v[12:15], v[162:165], v[194:197], v[12:15]
	v_mfma_f32_16x16x32_bf16 v[8:11], v[166:169], v[190:193], v[8:11]
	v_mfma_f32_16x16x32_bf16 v[8:11], v[170:173], v[194:197], v[8:11]
	v_mfma_f32_16x16x32_bf16 v[4:7], v[158:161], v[198:201], v[4:7]
	v_mfma_f32_16x16x32_bf16 v[4:7], v[162:165], v[202:205], v[4:7]
	v_mfma_f32_16x16x32_bf16 v[0:3], v[166:169], v[198:201], v[0:3]
	v_mfma_f32_16x16x32_bf16 v[0:3], v[170:173], v[202:205], v[0:3]
	s_barrier
	s_add_i32 s63, 0, 0x18000
	s_add_i32 s64, 0, 0x1c000
	v_add_u32_e32 v154, s63, v138
	v_add_u32_e32 v170, s64, v138
	ds_read_b128 v[142:145], v154
	ds_read_b128 v[146:149], v154 offset:1024
	ds_read_b128 v[150:153], v154 offset:2048
	ds_read_b128 v[154:157], v154 offset:3072
	ds_read_b128 v[158:161], v170
	ds_read_b128 v[162:165], v170 offset:1024
	ds_read_b128 v[166:169], v170 offset:2048
	ds_read_b128 v[170:173], v170 offset:3072
	s_add_u32 s46, s46, 0x100000
	s_addc_u32 s47, s47, 0
	s_mov_b32 m0, s48
	v_lshl_add_u64 v[214:215], s[46:47], 0, v[128:129]
	ds_read_b128 v[174:177], v141 offset:32768
	ds_read_b128 v[178:181], v141 offset:33792
	ds_read_b128 v[182:185], v141 offset:34816
	ds_read_b128 v[186:189], v141 offset:35840
	ds_read_b128 v[190:193], v141 offset:36864
	ds_read_b128 v[194:197], v141 offset:37888
	ds_read_b128 v[198:201], v141 offset:38912
	ds_read_b128 v[202:205], v141 offset:39936
	global_load_lds_dwordx4 v[214:215], off
	v_lshl_add_u64 v[214:215], s[46:47], 0, v[134:135]
	s_mov_b32 m0, s49
	s_nop 0
	global_load_lds_dwordx4 v[214:215], off
	s_waitcnt vmcnt(8)
	s_waitcnt lgkmcnt(0)
	s_barrier
	s_waitcnt lgkmcnt(0)
	v_mfma_f32_16x16x32_bf16 v[124:127], v[142:145], v[174:177], v[124:127]
	v_mfma_f32_16x16x32_bf16 v[124:127], v[146:149], v[178:181], v[124:127]
	v_mfma_f32_16x16x32_bf16 v[120:123], v[150:153], v[174:177], v[120:123]
	v_mfma_f32_16x16x32_bf16 v[120:123], v[154:157], v[178:181], v[120:123]
	v_mfma_f32_16x16x32_bf16 v[116:119], v[142:145], v[182:185], v[116:119]
	v_mfma_f32_16x16x32_bf16 v[116:119], v[146:149], v[186:189], v[116:119]
	v_mfma_f32_16x16x32_bf16 v[112:115], v[150:153], v[182:185], v[112:115]
	v_mfma_f32_16x16x32_bf16 v[112:115], v[154:157], v[186:189], v[112:115]
	v_mfma_f32_16x16x32_bf16 v[100:103], v[142:145], v[190:193], v[100:103]
	v_mfma_f32_16x16x32_bf16 v[100:103], v[146:149], v[194:197], v[100:103]
	v_mfma_f32_16x16x32_bf16 v[96:99], v[150:153], v[190:193], v[96:99]
	v_mfma_f32_16x16x32_bf16 v[96:99], v[154:157], v[194:197], v[96:99]
	v_mfma_f32_16x16x32_bf16 v[84:87], v[142:145], v[198:201], v[84:87]
	v_mfma_f32_16x16x32_bf16 v[84:87], v[146:149], v[202:205], v[84:87]
	v_mfma_f32_16x16x32_bf16 v[80:83], v[150:153], v[198:201], v[80:83]
	v_mfma_f32_16x16x32_bf16 v[80:83], v[154:157], v[202:205], v[80:83]
	v_mfma_f32_16x16x32_bf16 v[108:111], v[158:161], v[174:177], v[108:111]
	v_mfma_f32_16x16x32_bf16 v[108:111], v[162:165], v[178:181], v[108:111]
	v_mfma_f32_16x16x32_bf16 v[104:107], v[166:169], v[174:177], v[104:107]
	v_mfma_f32_16x16x32_bf16 v[104:107], v[170:173], v[178:181], v[104:107]
	v_mfma_f32_16x16x32_bf16 v[92:95], v[158:161], v[182:185], v[92:95]
	v_mfma_f32_16x16x32_bf16 v[92:95], v[162:165], v[186:189], v[92:95]
	v_mfma_f32_16x16x32_bf16 v[88:91], v[166:169], v[182:185], v[88:91]
	v_mfma_f32_16x16x32_bf16 v[88:91], v[170:173], v[186:189], v[88:91]
	v_mfma_f32_16x16x32_bf16 v[76:79], v[158:161], v[190:193], v[76:79]
	v_mfma_f32_16x16x32_bf16 v[76:79], v[162:165], v[194:197], v[76:79]
	v_mfma_f32_16x16x32_bf16 v[72:75], v[166:169], v[190:193], v[72:75]
	v_mfma_f32_16x16x32_bf16 v[72:75], v[170:173], v[194:197], v[72:75]
	v_mfma_f32_16x16x32_bf16 v[68:71], v[158:161], v[198:201], v[68:71]
	v_mfma_f32_16x16x32_bf16 v[68:71], v[162:165], v[202:205], v[68:71]
	v_mfma_f32_16x16x32_bf16 v[64:67], v[166:169], v[198:201], v[64:67]
	v_mfma_f32_16x16x32_bf16 v[64:67], v[170:173], v[202:205], v[64:67]
	s_barrier
; #define PG8_STAGE(bufoff, gbase, voff) do { _Pragma("unroll") for (int _i = 0; _i < 2; ++_i) \
;         __builtin_amdgcn_global_load_lds((const unsigned*)((const char*)(gbase) + (voff)[_i]), (LAS unsigned*)(lds + (bufoff) + ldsw + _i * 8192), 16, 0, 0); } while (0)
; #define PG8_LDA(dst, b, h) do { _Pragma("unroll") for (int m = 0; m < 4; ++m) _Pragma("unroll") for (int k = 0; k < 2; ++k) dst[m][k] = *(const LAS bf16x8*)(lds + PG8_SA(b, h) + aoff + m * 2048 + k * 1024); } while (0)
; #define PG8_MMA(ai, bj, At, Bt) do { __builtin_amdgcn_s_setprio(1); _Pragma("unroll") for (int m = 0; m < 4; ++m) _Pragma("unroll") for (int n = 0; n < 2; ++n) _Pragma("unroll") for (int k = 0; k < 2; ++k) \
;         acc[ai][bj][m][n] = __builtin_amdgcn_mfma_f32_16x16x32_bf16(Bt[n][k], At[m][k], acc[ai][bj][m][n], 0, 0, 0); __builtin_amdgcn_s_setprio(0); } while (0)
; #define PG8_WAIT_V(n) asm volatile("s_waitcnt vmcnt(" #n ")" ::: "memory")
; #define PG8_WAIT_L(n) asm volatile("s_waitcnt lgkmcnt(" #n ")" ::: "memory")
; #define PG8_BAR __builtin_amdgcn_s_barrier()
; #define PG8_SCHED __builtin_amdgcn_sched_barrier(0)
; template <class Epi>
; __device__ __forceinline__ void gemm_phase(LAS unsigned char* lds, const Gemm g, const Order& S, const Epi& E, const int wid) {
;     ...
;         for (int t = 0; t < nt; t += 2) {
;     ...
;             PG8_LDA(At, 1, 1); PG8_STAGE(PG8_SB(1, 0), b3, voffB); PG8_STAGE(PG8_SB(1, 1), b3 + hB, voffB); PG8_STAGE(PG8_SA(1, 0), a3, voffA);
;             PG8_WAIT_V(8); PG8_WAIT_L(0); PG8_BAR; PG8_MMA(1, 0, At, B0); PG8_MMA(1, 1, At, B1); PG8_BAR; PG8_SCHED;
	s_add_i32 s46, s63, s24
	v_lshl_add_u64 v[206:207], v[206:207], 0, s[8:9]
	s_mov_b32 m0, s46
	ds_read_b128 v[174:177], v141 offset:49152
	ds_read_b128 v[178:181], v141 offset:50176
	ds_read_b128 v[182:185], v141 offset:51200
	ds_read_b128 v[186:189], v141 offset:52224
	ds_read_b128 v[190:193], v141 offset:53248
	ds_read_b128 v[194:197], v141 offset:54272
	ds_read_b128 v[198:201], v141 offset:55296
	ds_read_b128 v[202:205], v141 offset:56320
	global_load_lds_dwordx4 v[206:207], off
	s_add_i32 m0, s46, 0x2000
	s_add_u32 s44, s44, 0x100080
	v_lshl_add_u64 v[206:207], v[208:209], 0, s[8:9]
	s_addc_u32 s45, s45, 0
	s_add_i32 s46, s64, s24
	global_load_lds_dwordx4 v[206:207], off
	v_lshl_add_u64 v[206:207], s[44:45], 0, v[130:131]
	s_mov_b32 m0, s46
	s_nop 0
	global_load_lds_dwordx4 v[206:207], off
	v_lshl_add_u64 v[206:207], s[44:45], 0, v[132:133]
	s_add_i32 m0, s46, 0x2000
	s_nop 0
	global_load_lds_dwordx4 v[206:207], off
	v_lshl_add_u64 v[206:207], v[210:211], 0, s[8:9]
	s_mov_b32 m0, s50
	s_nop 0
	global_load_lds_dwordx4 v[206:207], off
	v_lshl_add_u64 v[206:207], v[212:213], 0, s[8:9]
	s_mov_b32 m0, s51
	s_nop 0
	global_load_lds_dwordx4 v[206:207], off
	s_waitcnt vmcnt(8)
	s_waitcnt lgkmcnt(0)
	s_barrier
	s_waitcnt lgkmcnt(0)
	v_mfma_f32_16x16x32_bf16 v[60:63], v[142:145], v[174:177], v[60:63]
	v_mfma_f32_16x16x32_bf16 v[60:63], v[146:149], v[178:181], v[60:63]
	v_mfma_f32_16x16x32_bf16 v[56:59], v[150:153], v[174:177], v[56:59]
	v_mfma_f32_16x16x32_bf16 v[56:59], v[154:157], v[178:181], v[56:59]
	v_mfma_f32_16x16x32_bf16 v[52:55], v[142:145], v[182:185], v[52:55]
	v_mfma_f32_16x16x32_bf16 v[52:55], v[146:149], v[186:189], v[52:55]
	v_mfma_f32_16x16x32_bf16 v[48:51], v[150:153], v[182:185], v[48:51]
	v_mfma_f32_16x16x32_bf16 v[48:51], v[154:157], v[186:189], v[48:51]
	v_mfma_f32_16x16x32_bf16 v[36:39], v[142:145], v[190:193], v[36:39]
	v_mfma_f32_16x16x32_bf16 v[36:39], v[146:149], v[194:197], v[36:39]
	v_mfma_f32_16x16x32_bf16 v[32:35], v[150:153], v[190:193], v[32:35]
	v_mfma_f32_16x16x32_bf16 v[32:35], v[154:157], v[194:197], v[32:35]
	v_mfma_f32_16x16x32_bf16 v[20:23], v[142:145], v[198:201], v[20:23]
	v_mfma_f32_16x16x32_bf16 v[20:23], v[146:149], v[202:205], v[20:23]
	v_mfma_f32_16x16x32_bf16 v[16:19], v[150:153], v[198:201], v[16:19]
	v_mfma_f32_16x16x32_bf16 v[16:19], v[154:157], v[202:205], v[16:19]
	v_mfma_f32_16x16x32_bf16 v[44:47], v[158:161], v[174:177], v[44:47]
	v_mfma_f32_16x16x32_bf16 v[44:47], v[162:165], v[178:181], v[44:47]
	v_mfma_f32_16x16x32_bf16 v[40:43], v[166:169], v[174:177], v[40:43]
	v_mfma_f32_16x16x32_bf16 v[40:43], v[170:173], v[178:181], v[40:43]
	v_mfma_f32_16x16x32_bf16 v[28:31], v[158:161], v[182:185], v[28:31]
	v_mfma_f32_16x16x32_bf16 v[28:31], v[162:165], v[186:189], v[28:31]
	v_mfma_f32_16x16x32_bf16 v[24:27], v[166:169], v[182:185], v[24:27]
	v_mfma_f32_16x16x32_bf16 v[24:27], v[170:173], v[186:189], v[24:27]
	v_mfma_f32_16x16x32_bf16 v[12:15], v[158:161], v[190:193], v[12:15]
	v_mfma_f32_16x16x32_bf16 v[12:15], v[162:165], v[194:197], v[12:15]
	v_mfma_f32_16x16x32_bf16 v[8:11], v[166:169], v[190:193], v[8:11]
	v_mfma_f32_16x16x32_bf16 v[8:11], v[170:173], v[194:197], v[8:11]
	v_mfma_f32_16x16x32_bf16 v[4:7], v[158:161], v[198:201], v[4:7]
	v_mfma_f32_16x16x32_bf16 v[4:7], v[162:165], v[202:205], v[4:7]
	v_mfma_f32_16x16x32_bf16 v[0:3], v[166:169], v[198:201], v[0:3]
	v_mfma_f32_16x16x32_bf16 v[0:3], v[170:173], v[202:205], v[0:3]
	s_add_i32 s62, s62, 2
	s_add_u32 s42, s42, 0x100
	s_addc_u32 s43, s43, 0
	s_add_u32 s60, s60, 0x100
	s_addc_u32 s61, s61, 0
	s_cmp_gt_u32 s62, 61
	s_barrier
	s_cbranch_scc0 .LBB0_915
	s_and_b64 vcc, exec, s[16:17]
	s_cbranch_vccz .LBB0_918
	s_barrier

; #define PG8_STAGE(bufoff, gbase, voff) do { _Pragma("unroll") for (int _i = 0; _i < 2; ++_i) \
;         __builtin_amdgcn_global_load_lds((const unsigned*)((const char*)(gbase) + (voff)[_i]), (LAS unsigned*)(lds + (bufoff) + ldsw + _i * 8192), 16, 0, 0); } while (0)
; #define PG8_LDA(dst, b, h) do { _Pragma("unroll") for (int m = 0; m < 4; ++m) _Pragma("unroll") for (int k = 0; k < 2; ++k) dst[m][k] = *(const LAS bf16x8*)(lds + PG8_SA(b, h) + aoff + m * 2048 + k * 1024); } while (0)
; #define PG8_LDB(dst, b, h) do { _Pragma("unroll") for (int n = 0; n < 2; ++n) _Pragma("unroll") for (int k = 0; k < 2; ++k) dst[n][k] = *(const LAS bf16x8*)(lds + PG8_SB(b, h) + boff + n * 2048 + k * 1024); } while (0)
; #define PG8_MMA(ai, bj, At, Bt) do { __builtin_amdgcn_s_setprio(1); _Pragma("unroll") for (int m = 0; m < 4; ++m) _Pragma("unroll") for (int n = 0; n < 2; ++n) _Pragma("unroll") for (int k = 0; k < 2; ++k) \
;         acc[ai][bj][m][n] = __builtin_amdgcn_mfma_f32_16x16x32_bf16(Bt[n][k], At[m][k], acc[ai][bj][m][n], 0, 0, 0); __builtin_amdgcn_s_setprio(0); } while (0)
; #define PG8_WAIT_V(n) asm volatile("s_waitcnt vmcnt(" #n ")" ::: "memory")
; #define PG8_WAIT_L(n) asm volatile("s_waitcnt lgkmcnt(" #n ")" ::: "memory")
; #define PG8_BAR __builtin_amdgcn_s_barrier()
; #define PG8_SCHED __builtin_amdgcn_sched_barrier(0)
; template <class Epi>
; __device__ __forceinline__ void gemm_phase(LAS unsigned char* lds, const Gemm g, const Order& S, const Epi& E, const int wid) {
;     ...
;         for (int t = 0; t < nt; t += 2) {
;             const bool last = (t == nt - 2);
;             const char* a1 = cA + (size_t)(t + 1) * kstep;
;             const char* a2 = last ? nA : cA + (size_t)(t + 2) * kstep; const char* b2 = last ? nB : cB + (size_t)(t + 2) * kstep;
;             const char* a3 = a2 + kstep; const char* b3 = b2 + kstep;
;     ...
;             PG8_LDB(B0, 0, 0); PG8_LDB(B1, 0, 1); PG8_SCHED; PG8_LDA(At, 0, 0); PG8_STAGE(PG8_SA(1, 1), a1 + hA, voffA);
;             PG8_WAIT_V(8); PG8_WAIT_L(0); PG8_BAR; PG8_MMA(0, 0, At, B0); PG8_MMA(0, 1, At, B1); PG8_BAR; PG8_SCHED;
;             PG8_LDA(At, 0, 1); PG8_STAGE(PG8_SB(0, 0), b2, voffB); PG8_STAGE(PG8_SB(0, 1), b2 + hB, voffB); PG8_STAGE(PG8_SA(0, 0), a2, voffA);
.LBB0_954:
	ds_read_b128 v[142:145], v138
	ds_read_b128 v[146:149], v138 offset:1024
	ds_read_b128 v[150:153], v138 offset:2048
	ds_read_b128 v[154:157], v138 offset:3072
	ds_read_b128 v[158:161], v139
	ds_read_b128 v[162:165], v139 offset:1024
	ds_read_b128 v[166:169], v139 offset:2048
	ds_read_b128 v[170:173], v139 offset:3072
	s_add_u32 s38, s36, 0xfff00080
	s_addc_u32 s39, s37, -1
	s_cmp_eq_u32 s59, 60
	s_cselect_b32 s41, s11, s39
	s_cselect_b32 s40, s55, s38
	s_cselect_b32 s39, s19, s58
	s_cselect_b32 s38, s56, s57
	v_lshl_add_u64 v[206:207], s[36:37], 0, v[128:129]
	s_add_i32 m0, s43, 0xc000
	ds_read_b128 v[174:177], v140
	ds_read_b128 v[178:181], v140 offset:1024
	ds_read_b128 v[182:185], v140 offset:2048
	ds_read_b128 v[186:189], v140 offset:3072
	ds_read_b128 v[190:193], v140 offset:4096
	ds_read_b128 v[194:197], v140 offset:5120
	ds_read_b128 v[198:201], v140 offset:6144
	ds_read_b128 v[202:205], v140 offset:7168
	global_load_lds_dwordx4 v[206:207], off
	v_lshl_add_u64 v[206:207], s[36:37], 0, v[134:135]
	s_add_i32 m0, s43, 0xe000
	s_nop 0
	global_load_lds_dwordx4 v[206:207], off
	s_waitcnt vmcnt(8)
	s_waitcnt lgkmcnt(0)
	s_barrier
	s_waitcnt lgkmcnt(0)
	v_mfma_f32_16x16x32_bf16 v[124:127], v[142:145], v[174:177], v[124:127]
	v_mfma_f32_16x16x32_bf16 v[124:127], v[146:149], v[178:181], v[124:127]
	v_mfma_f32_16x16x32_bf16 v[120:123], v[150:153], v[174:177], v[120:123]
	v_mfma_f32_16x16x32_bf16 v[120:123], v[154:157], v[178:181], v[120:123]
	v_mfma_f32_16x16x32_bf16 v[116:119], v[142:145], v[182:185], v[116:119]
	v_mfma_f32_16x16x32_bf16 v[116:119], v[146:149], v[186:189], v[116:119]
	v_mfma_f32_16x16x32_bf16 v[112:115], v[150:153], v[182:185], v[112:115]
	v_mfma_f32_16x16x32_bf16 v[112:115], v[154:157], v[186:189], v[112:115]
	v_mfma_f32_16x16x32_bf16 v[100:103], v[142:145], v[190:193], v[100:103]
	v_mfma_f32_16x16x32_bf16 v[100:103], v[146:149], v[194:197], v[100:103]
	v_mfma_f32_16x16x32_bf16 v[96:99], v[150:153], v[190:193], v[96:99]
	v_mfma_f32_16x16x32_bf16 v[96:99], v[154:157], v[194:197], v[96:99]
	v_mfma_f32_16x16x32_bf16 v[84:87], v[142:145], v[198:201], v[84:87]
	v_mfma_f32_16x16x32_bf16 v[84:87], v[146:149], v[202:205], v[84:87]
	v_mfma_f32_16x16x32_bf16 v[80:83], v[150:153], v[198:201], v[80:83]
	v_mfma_f32_16x16x32_bf16 v[80:83], v[154:157], v[202:205], v[80:83]
	v_mfma_f32_16x16x32_bf16 v[108:111], v[158:161], v[174:177], v[108:111]
	v_mfma_f32_16x16x32_bf16 v[108:111], v[162:165], v[178:181], v[108:111]
	v_mfma_f32_16x16x32_bf16 v[104:107], v[166:169], v[174:177], v[104:107]
	v_mfma_f32_16x16x32_bf16 v[104:107], v[170:173], v[178:181], v[104:107]
	v_mfma_f32_16x16x32_bf16 v[92:95], v[158:161], v[182:185], v[92:95]
	v_mfma_f32_16x16x32_bf16 v[92:95], v[162:165], v[186:189], v[92:95]
	v_mfma_f32_16x16x32_bf16 v[88:91], v[166:169], v[182:185], v[88:91]
	v_mfma_f32_16x16x32_bf16 v[88:91], v[170:173], v[186:189], v[88:91]
	v_mfma_f32_16x16x32_bf16 v[76:79], v[158:161], v[190:193], v[76:79]
	v_mfma_f32_16x16x32_bf16 v[76:79], v[162:165], v[194:197], v[76:79]
	v_mfma_f32_16x16x32_bf16 v[72:75], v[166:169], v[190:193], v[72:75]
	v_mfma_f32_16x16x32_bf16 v[72:75], v[170:173], v[194:197], v[72:75]
	v_mfma_f32_16x16x32_bf16 v[68:71], v[158:161], v[198:201], v[68:71]
	v_mfma_f32_16x16x32_bf16 v[68:71], v[162:165], v[202:205], v[68:71]
	v_mfma_f32_16x16x32_bf16 v[64:67], v[166:169], v[198:201], v[64:67]
	v_mfma_f32_16x16x32_bf16 v[64:67], v[170:173], v[202:205], v[64:67]
	s_barrier
	s_add_i32 s60, s50, s24
	v_lshl_add_u64 v[206:207], s[38:39], 0, v[130:131]
	s_mov_b32 m0, s60
	ds_read_b128 v[174:177], v140 offset:16384
	ds_read_b128 v[178:181], v140 offset:17408
	ds_read_b128 v[182:185], v140 offset:18432
	ds_read_b128 v[186:189], v140 offset:19456
	ds_read_b128 v[190:193], v140 offset:20480
	ds_read_b128 v[194:197], v140 offset:21504
	ds_read_b128 v[198:201], v140 offset:22528
	ds_read_b128 v[202:205], v140 offset:23552
	global_load_lds_dwordx4 v[206:207], off
	s_add_i32 m0, s60, 0x2000
	s_add_u32 s60, s38, 0x100000
	v_lshl_add_u64 v[208:209], s[38:39], 0, v[132:133]
	s_addc_u32 s61, s39, 0
	s_add_i32 s62, s51, s24
	global_load_lds_dwordx4 v[208:209], off
	v_lshl_add_u64 v[210:211], s[60:61], 0, v[130:131]
	s_mov_b32 m0, s62
	v_lshl_add_u64 v[212:213], s[40:41], 0, v[134:135]
	global_load_lds_dwordx4 v[210:211], off
	v_lshl_add_u64 v[210:211], s[60:61], 0, v[132:133]
	s_add_i32 m0, s62, 0x2000
	s_nop 0
	global_load_lds_dwordx4 v[210:211], off
	v_lshl_add_u64 v[210:211], s[40:41], 0, v[128:129]
	s_mov_b32 m0, s43
	s_nop 0
	global_load_lds_dwordx4 v[210:211], off
	s_mov_b32 m0, s44
	s_nop 0
	global_load_lds_dwordx4 v[212:213], off
	s_waitcnt vmcnt(8)
	s_waitcnt lgkmcnt(0)
	s_barrier
; #define PG8_STAGE(bufoff, gbase, voff) do { _Pragma("unroll") for (int _i = 0; _i < 2; ++_i) \
;         __builtin_amdgcn_global_load_lds((const unsigned*)((const char*)(gbase) + (voff)[_i]), (LAS unsigned*)(lds + (bufoff) + ldsw + _i * 8192), 16, 0, 0); } while (0)
; #define PG8_LDA(dst, b, h) do { _Pragma("unroll") for (int m = 0; m < 4; ++m) _Pragma("unroll") for (int k = 0; k < 2; ++k) dst[m][k] = *(const LAS bf16x8*)(lds + PG8_SA(b, h) + aoff + m * 2048 + k * 1024); } while (0)
; #define PG8_LDB(dst, b, h) do { _Pragma("unroll") for (int n = 0; n < 2; ++n) _Pragma("unroll") for (int k = 0; k < 2; ++k) dst[n][k] = *(const LAS bf16x8*)(lds + PG8_SB(b, h) + boff + n * 2048 + k * 1024); } while (0)
; #define PG8_MMA(ai, bj, At, Bt) do { __builtin_amdgcn_s_setprio(1); _Pragma("unroll") for (int m = 0; m < 4; ++m) _Pragma("unroll") for (int n = 0; n < 2; ++n) _Pragma("unroll") for (int k = 0; k < 2; ++k) \
;         acc[ai][bj][m][n] = __builtin_amdgcn_mfma_f32_16x16x32_bf16(Bt[n][k], At[m][k], acc[ai][bj][m][n], 0, 0, 0); __builtin_amdgcn_s_setprio(0); } while (0)
; #define PG8_WAIT_V(n) asm volatile("s_waitcnt vmcnt(" #n ")" ::: "memory")
; #define PG8_WAIT_L(n) asm volatile("s_waitcnt lgkmcnt(" #n ")" ::: "memory")
; #define PG8_BAR __builtin_amdgcn_s_barrier()
; #define PG8_SCHED __builtin_amdgcn_sched_barrier(0)
; template <class Epi>
; __device__ __forceinline__ void gemm_phase(LAS unsigned char* lds, const Gemm g, const Order& S, const Epi& E, const int wid) {
;     ...
;             PG8_WAIT_V(8); PG8_WAIT_L(0); PG8_BAR; PG8_MMA(1, 0, At, B0); PG8_MMA(1, 1, At, B1); PG8_BAR; PG8_SCHED;
;             PG8_LDB(B0, 1, 0); PG8_LDB(B1, 1, 1); PG8_SCHED; PG8_LDA(At, 1, 0); PG8_STAGE(PG8_SA(0, 1), a2 + hA, voffA);
;             PG8_WAIT_V(8); PG8_WAIT_L(0); PG8_BAR; PG8_MMA(0, 0, At, B0); PG8_MMA(0, 1, At, B1); PG8_BAR; PG8_SCHED;
	s_waitcnt lgkmcnt(0)
	v_mfma_f32_16x16x32_bf16 v[60:63], v[142:145], v[174:177], v[60:63]
	v_mfma_f32_16x16x32_bf16 v[60:63], v[146:149], v[178:181], v[60:63]
	v_mfma_f32_16x16x32_bf16 v[56:59], v[150:153], v[174:177], v[56:59]
	v_mfma_f32_16x16x32_bf16 v[56:59], v[154:157], v[178:181], v[56:59]
	v_mfma_f32_16x16x32_bf16 v[52:55], v[142:145], v[182:185], v[52:55]
	v_mfma_f32_16x16x32_bf16 v[52:55], v[146:149], v[186:189], v[52:55]
	v_mfma_f32_16x16x32_bf16 v[48:51], v[150:153], v[182:185], v[48:51]
	v_mfma_f32_16x16x32_bf16 v[48:51], v[154:157], v[186:189], v[48:51]
	v_mfma_f32_16x16x32_bf16 v[36:39], v[142:145], v[190:193], v[36:39]
	v_mfma_f32_16x16x32_bf16 v[36:39], v[146:149], v[194:197], v[36:39]
	v_mfma_f32_16x16x32_bf16 v[32:35], v[150:153], v[190:193], v[32:35]
	v_mfma_f32_16x16x32_bf16 v[32:35], v[154:157], v[194:197], v[32:35]
	v_mfma_f32_16x16x32_bf16 v[20:23], v[142:145], v[198:201], v[20:23]
	v_mfma_f32_16x16x32_bf16 v[20:23], v[146:149], v[202:205], v[20:23]
	v_mfma_f32_16x16x32_bf16 v[16:19], v[150:153], v[198:201], v[16:19]
	v_mfma_f32_16x16x32_bf16 v[16:19], v[154:157], v[202:205], v[16:19]
	v_mfma_f32_16x16x32_bf16 v[44:47], v[158:161], v[174:177], v[44:47]
	v_mfma_f32_16x16x32_bf16 v[44:47], v[162:165], v[178:181], v[44:47]
	v_mfma_f32_16x16x32_bf16 v[40:43], v[166:169], v[174:177], v[40:43]
	v_mfma_f32_16x16x32_bf16 v[40:43], v[170:173], v[178:181], v[40:43]
	v_mfma_f32_16x16x32_bf16 v[28:31], v[158:161], v[182:185], v[28:31]
	v_mfma_f32_16x16x32_bf16 v[28:31], v[162:165], v[186:189], v[28:31]
	v_mfma_f32_16x16x32_bf16 v[24:27], v[166:169], v[182:185], v[24:27]
	v_mfma_f32_16x16x32_bf16 v[24:27], v[170:173], v[186:189], v[24:27]
	v_mfma_f32_16x16x32_bf16 v[12:15], v[158:161], v[190:193], v[12:15]
	v_mfma_f32_16x16x32_bf16 v[12:15], v[162:165], v[194:197], v[12:15]
	v_mfma_f32_16x16x32_bf16 v[8:11], v[166:169], v[190:193], v[8:11]
	v_mfma_f32_16x16x32_bf16 v[8:11], v[170:173], v[194:197], v[8:11]
	v_mfma_f32_16x16x32_bf16 v[4:7], v[158:161], v[198:201], v[4:7]
	v_mfma_f32_16x16x32_bf16 v[4:7], v[162:165], v[202:205], v[4:7]
	v_mfma_f32_16x16x32_bf16 v[0:3], v[166:169], v[198:201], v[0:3]
	v_mfma_f32_16x16x32_bf16 v[0:3], v[170:173], v[202:205], v[0:3]
	s_barrier
	s_add_i32 s60, 0, 0x18000
	v_add_u32_e32 v141, s60, v137
	s_add_i32 s61, 0, 0x1c000
	ds_read_b128 v[142:145], v141
	ds_read_b128 v[146:149], v141 offset:1024
	ds_read_b128 v[150:153], v141 offset:2048
	ds_read_b128 v[154:157], v141 offset:3072
	v_add_u32_e32 v141, s61, v137
	ds_read_b128 v[158:161], v141
	ds_read_b128 v[162:165], v141 offset:1024
	ds_read_b128 v[166:169], v141 offset:2048
	ds_read_b128 v[170:173], v141 offset:3072
	s_add_u32 s40, s40, 0x100000
	s_addc_u32 s41, s41, 0
	s_mov_b32 m0, s45
	v_lshl_add_u64 v[214:215], s[40:41], 0, v[128:129]
	ds_read_b128 v[174:177], v140 offset:32768
	ds_read_b128 v[178:181], v140 offset:33792
	ds_read_b128 v[182:185], v140 offset:34816
	ds_read_b128 v[186:189], v140 offset:35840
	ds_read_b128 v[190:193], v140 offset:36864
	ds_read_b128 v[194:197], v140 offset:37888
	ds_read_b128 v[198:201], v140 offset:38912
	ds_read_b128 v[202:205], v140 offset:39936
	global_load_lds_dwordx4 v[214:215], off
	v_lshl_add_u64 v[214:215], s[40:41], 0, v[134:135]
	s_mov_b32 m0, s46
	s_nop 0
	global_load_lds_dwordx4 v[214:215], off
	s_waitcnt vmcnt(8)
	s_waitcnt lgkmcnt(0)
	s_barrier
	s_waitcnt lgkmcnt(0)
	v_mfma_f32_16x16x32_bf16 v[124:127], v[142:145], v[174:177], v[124:127]
	v_mfma_f32_16x16x32_bf16 v[124:127], v[146:149], v[178:181], v[124:127]
	v_mfma_f32_16x16x32_bf16 v[120:123], v[150:153], v[174:177], v[120:123]
	v_mfma_f32_16x16x32_bf16 v[120:123], v[154:157], v[178:181], v[120:123]
	v_mfma_f32_16x16x32_bf16 v[116:119], v[142:145], v[182:185], v[116:119]
	v_mfma_f32_16x16x32_bf16 v[116:119], v[146:149], v[186:189], v[116:119]
	v_mfma_f32_16x16x32_bf16 v[112:115], v[150:153], v[182:185], v[112:115]
	v_mfma_f32_16x16x32_bf16 v[112:115], v[154:157], v[186:189], v[112:115]
	v_mfma_f32_16x16x32_bf16 v[100:103], v[142:145], v[190:193], v[100:103]
	v_mfma_f32_16x16x32_bf16 v[100:103], v[146:149], v[194:197], v[100:103]
	v_mfma_f32_16x16x32_bf16 v[96:99], v[150:153], v[190:193], v[96:99]
	v_mfma_f32_16x16x32_bf16 v[96:99], v[154:157], v[194:197], v[96:99]
	v_mfma_f32_16x16x32_bf16 v[84:87], v[142:145], v[198:201], v[84:87]
	v_mfma_f32_16x16x32_bf16 v[84:87], v[146:149], v[202:205], v[84:87]
	v_mfma_f32_16x16x32_bf16 v[80:83], v[150:153], v[198:201], v[80:83]
	v_mfma_f32_16x16x32_bf16 v[80:83], v[154:157], v[202:205], v[80:83]
	v_mfma_f32_16x16x32_bf16 v[108:111], v[158:161], v[174:177], v[108:111]
	v_mfma_f32_16x16x32_bf16 v[108:111], v[162:165], v[178:181], v[108:111]
	v_mfma_f32_16x16x32_bf16 v[104:107], v[166:169], v[174:177], v[104:107]
	v_mfma_f32_16x16x32_bf16 v[104:107], v[170:173], v[178:181], v[104:107]
	v_mfma_f32_16x16x32_bf16 v[92:95], v[158:161], v[182:185], v[92:95]
	v_mfma_f32_16x16x32_bf16 v[92:95], v[162:165], v[186:189], v[92:95]
	v_mfma_f32_16x16x32_bf16 v[88:91], v[166:169], v[182:185], v[88:91]
	v_mfma_f32_16x16x32_bf16 v[88:91], v[170:173], v[186:189], v[88:91]
	v_mfma_f32_16x16x32_bf16 v[76:79], v[158:161], v[190:193], v[76:79]
	v_mfma_f32_16x16x32_bf16 v[76:79], v[162:165], v[194:197], v[76:79]
	v_mfma_f32_16x16x32_bf16 v[72:75], v[166:169], v[190:193], v[72:75]
	v_mfma_f32_16x16x32_bf16 v[72:75], v[170:173], v[194:197], v[72:75]
	v_mfma_f32_16x16x32_bf16 v[68:71], v[158:161], v[198:201], v[68:71]
	v_mfma_f32_16x16x32_bf16 v[68:71], v[162:165], v[202:205], v[68:71]
	v_mfma_f32_16x16x32_bf16 v[64:67], v[166:169], v[198:201], v[64:67]
	v_mfma_f32_16x16x32_bf16 v[64:67], v[170:173], v[202:205], v[64:67]
	s_barrier
; #define PG8_STAGE(bufoff, gbase, voff) do { _Pragma("unroll") for (int _i = 0; _i < 2; ++_i) \
;         __builtin_amdgcn_global_load_lds((const unsigned*)((const char*)(gbase) + (voff)[_i]), (LAS unsigned*)(lds + (bufoff) + ldsw + _i * 8192), 16, 0, 0); } while (0)
; #define PG8_LDA(dst, b, h) do { _Pragma("unroll") for (int m = 0; m < 4; ++m) _Pragma("unroll") for (int k = 0; k < 2; ++k) dst[m][k] = *(const LAS bf16x8*)(lds + PG8_SA(b, h) + aoff + m * 2048 + k * 1024); } while (0)
; #define PG8_MMA(ai, bj, At, Bt) do { __builtin_amdgcn_s_setprio(1); _Pragma("unroll") for (int m = 0; m < 4; ++m) _Pragma("unroll") for (int n = 0; n < 2; ++n) _Pragma("unroll") for (int k = 0; k < 2; ++k) \
;         acc[ai][bj][m][n] = __builtin_amdgcn_mfma_f32_16x16x32_bf16(Bt[n][k], At[m][k], acc[ai][bj][m][n], 0, 0, 0); __builtin_amdgcn_s_setprio(0); } while (0)
; #define PG8_WAIT_V(n) asm volatile("s_waitcnt vmcnt(" #n ")" ::: "memory")
; #define PG8_WAIT_L(n) asm volatile("s_waitcnt lgkmcnt(" #n ")" ::: "memory")
; #define PG8_BAR __builtin_amdgcn_s_barrier()
; #define PG8_SCHED __builtin_amdgcn_sched_barrier(0)
; template <class Epi>
; __device__ __forceinline__ void gemm_phase(LAS unsigned char* lds, const Gemm g, const Order& S, const Epi& E, const int wid) {
;     ...
;         for (int t = 0; t < nt; t += 2) {
;     ...
;             PG8_LDA(At, 1, 1); PG8_STAGE(PG8_SB(1, 0), b3, voffB); PG8_STAGE(PG8_SB(1, 1), b3 + hB, voffB); PG8_STAGE(PG8_SA(1, 0), a3, voffA);
;             PG8_WAIT_V(8); PG8_WAIT_L(0); PG8_BAR; PG8_MMA(1, 0, At, B0); PG8_MMA(1, 1, At, B1); PG8_BAR; PG8_SCHED;
	s_add_i32 s40, s60, s24
	v_lshl_add_u64 v[206:207], v[206:207], 0, s[8:9]
	s_mov_b32 m0, s40
	ds_read_b128 v[174:177], v140 offset:49152
	ds_read_b128 v[178:181], v140 offset:50176
	ds_read_b128 v[182:185], v140 offset:51200
	ds_read_b128 v[186:189], v140 offset:52224
	ds_read_b128 v[190:193], v140 offset:53248
	ds_read_b128 v[194:197], v140 offset:54272
	ds_read_b128 v[198:201], v140 offset:55296
	ds_read_b128 v[202:205], v140 offset:56320
	global_load_lds_dwordx4 v[206:207], off
	s_add_i32 m0, s40, 0x2000
	s_add_u32 s38, s38, 0x100080
	v_lshl_add_u64 v[206:207], v[208:209], 0, s[8:9]
	s_addc_u32 s39, s39, 0
	s_add_i32 s40, s61, s24
	global_load_lds_dwordx4 v[206:207], off
	v_lshl_add_u64 v[206:207], s[38:39], 0, v[130:131]
	s_mov_b32 m0, s40
	s_nop 0
	global_load_lds_dwordx4 v[206:207], off
	v_lshl_add_u64 v[206:207], s[38:39], 0, v[132:133]
	s_add_i32 m0, s40, 0x2000
	s_nop 0
	global_load_lds_dwordx4 v[206:207], off
	v_lshl_add_u64 v[206:207], v[210:211], 0, s[8:9]
	s_mov_b32 m0, s47
	s_nop 0
	global_load_lds_dwordx4 v[206:207], off
	v_lshl_add_u64 v[206:207], v[212:213], 0, s[8:9]
	s_mov_b32 m0, s48
	s_nop 0
	global_load_lds_dwordx4 v[206:207], off
	s_waitcnt vmcnt(8)
	s_waitcnt lgkmcnt(0)
	s_barrier
	s_waitcnt lgkmcnt(0)
	v_mfma_f32_16x16x32_bf16 v[60:63], v[142:145], v[174:177], v[60:63]
	v_mfma_f32_16x16x32_bf16 v[60:63], v[146:149], v[178:181], v[60:63]
	v_mfma_f32_16x16x32_bf16 v[56:59], v[150:153], v[174:177], v[56:59]
	v_mfma_f32_16x16x32_bf16 v[56:59], v[154:157], v[178:181], v[56:59]
	v_mfma_f32_16x16x32_bf16 v[52:55], v[142:145], v[182:185], v[52:55]
	v_mfma_f32_16x16x32_bf16 v[52:55], v[146:149], v[186:189], v[52:55]
	v_mfma_f32_16x16x32_bf16 v[48:51], v[150:153], v[182:185], v[48:51]
	v_mfma_f32_16x16x32_bf16 v[48:51], v[154:157], v[186:189], v[48:51]
	v_mfma_f32_16x16x32_bf16 v[36:39], v[142:145], v[190:193], v[36:39]
	v_mfma_f32_16x16x32_bf16 v[36:39], v[146:149], v[194:197], v[36:39]
	v_mfma_f32_16x16x32_bf16 v[32:35], v[150:153], v[190:193], v[32:35]
	v_mfma_f32_16x16x32_bf16 v[32:35], v[154:157], v[194:197], v[32:35]
	v_mfma_f32_16x16x32_bf16 v[20:23], v[142:145], v[198:201], v[20:23]
	v_mfma_f32_16x16x32_bf16 v[20:23], v[146:149], v[202:205], v[20:23]
	v_mfma_f32_16x16x32_bf16 v[16:19], v[150:153], v[198:201], v[16:19]
	v_mfma_f32_16x16x32_bf16 v[16:19], v[154:157], v[202:205], v[16:19]
	v_mfma_f32_16x16x32_bf16 v[44:47], v[158:161], v[174:177], v[44:47]
	v_mfma_f32_16x16x32_bf16 v[44:47], v[162:165], v[178:181], v[44:47]
	v_mfma_f32_16x16x32_bf16 v[40:43], v[166:169], v[174:177], v[40:43]
	v_mfma_f32_16x16x32_bf16 v[40:43], v[170:173], v[178:181], v[40:43]
	v_mfma_f32_16x16x32_bf16 v[28:31], v[158:161], v[182:185], v[28:31]
	v_mfma_f32_16x16x32_bf16 v[28:31], v[162:165], v[186:189], v[28:31]
	v_mfma_f32_16x16x32_bf16 v[24:27], v[166:169], v[182:185], v[24:27]
	v_mfma_f32_16x16x32_bf16 v[24:27], v[170:173], v[186:189], v[24:27]
	v_mfma_f32_16x16x32_bf16 v[12:15], v[158:161], v[190:193], v[12:15]
	v_mfma_f32_16x16x32_bf16 v[12:15], v[162:165], v[194:197], v[12:15]
	v_mfma_f32_16x16x32_bf16 v[8:11], v[166:169], v[190:193], v[8:11]
	v_mfma_f32_16x16x32_bf16 v[8:11], v[170:173], v[194:197], v[8:11]
	v_mfma_f32_16x16x32_bf16 v[4:7], v[158:161], v[198:201], v[4:7]
	v_mfma_f32_16x16x32_bf16 v[4:7], v[162:165], v[202:205], v[4:7]
	v_mfma_f32_16x16x32_bf16 v[0:3], v[166:169], v[198:201], v[0:3]
	v_mfma_f32_16x16x32_bf16 v[0:3], v[170:173], v[202:205], v[0:3]
	s_add_i32 s59, s59, 2
	s_add_u32 s36, s36, 0x100
	s_addc_u32 s37, s37, 0
	s_add_u32 s57, s57, 0x100
	s_addc_u32 s58, s58, 0
	s_cmp_gt_u32 s59, 61
	s_barrier
	s_cbranch_scc0 .LBB0_954
	s_and_b64 vcc, exec, s[16:17]
	s_cbranch_vccz .LBB0_957
	s_barrier

; #define PG8_STAGE(bufoff, gbase, voff) do { _Pragma("unroll") for (int _i = 0; _i < 2; ++_i) \
;         __builtin_amdgcn_global_load_lds((const unsigned*)((const char*)(gbase) + (voff)[_i]), (LAS unsigned*)(lds + (bufoff) + ldsw + _i * 8192), 16, 0, 0); } while (0)
; #define PG8_LDA(dst, b, h) do { _Pragma("unroll") for (int m = 0; m < 4; ++m) _Pragma("unroll") for (int k = 0; k < 2; ++k) dst[m][k] = *(const LAS bf16x8*)(lds + PG8_SA(b, h) + aoff + m * 2048 + k * 1024); } while (0)
; #define PG8_LDB(dst, b, h) do { _Pragma("unroll") for (int n = 0; n < 2; ++n) _Pragma("unroll") for (int k = 0; k < 2; ++k) dst[n][k] = *(const LAS bf16x8*)(lds + PG8_SB(b, h) + boff + n * 2048 + k * 1024); } while (0)
; #define PG8_MMA(ai, bj, At, Bt) do { __builtin_amdgcn_s_setprio(1); _Pragma("unroll") for (int m = 0; m < 4; ++m) _Pragma("unroll") for (int n = 0; n < 2; ++n) _Pragma("unroll") for (int k = 0; k < 2; ++k) \
;         acc[ai][bj][m][n] = __builtin_amdgcn_mfma_f32_16x16x32_bf16(Bt[n][k], At[m][k], acc[ai][bj][m][n], 0, 0, 0); __builtin_amdgcn_s_setprio(0); } while (0)
; #define PG8_WAIT_V(n) asm volatile("s_waitcnt vmcnt(" #n ")" ::: "memory")
; #define PG8_WAIT_L(n) asm volatile("s_waitcnt lgkmcnt(" #n ")" ::: "memory")
; #define PG8_BAR __builtin_amdgcn_s_barrier()
; #define PG8_SCHED __builtin_amdgcn_sched_barrier(0)
; template <class Epi>
; __device__ __forceinline__ void gemm_phase(LAS unsigned char* lds, const Gemm g, const Order& S, const Epi& E, const int wid) {
;     ...
;         for (int t = 0; t < nt; t += 2) {
;             const bool last = (t == nt - 2);
;             const char* a1 = cA + (size_t)(t + 1) * kstep;
;             const char* a2 = last ? nA : cA + (size_t)(t + 2) * kstep; const char* b2 = last ? nB : cB + (size_t)(t + 2) * kstep;
;             const char* a3 = a2 + kstep; const char* b3 = b2 + kstep;
;     ...
;             PG8_LDB(B0, 0, 0); PG8_LDB(B1, 0, 1); PG8_SCHED; PG8_LDA(At, 0, 0); PG8_STAGE(PG8_SA(1, 1), a1 + hA, voffA);
;             PG8_WAIT_V(8); PG8_WAIT_L(0); PG8_BAR; PG8_MMA(0, 0, At, B0); PG8_MMA(0, 1, At, B1); PG8_BAR; PG8_SCHED;
;             PG8_LDA(At, 0, 1); PG8_STAGE(PG8_SB(0, 0), b2, voffB); PG8_STAGE(PG8_SB(0, 1), b2 + hB, voffB); PG8_STAGE(PG8_SA(0, 0), a2, voffA);
.LBB0_1035:
	ds_read_b128 v[146:149], v142
	ds_read_b128 v[150:153], v142 offset:1024
	ds_read_b128 v[154:157], v142 offset:2048
	ds_read_b128 v[158:161], v142 offset:3072
	ds_read_b128 v[162:165], v143
	ds_read_b128 v[166:169], v143 offset:1024
	ds_read_b128 v[170:173], v143 offset:2048
	ds_read_b128 v[174:177], v143 offset:3072
	s_add_u32 s38, s36, 0xfff00080
	s_addc_u32 s39, s37, -1
	s_cmp_eq_u32 s61, 12
	s_cselect_b32 s41, s7, s39
	s_cselect_b32 s40, s6, s38
	s_cselect_b32 s39, s23, s60
	s_cselect_b32 s38, s22, s21
	v_lshl_add_u64 v[210:211], s[36:37], 0, v[128:129]
	s_add_i32 m0, s29, 0xc000
	ds_read_b128 v[178:181], v144
	ds_read_b128 v[182:185], v144 offset:1024
	ds_read_b128 v[186:189], v144 offset:2048
	ds_read_b128 v[190:193], v144 offset:3072
	ds_read_b128 v[194:197], v144 offset:4096
	ds_read_b128 v[198:201], v144 offset:5120
	ds_read_b128 v[202:205], v144 offset:6144
	ds_read_b128 v[206:209], v144 offset:7168
	global_load_lds_dwordx4 v[210:211], off
	v_lshl_add_u64 v[210:211], s[36:37], 0, v[138:139]
	s_add_i32 m0, s29, 0xe000
	s_nop 0
	global_load_lds_dwordx4 v[210:211], off
	s_waitcnt vmcnt(8)
	s_waitcnt lgkmcnt(0)
	s_barrier
	s_waitcnt lgkmcnt(0)
	v_mfma_f32_16x16x32_bf16 v[124:127], v[146:149], v[178:181], v[124:127]
	v_mfma_f32_16x16x32_bf16 v[124:127], v[150:153], v[182:185], v[124:127]
	v_mfma_f32_16x16x32_bf16 v[120:123], v[154:157], v[178:181], v[120:123]
	v_mfma_f32_16x16x32_bf16 v[120:123], v[158:161], v[182:185], v[120:123]
	v_mfma_f32_16x16x32_bf16 v[116:119], v[146:149], v[186:189], v[116:119]
	v_mfma_f32_16x16x32_bf16 v[116:119], v[150:153], v[190:193], v[116:119]
	v_mfma_f32_16x16x32_bf16 v[112:115], v[154:157], v[186:189], v[112:115]
	v_mfma_f32_16x16x32_bf16 v[112:115], v[158:161], v[190:193], v[112:115]
	v_mfma_f32_16x16x32_bf16 v[100:103], v[146:149], v[194:197], v[100:103]
	v_mfma_f32_16x16x32_bf16 v[100:103], v[150:153], v[198:201], v[100:103]
	v_mfma_f32_16x16x32_bf16 v[96:99], v[154:157], v[194:197], v[96:99]
	v_mfma_f32_16x16x32_bf16 v[96:99], v[158:161], v[198:201], v[96:99]
	v_mfma_f32_16x16x32_bf16 v[84:87], v[146:149], v[202:205], v[84:87]
	v_mfma_f32_16x16x32_bf16 v[84:87], v[150:153], v[206:209], v[84:87]
	v_mfma_f32_16x16x32_bf16 v[80:83], v[154:157], v[202:205], v[80:83]
	v_mfma_f32_16x16x32_bf16 v[80:83], v[158:161], v[206:209], v[80:83]
	v_mfma_f32_16x16x32_bf16 v[108:111], v[162:165], v[178:181], v[108:111]
	v_mfma_f32_16x16x32_bf16 v[108:111], v[166:169], v[182:185], v[108:111]
	v_mfma_f32_16x16x32_bf16 v[104:107], v[170:173], v[178:181], v[104:107]
	v_mfma_f32_16x16x32_bf16 v[104:107], v[174:177], v[182:185], v[104:107]
	v_mfma_f32_16x16x32_bf16 v[92:95], v[162:165], v[186:189], v[92:95]
	v_mfma_f32_16x16x32_bf16 v[92:95], v[166:169], v[190:193], v[92:95]
	v_mfma_f32_16x16x32_bf16 v[88:91], v[170:173], v[186:189], v[88:91]
	v_mfma_f32_16x16x32_bf16 v[88:91], v[174:177], v[190:193], v[88:91]
	v_mfma_f32_16x16x32_bf16 v[76:79], v[162:165], v[194:197], v[76:79]
	v_mfma_f32_16x16x32_bf16 v[76:79], v[166:169], v[198:201], v[76:79]
	v_mfma_f32_16x16x32_bf16 v[72:75], v[170:173], v[194:197], v[72:75]
	v_mfma_f32_16x16x32_bf16 v[72:75], v[174:177], v[198:201], v[72:75]
	v_mfma_f32_16x16x32_bf16 v[68:71], v[162:165], v[202:205], v[68:71]
	v_mfma_f32_16x16x32_bf16 v[68:71], v[166:169], v[206:209], v[68:71]
	v_mfma_f32_16x16x32_bf16 v[64:67], v[170:173], v[202:205], v[64:67]
	v_mfma_f32_16x16x32_bf16 v[64:67], v[174:177], v[206:209], v[64:67]
	s_barrier
	s_add_i32 s62, s56, s24
	v_lshl_add_u64 v[210:211], s[38:39], 0, v[134:135]
	s_mov_b32 m0, s62
	ds_read_b128 v[178:181], v144 offset:16384
	ds_read_b128 v[182:185], v144 offset:17408
	ds_read_b128 v[186:189], v144 offset:18432
	ds_read_b128 v[190:193], v144 offset:19456
	ds_read_b128 v[194:197], v144 offset:20480
	ds_read_b128 v[198:201], v144 offset:21504
	ds_read_b128 v[202:205], v144 offset:22528
	ds_read_b128 v[206:209], v144 offset:23552
	global_load_lds_dwordx4 v[210:211], off
	s_add_i32 m0, s62, 0x2000
	s_add_u32 s62, s38, 0x100000
	v_lshl_add_u64 v[212:213], s[38:39], 0, v[136:137]
	s_addc_u32 s63, s39, 0
	s_add_i32 s64, s57, s24
	global_load_lds_dwordx4 v[212:213], off
	v_lshl_add_u64 v[214:215], s[62:63], 0, v[134:135]
	s_mov_b32 m0, s64
	v_lshl_add_u64 v[216:217], s[40:41], 0, v[138:139]
	global_load_lds_dwordx4 v[214:215], off
	v_lshl_add_u64 v[214:215], s[62:63], 0, v[136:137]
	s_add_i32 m0, s64, 0x2000
	s_nop 0
	global_load_lds_dwordx4 v[214:215], off
	v_lshl_add_u64 v[214:215], s[40:41], 0, v[128:129]
	s_mov_b32 m0, s29
	s_nop 0
	global_load_lds_dwordx4 v[214:215], off
	s_mov_b32 m0, s47
	s_nop 0
	global_load_lds_dwordx4 v[216:217], off
	s_waitcnt vmcnt(8)
	s_waitcnt lgkmcnt(0)
	s_barrier
; #define PG8_STAGE(bufoff, gbase, voff) do { _Pragma("unroll") for (int _i = 0; _i < 2; ++_i) \
;         __builtin_amdgcn_global_load_lds((const unsigned*)((const char*)(gbase) + (voff)[_i]), (LAS unsigned*)(lds + (bufoff) + ldsw + _i * 8192), 16, 0, 0); } while (0)
; #define PG8_LDA(dst, b, h) do { _Pragma("unroll") for (int m = 0; m < 4; ++m) _Pragma("unroll") for (int k = 0; k < 2; ++k) dst[m][k] = *(const LAS bf16x8*)(lds + PG8_SA(b, h) + aoff + m * 2048 + k * 1024); } while (0)
; #define PG8_LDB(dst, b, h) do { _Pragma("unroll") for (int n = 0; n < 2; ++n) _Pragma("unroll") for (int k = 0; k < 2; ++k) dst[n][k] = *(const LAS bf16x8*)(lds + PG8_SB(b, h) + boff + n * 2048 + k * 1024); } while (0)
; #define PG8_MMA(ai, bj, At, Bt) do { __builtin_amdgcn_s_setprio(1); _Pragma("unroll") for (int m = 0; m < 4; ++m) _Pragma("unroll") for (int n = 0; n < 2; ++n) _Pragma("unroll") for (int k = 0; k < 2; ++k) \
;         acc[ai][bj][m][n] = __builtin_amdgcn_mfma_f32_16x16x32_bf16(Bt[n][k], At[m][k], acc[ai][bj][m][n], 0, 0, 0); __builtin_amdgcn_s_setprio(0); } while (0)
; #define PG8_WAIT_V(n) asm volatile("s_waitcnt vmcnt(" #n ")" ::: "memory")
; #define PG8_WAIT_L(n) asm volatile("s_waitcnt lgkmcnt(" #n ")" ::: "memory")
; #define PG8_BAR __builtin_amdgcn_s_barrier()
; #define PG8_SCHED __builtin_amdgcn_sched_barrier(0)
; template <class Epi>
; __device__ __forceinline__ void gemm_phase(LAS unsigned char* lds, const Gemm g, const Order& S, const Epi& E, const int wid) {
;     ...
;             PG8_WAIT_V(8); PG8_WAIT_L(0); PG8_BAR; PG8_MMA(1, 0, At, B0); PG8_MMA(1, 1, At, B1); PG8_BAR; PG8_SCHED;
;             PG8_LDB(B0, 1, 0); PG8_LDB(B1, 1, 1); PG8_SCHED; PG8_LDA(At, 1, 0); PG8_STAGE(PG8_SA(0, 1), a2 + hA, voffA);
;             PG8_WAIT_V(8); PG8_WAIT_L(0); PG8_BAR; PG8_MMA(0, 0, At, B0); PG8_MMA(0, 1, At, B1); PG8_BAR; PG8_SCHED;
	s_waitcnt lgkmcnt(0)
	v_mfma_f32_16x16x32_bf16 v[60:63], v[146:149], v[178:181], v[60:63]
	v_mfma_f32_16x16x32_bf16 v[60:63], v[150:153], v[182:185], v[60:63]
	v_mfma_f32_16x16x32_bf16 v[56:59], v[154:157], v[178:181], v[56:59]
	v_mfma_f32_16x16x32_bf16 v[56:59], v[158:161], v[182:185], v[56:59]
	v_mfma_f32_16x16x32_bf16 v[52:55], v[146:149], v[186:189], v[52:55]
	v_mfma_f32_16x16x32_bf16 v[52:55], v[150:153], v[190:193], v[52:55]
	v_mfma_f32_16x16x32_bf16 v[48:51], v[154:157], v[186:189], v[48:51]
	v_mfma_f32_16x16x32_bf16 v[48:51], v[158:161], v[190:193], v[48:51]
	v_mfma_f32_16x16x32_bf16 v[36:39], v[146:149], v[194:197], v[36:39]
	v_mfma_f32_16x16x32_bf16 v[36:39], v[150:153], v[198:201], v[36:39]
	v_mfma_f32_16x16x32_bf16 v[32:35], v[154:157], v[194:197], v[32:35]
	v_mfma_f32_16x16x32_bf16 v[32:35], v[158:161], v[198:201], v[32:35]
	v_mfma_f32_16x16x32_bf16 v[20:23], v[146:149], v[202:205], v[20:23]
	v_mfma_f32_16x16x32_bf16 v[20:23], v[150:153], v[206:209], v[20:23]
	v_mfma_f32_16x16x32_bf16 v[16:19], v[154:157], v[202:205], v[16:19]
	v_mfma_f32_16x16x32_bf16 v[16:19], v[158:161], v[206:209], v[16:19]
	v_mfma_f32_16x16x32_bf16 v[44:47], v[162:165], v[178:181], v[44:47]
	v_mfma_f32_16x16x32_bf16 v[44:47], v[166:169], v[182:185], v[44:47]
	v_mfma_f32_16x16x32_bf16 v[40:43], v[170:173], v[178:181], v[40:43]
	v_mfma_f32_16x16x32_bf16 v[40:43], v[174:177], v[182:185], v[40:43]
	v_mfma_f32_16x16x32_bf16 v[28:31], v[162:165], v[186:189], v[28:31]
	v_mfma_f32_16x16x32_bf16 v[28:31], v[166:169], v[190:193], v[28:31]
	v_mfma_f32_16x16x32_bf16 v[24:27], v[170:173], v[186:189], v[24:27]
	v_mfma_f32_16x16x32_bf16 v[24:27], v[174:177], v[190:193], v[24:27]
	v_mfma_f32_16x16x32_bf16 v[12:15], v[162:165], v[194:197], v[12:15]
	v_mfma_f32_16x16x32_bf16 v[12:15], v[166:169], v[198:201], v[12:15]
	v_mfma_f32_16x16x32_bf16 v[8:11], v[170:173], v[194:197], v[8:11]
	v_mfma_f32_16x16x32_bf16 v[8:11], v[174:177], v[198:201], v[8:11]
	v_mfma_f32_16x16x32_bf16 v[4:7], v[162:165], v[202:205], v[4:7]
	v_mfma_f32_16x16x32_bf16 v[4:7], v[166:169], v[206:209], v[4:7]
	v_mfma_f32_16x16x32_bf16 v[0:3], v[170:173], v[202:205], v[0:3]
	v_mfma_f32_16x16x32_bf16 v[0:3], v[174:177], v[206:209], v[0:3]
	s_barrier
	s_add_i32 s62, 0, 0x18000
	v_add_u32_e32 v145, s62, v141
	s_add_i32 s63, 0, 0x1c000
	ds_read_b128 v[146:149], v145
	ds_read_b128 v[150:153], v145 offset:1024
	ds_read_b128 v[154:157], v145 offset:2048
	ds_read_b128 v[158:161], v145 offset:3072
	v_add_u32_e32 v145, s63, v141
	ds_read_b128 v[162:165], v145
	ds_read_b128 v[166:169], v145 offset:1024
	ds_read_b128 v[170:173], v145 offset:2048
	ds_read_b128 v[174:177], v145 offset:3072
	s_add_u32 s40, s40, 0x100000
	s_addc_u32 s41, s41, 0
	s_mov_b32 m0, s48
	v_lshl_add_u64 v[218:219], s[40:41], 0, v[128:129]
	ds_read_b128 v[178:181], v144 offset:32768
	ds_read_b128 v[182:185], v144 offset:33792
	ds_read_b128 v[186:189], v144 offset:34816
	ds_read_b128 v[190:193], v144 offset:35840
	ds_read_b128 v[194:197], v144 offset:36864
	ds_read_b128 v[198:201], v144 offset:37888
	ds_read_b128 v[202:205], v144 offset:38912
	ds_read_b128 v[206:209], v144 offset:39936
	global_load_lds_dwordx4 v[218:219], off
	v_lshl_add_u64 v[218:219], s[40:41], 0, v[138:139]
	s_mov_b32 m0, s49
	s_nop 0
	global_load_lds_dwordx4 v[218:219], off
	s_waitcnt vmcnt(8)
	s_waitcnt lgkmcnt(0)
	s_barrier
	s_waitcnt lgkmcnt(0)
	v_mfma_f32_16x16x32_bf16 v[124:127], v[146:149], v[178:181], v[124:127]
	v_mfma_f32_16x16x32_bf16 v[124:127], v[150:153], v[182:185], v[124:127]
	v_mfma_f32_16x16x32_bf16 v[120:123], v[154:157], v[178:181], v[120:123]
	v_mfma_f32_16x16x32_bf16 v[120:123], v[158:161], v[182:185], v[120:123]
	v_mfma_f32_16x16x32_bf16 v[116:119], v[146:149], v[186:189], v[116:119]
	v_mfma_f32_16x16x32_bf16 v[116:119], v[150:153], v[190:193], v[116:119]
	v_mfma_f32_16x16x32_bf16 v[112:115], v[154:157], v[186:189], v[112:115]
	v_mfma_f32_16x16x32_bf16 v[112:115], v[158:161], v[190:193], v[112:115]
	v_mfma_f32_16x16x32_bf16 v[100:103], v[146:149], v[194:197], v[100:103]
	v_mfma_f32_16x16x32_bf16 v[100:103], v[150:153], v[198:201], v[100:103]
	v_mfma_f32_16x16x32_bf16 v[96:99], v[154:157], v[194:197], v[96:99]
	v_mfma_f32_16x16x32_bf16 v[96:99], v[158:161], v[198:201], v[96:99]
	v_mfma_f32_16x16x32_bf16 v[84:87], v[146:149], v[202:205], v[84:87]
	v_mfma_f32_16x16x32_bf16 v[84:87], v[150:153], v[206:209], v[84:87]
	v_mfma_f32_16x16x32_bf16 v[80:83], v[154:157], v[202:205], v[80:83]
	v_mfma_f32_16x16x32_bf16 v[80:83], v[158:161], v[206:209], v[80:83]
	v_mfma_f32_16x16x32_bf16 v[108:111], v[162:165], v[178:181], v[108:111]
	v_mfma_f32_16x16x32_bf16 v[108:111], v[166:169], v[182:185], v[108:111]
	v_mfma_f32_16x16x32_bf16 v[104:107], v[170:173], v[178:181], v[104:107]
	v_mfma_f32_16x16x32_bf16 v[104:107], v[174:177], v[182:185], v[104:107]
	v_mfma_f32_16x16x32_bf16 v[92:95], v[162:165], v[186:189], v[92:95]
	v_mfma_f32_16x16x32_bf16 v[92:95], v[166:169], v[190:193], v[92:95]
	v_mfma_f32_16x16x32_bf16 v[88:91], v[170:173], v[186:189], v[88:91]
	v_mfma_f32_16x16x32_bf16 v[88:91], v[174:177], v[190:193], v[88:91]
	v_mfma_f32_16x16x32_bf16 v[76:79], v[162:165], v[194:197], v[76:79]
	v_mfma_f32_16x16x32_bf16 v[76:79], v[166:169], v[198:201], v[76:79]
	v_mfma_f32_16x16x32_bf16 v[72:75], v[170:173], v[194:197], v[72:75]
	v_mfma_f32_16x16x32_bf16 v[72:75], v[174:177], v[198:201], v[72:75]
	v_mfma_f32_16x16x32_bf16 v[68:71], v[162:165], v[202:205], v[68:71]
	v_mfma_f32_16x16x32_bf16 v[68:71], v[166:169], v[206:209], v[68:71]
	v_mfma_f32_16x16x32_bf16 v[64:67], v[170:173], v[202:205], v[64:67]
	v_mfma_f32_16x16x32_bf16 v[64:67], v[174:177], v[206:209], v[64:67]
	s_barrier
; #define PG8_STAGE(bufoff, gbase, voff) do { _Pragma("unroll") for (int _i = 0; _i < 2; ++_i) \
;         __builtin_amdgcn_global_load_lds((const unsigned*)((const char*)(gbase) + (voff)[_i]), (LAS unsigned*)(lds + (bufoff) + ldsw + _i * 8192), 16, 0, 0); } while (0)
; #define PG8_LDA(dst, b, h) do { _Pragma("unroll") for (int m = 0; m < 4; ++m) _Pragma("unroll") for (int k = 0; k < 2; ++k) dst[m][k] = *(const LAS bf16x8*)(lds + PG8_SA(b, h) + aoff + m * 2048 + k * 1024); } while (0)
; #define PG8_MMA(ai, bj, At, Bt) do { __builtin_amdgcn_s_setprio(1); _Pragma("unroll") for (int m = 0; m < 4; ++m) _Pragma("unroll") for (int n = 0; n < 2; ++n) _Pragma("unroll") for (int k = 0; k < 2; ++k) \
;         acc[ai][bj][m][n] = __builtin_amdgcn_mfma_f32_16x16x32_bf16(Bt[n][k], At[m][k], acc[ai][bj][m][n], 0, 0, 0); __builtin_amdgcn_s_setprio(0); } while (0)
; #define PG8_WAIT_V(n) asm volatile("s_waitcnt vmcnt(" #n ")" ::: "memory")
; #define PG8_WAIT_L(n) asm volatile("s_waitcnt lgkmcnt(" #n ")" ::: "memory")
; #define PG8_BAR __builtin_amdgcn_s_barrier()
; #define PG8_SCHED __builtin_amdgcn_sched_barrier(0)
; template <class Epi>
; __device__ __forceinline__ void gemm_phase(LAS unsigned char* lds, const Gemm g, const Order& S, const Epi& E, const int wid) {
;     ...
;         for (int t = 0; t < nt; t += 2) {
;     ...
;             PG8_LDA(At, 1, 1); PG8_STAGE(PG8_SB(1, 0), b3, voffB); PG8_STAGE(PG8_SB(1, 1), b3 + hB, voffB); PG8_STAGE(PG8_SA(1, 0), a3, voffA);
;             PG8_WAIT_V(8); PG8_WAIT_L(0); PG8_BAR; PG8_MMA(1, 0, At, B0); PG8_MMA(1, 1, At, B1); PG8_BAR; PG8_SCHED;
	s_add_i32 s40, s62, s24
	v_lshl_add_u64 v[210:211], v[210:211], 0, s[18:19]
	s_mov_b32 m0, s40
	ds_read_b128 v[178:181], v144 offset:49152
	ds_read_b128 v[182:185], v144 offset:50176
	ds_read_b128 v[186:189], v144 offset:51200
	ds_read_b128 v[190:193], v144 offset:52224
	ds_read_b128 v[194:197], v144 offset:53248
	ds_read_b128 v[198:201], v144 offset:54272
	ds_read_b128 v[202:205], v144 offset:55296
	ds_read_b128 v[206:209], v144 offset:56320
	global_load_lds_dwordx4 v[210:211], off
	s_add_i32 m0, s40, 0x2000
	s_add_u32 s38, s38, 0x100080
	v_lshl_add_u64 v[210:211], v[212:213], 0, s[18:19]
	s_addc_u32 s39, s39, 0
	s_add_i32 s40, s63, s24
	global_load_lds_dwordx4 v[210:211], off
	v_lshl_add_u64 v[210:211], s[38:39], 0, v[134:135]
	s_mov_b32 m0, s40
	s_nop 0
	global_load_lds_dwordx4 v[210:211], off
	v_lshl_add_u64 v[210:211], s[38:39], 0, v[136:137]
	s_add_i32 m0, s40, 0x2000
	s_nop 0
	global_load_lds_dwordx4 v[210:211], off
	v_lshl_add_u64 v[210:211], v[214:215], 0, s[18:19]
	s_mov_b32 m0, s52
	s_nop 0
	global_load_lds_dwordx4 v[210:211], off
	v_lshl_add_u64 v[210:211], v[216:217], 0, s[18:19]
	s_mov_b32 m0, s53
	s_nop 0
	global_load_lds_dwordx4 v[210:211], off
	s_waitcnt vmcnt(8)
	s_waitcnt lgkmcnt(0)
	s_barrier
	s_waitcnt lgkmcnt(0)
	v_mfma_f32_16x16x32_bf16 v[60:63], v[146:149], v[178:181], v[60:63]
	v_mfma_f32_16x16x32_bf16 v[60:63], v[150:153], v[182:185], v[60:63]
	v_mfma_f32_16x16x32_bf16 v[56:59], v[154:157], v[178:181], v[56:59]
	v_mfma_f32_16x16x32_bf16 v[56:59], v[158:161], v[182:185], v[56:59]
	v_mfma_f32_16x16x32_bf16 v[52:55], v[146:149], v[186:189], v[52:55]
	v_mfma_f32_16x16x32_bf16 v[52:55], v[150:153], v[190:193], v[52:55]
	v_mfma_f32_16x16x32_bf16 v[48:51], v[154:157], v[186:189], v[48:51]
	v_mfma_f32_16x16x32_bf16 v[48:51], v[158:161], v[190:193], v[48:51]
	v_mfma_f32_16x16x32_bf16 v[36:39], v[146:149], v[194:197], v[36:39]
	v_mfma_f32_16x16x32_bf16 v[36:39], v[150:153], v[198:201], v[36:39]
	v_mfma_f32_16x16x32_bf16 v[32:35], v[154:157], v[194:197], v[32:35]
	v_mfma_f32_16x16x32_bf16 v[32:35], v[158:161], v[198:201], v[32:35]
	v_mfma_f32_16x16x32_bf16 v[20:23], v[146:149], v[202:205], v[20:23]
	v_mfma_f32_16x16x32_bf16 v[20:23], v[150:153], v[206:209], v[20:23]
	v_mfma_f32_16x16x32_bf16 v[16:19], v[154:157], v[202:205], v[16:19]
	v_mfma_f32_16x16x32_bf16 v[16:19], v[158:161], v[206:209], v[16:19]
	v_mfma_f32_16x16x32_bf16 v[44:47], v[162:165], v[178:181], v[44:47]
	v_mfma_f32_16x16x32_bf16 v[44:47], v[166:169], v[182:185], v[44:47]
	v_mfma_f32_16x16x32_bf16 v[40:43], v[170:173], v[178:181], v[40:43]
	v_mfma_f32_16x16x32_bf16 v[40:43], v[174:177], v[182:185], v[40:43]
	v_mfma_f32_16x16x32_bf16 v[28:31], v[162:165], v[186:189], v[28:31]
	v_mfma_f32_16x16x32_bf16 v[28:31], v[166:169], v[190:193], v[28:31]
	v_mfma_f32_16x16x32_bf16 v[24:27], v[170:173], v[186:189], v[24:27]
	v_mfma_f32_16x16x32_bf16 v[24:27], v[174:177], v[190:193], v[24:27]
	v_mfma_f32_16x16x32_bf16 v[12:15], v[162:165], v[194:197], v[12:15]
	v_mfma_f32_16x16x32_bf16 v[12:15], v[166:169], v[198:201], v[12:15]
	v_mfma_f32_16x16x32_bf16 v[8:11], v[170:173], v[194:197], v[8:11]
	v_mfma_f32_16x16x32_bf16 v[8:11], v[174:177], v[198:201], v[8:11]
	v_mfma_f32_16x16x32_bf16 v[4:7], v[162:165], v[202:205], v[4:7]
	v_mfma_f32_16x16x32_bf16 v[4:7], v[166:169], v[206:209], v[4:7]
	v_mfma_f32_16x16x32_bf16 v[0:3], v[170:173], v[202:205], v[0:3]
	v_mfma_f32_16x16x32_bf16 v[0:3], v[174:177], v[206:209], v[0:3]
	s_add_i32 s61, s61, 2
	s_add_u32 s36, s36, 0x100
	s_addc_u32 s37, s37, 0
	s_add_u32 s21, s21, 0x100
	s_addc_u32 s60, s60, 0
	s_cmp_gt_u32 s61, 13
	s_barrier
	s_cbranch_scc0 .LBB0_1035
	s_and_b64 vcc, exec, s[10:11]
	s_cbranch_vccz .LBB0_1038
	s_barrier

; #define PG8_STAGE(bufoff, gbase, voff) do { _Pragma("unroll") for (int _i = 0; _i < 2; ++_i) \
;         __builtin_amdgcn_global_load_lds((const unsigned*)((const char*)(gbase) + (voff)[_i]), (LAS unsigned*)(lds + (bufoff) + ldsw + _i * 8192), 16, 0, 0); } while (0)
; #define PG8_LDA(dst, b, h) do { _Pragma("unroll") for (int m = 0; m < 4; ++m) _Pragma("unroll") for (int k = 0; k < 2; ++k) dst[m][k] = *(const LAS bf16x8*)(lds + PG8_SA(b, h) + aoff + m * 2048 + k * 1024); } while (0)
; #define PG8_LDB(dst, b, h) do { _Pragma("unroll") for (int n = 0; n < 2; ++n) _Pragma("unroll") for (int k = 0; k < 2; ++k) dst[n][k] = *(const LAS bf16x8*)(lds + PG8_SB(b, h) + boff + n * 2048 + k * 1024); } while (0)
; #define PG8_MMA(ai, bj, At, Bt) do { __builtin_amdgcn_s_setprio(1); _Pragma("unroll") for (int m = 0; m < 4; ++m) _Pragma("unroll") for (int n = 0; n < 2; ++n) _Pragma("unroll") for (int k = 0; k < 2; ++k) \
;         acc[ai][bj][m][n] = __builtin_amdgcn_mfma_f32_16x16x32_bf16(Bt[n][k], At[m][k], acc[ai][bj][m][n], 0, 0, 0); __builtin_amdgcn_s_setprio(0); } while (0)
; #define PG8_WAIT_V(n) asm volatile("s_waitcnt vmcnt(" #n ")" ::: "memory")
; #define PG8_WAIT_L(n) asm volatile("s_waitcnt lgkmcnt(" #n ")" ::: "memory")
; #define PG8_BAR __builtin_amdgcn_s_barrier()
; #define PG8_SCHED __builtin_amdgcn_sched_barrier(0)
; template <class Epi>
; __device__ __forceinline__ void gemm_phase(LAS unsigned char* lds, const Gemm g, const Order& S, const Epi& E, const int wid) {
;     ...
;         for (int t = 0; t < nt; t += 2) {
;             const bool last = (t == nt - 2);
;             const char* a1 = cA + (size_t)(t + 1) * kstep;
;             const char* a2 = last ? nA : cA + (size_t)(t + 2) * kstep; const char* b2 = last ? nB : cB + (size_t)(t + 2) * kstep;
;             const char* a3 = a2 + kstep; const char* b3 = b2 + kstep;
;     ...
;             PG8_LDB(B0, 0, 0); PG8_LDB(B1, 0, 1); PG8_SCHED; PG8_LDA(At, 0, 0); PG8_STAGE(PG8_SA(1, 1), a1 + hA, voffA);
;             PG8_WAIT_V(8); PG8_WAIT_L(0); PG8_BAR; PG8_MMA(0, 0, At, B0); PG8_MMA(0, 1, At, B1); PG8_BAR; PG8_SCHED;
;             PG8_LDA(At, 0, 1); PG8_STAGE(PG8_SB(0, 0), b2, voffB); PG8_STAGE(PG8_SB(0, 1), b2 + hB, voffB); PG8_STAGE(PG8_SA(0, 0), a2, voffA);
.LBB0_1059:
	ds_read_b128 v[146:149], v142
	ds_read_b128 v[150:153], v142 offset:1024
	ds_read_b128 v[154:157], v142 offset:2048
	ds_read_b128 v[158:161], v142 offset:3072
	ds_read_b128 v[162:165], v143
	ds_read_b128 v[166:169], v143 offset:1024
	ds_read_b128 v[170:173], v143 offset:2048
	ds_read_b128 v[174:177], v143 offset:3072
	s_add_u32 s36, s28, 0xfff00080
	s_addc_u32 s37, s29, -1
	s_cmp_eq_u32 s60, 12
	s_cselect_b32 s39, s7, s37
	s_cselect_b32 s38, s6, s36
	s_cselect_b32 s37, s23, s59
	s_cselect_b32 s36, s22, s19
	v_lshl_add_u64 v[210:211], s[28:29], 0, v[128:129]
	s_add_i32 m0, s21, 0xc000
	ds_read_b128 v[178:181], v144
	ds_read_b128 v[182:185], v144 offset:1024
	ds_read_b128 v[186:189], v144 offset:2048
	ds_read_b128 v[190:193], v144 offset:3072
	ds_read_b128 v[194:197], v144 offset:4096
	ds_read_b128 v[198:201], v144 offset:5120
	ds_read_b128 v[202:205], v144 offset:6144
	ds_read_b128 v[206:209], v144 offset:7168
	global_load_lds_dwordx4 v[210:211], off
	v_lshl_add_u64 v[210:211], s[28:29], 0, v[138:139]
	s_add_i32 m0, s21, 0xe000
	s_nop 0
	global_load_lds_dwordx4 v[210:211], off
	s_waitcnt vmcnt(8)
	s_waitcnt lgkmcnt(0)
	s_barrier
	s_waitcnt lgkmcnt(0)
	v_mfma_f32_16x16x32_bf16 v[124:127], v[146:149], v[178:181], v[124:127]
	v_mfma_f32_16x16x32_bf16 v[124:127], v[150:153], v[182:185], v[124:127]
	v_mfma_f32_16x16x32_bf16 v[120:123], v[154:157], v[178:181], v[120:123]
	v_mfma_f32_16x16x32_bf16 v[120:123], v[158:161], v[182:185], v[120:123]
	v_mfma_f32_16x16x32_bf16 v[116:119], v[146:149], v[186:189], v[116:119]
	v_mfma_f32_16x16x32_bf16 v[116:119], v[150:153], v[190:193], v[116:119]
	v_mfma_f32_16x16x32_bf16 v[112:115], v[154:157], v[186:189], v[112:115]
	v_mfma_f32_16x16x32_bf16 v[112:115], v[158:161], v[190:193], v[112:115]
	v_mfma_f32_16x16x32_bf16 v[100:103], v[146:149], v[194:197], v[100:103]
	v_mfma_f32_16x16x32_bf16 v[100:103], v[150:153], v[198:201], v[100:103]
	v_mfma_f32_16x16x32_bf16 v[96:99], v[154:157], v[194:197], v[96:99]
	v_mfma_f32_16x16x32_bf16 v[96:99], v[158:161], v[198:201], v[96:99]
	v_mfma_f32_16x16x32_bf16 v[84:87], v[146:149], v[202:205], v[84:87]
	v_mfma_f32_16x16x32_bf16 v[84:87], v[150:153], v[206:209], v[84:87]
	v_mfma_f32_16x16x32_bf16 v[80:83], v[154:157], v[202:205], v[80:83]
	v_mfma_f32_16x16x32_bf16 v[80:83], v[158:161], v[206:209], v[80:83]
	v_mfma_f32_16x16x32_bf16 v[108:111], v[162:165], v[178:181], v[108:111]
	v_mfma_f32_16x16x32_bf16 v[108:111], v[166:169], v[182:185], v[108:111]
	v_mfma_f32_16x16x32_bf16 v[104:107], v[170:173], v[178:181], v[104:107]
	v_mfma_f32_16x16x32_bf16 v[104:107], v[174:177], v[182:185], v[104:107]
	v_mfma_f32_16x16x32_bf16 v[92:95], v[162:165], v[186:189], v[92:95]
	v_mfma_f32_16x16x32_bf16 v[92:95], v[166:169], v[190:193], v[92:95]
	v_mfma_f32_16x16x32_bf16 v[88:91], v[170:173], v[186:189], v[88:91]
	v_mfma_f32_16x16x32_bf16 v[88:91], v[174:177], v[190:193], v[88:91]
	v_mfma_f32_16x16x32_bf16 v[76:79], v[162:165], v[194:197], v[76:79]
	v_mfma_f32_16x16x32_bf16 v[76:79], v[166:169], v[198:201], v[76:79]
	v_mfma_f32_16x16x32_bf16 v[72:75], v[170:173], v[194:197], v[72:75]
	v_mfma_f32_16x16x32_bf16 v[72:75], v[174:177], v[198:201], v[72:75]
	v_mfma_f32_16x16x32_bf16 v[68:71], v[162:165], v[202:205], v[68:71]
	v_mfma_f32_16x16x32_bf16 v[68:71], v[166:169], v[206:209], v[68:71]
	v_mfma_f32_16x16x32_bf16 v[64:67], v[170:173], v[202:205], v[64:67]
	v_mfma_f32_16x16x32_bf16 v[64:67], v[174:177], v[206:209], v[64:67]
	s_barrier
	s_add_i32 s61, s53, s24
	v_lshl_add_u64 v[210:211], s[36:37], 0, v[134:135]
	s_mov_b32 m0, s61
	ds_read_b128 v[178:181], v144 offset:16384
	ds_read_b128 v[182:185], v144 offset:17408
	ds_read_b128 v[186:189], v144 offset:18432
	ds_read_b128 v[190:193], v144 offset:19456
	ds_read_b128 v[194:197], v144 offset:20480
	ds_read_b128 v[198:201], v144 offset:21504
	ds_read_b128 v[202:205], v144 offset:22528
	ds_read_b128 v[206:209], v144 offset:23552
	global_load_lds_dwordx4 v[210:211], off
	s_add_i32 m0, s61, 0x2000
	s_add_u32 s62, s36, 0x100000
	v_lshl_add_u64 v[212:213], s[36:37], 0, v[136:137]
	s_addc_u32 s63, s37, 0
	s_add_i32 s61, s54, s24
	global_load_lds_dwordx4 v[212:213], off
	v_lshl_add_u64 v[214:215], s[62:63], 0, v[134:135]
	s_mov_b32 m0, s61
	v_lshl_add_u64 v[216:217], s[38:39], 0, v[138:139]
	global_load_lds_dwordx4 v[214:215], off
	v_lshl_add_u64 v[214:215], s[62:63], 0, v[136:137]
	s_add_i32 m0, s61, 0x2000
	s_nop 0
	global_load_lds_dwordx4 v[214:215], off
	v_lshl_add_u64 v[214:215], s[38:39], 0, v[128:129]
	s_mov_b32 m0, s21
	s_nop 0
	global_load_lds_dwordx4 v[214:215], off
	s_mov_b32 m0, s35
	s_nop 0
	global_load_lds_dwordx4 v[216:217], off
	s_waitcnt vmcnt(8)
	s_waitcnt lgkmcnt(0)
	s_barrier
; #define PG8_STAGE(bufoff, gbase, voff) do { _Pragma("unroll") for (int _i = 0; _i < 2; ++_i) \
;         __builtin_amdgcn_global_load_lds((const unsigned*)((const char*)(gbase) + (voff)[_i]), (LAS unsigned*)(lds + (bufoff) + ldsw + _i * 8192), 16, 0, 0); } while (0)
; #define PG8_LDA(dst, b, h) do { _Pragma("unroll") for (int m = 0; m < 4; ++m) _Pragma("unroll") for (int k = 0; k < 2; ++k) dst[m][k] = *(const LAS bf16x8*)(lds + PG8_SA(b, h) + aoff + m * 2048 + k * 1024); } while (0)
; #define PG8_LDB(dst, b, h) do { _Pragma("unroll") for (int n = 0; n < 2; ++n) _Pragma("unroll") for (int k = 0; k < 2; ++k) dst[n][k] = *(const LAS bf16x8*)(lds + PG8_SB(b, h) + boff + n * 2048 + k * 1024); } while (0)
; #define PG8_MMA(ai, bj, At, Bt) do { __builtin_amdgcn_s_setprio(1); _Pragma("unroll") for (int m = 0; m < 4; ++m) _Pragma("unroll") for (int n = 0; n < 2; ++n) _Pragma("unroll") for (int k = 0; k < 2; ++k) \
;         acc[ai][bj][m][n] = __builtin_amdgcn_mfma_f32_16x16x32_bf16(Bt[n][k], At[m][k], acc[ai][bj][m][n], 0, 0, 0); __builtin_amdgcn_s_setprio(0); } while (0)
; #define PG8_WAIT_V(n) asm volatile("s_waitcnt vmcnt(" #n ")" ::: "memory")
; #define PG8_WAIT_L(n) asm volatile("s_waitcnt lgkmcnt(" #n ")" ::: "memory")
; #define PG8_BAR __builtin_amdgcn_s_barrier()
; #define PG8_SCHED __builtin_amdgcn_sched_barrier(0)
; template <class Epi>
; __device__ __forceinline__ void gemm_phase(LAS unsigned char* lds, const Gemm g, const Order& S, const Epi& E, const int wid) {
;     ...
;             PG8_WAIT_V(8); PG8_WAIT_L(0); PG8_BAR; PG8_MMA(1, 0, At, B0); PG8_MMA(1, 1, At, B1); PG8_BAR; PG8_SCHED;
;             PG8_LDB(B0, 1, 0); PG8_LDB(B1, 1, 1); PG8_SCHED; PG8_LDA(At, 1, 0); PG8_STAGE(PG8_SA(0, 1), a2 + hA, voffA);
;             PG8_WAIT_V(8); PG8_WAIT_L(0); PG8_BAR; PG8_MMA(0, 0, At, B0); PG8_MMA(0, 1, At, B1); PG8_BAR; PG8_SCHED;
	s_waitcnt lgkmcnt(0)
	v_mfma_f32_16x16x32_bf16 v[60:63], v[146:149], v[178:181], v[60:63]
	v_mfma_f32_16x16x32_bf16 v[60:63], v[150:153], v[182:185], v[60:63]
	v_mfma_f32_16x16x32_bf16 v[56:59], v[154:157], v[178:181], v[56:59]
	v_mfma_f32_16x16x32_bf16 v[56:59], v[158:161], v[182:185], v[56:59]
	v_mfma_f32_16x16x32_bf16 v[52:55], v[146:149], v[186:189], v[52:55]
	v_mfma_f32_16x16x32_bf16 v[52:55], v[150:153], v[190:193], v[52:55]
	v_mfma_f32_16x16x32_bf16 v[48:51], v[154:157], v[186:189], v[48:51]
	v_mfma_f32_16x16x32_bf16 v[48:51], v[158:161], v[190:193], v[48:51]
	v_mfma_f32_16x16x32_bf16 v[36:39], v[146:149], v[194:197], v[36:39]
	v_mfma_f32_16x16x32_bf16 v[36:39], v[150:153], v[198:201], v[36:39]
	v_mfma_f32_16x16x32_bf16 v[32:35], v[154:157], v[194:197], v[32:35]
	v_mfma_f32_16x16x32_bf16 v[32:35], v[158:161], v[198:201], v[32:35]
	v_mfma_f32_16x16x32_bf16 v[20:23], v[146:149], v[202:205], v[20:23]
	v_mfma_f32_16x16x32_bf16 v[20:23], v[150:153], v[206:209], v[20:23]
	v_mfma_f32_16x16x32_bf16 v[16:19], v[154:157], v[202:205], v[16:19]
	v_mfma_f32_16x16x32_bf16 v[16:19], v[158:161], v[206:209], v[16:19]
	v_mfma_f32_16x16x32_bf16 v[44:47], v[162:165], v[178:181], v[44:47]
	v_mfma_f32_16x16x32_bf16 v[44:47], v[166:169], v[182:185], v[44:47]
	v_mfma_f32_16x16x32_bf16 v[40:43], v[170:173], v[178:181], v[40:43]
	v_mfma_f32_16x16x32_bf16 v[40:43], v[174:177], v[182:185], v[40:43]
	v_mfma_f32_16x16x32_bf16 v[28:31], v[162:165], v[186:189], v[28:31]
	v_mfma_f32_16x16x32_bf16 v[28:31], v[166:169], v[190:193], v[28:31]
	v_mfma_f32_16x16x32_bf16 v[24:27], v[170:173], v[186:189], v[24:27]
	v_mfma_f32_16x16x32_bf16 v[24:27], v[174:177], v[190:193], v[24:27]
	v_mfma_f32_16x16x32_bf16 v[12:15], v[162:165], v[194:197], v[12:15]
	v_mfma_f32_16x16x32_bf16 v[12:15], v[166:169], v[198:201], v[12:15]
	v_mfma_f32_16x16x32_bf16 v[8:11], v[170:173], v[194:197], v[8:11]
	v_mfma_f32_16x16x32_bf16 v[8:11], v[174:177], v[198:201], v[8:11]
	v_mfma_f32_16x16x32_bf16 v[4:7], v[162:165], v[202:205], v[4:7]
	v_mfma_f32_16x16x32_bf16 v[4:7], v[166:169], v[206:209], v[4:7]
	v_mfma_f32_16x16x32_bf16 v[0:3], v[170:173], v[202:205], v[0:3]
	v_mfma_f32_16x16x32_bf16 v[0:3], v[174:177], v[206:209], v[0:3]
	s_barrier
	s_add_i32 s61, 0, 0x18000
	v_add_u32_e32 v145, s61, v141
	s_add_i32 s62, 0, 0x1c000
	ds_read_b128 v[146:149], v145
	ds_read_b128 v[150:153], v145 offset:1024
	ds_read_b128 v[154:157], v145 offset:2048
	ds_read_b128 v[158:161], v145 offset:3072
	v_add_u32_e32 v145, s62, v141
	ds_read_b128 v[162:165], v145
	ds_read_b128 v[166:169], v145 offset:1024
	ds_read_b128 v[170:173], v145 offset:2048
	ds_read_b128 v[174:177], v145 offset:3072
	s_add_u32 s38, s38, 0x100000
	s_addc_u32 s39, s39, 0
	s_mov_b32 m0, s42
	v_lshl_add_u64 v[218:219], s[38:39], 0, v[128:129]
	ds_read_b128 v[178:181], v144 offset:32768
	ds_read_b128 v[182:185], v144 offset:33792
	ds_read_b128 v[186:189], v144 offset:34816
	ds_read_b128 v[190:193], v144 offset:35840
	ds_read_b128 v[194:197], v144 offset:36864
	ds_read_b128 v[198:201], v144 offset:37888
	ds_read_b128 v[202:205], v144 offset:38912
	ds_read_b128 v[206:209], v144 offset:39936
	global_load_lds_dwordx4 v[218:219], off
	v_lshl_add_u64 v[218:219], s[38:39], 0, v[138:139]
	s_mov_b32 m0, s43
	s_nop 0
	global_load_lds_dwordx4 v[218:219], off
	s_waitcnt vmcnt(8)
	s_waitcnt lgkmcnt(0)
	s_barrier
	s_waitcnt lgkmcnt(0)
	v_mfma_f32_16x16x32_bf16 v[124:127], v[146:149], v[178:181], v[124:127]
	v_mfma_f32_16x16x32_bf16 v[124:127], v[150:153], v[182:185], v[124:127]
	v_mfma_f32_16x16x32_bf16 v[120:123], v[154:157], v[178:181], v[120:123]
	v_mfma_f32_16x16x32_bf16 v[120:123], v[158:161], v[182:185], v[120:123]
	v_mfma_f32_16x16x32_bf16 v[116:119], v[146:149], v[186:189], v[116:119]
	v_mfma_f32_16x16x32_bf16 v[116:119], v[150:153], v[190:193], v[116:119]
	v_mfma_f32_16x16x32_bf16 v[112:115], v[154:157], v[186:189], v[112:115]
	v_mfma_f32_16x16x32_bf16 v[112:115], v[158:161], v[190:193], v[112:115]
	v_mfma_f32_16x16x32_bf16 v[100:103], v[146:149], v[194:197], v[100:103]
	v_mfma_f32_16x16x32_bf16 v[100:103], v[150:153], v[198:201], v[100:103]
	v_mfma_f32_16x16x32_bf16 v[96:99], v[154:157], v[194:197], v[96:99]
	v_mfma_f32_16x16x32_bf16 v[96:99], v[158:161], v[198:201], v[96:99]
	v_mfma_f32_16x16x32_bf16 v[84:87], v[146:149], v[202:205], v[84:87]
	v_mfma_f32_16x16x32_bf16 v[84:87], v[150:153], v[206:209], v[84:87]
	v_mfma_f32_16x16x32_bf16 v[80:83], v[154:157], v[202:205], v[80:83]
	v_mfma_f32_16x16x32_bf16 v[80:83], v[158:161], v[206:209], v[80:83]
	v_mfma_f32_16x16x32_bf16 v[108:111], v[162:165], v[178:181], v[108:111]
	v_mfma_f32_16x16x32_bf16 v[108:111], v[166:169], v[182:185], v[108:111]
	v_mfma_f32_16x16x32_bf16 v[104:107], v[170:173], v[178:181], v[104:107]
	v_mfma_f32_16x16x32_bf16 v[104:107], v[174:177], v[182:185], v[104:107]
	v_mfma_f32_16x16x32_bf16 v[92:95], v[162:165], v[186:189], v[92:95]
	v_mfma_f32_16x16x32_bf16 v[92:95], v[166:169], v[190:193], v[92:95]
	v_mfma_f32_16x16x32_bf16 v[88:91], v[170:173], v[186:189], v[88:91]
	v_mfma_f32_16x16x32_bf16 v[88:91], v[174:177], v[190:193], v[88:91]
	v_mfma_f32_16x16x32_bf16 v[76:79], v[162:165], v[194:197], v[76:79]
	v_mfma_f32_16x16x32_bf16 v[76:79], v[166:169], v[198:201], v[76:79]
	v_mfma_f32_16x16x32_bf16 v[72:75], v[170:173], v[194:197], v[72:75]
	v_mfma_f32_16x16x32_bf16 v[72:75], v[174:177], v[198:201], v[72:75]
	v_mfma_f32_16x16x32_bf16 v[68:71], v[162:165], v[202:205], v[68:71]
	v_mfma_f32_16x16x32_bf16 v[68:71], v[166:169], v[206:209], v[68:71]
	v_mfma_f32_16x16x32_bf16 v[64:67], v[170:173], v[202:205], v[64:67]
	v_mfma_f32_16x16x32_bf16 v[64:67], v[174:177], v[206:209], v[64:67]
	s_barrier
; #define PG8_STAGE(bufoff, gbase, voff) do { _Pragma("unroll") for (int _i = 0; _i < 2; ++_i) \
;         __builtin_amdgcn_global_load_lds((const unsigned*)((const char*)(gbase) + (voff)[_i]), (LAS unsigned*)(lds + (bufoff) + ldsw + _i * 8192), 16, 0, 0); } while (0)
; #define PG8_LDA(dst, b, h) do { _Pragma("unroll") for (int m = 0; m < 4; ++m) _Pragma("unroll") for (int k = 0; k < 2; ++k) dst[m][k] = *(const LAS bf16x8*)(lds + PG8_SA(b, h) + aoff + m * 2048 + k * 1024); } while (0)
; #define PG8_MMA(ai, bj, At, Bt) do { __builtin_amdgcn_s_setprio(1); _Pragma("unroll") for (int m = 0; m < 4; ++m) _Pragma("unroll") for (int n = 0; n < 2; ++n) _Pragma("unroll") for (int k = 0; k < 2; ++k) \
;         acc[ai][bj][m][n] = __builtin_amdgcn_mfma_f32_16x16x32_bf16(Bt[n][k], At[m][k], acc[ai][bj][m][n], 0, 0, 0); __builtin_amdgcn_s_setprio(0); } while (0)
; #define PG8_WAIT_V(n) asm volatile("s_waitcnt vmcnt(" #n ")" ::: "memory")
; #define PG8_WAIT_L(n) asm volatile("s_waitcnt lgkmcnt(" #n ")" ::: "memory")
; #define PG8_BAR __builtin_amdgcn_s_barrier()
; #define PG8_SCHED __builtin_amdgcn_sched_barrier(0)
; template <class Epi>
; __device__ __forceinline__ void gemm_phase(LAS unsigned char* lds, const Gemm g, const Order& S, const Epi& E, const int wid) {
;     ...
;         for (int t = 0; t < nt; t += 2) {
;     ...
;             PG8_LDA(At, 1, 1); PG8_STAGE(PG8_SB(1, 0), b3, voffB); PG8_STAGE(PG8_SB(1, 1), b3 + hB, voffB); PG8_STAGE(PG8_SA(1, 0), a3, voffA);
;             PG8_WAIT_V(8); PG8_WAIT_L(0); PG8_BAR; PG8_MMA(1, 0, At, B0); PG8_MMA(1, 1, At, B1); PG8_BAR; PG8_SCHED;
	s_add_i32 s38, s61, s24
	v_lshl_add_u64 v[210:211], v[210:211], 0, s[12:13]
	s_mov_b32 m0, s38
	ds_read_b128 v[178:181], v144 offset:49152
	ds_read_b128 v[182:185], v144 offset:50176
	ds_read_b128 v[186:189], v144 offset:51200
	ds_read_b128 v[190:193], v144 offset:52224
	ds_read_b128 v[194:197], v144 offset:53248
	ds_read_b128 v[198:201], v144 offset:54272
	ds_read_b128 v[202:205], v144 offset:55296
	ds_read_b128 v[206:209], v144 offset:56320
	global_load_lds_dwordx4 v[210:211], off
	s_add_i32 m0, s38, 0x2000
	s_add_u32 s36, s36, 0x100080
	v_lshl_add_u64 v[210:211], v[212:213], 0, s[12:13]
	s_addc_u32 s37, s37, 0
	s_add_i32 s38, s62, s24
	global_load_lds_dwordx4 v[210:211], off
	v_lshl_add_u64 v[210:211], s[36:37], 0, v[134:135]
	s_mov_b32 m0, s38
	s_nop 0
	global_load_lds_dwordx4 v[210:211], off
	v_lshl_add_u64 v[210:211], s[36:37], 0, v[136:137]
	s_add_i32 m0, s38, 0x2000
	s_nop 0
	global_load_lds_dwordx4 v[210:211], off
	v_lshl_add_u64 v[210:211], v[214:215], 0, s[12:13]
	s_mov_b32 m0, s50
	s_nop 0
	global_load_lds_dwordx4 v[210:211], off
	v_lshl_add_u64 v[210:211], v[216:217], 0, s[12:13]
	s_mov_b32 m0, s51
	s_nop 0
	global_load_lds_dwordx4 v[210:211], off
	s_waitcnt vmcnt(8)
	s_waitcnt lgkmcnt(0)
	s_barrier
	s_waitcnt lgkmcnt(0)
	v_mfma_f32_16x16x32_bf16 v[60:63], v[146:149], v[178:181], v[60:63]
	v_mfma_f32_16x16x32_bf16 v[60:63], v[150:153], v[182:185], v[60:63]
	v_mfma_f32_16x16x32_bf16 v[56:59], v[154:157], v[178:181], v[56:59]
	v_mfma_f32_16x16x32_bf16 v[56:59], v[158:161], v[182:185], v[56:59]
	v_mfma_f32_16x16x32_bf16 v[52:55], v[146:149], v[186:189], v[52:55]
	v_mfma_f32_16x16x32_bf16 v[52:55], v[150:153], v[190:193], v[52:55]
	v_mfma_f32_16x16x32_bf16 v[48:51], v[154:157], v[186:189], v[48:51]
	v_mfma_f32_16x16x32_bf16 v[48:51], v[158:161], v[190:193], v[48:51]
	v_mfma_f32_16x16x32_bf16 v[36:39], v[146:149], v[194:197], v[36:39]
	v_mfma_f32_16x16x32_bf16 v[36:39], v[150:153], v[198:201], v[36:39]
	v_mfma_f32_16x16x32_bf16 v[32:35], v[154:157], v[194:197], v[32:35]
	v_mfma_f32_16x16x32_bf16 v[32:35], v[158:161], v[198:201], v[32:35]
	v_mfma_f32_16x16x32_bf16 v[20:23], v[146:149], v[202:205], v[20:23]
	v_mfma_f32_16x16x32_bf16 v[20:23], v[150:153], v[206:209], v[20:23]
	v_mfma_f32_16x16x32_bf16 v[16:19], v[154:157], v[202:205], v[16:19]
	v_mfma_f32_16x16x32_bf16 v[16:19], v[158:161], v[206:209], v[16:19]
	v_mfma_f32_16x16x32_bf16 v[44:47], v[162:165], v[178:181], v[44:47]
	v_mfma_f32_16x16x32_bf16 v[44:47], v[166:169], v[182:185], v[44:47]
	v_mfma_f32_16x16x32_bf16 v[40:43], v[170:173], v[178:181], v[40:43]
	v_mfma_f32_16x16x32_bf16 v[40:43], v[174:177], v[182:185], v[40:43]
	v_mfma_f32_16x16x32_bf16 v[28:31], v[162:165], v[186:189], v[28:31]
	v_mfma_f32_16x16x32_bf16 v[28:31], v[166:169], v[190:193], v[28:31]
	v_mfma_f32_16x16x32_bf16 v[24:27], v[170:173], v[186:189], v[24:27]
	v_mfma_f32_16x16x32_bf16 v[24:27], v[174:177], v[190:193], v[24:27]
	v_mfma_f32_16x16x32_bf16 v[12:15], v[162:165], v[194:197], v[12:15]
	v_mfma_f32_16x16x32_bf16 v[12:15], v[166:169], v[198:201], v[12:15]
	v_mfma_f32_16x16x32_bf16 v[8:11], v[170:173], v[194:197], v[8:11]
	v_mfma_f32_16x16x32_bf16 v[8:11], v[174:177], v[198:201], v[8:11]
	v_mfma_f32_16x16x32_bf16 v[4:7], v[162:165], v[202:205], v[4:7]
	v_mfma_f32_16x16x32_bf16 v[4:7], v[166:169], v[206:209], v[4:7]
	v_mfma_f32_16x16x32_bf16 v[0:3], v[170:173], v[202:205], v[0:3]
	v_mfma_f32_16x16x32_bf16 v[0:3], v[174:177], v[206:209], v[0:3]
	s_add_i32 s60, s60, 2
	s_add_u32 s28, s28, 0x100
	s_addc_u32 s29, s29, 0
	s_add_u32 s19, s19, 0x100
	s_addc_u32 s59, s59, 0
	s_cmp_gt_u32 s60, 13
	s_barrier
	s_cbranch_scc0 .LBB0_1059
	s_and_b64 vcc, exec, s[10:11]
	s_cbranch_vccz .LBB0_1062
	s_barrier

; #define PG8_STAGE(bufoff, gbase, voff) do { _Pragma("unroll") for (int _i = 0; _i < 2; ++_i) \
;         __builtin_amdgcn_global_load_lds((const unsigned*)((const char*)(gbase) + (voff)[_i]), (LAS unsigned*)(lds + (bufoff) + ldsw + _i * 8192), 16, 0, 0); } while (0)
; #define PG8_LDA(dst, b, h) do { _Pragma("unroll") for (int m = 0; m < 4; ++m) _Pragma("unroll") for (int k = 0; k < 2; ++k) dst[m][k] = *(const LAS bf16x8*)(lds + PG8_SA(b, h) + aoff + m * 2048 + k * 1024); } while (0)
; #define PG8_LDB(dst, b, h) do { _Pragma("unroll") for (int n = 0; n < 2; ++n) _Pragma("unroll") for (int k = 0; k < 2; ++k) dst[n][k] = *(const LAS bf16x8*)(lds + PG8_SB(b, h) + boff + n * 2048 + k * 1024); } while (0)
; #define PG8_MMA(ai, bj, At, Bt) do { __builtin_amdgcn_s_setprio(1); _Pragma("unroll") for (int m = 0; m < 4; ++m) _Pragma("unroll") for (int n = 0; n < 2; ++n) _Pragma("unroll") for (int k = 0; k < 2; ++k) \
;         acc[ai][bj][m][n] = __builtin_amdgcn_mfma_f32_16x16x32_bf16(Bt[n][k], At[m][k], acc[ai][bj][m][n], 0, 0, 0); __builtin_amdgcn_s_setprio(0); } while (0)
; #define PG8_WAIT_V(n) asm volatile("s_waitcnt vmcnt(" #n ")" ::: "memory")
; #define PG8_WAIT_L(n) asm volatile("s_waitcnt lgkmcnt(" #n ")" ::: "memory")
; #define PG8_BAR __builtin_amdgcn_s_barrier()
; #define PG8_SCHED __builtin_amdgcn_sched_barrier(0)
; template <class Epi>
; __device__ __forceinline__ void gemm_phase(LAS unsigned char* lds, const Gemm g, const Order& S, const Epi& E, const int wid) {
;     ...
;         for (int t = 0; t < nt; t += 2) {
;             const bool last = (t == nt - 2);
;             const char* a1 = cA + (size_t)(t + 1) * kstep;
;             const char* a2 = last ? nA : cA + (size_t)(t + 2) * kstep; const char* b2 = last ? nB : cB + (size_t)(t + 2) * kstep;
;             const char* a3 = a2 + kstep; const char* b3 = b2 + kstep;
;     ...
;             PG8_LDB(B0, 0, 0); PG8_LDB(B1, 0, 1); PG8_SCHED; PG8_LDA(At, 0, 0); PG8_STAGE(PG8_SA(1, 1), a1 + hA, voffA);
;             PG8_WAIT_V(8); PG8_WAIT_L(0); PG8_BAR; PG8_MMA(0, 0, At, B0); PG8_MMA(0, 1, At, B1); PG8_BAR; PG8_SCHED;
;             PG8_LDA(At, 0, 1); PG8_STAGE(PG8_SB(0, 0), b2, voffB); PG8_STAGE(PG8_SB(0, 1), b2 + hB, voffB); PG8_STAGE(PG8_SA(0, 0), a2, voffA);
.LBB0_1145:
	ds_read_b128 v[142:145], v138
	ds_read_b128 v[146:149], v138 offset:1024
	ds_read_b128 v[150:153], v138 offset:2048
	ds_read_b128 v[154:157], v138 offset:3072
	ds_read_b128 v[158:161], v139
	ds_read_b128 v[162:165], v139 offset:1024
	ds_read_b128 v[166:169], v139 offset:2048
	ds_read_b128 v[170:173], v139 offset:3072
	s_add_u32 s38, s36, 0xfff00080
	s_addc_u32 s39, s37, -1
	s_cmp_eq_u32 s60, 28
	s_cselect_b32 s41, s5, s39
	s_cselect_b32 s40, s4, s38
	s_cselect_b32 s39, s29, s23
	s_cselect_b32 s38, s28, s21
	v_lshl_add_u64 v[206:207], s[36:37], 0, v[128:129]
	s_add_i32 m0, s30, 0xc000
	ds_read_b128 v[174:177], v140
	ds_read_b128 v[178:181], v140 offset:1024
	ds_read_b128 v[182:185], v140 offset:2048
	ds_read_b128 v[186:189], v140 offset:3072
	ds_read_b128 v[190:193], v140 offset:4096
	ds_read_b128 v[194:197], v140 offset:5120
	ds_read_b128 v[198:201], v140 offset:6144
	ds_read_b128 v[202:205], v140 offset:7168
	global_load_lds_dwordx4 v[206:207], off
	v_lshl_add_u64 v[206:207], s[36:37], 0, v[134:135]
	s_add_i32 m0, s30, 0xe000
	s_nop 0
	global_load_lds_dwordx4 v[206:207], off
	s_waitcnt vmcnt(8)
	s_waitcnt lgkmcnt(0)
	s_barrier
	s_waitcnt lgkmcnt(0)
	v_mfma_f32_16x16x32_bf16 v[124:127], v[142:145], v[174:177], v[124:127]
	v_mfma_f32_16x16x32_bf16 v[124:127], v[146:149], v[178:181], v[124:127]
	v_mfma_f32_16x16x32_bf16 v[120:123], v[150:153], v[174:177], v[120:123]
	v_mfma_f32_16x16x32_bf16 v[120:123], v[154:157], v[178:181], v[120:123]
	v_mfma_f32_16x16x32_bf16 v[116:119], v[142:145], v[182:185], v[116:119]
	v_mfma_f32_16x16x32_bf16 v[116:119], v[146:149], v[186:189], v[116:119]
	v_mfma_f32_16x16x32_bf16 v[112:115], v[150:153], v[182:185], v[112:115]
	v_mfma_f32_16x16x32_bf16 v[112:115], v[154:157], v[186:189], v[112:115]
	v_mfma_f32_16x16x32_bf16 v[104:107], v[142:145], v[190:193], v[104:107]
	v_mfma_f32_16x16x32_bf16 v[104:107], v[146:149], v[194:197], v[104:107]
	v_mfma_f32_16x16x32_bf16 v[96:99], v[150:153], v[190:193], v[96:99]
	v_mfma_f32_16x16x32_bf16 v[96:99], v[154:157], v[194:197], v[96:99]
	v_mfma_f32_16x16x32_bf16 v[88:91], v[142:145], v[198:201], v[88:91]
	v_mfma_f32_16x16x32_bf16 v[88:91], v[146:149], v[202:205], v[88:91]
	v_mfma_f32_16x16x32_bf16 v[80:83], v[150:153], v[198:201], v[80:83]
	v_mfma_f32_16x16x32_bf16 v[80:83], v[154:157], v[202:205], v[80:83]
	v_mfma_f32_16x16x32_bf16 v[108:111], v[158:161], v[174:177], v[108:111]
	v_mfma_f32_16x16x32_bf16 v[108:111], v[162:165], v[178:181], v[108:111]
	v_mfma_f32_16x16x32_bf16 v[100:103], v[166:169], v[174:177], v[100:103]
	v_mfma_f32_16x16x32_bf16 v[100:103], v[170:173], v[178:181], v[100:103]
	v_mfma_f32_16x16x32_bf16 v[92:95], v[158:161], v[182:185], v[92:95]
	v_mfma_f32_16x16x32_bf16 v[92:95], v[162:165], v[186:189], v[92:95]
	v_mfma_f32_16x16x32_bf16 v[84:87], v[166:169], v[182:185], v[84:87]
	v_mfma_f32_16x16x32_bf16 v[84:87], v[170:173], v[186:189], v[84:87]
	v_mfma_f32_16x16x32_bf16 v[76:79], v[158:161], v[190:193], v[76:79]
	v_mfma_f32_16x16x32_bf16 v[76:79], v[162:165], v[194:197], v[76:79]
	v_mfma_f32_16x16x32_bf16 v[72:75], v[166:169], v[190:193], v[72:75]
	v_mfma_f32_16x16x32_bf16 v[72:75], v[170:173], v[194:197], v[72:75]
	v_mfma_f32_16x16x32_bf16 v[68:71], v[158:161], v[198:201], v[68:71]
	v_mfma_f32_16x16x32_bf16 v[68:71], v[162:165], v[202:205], v[68:71]
	v_mfma_f32_16x16x32_bf16 v[64:67], v[166:169], v[198:201], v[64:67]
	v_mfma_f32_16x16x32_bf16 v[64:67], v[170:173], v[202:205], v[64:67]
	s_barrier
	s_add_i32 s61, s54, s26
	v_lshl_add_u64 v[206:207], s[38:39], 0, v[128:129]
	s_mov_b32 m0, s61
	ds_read_b128 v[174:177], v140 offset:16384
	ds_read_b128 v[178:181], v140 offset:17408
	ds_read_b128 v[182:185], v140 offset:18432
	ds_read_b128 v[186:189], v140 offset:19456
	ds_read_b128 v[190:193], v140 offset:20480
	ds_read_b128 v[194:197], v140 offset:21504
	ds_read_b128 v[198:201], v140 offset:22528
	ds_read_b128 v[202:205], v140 offset:23552
	global_load_lds_dwordx4 v[206:207], off
	s_add_i32 m0, s61, 0x2000
	s_add_u32 s62, s38, 0x100000
	v_lshl_add_u64 v[208:209], s[38:39], 0, v[134:135]
	s_addc_u32 s63, s39, 0
	s_add_i32 s61, s55, s26
	global_load_lds_dwordx4 v[208:209], off
	v_lshl_add_u64 v[210:211], s[62:63], 0, v[128:129]
	s_mov_b32 m0, s61
	v_lshl_add_u64 v[212:213], s[40:41], 0, v[134:135]
	global_load_lds_dwordx4 v[210:211], off
	v_lshl_add_u64 v[210:211], s[62:63], 0, v[134:135]
	s_add_i32 m0, s61, 0x2000
	s_nop 0
	global_load_lds_dwordx4 v[210:211], off
	v_lshl_add_u64 v[210:211], s[40:41], 0, v[128:129]
	s_mov_b32 m0, s30
	s_nop 0
	global_load_lds_dwordx4 v[210:211], off
	s_mov_b32 m0, s31
	s_nop 0
	global_load_lds_dwordx4 v[212:213], off
	s_waitcnt vmcnt(8)
	s_waitcnt lgkmcnt(0)
	s_barrier
; #define PG8_STAGE(bufoff, gbase, voff) do { _Pragma("unroll") for (int _i = 0; _i < 2; ++_i) \
;         __builtin_amdgcn_global_load_lds((const unsigned*)((const char*)(gbase) + (voff)[_i]), (LAS unsigned*)(lds + (bufoff) + ldsw + _i * 8192), 16, 0, 0); } while (0)
; #define PG8_LDA(dst, b, h) do { _Pragma("unroll") for (int m = 0; m < 4; ++m) _Pragma("unroll") for (int k = 0; k < 2; ++k) dst[m][k] = *(const LAS bf16x8*)(lds + PG8_SA(b, h) + aoff + m * 2048 + k * 1024); } while (0)
; #define PG8_LDB(dst, b, h) do { _Pragma("unroll") for (int n = 0; n < 2; ++n) _Pragma("unroll") for (int k = 0; k < 2; ++k) dst[n][k] = *(const LAS bf16x8*)(lds + PG8_SB(b, h) + boff + n * 2048 + k * 1024); } while (0)
; #define PG8_MMA(ai, bj, At, Bt) do { __builtin_amdgcn_s_setprio(1); _Pragma("unroll") for (int m = 0; m < 4; ++m) _Pragma("unroll") for (int n = 0; n < 2; ++n) _Pragma("unroll") for (int k = 0; k < 2; ++k) \
;         acc[ai][bj][m][n] = __builtin_amdgcn_mfma_f32_16x16x32_bf16(Bt[n][k], At[m][k], acc[ai][bj][m][n], 0, 0, 0); __builtin_amdgcn_s_setprio(0); } while (0)
; #define PG8_WAIT_V(n) asm volatile("s_waitcnt vmcnt(" #n ")" ::: "memory")
; #define PG8_WAIT_L(n) asm volatile("s_waitcnt lgkmcnt(" #n ")" ::: "memory")
; #define PG8_BAR __builtin_amdgcn_s_barrier()
; #define PG8_SCHED __builtin_amdgcn_sched_barrier(0)
; template <class Epi>
; __device__ __forceinline__ void gemm_phase(LAS unsigned char* lds, const Gemm g, const Order& S, const Epi& E, const int wid) {
;     ...
;             PG8_WAIT_V(8); PG8_WAIT_L(0); PG8_BAR; PG8_MMA(1, 0, At, B0); PG8_MMA(1, 1, At, B1); PG8_BAR; PG8_SCHED;
;             PG8_LDB(B0, 1, 0); PG8_LDB(B1, 1, 1); PG8_SCHED; PG8_LDA(At, 1, 0); PG8_STAGE(PG8_SA(0, 1), a2 + hA, voffA);
;             PG8_WAIT_V(8); PG8_WAIT_L(0); PG8_BAR; PG8_MMA(0, 0, At, B0); PG8_MMA(0, 1, At, B1); PG8_BAR; PG8_SCHED;
	s_waitcnt lgkmcnt(0)
	v_mfma_f32_16x16x32_bf16 v[60:63], v[142:145], v[174:177], v[60:63]
	v_mfma_f32_16x16x32_bf16 v[60:63], v[146:149], v[178:181], v[60:63]
	v_mfma_f32_16x16x32_bf16 v[56:59], v[150:153], v[174:177], v[56:59]
	v_mfma_f32_16x16x32_bf16 v[56:59], v[154:157], v[178:181], v[56:59]
	v_mfma_f32_16x16x32_bf16 v[52:55], v[142:145], v[182:185], v[52:55]
	v_mfma_f32_16x16x32_bf16 v[52:55], v[146:149], v[186:189], v[52:55]
	v_mfma_f32_16x16x32_bf16 v[48:51], v[150:153], v[182:185], v[48:51]
	v_mfma_f32_16x16x32_bf16 v[48:51], v[154:157], v[186:189], v[48:51]
	v_mfma_f32_16x16x32_bf16 v[40:43], v[142:145], v[190:193], v[40:43]
	v_mfma_f32_16x16x32_bf16 v[40:43], v[146:149], v[194:197], v[40:43]
	v_mfma_f32_16x16x32_bf16 v[32:35], v[150:153], v[190:193], v[32:35]
	v_mfma_f32_16x16x32_bf16 v[32:35], v[154:157], v[194:197], v[32:35]
	v_mfma_f32_16x16x32_bf16 v[24:27], v[142:145], v[198:201], v[24:27]
	v_mfma_f32_16x16x32_bf16 v[24:27], v[146:149], v[202:205], v[24:27]
	v_mfma_f32_16x16x32_bf16 v[16:19], v[150:153], v[198:201], v[16:19]
	v_mfma_f32_16x16x32_bf16 v[16:19], v[154:157], v[202:205], v[16:19]
	v_mfma_f32_16x16x32_bf16 v[44:47], v[158:161], v[174:177], v[44:47]
	v_mfma_f32_16x16x32_bf16 v[44:47], v[162:165], v[178:181], v[44:47]
	v_mfma_f32_16x16x32_bf16 v[36:39], v[166:169], v[174:177], v[36:39]
	v_mfma_f32_16x16x32_bf16 v[36:39], v[170:173], v[178:181], v[36:39]
	v_mfma_f32_16x16x32_bf16 v[28:31], v[158:161], v[182:185], v[28:31]
	v_mfma_f32_16x16x32_bf16 v[28:31], v[162:165], v[186:189], v[28:31]
	v_mfma_f32_16x16x32_bf16 v[20:23], v[166:169], v[182:185], v[20:23]
	v_mfma_f32_16x16x32_bf16 v[20:23], v[170:173], v[186:189], v[20:23]
	v_mfma_f32_16x16x32_bf16 v[12:15], v[158:161], v[190:193], v[12:15]
	v_mfma_f32_16x16x32_bf16 v[12:15], v[162:165], v[194:197], v[12:15]
	v_mfma_f32_16x16x32_bf16 v[8:11], v[166:169], v[190:193], v[8:11]
	v_mfma_f32_16x16x32_bf16 v[8:11], v[170:173], v[194:197], v[8:11]
	v_mfma_f32_16x16x32_bf16 v[4:7], v[158:161], v[198:201], v[4:7]
	v_mfma_f32_16x16x32_bf16 v[4:7], v[162:165], v[202:205], v[4:7]
	v_mfma_f32_16x16x32_bf16 v[0:3], v[166:169], v[198:201], v[0:3]
	v_mfma_f32_16x16x32_bf16 v[0:3], v[170:173], v[202:205], v[0:3]
	s_barrier
	s_add_i32 s61, 0, 0x18000
	v_add_u32_e32 v141, s61, v137
	s_add_i32 s62, 0, 0x1c000
	ds_read_b128 v[142:145], v141
	ds_read_b128 v[146:149], v141 offset:1024
	ds_read_b128 v[150:153], v141 offset:2048
	ds_read_b128 v[154:157], v141 offset:3072
	v_add_u32_e32 v141, s62, v137
	ds_read_b128 v[158:161], v141
	ds_read_b128 v[162:165], v141 offset:1024
	ds_read_b128 v[166:169], v141 offset:2048
	ds_read_b128 v[170:173], v141 offset:3072
	s_add_u32 s40, s40, 0x100000
	s_addc_u32 s41, s41, 0
	s_mov_b32 m0, s33
	v_lshl_add_u64 v[214:215], s[40:41], 0, v[128:129]
	ds_read_b128 v[174:177], v140 offset:32768
	ds_read_b128 v[178:181], v140 offset:33792
	ds_read_b128 v[182:185], v140 offset:34816
	ds_read_b128 v[186:189], v140 offset:35840
	ds_read_b128 v[190:193], v140 offset:36864
	ds_read_b128 v[194:197], v140 offset:37888
	ds_read_b128 v[198:201], v140 offset:38912
	ds_read_b128 v[202:205], v140 offset:39936
	global_load_lds_dwordx4 v[214:215], off
	v_lshl_add_u64 v[214:215], s[40:41], 0, v[134:135]
	s_mov_b32 m0, s35
	s_nop 0
	global_load_lds_dwordx4 v[214:215], off
	s_waitcnt vmcnt(8)
	s_waitcnt lgkmcnt(0)
	s_barrier
	s_waitcnt lgkmcnt(0)
	v_mfma_f32_16x16x32_bf16 v[124:127], v[142:145], v[174:177], v[124:127]
	v_mfma_f32_16x16x32_bf16 v[124:127], v[146:149], v[178:181], v[124:127]
	v_mfma_f32_16x16x32_bf16 v[120:123], v[150:153], v[174:177], v[120:123]
	v_mfma_f32_16x16x32_bf16 v[120:123], v[154:157], v[178:181], v[120:123]
	v_mfma_f32_16x16x32_bf16 v[116:119], v[142:145], v[182:185], v[116:119]
	v_mfma_f32_16x16x32_bf16 v[116:119], v[146:149], v[186:189], v[116:119]
	v_mfma_f32_16x16x32_bf16 v[112:115], v[150:153], v[182:185], v[112:115]
	v_mfma_f32_16x16x32_bf16 v[112:115], v[154:157], v[186:189], v[112:115]
	v_mfma_f32_16x16x32_bf16 v[104:107], v[142:145], v[190:193], v[104:107]
	v_mfma_f32_16x16x32_bf16 v[104:107], v[146:149], v[194:197], v[104:107]
	v_mfma_f32_16x16x32_bf16 v[96:99], v[150:153], v[190:193], v[96:99]
	v_mfma_f32_16x16x32_bf16 v[96:99], v[154:157], v[194:197], v[96:99]
	v_mfma_f32_16x16x32_bf16 v[88:91], v[142:145], v[198:201], v[88:91]
	v_mfma_f32_16x16x32_bf16 v[88:91], v[146:149], v[202:205], v[88:91]
	v_mfma_f32_16x16x32_bf16 v[80:83], v[150:153], v[198:201], v[80:83]
	v_mfma_f32_16x16x32_bf16 v[80:83], v[154:157], v[202:205], v[80:83]
	v_mfma_f32_16x16x32_bf16 v[108:111], v[158:161], v[174:177], v[108:111]
	v_mfma_f32_16x16x32_bf16 v[108:111], v[162:165], v[178:181], v[108:111]
	v_mfma_f32_16x16x32_bf16 v[100:103], v[166:169], v[174:177], v[100:103]
	v_mfma_f32_16x16x32_bf16 v[100:103], v[170:173], v[178:181], v[100:103]
	v_mfma_f32_16x16x32_bf16 v[92:95], v[158:161], v[182:185], v[92:95]
	v_mfma_f32_16x16x32_bf16 v[92:95], v[162:165], v[186:189], v[92:95]
	v_mfma_f32_16x16x32_bf16 v[84:87], v[166:169], v[182:185], v[84:87]
	v_mfma_f32_16x16x32_bf16 v[84:87], v[170:173], v[186:189], v[84:87]
	v_mfma_f32_16x16x32_bf16 v[76:79], v[158:161], v[190:193], v[76:79]
	v_mfma_f32_16x16x32_bf16 v[76:79], v[162:165], v[194:197], v[76:79]
	v_mfma_f32_16x16x32_bf16 v[72:75], v[166:169], v[190:193], v[72:75]
	v_mfma_f32_16x16x32_bf16 v[72:75], v[170:173], v[194:197], v[72:75]
	v_mfma_f32_16x16x32_bf16 v[68:71], v[158:161], v[198:201], v[68:71]
	v_mfma_f32_16x16x32_bf16 v[68:71], v[162:165], v[202:205], v[68:71]
	v_mfma_f32_16x16x32_bf16 v[64:67], v[166:169], v[198:201], v[64:67]
	v_mfma_f32_16x16x32_bf16 v[64:67], v[170:173], v[202:205], v[64:67]
	s_barrier
; #define PG8_STAGE(bufoff, gbase, voff) do { _Pragma("unroll") for (int _i = 0; _i < 2; ++_i) \
;         __builtin_amdgcn_global_load_lds((const unsigned*)((const char*)(gbase) + (voff)[_i]), (LAS unsigned*)(lds + (bufoff) + ldsw + _i * 8192), 16, 0, 0); } while (0)
; #define PG8_LDA(dst, b, h) do { _Pragma("unroll") for (int m = 0; m < 4; ++m) _Pragma("unroll") for (int k = 0; k < 2; ++k) dst[m][k] = *(const LAS bf16x8*)(lds + PG8_SA(b, h) + aoff + m * 2048 + k * 1024); } while (0)
; #define PG8_MMA(ai, bj, At, Bt) do { __builtin_amdgcn_s_setprio(1); _Pragma("unroll") for (int m = 0; m < 4; ++m) _Pragma("unroll") for (int n = 0; n < 2; ++n) _Pragma("unroll") for (int k = 0; k < 2; ++k) \
;         acc[ai][bj][m][n] = __builtin_amdgcn_mfma_f32_16x16x32_bf16(Bt[n][k], At[m][k], acc[ai][bj][m][n], 0, 0, 0); __builtin_amdgcn_s_setprio(0); } while (0)
; #define PG8_WAIT_V(n) asm volatile("s_waitcnt vmcnt(" #n ")" ::: "memory")
; #define PG8_WAIT_L(n) asm volatile("s_waitcnt lgkmcnt(" #n ")" ::: "memory")
; #define PG8_BAR __builtin_amdgcn_s_barrier()
; #define PG8_SCHED __builtin_amdgcn_sched_barrier(0)
; template <class Epi>
; __device__ __forceinline__ void gemm_phase(LAS unsigned char* lds, const Gemm g, const Order& S, const Epi& E, const int wid) {
;     ...
;         for (int t = 0; t < nt; t += 2) {
;     ...
;             PG8_LDA(At, 1, 1); PG8_STAGE(PG8_SB(1, 0), b3, voffB); PG8_STAGE(PG8_SB(1, 1), b3 + hB, voffB); PG8_STAGE(PG8_SA(1, 0), a3, voffA);
;             PG8_WAIT_V(8); PG8_WAIT_L(0); PG8_BAR; PG8_MMA(1, 0, At, B0); PG8_MMA(1, 1, At, B1); PG8_BAR; PG8_SCHED;
	s_add_i32 s40, s61, s26
	v_lshl_add_u64 v[206:207], v[206:207], 0, s[12:13]
	s_mov_b32 m0, s40
	ds_read_b128 v[174:177], v140 offset:49152
	ds_read_b128 v[178:181], v140 offset:50176
	ds_read_b128 v[182:185], v140 offset:51200
	ds_read_b128 v[186:189], v140 offset:52224
	ds_read_b128 v[190:193], v140 offset:53248
	ds_read_b128 v[194:197], v140 offset:54272
	ds_read_b128 v[198:201], v140 offset:55296
	ds_read_b128 v[202:205], v140 offset:56320
	global_load_lds_dwordx4 v[206:207], off
	s_add_i32 m0, s40, 0x2000
	s_add_u32 s38, s38, 0x100080
	v_lshl_add_u64 v[206:207], v[208:209], 0, s[12:13]
	s_addc_u32 s39, s39, 0
	s_add_i32 s40, s62, s26
	global_load_lds_dwordx4 v[206:207], off
	v_lshl_add_u64 v[206:207], s[38:39], 0, v[128:129]
	s_mov_b32 m0, s40
	s_nop 0
	global_load_lds_dwordx4 v[206:207], off
	v_lshl_add_u64 v[206:207], s[38:39], 0, v[134:135]
	s_add_i32 m0, s40, 0x2000
	s_nop 0
	global_load_lds_dwordx4 v[206:207], off
	v_lshl_add_u64 v[206:207], v[210:211], 0, s[12:13]
	s_mov_b32 m0, s50
	s_nop 0
	global_load_lds_dwordx4 v[206:207], off
	v_lshl_add_u64 v[206:207], v[212:213], 0, s[12:13]
	s_mov_b32 m0, s51
	s_nop 0
	global_load_lds_dwordx4 v[206:207], off
	s_waitcnt vmcnt(8)
	s_waitcnt lgkmcnt(0)
	s_barrier
	s_waitcnt lgkmcnt(0)
	v_mfma_f32_16x16x32_bf16 v[60:63], v[142:145], v[174:177], v[60:63]
	v_mfma_f32_16x16x32_bf16 v[60:63], v[146:149], v[178:181], v[60:63]
	v_mfma_f32_16x16x32_bf16 v[56:59], v[150:153], v[174:177], v[56:59]
	v_mfma_f32_16x16x32_bf16 v[56:59], v[154:157], v[178:181], v[56:59]
	v_mfma_f32_16x16x32_bf16 v[52:55], v[142:145], v[182:185], v[52:55]
	v_mfma_f32_16x16x32_bf16 v[52:55], v[146:149], v[186:189], v[52:55]
	v_mfma_f32_16x16x32_bf16 v[48:51], v[150:153], v[182:185], v[48:51]
	v_mfma_f32_16x16x32_bf16 v[48:51], v[154:157], v[186:189], v[48:51]
	v_mfma_f32_16x16x32_bf16 v[40:43], v[142:145], v[190:193], v[40:43]
	v_mfma_f32_16x16x32_bf16 v[40:43], v[146:149], v[194:197], v[40:43]
	v_mfma_f32_16x16x32_bf16 v[32:35], v[150:153], v[190:193], v[32:35]
	v_mfma_f32_16x16x32_bf16 v[32:35], v[154:157], v[194:197], v[32:35]
	v_mfma_f32_16x16x32_bf16 v[24:27], v[142:145], v[198:201], v[24:27]
	v_mfma_f32_16x16x32_bf16 v[24:27], v[146:149], v[202:205], v[24:27]
	v_mfma_f32_16x16x32_bf16 v[16:19], v[150:153], v[198:201], v[16:19]
	v_mfma_f32_16x16x32_bf16 v[16:19], v[154:157], v[202:205], v[16:19]
	v_mfma_f32_16x16x32_bf16 v[44:47], v[158:161], v[174:177], v[44:47]
	v_mfma_f32_16x16x32_bf16 v[44:47], v[162:165], v[178:181], v[44:47]
	v_mfma_f32_16x16x32_bf16 v[36:39], v[166:169], v[174:177], v[36:39]
	v_mfma_f32_16x16x32_bf16 v[36:39], v[170:173], v[178:181], v[36:39]
	v_mfma_f32_16x16x32_bf16 v[28:31], v[158:161], v[182:185], v[28:31]
	v_mfma_f32_16x16x32_bf16 v[28:31], v[162:165], v[186:189], v[28:31]
	v_mfma_f32_16x16x32_bf16 v[20:23], v[166:169], v[182:185], v[20:23]
	v_mfma_f32_16x16x32_bf16 v[20:23], v[170:173], v[186:189], v[20:23]
	v_mfma_f32_16x16x32_bf16 v[12:15], v[158:161], v[190:193], v[12:15]
	v_mfma_f32_16x16x32_bf16 v[12:15], v[162:165], v[194:197], v[12:15]
	v_mfma_f32_16x16x32_bf16 v[8:11], v[166:169], v[190:193], v[8:11]
	v_mfma_f32_16x16x32_bf16 v[8:11], v[170:173], v[194:197], v[8:11]
	v_mfma_f32_16x16x32_bf16 v[4:7], v[158:161], v[198:201], v[4:7]
	v_mfma_f32_16x16x32_bf16 v[4:7], v[162:165], v[202:205], v[4:7]
	v_mfma_f32_16x16x32_bf16 v[0:3], v[166:169], v[198:201], v[0:3]
	v_mfma_f32_16x16x32_bf16 v[0:3], v[170:173], v[202:205], v[0:3]
	s_add_i32 s60, s60, 2
	s_add_u32 s36, s36, 0x100
	s_addc_u32 s37, s37, 0
	s_add_u32 s21, s21, 0x100
	s_addc_u32 s23, s23, 0
	s_cmp_gt_u32 s60, 29
	s_barrier
	s_cbranch_scc0 .LBB0_1145
	s_and_b64 vcc, exec, s[10:11]
	s_cbranch_vccz .LBB0_1148
	s_barrier

; #define PG8_STAGE(bufoff, gbase, voff) do { _Pragma("unroll") for (int _i = 0; _i < 2; ++_i) \
;         __builtin_amdgcn_global_load_lds((const unsigned*)((const char*)(gbase) + (voff)[_i]), (LAS unsigned*)(lds + (bufoff) + ldsw + _i * 8192), 16, 0, 0); } while (0)
; #define PG8_LDA(dst, b, h) do { _Pragma("unroll") for (int m = 0; m < 4; ++m) _Pragma("unroll") for (int k = 0; k < 2; ++k) dst[m][k] = *(const LAS bf16x8*)(lds + PG8_SA(b, h) + aoff + m * 2048 + k * 1024); } while (0)
; #define PG8_LDB(dst, b, h) do { _Pragma("unroll") for (int n = 0; n < 2; ++n) _Pragma("unroll") for (int k = 0; k < 2; ++k) dst[n][k] = *(const LAS bf16x8*)(lds + PG8_SB(b, h) + boff + n * 2048 + k * 1024); } while (0)
; #define PG8_MMA(ai, bj, At, Bt) do { __builtin_amdgcn_s_setprio(1); _Pragma("unroll") for (int m = 0; m < 4; ++m) _Pragma("unroll") for (int n = 0; n < 2; ++n) _Pragma("unroll") for (int k = 0; k < 2; ++k) \
;         acc[ai][bj][m][n] = __builtin_amdgcn_mfma_f32_16x16x32_bf16(Bt[n][k], At[m][k], acc[ai][bj][m][n], 0, 0, 0); __builtin_amdgcn_s_setprio(0); } while (0)
; #define PG8_WAIT_V(n) asm volatile("s_waitcnt vmcnt(" #n ")" ::: "memory")
; #define PG8_WAIT_L(n) asm volatile("s_waitcnt lgkmcnt(" #n ")" ::: "memory")
; #define PG8_BAR __builtin_amdgcn_s_barrier()
; #define PG8_SCHED __builtin_amdgcn_sched_barrier(0)
; template <class Epi>
; __device__ __forceinline__ void gemm_phase(LAS unsigned char* lds, const Gemm g, const Order& S, const Epi& E, const int wid) {
;     ...
;         for (int t = 0; t < nt; t += 2) {
;             const bool last = (t == nt - 2);
;             const char* a1 = cA + (size_t)(t + 1) * kstep;
;             const char* a2 = last ? nA : cA + (size_t)(t + 2) * kstep; const char* b2 = last ? nB : cB + (size_t)(t + 2) * kstep;
;             const char* a3 = a2 + kstep; const char* b3 = b2 + kstep;
;     ...
;             PG8_LDB(B0, 0, 0); PG8_LDB(B1, 0, 1); PG8_SCHED; PG8_LDA(At, 0, 0); PG8_STAGE(PG8_SA(1, 1), a1 + hA, voffA);
;             PG8_WAIT_V(8); PG8_WAIT_L(0); PG8_BAR; PG8_MMA(0, 0, At, B0); PG8_MMA(0, 1, At, B1); PG8_BAR; PG8_SCHED;
;             PG8_LDA(At, 0, 1); PG8_STAGE(PG8_SB(0, 0), b2, voffB); PG8_STAGE(PG8_SB(0, 1), b2 + hB, voffB); PG8_STAGE(PG8_SA(0, 0), a2, voffA);
.LBB0_1289:
	ds_read_b128 v[74:77], v71
	ds_read_b128 v[78:81], v71 offset:1024
	ds_read_b128 v[82:85], v71 offset:2048
	ds_read_b128 v[86:89], v71 offset:3072
	ds_read_b128 v[90:93], v72
	ds_read_b128 v[160:163], v72 offset:1024
	ds_read_b128 v[164:167], v72 offset:2048
	ds_read_b128 v[174:177], v72 offset:3072
	s_add_u32 s43, s4, 0xfffc0080
	s_addc_u32 s56, s5, -1
	s_cmp_eq_u32 s41, 12
	s_cselect_b32 s59, s69, s56
	s_cselect_b32 s58, s68, s43
	s_cselect_b32 s57, s71, s39
	s_cselect_b32 s56, s70, s7
	v_lshl_add_u64 v[94:95], s[4:5], 0, v[168:169]
	s_add_i32 m0, s27, 0xc000
	ds_read_b128 v[178:181], v73
	ds_read_b128 v[182:185], v73 offset:1024
	ds_read_b128 v[186:189], v73 offset:2048
	ds_read_b128 v[192:195], v73 offset:3072
	ds_read_b128 v[196:199], v73 offset:4096
	ds_read_b128 v[200:203], v73 offset:5120
	ds_read_b128 v[204:207], v73 offset:6144
	ds_read_b128 v[208:211], v73 offset:7168
	global_load_lds_dwordx4 v[94:95], off
	v_lshl_add_u64 v[94:95], s[4:5], 0, v[68:69]
	s_add_i32 m0, s27, 0xe000
	s_nop 0
	global_load_lds_dwordx4 v[94:95], off
	s_waitcnt vmcnt(8)
	s_waitcnt lgkmcnt(0)
	s_barrier
	s_waitcnt lgkmcnt(0)
	v_mfma_f32_16x16x32_bf16 v[156:159], v[74:77], v[178:181], v[156:159]
	v_mfma_f32_16x16x32_bf16 v[156:159], v[78:81], v[182:185], v[156:159]
	v_mfma_f32_16x16x32_bf16 v[152:155], v[82:85], v[178:181], v[152:155]
	v_mfma_f32_16x16x32_bf16 v[152:155], v[86:89], v[182:185], v[152:155]
	v_mfma_f32_16x16x32_bf16 v[140:143], v[74:77], v[186:189], v[140:143]
	v_mfma_f32_16x16x32_bf16 v[140:143], v[78:81], v[192:195], v[140:143]
	v_mfma_f32_16x16x32_bf16 v[136:139], v[82:85], v[186:189], v[136:139]
	v_mfma_f32_16x16x32_bf16 v[136:139], v[86:89], v[192:195], v[136:139]
	v_mfma_f32_16x16x32_bf16 v[124:127], v[74:77], v[196:199], v[124:127]
	v_mfma_f32_16x16x32_bf16 v[124:127], v[78:81], v[200:203], v[124:127]
	v_mfma_f32_16x16x32_bf16 v[120:123], v[82:85], v[196:199], v[120:123]
	v_mfma_f32_16x16x32_bf16 v[120:123], v[86:89], v[200:203], v[120:123]
	v_mfma_f32_16x16x32_bf16 v[108:111], v[74:77], v[204:207], v[108:111]
	v_mfma_f32_16x16x32_bf16 v[108:111], v[78:81], v[208:211], v[108:111]
	v_mfma_f32_16x16x32_bf16 v[104:107], v[82:85], v[204:207], v[104:107]
	v_mfma_f32_16x16x32_bf16 v[104:107], v[86:89], v[208:211], v[104:107]
	v_mfma_f32_16x16x32_bf16 v[148:151], v[90:93], v[178:181], v[148:151]
	v_mfma_f32_16x16x32_bf16 v[144:147], v[164:167], v[178:181], v[144:147]
	v_mfma_f32_16x16x32_bf16 v[132:135], v[90:93], v[186:189], v[132:135]
	v_mfma_f32_16x16x32_bf16 v[128:131], v[164:167], v[186:189], v[128:131]
	v_mfma_f32_16x16x32_bf16 v[116:119], v[90:93], v[196:199], v[116:119]
	v_mfma_f32_16x16x32_bf16 v[112:115], v[164:167], v[196:199], v[112:115]
	v_mfma_f32_16x16x32_bf16 v[100:103], v[90:93], v[204:207], v[100:103]
	v_mfma_f32_16x16x32_bf16 v[94:97], v[164:167], v[204:207], v[96:99]
	v_mfma_f32_16x16x32_bf16 v[148:151], v[160:163], v[182:185], v[148:151]
	v_mfma_f32_16x16x32_bf16 v[144:147], v[174:177], v[182:185], v[144:147]
	v_mfma_f32_16x16x32_bf16 v[132:135], v[160:163], v[192:195], v[132:135]
	v_mfma_f32_16x16x32_bf16 v[128:131], v[174:177], v[192:195], v[128:131]
	v_mfma_f32_16x16x32_bf16 v[116:119], v[160:163], v[200:203], v[116:119]
	v_mfma_f32_16x16x32_bf16 v[112:115], v[174:177], v[200:203], v[112:115]
	v_mfma_f32_16x16x32_bf16 v[100:103], v[160:163], v[208:211], v[100:103]
	v_mfma_f32_16x16x32_bf16 v[94:97], v[174:177], v[208:211], v[94:97]
	s_barrier
	s_add_i32 s43, s62, s26
	v_lshl_add_u64 v[212:213], s[56:57], 0, v[64:65]
	s_mov_b32 m0, s43
	ds_read_b128 v[178:181], v73 offset:16384
	ds_read_b128 v[182:185], v73 offset:17408
	ds_read_b128 v[186:189], v73 offset:18432
	ds_read_b128 v[192:195], v73 offset:19456
	ds_read_b128 v[196:199], v73 offset:20480
	ds_read_b128 v[200:203], v73 offset:21504
	ds_read_b128 v[204:207], v73 offset:22528
	ds_read_b128 v[208:211], v73 offset:23552
	global_load_lds_dwordx4 v[212:213], off
	s_add_i32 m0, s43, 0x2000
	s_add_u32 s66, s56, 0x40000
	v_lshl_add_u64 v[214:215], s[56:57], 0, v[66:67]
	s_addc_u32 s67, s57, 0
	s_add_i32 s43, s63, s26
	global_load_lds_dwordx4 v[214:215], off
	v_lshl_add_u64 v[98:99], s[66:67], 0, v[64:65]
	s_mov_b32 m0, s43
	v_lshl_add_u64 v[216:217], s[58:59], 0, v[168:169]
	global_load_lds_dwordx4 v[98:99], off
	v_lshl_add_u64 v[98:99], s[66:67], 0, v[66:67]
	s_add_i32 m0, s43, 0x2000
	v_lshl_add_u64 v[218:219], s[58:59], 0, v[68:69]
	global_load_lds_dwordx4 v[98:99], off
	s_mov_b32 m0, s27
	s_nop 0
	global_load_lds_dwordx4 v[216:217], off
	s_mov_b32 m0, s29
	s_nop 0
	global_load_lds_dwordx4 v[218:219], off
	s_waitcnt vmcnt(8)
	s_waitcnt lgkmcnt(0)
	s_barrier
; #define PG8_STAGE(bufoff, gbase, voff) do { _Pragma("unroll") for (int _i = 0; _i < 2; ++_i) \
;         __builtin_amdgcn_global_load_lds((const unsigned*)((const char*)(gbase) + (voff)[_i]), (LAS unsigned*)(lds + (bufoff) + ldsw + _i * 8192), 16, 0, 0); } while (0)
; #define PG8_LDA(dst, b, h) do { _Pragma("unroll") for (int m = 0; m < 4; ++m) _Pragma("unroll") for (int k = 0; k < 2; ++k) dst[m][k] = *(const LAS bf16x8*)(lds + PG8_SA(b, h) + aoff + m * 2048 + k * 1024); } while (0)
; #define PG8_LDB(dst, b, h) do { _Pragma("unroll") for (int n = 0; n < 2; ++n) _Pragma("unroll") for (int k = 0; k < 2; ++k) dst[n][k] = *(const LAS bf16x8*)(lds + PG8_SB(b, h) + boff + n * 2048 + k * 1024); } while (0)
; #define PG8_MMA(ai, bj, At, Bt) do { __builtin_amdgcn_s_setprio(1); _Pragma("unroll") for (int m = 0; m < 4; ++m) _Pragma("unroll") for (int n = 0; n < 2; ++n) _Pragma("unroll") for (int k = 0; k < 2; ++k) \
;         acc[ai][bj][m][n] = __builtin_amdgcn_mfma_f32_16x16x32_bf16(Bt[n][k], At[m][k], acc[ai][bj][m][n], 0, 0, 0); __builtin_amdgcn_s_setprio(0); } while (0)
; #define PG8_WAIT_V(n) asm volatile("s_waitcnt vmcnt(" #n ")" ::: "memory")
; #define PG8_WAIT_L(n) asm volatile("s_waitcnt lgkmcnt(" #n ")" ::: "memory")
; #define PG8_BAR __builtin_amdgcn_s_barrier()
; #define PG8_SCHED __builtin_amdgcn_sched_barrier(0)
; template <class Epi>
; __device__ __forceinline__ void gemm_phase(LAS unsigned char* lds, const Gemm g, const Order& S, const Epi& E, const int wid) {
;     ...
;             PG8_WAIT_V(8); PG8_WAIT_L(0); PG8_BAR; PG8_MMA(1, 0, At, B0); PG8_MMA(1, 1, At, B1); PG8_BAR; PG8_SCHED;
;             PG8_LDB(B0, 1, 0); PG8_LDB(B1, 1, 1); PG8_SCHED; PG8_LDA(At, 1, 0); PG8_STAGE(PG8_SA(0, 1), a2 + hA, voffA);
;             PG8_WAIT_V(8); PG8_WAIT_L(0); PG8_BAR; PG8_MMA(0, 0, At, B0); PG8_MMA(0, 1, At, B1); PG8_BAR; PG8_SCHED;
	s_waitcnt lgkmcnt(0)
	v_mfma_f32_16x16x32_bf16 v[60:63], v[74:77], v[178:181], v[60:63]
	v_mfma_f32_16x16x32_bf16 v[60:63], v[78:81], v[182:185], v[60:63]
	v_mfma_f32_16x16x32_bf16 v[56:59], v[82:85], v[178:181], v[56:59]
	v_mfma_f32_16x16x32_bf16 v[56:59], v[86:89], v[182:185], v[56:59]
	v_mfma_f32_16x16x32_bf16 v[44:47], v[74:77], v[186:189], v[44:47]
	v_mfma_f32_16x16x32_bf16 v[44:47], v[78:81], v[192:195], v[44:47]
	v_mfma_f32_16x16x32_bf16 v[40:43], v[82:85], v[186:189], v[40:43]
	v_mfma_f32_16x16x32_bf16 v[40:43], v[86:89], v[192:195], v[40:43]
	v_mfma_f32_16x16x32_bf16 v[28:31], v[74:77], v[196:199], v[28:31]
	v_mfma_f32_16x16x32_bf16 v[28:31], v[78:81], v[200:203], v[28:31]
	v_mfma_f32_16x16x32_bf16 v[24:27], v[82:85], v[196:199], v[24:27]
	v_mfma_f32_16x16x32_bf16 v[24:27], v[86:89], v[200:203], v[24:27]
	v_mfma_f32_16x16x32_bf16 v[12:15], v[74:77], v[204:207], v[12:15]
	v_mfma_f32_16x16x32_bf16 v[12:15], v[78:81], v[208:211], v[12:15]
	v_mfma_f32_16x16x32_bf16 v[8:11], v[82:85], v[204:207], v[8:11]
	v_mfma_f32_16x16x32_bf16 v[8:11], v[86:89], v[208:211], v[8:11]
	v_mfma_f32_16x16x32_bf16 v[52:55], v[90:93], v[178:181], v[52:55]
	v_mfma_f32_16x16x32_bf16 v[52:55], v[160:163], v[182:185], v[52:55]
	v_mfma_f32_16x16x32_bf16 v[48:51], v[164:167], v[178:181], v[48:51]
	v_mfma_f32_16x16x32_bf16 v[48:51], v[174:177], v[182:185], v[48:51]
	v_mfma_f32_16x16x32_bf16 v[36:39], v[90:93], v[186:189], v[36:39]
	v_mfma_f32_16x16x32_bf16 v[36:39], v[160:163], v[192:195], v[36:39]
	v_mfma_f32_16x16x32_bf16 v[32:35], v[164:167], v[186:189], v[32:35]
	v_mfma_f32_16x16x32_bf16 v[32:35], v[174:177], v[192:195], v[32:35]
	v_mfma_f32_16x16x32_bf16 v[20:23], v[90:93], v[196:199], v[20:23]
	v_mfma_f32_16x16x32_bf16 v[20:23], v[160:163], v[200:203], v[20:23]
	v_mfma_f32_16x16x32_bf16 v[16:19], v[164:167], v[196:199], v[16:19]
	v_mfma_f32_16x16x32_bf16 v[16:19], v[174:177], v[200:203], v[16:19]
	v_mfma_f32_16x16x32_bf16 v[4:7], v[90:93], v[204:207], v[4:7]
	v_mfma_f32_16x16x32_bf16 v[4:7], v[160:163], v[208:211], v[4:7]
	v_mfma_f32_16x16x32_bf16 v[0:3], v[164:167], v[204:207], v[0:3]
	v_mfma_f32_16x16x32_bf16 v[0:3], v[174:177], v[208:211], v[0:3]
	s_barrier
	s_add_i32 s43, 0, 0x18000
	s_add_i32 s65, 0, 0x1c000
	v_add_u32_e32 v86, s43, v70
	v_add_u32_e32 v98, s65, v70
	ds_read_b128 v[74:77], v86
	ds_read_b128 v[78:81], v86 offset:1024
	ds_read_b128 v[82:85], v86 offset:2048
	ds_read_b128 v[86:89], v86 offset:3072
	ds_read_b128 v[90:93], v98
	ds_read_b128 v[160:163], v98 offset:1024
	ds_read_b128 v[164:167], v98 offset:2048
	ds_read_b128 v[174:177], v98 offset:3072
	s_add_u32 s58, s58, 0x40000
	s_addc_u32 s59, s59, 0
	s_mov_b32 m0, s30
	v_lshl_add_u64 v[98:99], s[58:59], 0, v[168:169]
	ds_read_b128 v[178:181], v73 offset:32768
	ds_read_b128 v[182:185], v73 offset:33792
	ds_read_b128 v[186:189], v73 offset:34816
	ds_read_b128 v[192:195], v73 offset:35840
	ds_read_b128 v[196:199], v73 offset:36864
	ds_read_b128 v[200:203], v73 offset:37888
	ds_read_b128 v[204:207], v73 offset:38912
	ds_read_b128 v[208:211], v73 offset:39936
	global_load_lds_dwordx4 v[98:99], off
	v_lshl_add_u64 v[98:99], s[58:59], 0, v[68:69]
	s_mov_b32 m0, s31
	s_nop 0
	global_load_lds_dwordx4 v[98:99], off
	s_waitcnt vmcnt(8)
	s_waitcnt lgkmcnt(0)
	s_barrier
	s_waitcnt lgkmcnt(0)
	v_mfma_f32_16x16x32_bf16 v[156:159], v[74:77], v[178:181], v[156:159]
	v_mfma_f32_16x16x32_bf16 v[156:159], v[78:81], v[182:185], v[156:159]
	v_mfma_f32_16x16x32_bf16 v[152:155], v[82:85], v[178:181], v[152:155]
	v_mfma_f32_16x16x32_bf16 v[152:155], v[86:89], v[182:185], v[152:155]
	v_mfma_f32_16x16x32_bf16 v[140:143], v[74:77], v[186:189], v[140:143]
	v_mfma_f32_16x16x32_bf16 v[140:143], v[78:81], v[192:195], v[140:143]
	v_mfma_f32_16x16x32_bf16 v[136:139], v[82:85], v[186:189], v[136:139]
	v_mfma_f32_16x16x32_bf16 v[136:139], v[86:89], v[192:195], v[136:139]
	v_mfma_f32_16x16x32_bf16 v[124:127], v[74:77], v[196:199], v[124:127]
	v_mfma_f32_16x16x32_bf16 v[124:127], v[78:81], v[200:203], v[124:127]
	v_mfma_f32_16x16x32_bf16 v[120:123], v[82:85], v[196:199], v[120:123]
	v_mfma_f32_16x16x32_bf16 v[120:123], v[86:89], v[200:203], v[120:123]
	v_mfma_f32_16x16x32_bf16 v[108:111], v[74:77], v[204:207], v[108:111]
	v_mfma_f32_16x16x32_bf16 v[108:111], v[78:81], v[208:211], v[108:111]
	v_mfma_f32_16x16x32_bf16 v[104:107], v[82:85], v[204:207], v[104:107]
	v_mfma_f32_16x16x32_bf16 v[104:107], v[86:89], v[208:211], v[104:107]
	v_mfma_f32_16x16x32_bf16 v[148:151], v[90:93], v[178:181], v[148:151]
	v_mfma_f32_16x16x32_bf16 v[144:147], v[164:167], v[178:181], v[144:147]
	v_mfma_f32_16x16x32_bf16 v[132:135], v[90:93], v[186:189], v[132:135]
	v_mfma_f32_16x16x32_bf16 v[128:131], v[164:167], v[186:189], v[128:131]
	v_mfma_f32_16x16x32_bf16 v[116:119], v[90:93], v[196:199], v[116:119]
	v_mfma_f32_16x16x32_bf16 v[112:115], v[164:167], v[196:199], v[112:115]
	v_mfma_f32_16x16x32_bf16 v[98:101], v[90:93], v[204:207], v[100:103]
	v_mfma_f32_16x16x32_bf16 v[94:97], v[164:167], v[204:207], v[94:97]
	v_mfma_f32_16x16x32_bf16 v[148:151], v[160:163], v[182:185], v[148:151]
	v_mfma_f32_16x16x32_bf16 v[144:147], v[174:177], v[182:185], v[144:147]
	v_mfma_f32_16x16x32_bf16 v[132:135], v[160:163], v[192:195], v[132:135]
	v_mfma_f32_16x16x32_bf16 v[128:131], v[174:177], v[192:195], v[128:131]
	v_mfma_f32_16x16x32_bf16 v[116:119], v[160:163], v[200:203], v[116:119]
	v_mfma_f32_16x16x32_bf16 v[112:115], v[174:177], v[200:203], v[112:115]
	v_mfma_f32_16x16x32_bf16 v[100:103], v[160:163], v[208:211], v[98:101]
	v_mfma_f32_16x16x32_bf16 v[96:99], v[174:177], v[208:211], v[94:97]
	s_barrier
; #define PG8_STAGE(bufoff, gbase, voff) do { _Pragma("unroll") for (int _i = 0; _i < 2; ++_i) \
;         __builtin_amdgcn_global_load_lds((const unsigned*)((const char*)(gbase) + (voff)[_i]), (LAS unsigned*)(lds + (bufoff) + ldsw + _i * 8192), 16, 0, 0); } while (0)
; #define PG8_LDA(dst, b, h) do { _Pragma("unroll") for (int m = 0; m < 4; ++m) _Pragma("unroll") for (int k = 0; k < 2; ++k) dst[m][k] = *(const LAS bf16x8*)(lds + PG8_SA(b, h) + aoff + m * 2048 + k * 1024); } while (0)
; #define PG8_MMA(ai, bj, At, Bt) do { __builtin_amdgcn_s_setprio(1); _Pragma("unroll") for (int m = 0; m < 4; ++m) _Pragma("unroll") for (int n = 0; n < 2; ++n) _Pragma("unroll") for (int k = 0; k < 2; ++k) \
;         acc[ai][bj][m][n] = __builtin_amdgcn_mfma_f32_16x16x32_bf16(Bt[n][k], At[m][k], acc[ai][bj][m][n], 0, 0, 0); __builtin_amdgcn_s_setprio(0); } while (0)
; #define PG8_WAIT_V(n) asm volatile("s_waitcnt vmcnt(" #n ")" ::: "memory")
; #define PG8_WAIT_L(n) asm volatile("s_waitcnt lgkmcnt(" #n ")" ::: "memory")
; #define PG8_BAR __builtin_amdgcn_s_barrier()
; #define PG8_SCHED __builtin_amdgcn_sched_barrier(0)
; template <class Epi>
; __device__ __forceinline__ void gemm_phase(LAS unsigned char* lds, const Gemm g, const Order& S, const Epi& E, const int wid) {
;     ...
;             PG8_LDA(At, 1, 1); PG8_STAGE(PG8_SB(1, 0), b3, voffB); PG8_STAGE(PG8_SB(1, 1), b3 + hB, voffB); PG8_STAGE(PG8_SA(1, 0), a3, voffA);
;             PG8_WAIT_V(8); PG8_WAIT_L(0); PG8_BAR; PG8_MMA(1, 0, At, B0); PG8_MMA(1, 1, At, B1); PG8_BAR; PG8_SCHED;
;     ...
;         }
;         if (wr == 0) PG8_BAR;
	s_add_i32 s43, s43, s26
	v_lshl_add_u64 v[94:95], v[212:213], 0, s[22:23]
	s_mov_b32 m0, s43
	ds_read_b128 v[178:181], v73 offset:49152
	ds_read_b128 v[182:185], v73 offset:50176
	ds_read_b128 v[186:189], v73 offset:51200
	ds_read_b128 v[192:195], v73 offset:52224
	ds_read_b128 v[196:199], v73 offset:53248
	ds_read_b128 v[200:203], v73 offset:54272
	ds_read_b128 v[204:207], v73 offset:55296
	ds_read_b128 v[208:211], v73 offset:56320
	global_load_lds_dwordx4 v[94:95], off
	s_add_i32 m0, s43, 0x2000
	s_add_u32 s56, s56, 0x40080
	v_lshl_add_u64 v[94:95], v[214:215], 0, s[22:23]
	s_addc_u32 s57, s57, 0
	s_add_i32 s43, s65, s26
	global_load_lds_dwordx4 v[94:95], off
	v_lshl_add_u64 v[94:95], s[56:57], 0, v[64:65]
	s_mov_b32 m0, s43
	s_nop 0
	global_load_lds_dwordx4 v[94:95], off
	v_lshl_add_u64 v[94:95], s[56:57], 0, v[66:67]
	s_add_i32 m0, s43, 0x2000
	s_nop 0
	global_load_lds_dwordx4 v[94:95], off
	v_lshl_add_u64 v[94:95], v[216:217], 0, s[22:23]
	s_mov_b32 m0, s73
	s_nop 0
	global_load_lds_dwordx4 v[94:95], off
	v_lshl_add_u64 v[94:95], v[218:219], 0, s[22:23]
	s_mov_b32 m0, s60
	s_nop 0
	global_load_lds_dwordx4 v[94:95], off
	s_waitcnt vmcnt(8)
	s_waitcnt lgkmcnt(0)
	s_barrier
	s_waitcnt lgkmcnt(0)
	v_mfma_f32_16x16x32_bf16 v[60:63], v[74:77], v[178:181], v[60:63]
	v_mfma_f32_16x16x32_bf16 v[60:63], v[78:81], v[182:185], v[60:63]
	v_mfma_f32_16x16x32_bf16 v[56:59], v[82:85], v[178:181], v[56:59]
	v_mfma_f32_16x16x32_bf16 v[56:59], v[86:89], v[182:185], v[56:59]
	v_mfma_f32_16x16x32_bf16 v[44:47], v[74:77], v[186:189], v[44:47]
	v_mfma_f32_16x16x32_bf16 v[44:47], v[78:81], v[192:195], v[44:47]
	v_mfma_f32_16x16x32_bf16 v[40:43], v[82:85], v[186:189], v[40:43]
	v_mfma_f32_16x16x32_bf16 v[40:43], v[86:89], v[192:195], v[40:43]
	v_mfma_f32_16x16x32_bf16 v[28:31], v[74:77], v[196:199], v[28:31]
	v_mfma_f32_16x16x32_bf16 v[28:31], v[78:81], v[200:203], v[28:31]
	v_mfma_f32_16x16x32_bf16 v[24:27], v[82:85], v[196:199], v[24:27]
	v_mfma_f32_16x16x32_bf16 v[24:27], v[86:89], v[200:203], v[24:27]
	v_mfma_f32_16x16x32_bf16 v[12:15], v[74:77], v[204:207], v[12:15]
	v_mfma_f32_16x16x32_bf16 v[12:15], v[78:81], v[208:211], v[12:15]
	v_mfma_f32_16x16x32_bf16 v[8:11], v[82:85], v[204:207], v[8:11]
	v_mfma_f32_16x16x32_bf16 v[8:11], v[86:89], v[208:211], v[8:11]
	v_mfma_f32_16x16x32_bf16 v[52:55], v[90:93], v[178:181], v[52:55]
	v_mfma_f32_16x16x32_bf16 v[52:55], v[160:163], v[182:185], v[52:55]
	v_mfma_f32_16x16x32_bf16 v[48:51], v[164:167], v[178:181], v[48:51]
	v_mfma_f32_16x16x32_bf16 v[48:51], v[174:177], v[182:185], v[48:51]
	v_mfma_f32_16x16x32_bf16 v[36:39], v[90:93], v[186:189], v[36:39]
	v_mfma_f32_16x16x32_bf16 v[36:39], v[160:163], v[192:195], v[36:39]
	v_mfma_f32_16x16x32_bf16 v[32:35], v[164:167], v[186:189], v[32:35]
	v_mfma_f32_16x16x32_bf16 v[32:35], v[174:177], v[192:195], v[32:35]
	v_mfma_f32_16x16x32_bf16 v[20:23], v[90:93], v[196:199], v[20:23]
	v_mfma_f32_16x16x32_bf16 v[20:23], v[160:163], v[200:203], v[20:23]
	v_mfma_f32_16x16x32_bf16 v[16:19], v[164:167], v[196:199], v[16:19]
	v_mfma_f32_16x16x32_bf16 v[16:19], v[174:177], v[200:203], v[16:19]
	v_mfma_f32_16x16x32_bf16 v[4:7], v[90:93], v[204:207], v[4:7]
	v_mfma_f32_16x16x32_bf16 v[4:7], v[160:163], v[208:211], v[4:7]
	v_mfma_f32_16x16x32_bf16 v[0:3], v[164:167], v[204:207], v[0:3]
	v_mfma_f32_16x16x32_bf16 v[0:3], v[174:177], v[208:211], v[0:3]
	s_add_i32 s41, s41, 2
	s_add_u32 s4, s4, 0x100
	s_addc_u32 s5, s5, 0
	s_add_u32 s7, s7, 0x100
	s_addc_u32 s39, s39, 0
	s_cmp_gt_u32 s41, 13
	s_barrier
	s_cbranch_scc0 .LBB0_1289
	s_and_b64 vcc, exec, s[12:13]
	s_cbranch_vccz .LBB0_1292
	s_barrier

; #define PG8_STAGE(bufoff, gbase, voff) do { _Pragma("unroll") for (int _i = 0; _i < 2; ++_i) \
;         __builtin_amdgcn_global_load_lds((const unsigned*)((const char*)(gbase) + (voff)[_i]), (LAS unsigned*)(lds + (bufoff) + ldsw + _i * 8192), 16, 0, 0); } while (0)
; #define PG8_LDA(dst, b, h) do { _Pragma("unroll") for (int m = 0; m < 4; ++m) _Pragma("unroll") for (int k = 0; k < 2; ++k) dst[m][k] = *(const LAS bf16x8*)(lds + PG8_SA(b, h) + aoff + m * 2048 + k * 1024); } while (0)
; #define PG8_LDB(dst, b, h) do { _Pragma("unroll") for (int n = 0; n < 2; ++n) _Pragma("unroll") for (int k = 0; k < 2; ++k) dst[n][k] = *(const LAS bf16x8*)(lds + PG8_SB(b, h) + boff + n * 2048 + k * 1024); } while (0)
; #define PG8_MMA(ai, bj, At, Bt) do { __builtin_amdgcn_s_setprio(1); _Pragma("unroll") for (int m = 0; m < 4; ++m) _Pragma("unroll") for (int n = 0; n < 2; ++n) _Pragma("unroll") for (int k = 0; k < 2; ++k) \
;         acc[ai][bj][m][n] = __builtin_amdgcn_mfma_f32_16x16x32_bf16(Bt[n][k], At[m][k], acc[ai][bj][m][n], 0, 0, 0); __builtin_amdgcn_s_setprio(0); } while (0)
; #define PG8_WAIT_V(n) asm volatile("s_waitcnt vmcnt(" #n ")" ::: "memory")
; #define PG8_WAIT_L(n) asm volatile("s_waitcnt lgkmcnt(" #n ")" ::: "memory")
; #define PG8_BAR __builtin_amdgcn_s_barrier()
; #define PG8_SCHED __builtin_amdgcn_sched_barrier(0)
; template <class Epi>
; __device__ __forceinline__ void gemm_phase(LAS unsigned char* lds, const Gemm g, const Order& S, const Epi& E, const int wid) {
;     ...
;             const bool last = (t == nt - 2);
;             const char* a1 = cA + (size_t)(t + 1) * kstep;
;             const char* a2 = last ? nA : cA + (size_t)(t + 2) * kstep; const char* b2 = last ? nB : cB + (size_t)(t + 2) * kstep;
;             const char* a3 = a2 + kstep; const char* b3 = b2 + kstep;
;     ...
;             PG8_LDB(B0, 0, 0); PG8_LDB(B1, 0, 1); PG8_SCHED; PG8_LDA(At, 0, 0); PG8_STAGE(PG8_SA(1, 1), a1 + hA, voffA);
;             PG8_WAIT_V(8); PG8_WAIT_L(0); PG8_BAR; PG8_MMA(0, 0, At, B0); PG8_MMA(0, 1, At, B1); PG8_BAR; PG8_SCHED;
;             PG8_LDA(At, 0, 1); PG8_STAGE(PG8_SB(0, 0), b2, voffB); PG8_STAGE(PG8_SB(0, 1), b2 + hB, voffB); PG8_STAGE(PG8_SA(0, 0), a2, voffA);
.LBB0_1378:
	ds_read_b128 v[138:141], v135
	ds_read_b128 v[142:145], v135 offset:1024
	ds_read_b128 v[146:149], v135 offset:2048
	ds_read_b128 v[150:153], v135 offset:3072
	ds_read_b128 v[154:157], v136
	ds_read_b128 v[158:161], v136 offset:1024
	ds_read_b128 v[162:165], v136 offset:2048
	ds_read_b128 v[166:169], v136 offset:3072
	s_add_u32 s8, s6, 0xfff00080
	s_addc_u32 s9, s7, -1
	s_cmp_eq_u32 s55, 60
	s_cselect_b32 s11, s12, s9
	s_cselect_b32 s10, s13, s8
	s_cselect_b32 s9, s16, s31
	s_cselect_b32 s8, s17, s27
	v_lshl_add_u64 v[190:191], s[6:7], 0, v[192:193]
	s_add_i32 m0, s63, 0xc000
	ds_read_b128 v[170:173], v137
	ds_read_b128 v[174:177], v137 offset:1024
	ds_read_b128 v[178:181], v137 offset:2048
	ds_read_b128 v[182:185], v137 offset:3072
	ds_read_b128 v[186:189], v137 offset:4096
	ds_read_b128 v[198:201], v137 offset:5120
	ds_read_b128 v[202:205], v137 offset:6144
	ds_read_b128 v[206:209], v137 offset:7168
	global_load_lds_dwordx4 v[190:191], off
	v_lshl_add_u64 v[190:191], s[6:7], 0, v[132:133]
	s_add_i32 m0, s63, 0xe000
	s_nop 0
	global_load_lds_dwordx4 v[190:191], off
	s_waitcnt vmcnt(8)
	s_waitcnt lgkmcnt(0)
	s_barrier
	s_waitcnt lgkmcnt(0)
	v_mfma_f32_16x16x32_bf16 v[124:127], v[138:141], v[170:173], v[124:127]
	v_mfma_f32_16x16x32_bf16 v[124:127], v[142:145], v[174:177], v[124:127]
	v_mfma_f32_16x16x32_bf16 v[120:123], v[146:149], v[170:173], v[120:123]
	v_mfma_f32_16x16x32_bf16 v[120:123], v[150:153], v[174:177], v[120:123]
	v_mfma_f32_16x16x32_bf16 v[0:3], v[138:141], v[178:181], v[0:3]
	v_mfma_f32_16x16x32_bf16 v[0:3], v[142:145], v[182:185], v[0:3]
	v_mfma_f32_16x16x32_bf16 v[4:7], v[146:149], v[178:181], v[4:7]
	v_mfma_f32_16x16x32_bf16 v[4:7], v[150:153], v[182:185], v[4:7]
	v_mfma_f32_16x16x32_bf16 v[12:15], v[138:141], v[186:189], v[12:15]
	v_mfma_f32_16x16x32_bf16 v[12:15], v[142:145], v[198:201], v[12:15]
	v_mfma_f32_16x16x32_bf16 v[20:23], v[146:149], v[186:189], v[20:23]
	v_mfma_f32_16x16x32_bf16 v[20:23], v[150:153], v[198:201], v[20:23]
	v_mfma_f32_16x16x32_bf16 v[116:119], v[138:141], v[202:205], v[116:119]
	v_mfma_f32_16x16x32_bf16 v[116:119], v[142:145], v[206:209], v[116:119]
	v_mfma_f32_16x16x32_bf16 v[112:115], v[146:149], v[202:205], v[112:115]
	v_mfma_f32_16x16x32_bf16 v[112:115], v[150:153], v[206:209], v[112:115]
	v_mfma_f32_16x16x32_bf16 v[108:111], v[154:157], v[170:173], v[108:111]
	v_mfma_f32_16x16x32_bf16 v[108:111], v[158:161], v[174:177], v[108:111]
	v_mfma_f32_16x16x32_bf16 v[104:107], v[162:165], v[170:173], v[104:107]
	v_mfma_f32_16x16x32_bf16 v[104:107], v[166:169], v[174:177], v[104:107]
	v_mfma_f32_16x16x32_bf16 v[8:11], v[154:157], v[178:181], v[8:11]
	v_mfma_f32_16x16x32_bf16 v[8:11], v[158:161], v[182:185], v[8:11]
	v_mfma_f32_16x16x32_bf16 v[16:19], v[162:165], v[178:181], v[16:19]
	v_mfma_f32_16x16x32_bf16 v[16:19], v[166:169], v[182:185], v[16:19]
	v_mfma_f32_16x16x32_bf16 v[40:43], v[154:157], v[186:189], v[40:43]
	v_mfma_f32_16x16x32_bf16 v[40:43], v[158:161], v[198:201], v[40:43]
	v_mfma_f32_16x16x32_bf16 v[32:35], v[162:165], v[186:189], v[32:35]
	v_mfma_f32_16x16x32_bf16 v[32:35], v[166:169], v[198:201], v[32:35]
	v_mfma_f32_16x16x32_bf16 v[100:103], v[154:157], v[202:205], v[100:103]
	v_mfma_f32_16x16x32_bf16 v[100:103], v[158:161], v[206:209], v[100:103]
	v_mfma_f32_16x16x32_bf16 v[96:99], v[162:165], v[202:205], v[96:99]
	v_mfma_f32_16x16x32_bf16 v[96:99], v[166:169], v[206:209], v[96:99]
	s_barrier
	s_add_i32 s18, s33, s53
	v_lshl_add_u64 v[190:191], s[8:9], 0, v[128:129]
	s_mov_b32 m0, s18
	ds_read_b128 v[170:173], v137 offset:16384
	ds_read_b128 v[174:177], v137 offset:17408
	ds_read_b128 v[178:181], v137 offset:18432
	ds_read_b128 v[182:185], v137 offset:19456
	ds_read_b128 v[186:189], v137 offset:20480
	ds_read_b128 v[198:201], v137 offset:21504
	ds_read_b128 v[202:205], v137 offset:22528
	ds_read_b128 v[206:209], v137 offset:23552
	global_load_lds_dwordx4 v[190:191], off
	s_add_i32 m0, s18, 0x2000
	s_add_u32 s64, s8, 0x100000
	v_lshl_add_u64 v[210:211], s[8:9], 0, v[130:131]
	s_addc_u32 s65, s9, 0
	s_add_i32 s18, s67, s53
	global_load_lds_dwordx4 v[210:211], off
	v_lshl_add_u64 v[212:213], s[64:65], 0, v[128:129]
	s_mov_b32 m0, s18
	v_lshl_add_u64 v[214:215], s[10:11], 0, v[132:133]
	global_load_lds_dwordx4 v[212:213], off
	v_lshl_add_u64 v[212:213], s[64:65], 0, v[130:131]
	s_add_i32 m0, s18, 0x2000
	s_nop 0
	global_load_lds_dwordx4 v[212:213], off
	v_lshl_add_u64 v[212:213], s[10:11], 0, v[192:193]
	s_mov_b32 m0, s63
	s_nop 0
	global_load_lds_dwordx4 v[212:213], off
	s_mov_b32 m0, s68
	s_nop 0
	global_load_lds_dwordx4 v[214:215], off
	s_waitcnt vmcnt(8)
	s_waitcnt lgkmcnt(0)
	s_barrier
; #define PG8_STAGE(bufoff, gbase, voff) do { _Pragma("unroll") for (int _i = 0; _i < 2; ++_i) \
;         __builtin_amdgcn_global_load_lds((const unsigned*)((const char*)(gbase) + (voff)[_i]), (LAS unsigned*)(lds + (bufoff) + ldsw + _i * 8192), 16, 0, 0); } while (0)
; #define PG8_LDA(dst, b, h) do { _Pragma("unroll") for (int m = 0; m < 4; ++m) _Pragma("unroll") for (int k = 0; k < 2; ++k) dst[m][k] = *(const LAS bf16x8*)(lds + PG8_SA(b, h) + aoff + m * 2048 + k * 1024); } while (0)
; #define PG8_LDB(dst, b, h) do { _Pragma("unroll") for (int n = 0; n < 2; ++n) _Pragma("unroll") for (int k = 0; k < 2; ++k) dst[n][k] = *(const LAS bf16x8*)(lds + PG8_SB(b, h) + boff + n * 2048 + k * 1024); } while (0)
; #define PG8_MMA(ai, bj, At, Bt) do { __builtin_amdgcn_s_setprio(1); _Pragma("unroll") for (int m = 0; m < 4; ++m) _Pragma("unroll") for (int n = 0; n < 2; ++n) _Pragma("unroll") for (int k = 0; k < 2; ++k) \
;         acc[ai][bj][m][n] = __builtin_amdgcn_mfma_f32_16x16x32_bf16(Bt[n][k], At[m][k], acc[ai][bj][m][n], 0, 0, 0); __builtin_amdgcn_s_setprio(0); } while (0)
; #define PG8_WAIT_V(n) asm volatile("s_waitcnt vmcnt(" #n ")" ::: "memory")
; #define PG8_WAIT_L(n) asm volatile("s_waitcnt lgkmcnt(" #n ")" ::: "memory")
; #define PG8_BAR __builtin_amdgcn_s_barrier()
; #define PG8_SCHED __builtin_amdgcn_sched_barrier(0)
; template <class Epi>
; __device__ __forceinline__ void gemm_phase(LAS unsigned char* lds, const Gemm g, const Order& S, const Epi& E, const int wid) {
;     ...
;             PG8_WAIT_V(8); PG8_WAIT_L(0); PG8_BAR; PG8_MMA(1, 0, At, B0); PG8_MMA(1, 1, At, B1); PG8_BAR; PG8_SCHED;
;             PG8_LDB(B0, 1, 0); PG8_LDB(B1, 1, 1); PG8_SCHED; PG8_LDA(At, 1, 0); PG8_STAGE(PG8_SA(0, 1), a2 + hA, voffA);
;             PG8_WAIT_V(8); PG8_WAIT_L(0); PG8_BAR; PG8_MMA(0, 0, At, B0); PG8_MMA(0, 1, At, B1); PG8_BAR; PG8_SCHED;
	s_waitcnt lgkmcnt(0)
	v_mfma_f32_16x16x32_bf16 v[92:95], v[138:141], v[170:173], v[92:95]
	v_mfma_f32_16x16x32_bf16 v[92:95], v[142:145], v[174:177], v[92:95]
	v_mfma_f32_16x16x32_bf16 v[88:91], v[146:149], v[170:173], v[88:91]
	v_mfma_f32_16x16x32_bf16 v[88:91], v[150:153], v[174:177], v[88:91]
	v_mfma_f32_16x16x32_bf16 v[24:27], v[138:141], v[178:181], v[24:27]
	v_mfma_f32_16x16x32_bf16 v[24:27], v[142:145], v[182:185], v[24:27]
	v_mfma_f32_16x16x32_bf16 v[28:31], v[146:149], v[178:181], v[28:31]
	v_mfma_f32_16x16x32_bf16 v[28:31], v[150:153], v[182:185], v[28:31]
	v_mfma_f32_16x16x32_bf16 v[44:47], v[138:141], v[186:189], v[44:47]
	v_mfma_f32_16x16x32_bf16 v[44:47], v[142:145], v[198:201], v[44:47]
	v_mfma_f32_16x16x32_bf16 v[52:55], v[146:149], v[186:189], v[52:55]
	v_mfma_f32_16x16x32_bf16 v[52:55], v[150:153], v[198:201], v[52:55]
	v_mfma_f32_16x16x32_bf16 v[84:87], v[138:141], v[202:205], v[84:87]
	v_mfma_f32_16x16x32_bf16 v[84:87], v[142:145], v[206:209], v[84:87]
	v_mfma_f32_16x16x32_bf16 v[80:83], v[146:149], v[202:205], v[80:83]
	v_mfma_f32_16x16x32_bf16 v[80:83], v[150:153], v[206:209], v[80:83]
	v_mfma_f32_16x16x32_bf16 v[76:79], v[154:157], v[170:173], v[76:79]
	v_mfma_f32_16x16x32_bf16 v[76:79], v[158:161], v[174:177], v[76:79]
	v_mfma_f32_16x16x32_bf16 v[72:75], v[162:165], v[170:173], v[72:75]
	v_mfma_f32_16x16x32_bf16 v[72:75], v[166:169], v[174:177], v[72:75]
	v_mfma_f32_16x16x32_bf16 v[36:39], v[154:157], v[178:181], v[36:39]
	v_mfma_f32_16x16x32_bf16 v[36:39], v[158:161], v[182:185], v[36:39]
	v_mfma_f32_16x16x32_bf16 v[48:51], v[162:165], v[178:181], v[48:51]
	v_mfma_f32_16x16x32_bf16 v[48:51], v[166:169], v[182:185], v[48:51]
	v_mfma_f32_16x16x32_bf16 v[60:63], v[154:157], v[186:189], v[60:63]
	v_mfma_f32_16x16x32_bf16 v[60:63], v[158:161], v[198:201], v[60:63]
	v_mfma_f32_16x16x32_bf16 v[56:59], v[162:165], v[186:189], v[56:59]
	v_mfma_f32_16x16x32_bf16 v[56:59], v[166:169], v[198:201], v[56:59]
	v_mfma_f32_16x16x32_bf16 v[68:71], v[154:157], v[202:205], v[68:71]
	v_mfma_f32_16x16x32_bf16 v[68:71], v[158:161], v[206:209], v[68:71]
	v_mfma_f32_16x16x32_bf16 v[64:67], v[162:165], v[202:205], v[64:67]
	v_mfma_f32_16x16x32_bf16 v[64:67], v[166:169], v[206:209], v[64:67]
	s_barrier
	s_add_i32 s18, 0, 0x18000
	s_add_i32 s19, 0, 0x1c000
	v_add_u32_e32 v150, s18, v134
	v_add_u32_e32 v166, s19, v134
	ds_read_b128 v[138:141], v150
	ds_read_b128 v[142:145], v150 offset:1024
	ds_read_b128 v[146:149], v150 offset:2048
	ds_read_b128 v[150:153], v150 offset:3072
	ds_read_b128 v[154:157], v166
	ds_read_b128 v[158:161], v166 offset:1024
	ds_read_b128 v[162:165], v166 offset:2048
	ds_read_b128 v[166:169], v166 offset:3072
	s_add_u32 s10, s10, 0x100000
	s_addc_u32 s11, s11, 0
	s_mov_b32 m0, s69
	v_lshl_add_u64 v[216:217], s[10:11], 0, v[192:193]
	ds_read_b128 v[170:173], v137 offset:32768
	ds_read_b128 v[174:177], v137 offset:33792
	ds_read_b128 v[178:181], v137 offset:34816
	ds_read_b128 v[182:185], v137 offset:35840
	ds_read_b128 v[186:189], v137 offset:36864
	ds_read_b128 v[198:201], v137 offset:37888
	ds_read_b128 v[202:205], v137 offset:38912
	ds_read_b128 v[206:209], v137 offset:39936
	global_load_lds_dwordx4 v[216:217], off
	v_lshl_add_u64 v[216:217], s[10:11], 0, v[132:133]
	s_mov_b32 m0, s70
	s_nop 0
	global_load_lds_dwordx4 v[216:217], off
	s_waitcnt vmcnt(8)
	s_waitcnt lgkmcnt(0)
	s_barrier
	s_waitcnt lgkmcnt(0)
	v_mfma_f32_16x16x32_bf16 v[124:127], v[138:141], v[170:173], v[124:127]
	v_mfma_f32_16x16x32_bf16 v[124:127], v[142:145], v[174:177], v[124:127]
	v_mfma_f32_16x16x32_bf16 v[120:123], v[146:149], v[170:173], v[120:123]
	v_mfma_f32_16x16x32_bf16 v[120:123], v[150:153], v[174:177], v[120:123]
	v_mfma_f32_16x16x32_bf16 v[0:3], v[138:141], v[178:181], v[0:3]
	v_mfma_f32_16x16x32_bf16 v[0:3], v[142:145], v[182:185], v[0:3]
	v_mfma_f32_16x16x32_bf16 v[4:7], v[146:149], v[178:181], v[4:7]
	v_mfma_f32_16x16x32_bf16 v[4:7], v[150:153], v[182:185], v[4:7]
	v_mfma_f32_16x16x32_bf16 v[12:15], v[138:141], v[186:189], v[12:15]
	v_mfma_f32_16x16x32_bf16 v[12:15], v[142:145], v[198:201], v[12:15]
	v_mfma_f32_16x16x32_bf16 v[20:23], v[146:149], v[186:189], v[20:23]
	v_mfma_f32_16x16x32_bf16 v[20:23], v[150:153], v[198:201], v[20:23]
	v_mfma_f32_16x16x32_bf16 v[116:119], v[138:141], v[202:205], v[116:119]
	v_mfma_f32_16x16x32_bf16 v[116:119], v[142:145], v[206:209], v[116:119]
	v_mfma_f32_16x16x32_bf16 v[112:115], v[146:149], v[202:205], v[112:115]
	v_mfma_f32_16x16x32_bf16 v[112:115], v[150:153], v[206:209], v[112:115]
	v_mfma_f32_16x16x32_bf16 v[108:111], v[154:157], v[170:173], v[108:111]
	v_mfma_f32_16x16x32_bf16 v[108:111], v[158:161], v[174:177], v[108:111]
	v_mfma_f32_16x16x32_bf16 v[104:107], v[162:165], v[170:173], v[104:107]
	v_mfma_f32_16x16x32_bf16 v[104:107], v[166:169], v[174:177], v[104:107]
	v_mfma_f32_16x16x32_bf16 v[8:11], v[154:157], v[178:181], v[8:11]
	v_mfma_f32_16x16x32_bf16 v[8:11], v[158:161], v[182:185], v[8:11]
	v_mfma_f32_16x16x32_bf16 v[16:19], v[162:165], v[178:181], v[16:19]
	v_mfma_f32_16x16x32_bf16 v[16:19], v[166:169], v[182:185], v[16:19]
	v_mfma_f32_16x16x32_bf16 v[40:43], v[154:157], v[186:189], v[40:43]
	v_mfma_f32_16x16x32_bf16 v[40:43], v[158:161], v[198:201], v[40:43]
	v_mfma_f32_16x16x32_bf16 v[32:35], v[162:165], v[186:189], v[32:35]
	v_mfma_f32_16x16x32_bf16 v[32:35], v[166:169], v[198:201], v[32:35]
	v_mfma_f32_16x16x32_bf16 v[100:103], v[154:157], v[202:205], v[100:103]
	v_mfma_f32_16x16x32_bf16 v[100:103], v[158:161], v[206:209], v[100:103]
	v_mfma_f32_16x16x32_bf16 v[96:99], v[162:165], v[202:205], v[96:99]
	v_mfma_f32_16x16x32_bf16 v[96:99], v[166:169], v[206:209], v[96:99]
	s_barrier
; #define PG8_STAGE(bufoff, gbase, voff) do { _Pragma("unroll") for (int _i = 0; _i < 2; ++_i) \
;         __builtin_amdgcn_global_load_lds((const unsigned*)((const char*)(gbase) + (voff)[_i]), (LAS unsigned*)(lds + (bufoff) + ldsw + _i * 8192), 16, 0, 0); } while (0)
; #define PG8_LDA(dst, b, h) do { _Pragma("unroll") for (int m = 0; m < 4; ++m) _Pragma("unroll") for (int k = 0; k < 2; ++k) dst[m][k] = *(const LAS bf16x8*)(lds + PG8_SA(b, h) + aoff + m * 2048 + k * 1024); } while (0)
; #define PG8_MMA(ai, bj, At, Bt) do { __builtin_amdgcn_s_setprio(1); _Pragma("unroll") for (int m = 0; m < 4; ++m) _Pragma("unroll") for (int n = 0; n < 2; ++n) _Pragma("unroll") for (int k = 0; k < 2; ++k) \
;         acc[ai][bj][m][n] = __builtin_amdgcn_mfma_f32_16x16x32_bf16(Bt[n][k], At[m][k], acc[ai][bj][m][n], 0, 0, 0); __builtin_amdgcn_s_setprio(0); } while (0)
; #define PG8_WAIT_V(n) asm volatile("s_waitcnt vmcnt(" #n ")" ::: "memory")
; #define PG8_WAIT_L(n) asm volatile("s_waitcnt lgkmcnt(" #n ")" ::: "memory")
; #define PG8_BAR __builtin_amdgcn_s_barrier()
; #define PG8_SCHED __builtin_amdgcn_sched_barrier(0)
; template <class Epi>
; __device__ __forceinline__ void gemm_phase(LAS unsigned char* lds, const Gemm g, const Order& S, const Epi& E, const int wid) {
;     ...
;             PG8_LDA(At, 1, 1); PG8_STAGE(PG8_SB(1, 0), b3, voffB); PG8_STAGE(PG8_SB(1, 1), b3 + hB, voffB); PG8_STAGE(PG8_SA(1, 0), a3, voffA);
;             PG8_WAIT_V(8); PG8_WAIT_L(0); PG8_BAR; PG8_MMA(1, 0, At, B0); PG8_MMA(1, 1, At, B1); PG8_BAR; PG8_SCHED;
;     ...
;         }
;         if (wr == 0) PG8_BAR;
	s_add_i32 s10, s18, s53
	v_lshl_add_u64 v[190:191], v[190:191], 0, s[48:49]
	s_mov_b32 m0, s10
	ds_read_b128 v[170:173], v137 offset:49152
	ds_read_b128 v[174:177], v137 offset:50176
	ds_read_b128 v[178:181], v137 offset:51200
	ds_read_b128 v[182:185], v137 offset:52224
	ds_read_b128 v[186:189], v137 offset:53248
	ds_read_b128 v[198:201], v137 offset:54272
	ds_read_b128 v[202:205], v137 offset:55296
	ds_read_b128 v[206:209], v137 offset:56320
	global_load_lds_dwordx4 v[190:191], off
	s_add_i32 m0, s10, 0x2000
	s_add_u32 s8, s8, 0x100080
	v_lshl_add_u64 v[190:191], v[210:211], 0, s[48:49]
	s_addc_u32 s9, s9, 0
	s_add_i32 s10, s19, s53
	global_load_lds_dwordx4 v[190:191], off
	v_lshl_add_u64 v[190:191], s[8:9], 0, v[128:129]
	s_mov_b32 m0, s10
	s_nop 0
	global_load_lds_dwordx4 v[190:191], off
	v_lshl_add_u64 v[190:191], s[8:9], 0, v[130:131]
	s_add_i32 m0, s10, 0x2000
	s_nop 0
	global_load_lds_dwordx4 v[190:191], off
	v_lshl_add_u64 v[190:191], v[212:213], 0, s[48:49]
	s_mov_b32 m0, s97
	s_nop 0
	global_load_lds_dwordx4 v[190:191], off
	v_lshl_add_u64 v[190:191], v[214:215], 0, s[48:49]
	s_mov_b32 m0, s74
	s_nop 0
	global_load_lds_dwordx4 v[190:191], off
	s_waitcnt vmcnt(8)
	s_waitcnt lgkmcnt(0)
	s_barrier
	s_waitcnt lgkmcnt(0)
	v_mfma_f32_16x16x32_bf16 v[92:95], v[138:141], v[170:173], v[92:95]
	v_mfma_f32_16x16x32_bf16 v[92:95], v[142:145], v[174:177], v[92:95]
	v_mfma_f32_16x16x32_bf16 v[88:91], v[146:149], v[170:173], v[88:91]
	v_mfma_f32_16x16x32_bf16 v[88:91], v[150:153], v[174:177], v[88:91]
	v_mfma_f32_16x16x32_bf16 v[24:27], v[138:141], v[178:181], v[24:27]
	v_mfma_f32_16x16x32_bf16 v[24:27], v[142:145], v[182:185], v[24:27]
	v_mfma_f32_16x16x32_bf16 v[28:31], v[146:149], v[178:181], v[28:31]
	v_mfma_f32_16x16x32_bf16 v[28:31], v[150:153], v[182:185], v[28:31]
	v_mfma_f32_16x16x32_bf16 v[44:47], v[138:141], v[186:189], v[44:47]
	v_mfma_f32_16x16x32_bf16 v[44:47], v[142:145], v[198:201], v[44:47]
	v_mfma_f32_16x16x32_bf16 v[52:55], v[146:149], v[186:189], v[52:55]
	v_mfma_f32_16x16x32_bf16 v[52:55], v[150:153], v[198:201], v[52:55]
	v_mfma_f32_16x16x32_bf16 v[84:87], v[138:141], v[202:205], v[84:87]
	v_mfma_f32_16x16x32_bf16 v[84:87], v[142:145], v[206:209], v[84:87]
	v_mfma_f32_16x16x32_bf16 v[80:83], v[146:149], v[202:205], v[80:83]
	v_mfma_f32_16x16x32_bf16 v[80:83], v[150:153], v[206:209], v[80:83]
	v_mfma_f32_16x16x32_bf16 v[76:79], v[154:157], v[170:173], v[76:79]
	v_mfma_f32_16x16x32_bf16 v[76:79], v[158:161], v[174:177], v[76:79]
	v_mfma_f32_16x16x32_bf16 v[72:75], v[162:165], v[170:173], v[72:75]
	v_mfma_f32_16x16x32_bf16 v[72:75], v[166:169], v[174:177], v[72:75]
	v_mfma_f32_16x16x32_bf16 v[36:39], v[154:157], v[178:181], v[36:39]
	v_mfma_f32_16x16x32_bf16 v[36:39], v[158:161], v[182:185], v[36:39]
	v_mfma_f32_16x16x32_bf16 v[48:51], v[162:165], v[178:181], v[48:51]
	v_mfma_f32_16x16x32_bf16 v[48:51], v[166:169], v[182:185], v[48:51]
	v_mfma_f32_16x16x32_bf16 v[60:63], v[154:157], v[186:189], v[60:63]
	v_mfma_f32_16x16x32_bf16 v[60:63], v[158:161], v[198:201], v[60:63]
	v_mfma_f32_16x16x32_bf16 v[56:59], v[162:165], v[186:189], v[56:59]
	v_mfma_f32_16x16x32_bf16 v[56:59], v[166:169], v[198:201], v[56:59]
	v_mfma_f32_16x16x32_bf16 v[68:71], v[154:157], v[202:205], v[68:71]
	v_mfma_f32_16x16x32_bf16 v[68:71], v[158:161], v[206:209], v[68:71]
	v_mfma_f32_16x16x32_bf16 v[64:67], v[162:165], v[202:205], v[64:67]
	v_mfma_f32_16x16x32_bf16 v[64:67], v[166:169], v[206:209], v[64:67]
	s_add_i32 s55, s55, 2
	s_add_u32 s6, s6, 0x100
	s_addc_u32 s7, s7, 0
	s_add_u32 s27, s27, 0x100
	s_addc_u32 s31, s31, 0
	s_cmp_gt_u32 s55, 61
	s_barrier
	s_cbranch_scc0 .LBB0_1378
	s_and_b64 vcc, exec, s[2:3]
	s_cbranch_vccz .LBB0_1381
	s_barrier

; #define PG8_STAGE(bufoff, gbase, voff) do { _Pragma("unroll") for (int _i = 0; _i < 2; ++_i) \
;         __builtin_amdgcn_global_load_lds((const unsigned*)((const char*)(gbase) + (voff)[_i]), (LAS unsigned*)(lds + (bufoff) + ldsw + _i * 8192), 16, 0, 0); } while (0)
; #define PG8_LDA(dst, b, h) do { _Pragma("unroll") for (int m = 0; m < 4; ++m) _Pragma("unroll") for (int k = 0; k < 2; ++k) dst[m][k] = *(const LAS bf16x8*)(lds + PG8_SA(b, h) + aoff + m * 2048 + k * 1024); } while (0)
; #define PG8_LDB(dst, b, h) do { _Pragma("unroll") for (int n = 0; n < 2; ++n) _Pragma("unroll") for (int k = 0; k < 2; ++k) dst[n][k] = *(const LAS bf16x8*)(lds + PG8_SB(b, h) + boff + n * 2048 + k * 1024); } while (0)
; #define PG8_MMA(ai, bj, At, Bt) do { __builtin_amdgcn_s_setprio(1); _Pragma("unroll") for (int m = 0; m < 4; ++m) _Pragma("unroll") for (int n = 0; n < 2; ++n) _Pragma("unroll") for (int k = 0; k < 2; ++k) \
;         acc[ai][bj][m][n] = __builtin_amdgcn_mfma_f32_16x16x32_bf16(Bt[n][k], At[m][k], acc[ai][bj][m][n], 0, 0, 0); __builtin_amdgcn_s_setprio(0); } while (0)
; #define PG8_WAIT_V(n) asm volatile("s_waitcnt vmcnt(" #n ")" ::: "memory")
; #define PG8_WAIT_L(n) asm volatile("s_waitcnt lgkmcnt(" #n ")" ::: "memory")
; #define PG8_BAR __builtin_amdgcn_s_barrier()
; #define PG8_SCHED __builtin_amdgcn_sched_barrier(0)
; template <class Epi>
; __device__ __forceinline__ void gemm_phase(LAS unsigned char* lds, const Gemm g, const Order& S, const Epi& E, const int wid) {
;     ...
;             const bool last = (t == nt - 2);
;             const char* a1 = cA + (size_t)(t + 1) * kstep;
;             const char* a2 = last ? nA : cA + (size_t)(t + 2) * kstep; const char* b2 = last ? nB : cB + (size_t)(t + 2) * kstep;
;             const char* a3 = a2 + kstep; const char* b3 = b2 + kstep;
;     ...
;             PG8_LDB(B0, 0, 0); PG8_LDB(B1, 0, 1); PG8_SCHED; PG8_LDA(At, 0, 0); PG8_STAGE(PG8_SA(1, 1), a1 + hA, voffA);
;             PG8_WAIT_V(8); PG8_WAIT_L(0); PG8_BAR; PG8_MMA(0, 0, At, B0); PG8_MMA(0, 1, At, B1); PG8_BAR; PG8_SCHED;
;             PG8_LDA(At, 0, 1); PG8_STAGE(PG8_SB(0, 0), b2, voffB); PG8_STAGE(PG8_SB(0, 1), b2 + hB, voffB); PG8_STAGE(PG8_SA(0, 0), a2, voffA);
.LBB0_1549:
	ds_read_b128 v[114:117], v111
	ds_read_b128 v[128:131], v111 offset:1024
	ds_read_b128 v[132:135], v111 offset:2048
	ds_read_b128 v[140:143], v111 offset:3072
	ds_read_b128 v[144:147], v112
	ds_read_b128 v[166:169], v112 offset:1024
	ds_read_b128 v[170:173], v112 offset:2048
	ds_read_b128 v[176:179], v112 offset:3072
	s_add_u32 s40, s38, 0xffd50080
	s_addc_u32 s41, s39, -1
	s_cmpk_eq_i32 s64, 0xa8
	s_cselect_b32 s43, s5, s41
	s_cselect_b32 s42, s4, s40
	s_cselect_b32 s41, s37, s63
	s_cselect_b32 s40, s36, s62
	v_lshl_add_u64 v[118:119], s[38:39], 0, v[160:161]
	s_add_i32 m0, s26, 0xc000
	ds_read_b128 v[180:183], v113
	ds_read_b128 v[184:187], v113 offset:1024
	ds_read_b128 v[188:191], v113 offset:2048
	ds_read_b128 v[192:195], v113 offset:3072
	ds_read_b128 v[196:199], v113 offset:4096
	ds_read_b128 v[200:203], v113 offset:5120
	ds_read_b128 v[204:207], v113 offset:6144
	ds_read_b128 v[208:211], v113 offset:7168
	global_load_lds_dwordx4 v[118:119], off
	v_lshl_add_u64 v[118:119], s[38:39], 0, v[106:107]
	s_add_i32 m0, s26, 0xe000
	s_nop 0
	global_load_lds_dwordx4 v[118:119], off
	s_waitcnt vmcnt(8)
	s_waitcnt lgkmcnt(0)
	s_barrier
	s_waitcnt lgkmcnt(0)
	v_mfma_f32_16x16x32_bf16 v[156:159], v[114:117], v[180:183], v[156:159]
	v_mfma_f32_16x16x32_bf16 v[152:155], v[132:135], v[180:183], v[152:155]
	v_mfma_f32_16x16x32_bf16 v[124:127], v[114:117], v[188:191], v[124:127]
	v_mfma_f32_16x16x32_bf16 v[118:121], v[132:135], v[188:191], v[120:123]
	v_mfma_f32_16x16x32_bf16 v[92:95], v[114:117], v[196:199], v[92:95]
	v_mfma_f32_16x16x32_bf16 v[88:91], v[132:135], v[196:199], v[88:91]
	v_mfma_f32_16x16x32_bf16 v[76:79], v[114:117], v[204:207], v[76:79]
	v_mfma_f32_16x16x32_bf16 v[72:75], v[132:135], v[204:207], v[72:75]
	v_mfma_f32_16x16x32_bf16 v[156:159], v[128:131], v[184:187], v[156:159]
	v_mfma_f32_16x16x32_bf16 v[152:155], v[140:143], v[184:187], v[152:155]
	v_mfma_f32_16x16x32_bf16 v[124:127], v[128:131], v[192:195], v[124:127]
	v_mfma_f32_16x16x32_bf16 v[118:121], v[140:143], v[192:195], v[118:121]
	v_mfma_f32_16x16x32_bf16 v[92:95], v[128:131], v[200:203], v[92:95]
	v_mfma_f32_16x16x32_bf16 v[88:91], v[140:143], v[200:203], v[88:91]
	v_mfma_f32_16x16x32_bf16 v[76:79], v[128:131], v[208:211], v[76:79]
	v_mfma_f32_16x16x32_bf16 v[72:75], v[140:143], v[208:211], v[72:75]
	v_mfma_f32_16x16x32_bf16 v[148:151], v[144:147], v[180:183], v[148:151]
	v_mfma_f32_16x16x32_bf16 v[148:151], v[166:169], v[184:187], v[148:151]
	v_mfma_f32_16x16x32_bf16 v[136:139], v[170:173], v[180:183], v[136:139]
	v_mfma_f32_16x16x32_bf16 v[136:139], v[176:179], v[184:187], v[136:139]
	v_mfma_f32_16x16x32_bf16 v[100:103], v[144:147], v[188:191], v[100:103]
	v_mfma_f32_16x16x32_bf16 v[100:103], v[166:169], v[192:195], v[100:103]
	v_mfma_f32_16x16x32_bf16 v[96:99], v[170:173], v[188:191], v[96:99]
	v_mfma_f32_16x16x32_bf16 v[96:99], v[176:179], v[192:195], v[96:99]
	v_mfma_f32_16x16x32_bf16 v[84:87], v[144:147], v[196:199], v[84:87]
	v_mfma_f32_16x16x32_bf16 v[84:87], v[166:169], v[200:203], v[84:87]
	v_mfma_f32_16x16x32_bf16 v[80:83], v[170:173], v[196:199], v[80:83]
	v_mfma_f32_16x16x32_bf16 v[80:83], v[176:179], v[200:203], v[80:83]
	v_mfma_f32_16x16x32_bf16 v[68:71], v[144:147], v[204:207], v[68:71]
	v_mfma_f32_16x16x32_bf16 v[68:71], v[166:169], v[208:211], v[68:71]
	v_mfma_f32_16x16x32_bf16 v[64:67], v[170:173], v[204:207], v[64:67]
	v_mfma_f32_16x16x32_bf16 v[64:67], v[176:179], v[208:211], v[64:67]
	s_barrier
	s_add_i32 s65, s69, s24
	v_lshl_add_u64 v[212:213], s[40:41], 0, v[104:105]
	s_mov_b32 m0, s65
	ds_read_b128 v[180:183], v113 offset:16384
	ds_read_b128 v[184:187], v113 offset:17408
	ds_read_b128 v[188:191], v113 offset:18432
	ds_read_b128 v[192:195], v113 offset:19456
	ds_read_b128 v[196:199], v113 offset:20480
	ds_read_b128 v[200:203], v113 offset:21504
	ds_read_b128 v[204:207], v113 offset:22528
	ds_read_b128 v[208:211], v113 offset:23552
	global_load_lds_dwordx4 v[212:213], off
	s_add_i32 m0, s65, 0x2000
	s_add_u32 s66, s40, 0x2b0000
	v_lshl_add_u64 v[214:215], s[40:41], 0, v[108:109]
	s_addc_u32 s67, s41, 0
	s_add_i32 s65, s70, s24
	global_load_lds_dwordx4 v[214:215], off
	v_lshl_add_u64 v[122:123], s[66:67], 0, v[104:105]
	s_mov_b32 m0, s65
	v_lshl_add_u64 v[216:217], s[42:43], 0, v[160:161]
	global_load_lds_dwordx4 v[122:123], off
	v_lshl_add_u64 v[122:123], s[66:67], 0, v[108:109]
	s_add_i32 m0, s65, 0x2000
	v_lshl_add_u64 v[218:219], s[42:43], 0, v[106:107]
	global_load_lds_dwordx4 v[122:123], off
	s_mov_b32 m0, s26
	s_nop 0
	global_load_lds_dwordx4 v[216:217], off
	s_mov_b32 m0, s27
	s_nop 0
	global_load_lds_dwordx4 v[218:219], off
	s_waitcnt vmcnt(8)
	s_waitcnt lgkmcnt(0)
	s_barrier
; #define PG8_STAGE(bufoff, gbase, voff) do { _Pragma("unroll") for (int _i = 0; _i < 2; ++_i) \
;         __builtin_amdgcn_global_load_lds((const unsigned*)((const char*)(gbase) + (voff)[_i]), (LAS unsigned*)(lds + (bufoff) + ldsw + _i * 8192), 16, 0, 0); } while (0)
; #define PG8_LDA(dst, b, h) do { _Pragma("unroll") for (int m = 0; m < 4; ++m) _Pragma("unroll") for (int k = 0; k < 2; ++k) dst[m][k] = *(const LAS bf16x8*)(lds + PG8_SA(b, h) + aoff + m * 2048 + k * 1024); } while (0)
; #define PG8_LDB(dst, b, h) do { _Pragma("unroll") for (int n = 0; n < 2; ++n) _Pragma("unroll") for (int k = 0; k < 2; ++k) dst[n][k] = *(const LAS bf16x8*)(lds + PG8_SB(b, h) + boff + n * 2048 + k * 1024); } while (0)
; #define PG8_MMA(ai, bj, At, Bt) do { __builtin_amdgcn_s_setprio(1); _Pragma("unroll") for (int m = 0; m < 4; ++m) _Pragma("unroll") for (int n = 0; n < 2; ++n) _Pragma("unroll") for (int k = 0; k < 2; ++k) \
;         acc[ai][bj][m][n] = __builtin_amdgcn_mfma_f32_16x16x32_bf16(Bt[n][k], At[m][k], acc[ai][bj][m][n], 0, 0, 0); __builtin_amdgcn_s_setprio(0); } while (0)
; #define PG8_WAIT_V(n) asm volatile("s_waitcnt vmcnt(" #n ")" ::: "memory")
; #define PG8_WAIT_L(n) asm volatile("s_waitcnt lgkmcnt(" #n ")" ::: "memory")
; #define PG8_BAR __builtin_amdgcn_s_barrier()
; #define PG8_SCHED __builtin_amdgcn_sched_barrier(0)
; template <class Epi>
; __device__ __forceinline__ void gemm_phase(LAS unsigned char* lds, const Gemm g, const Order& S, const Epi& E, const int wid) {
;     ...
;             PG8_WAIT_V(8); PG8_WAIT_L(0); PG8_BAR; PG8_MMA(1, 0, At, B0); PG8_MMA(1, 1, At, B1); PG8_BAR; PG8_SCHED;
;             PG8_LDB(B0, 1, 0); PG8_LDB(B1, 1, 1); PG8_SCHED; PG8_LDA(At, 1, 0); PG8_STAGE(PG8_SA(0, 1), a2 + hA, voffA);
;             PG8_WAIT_V(8); PG8_WAIT_L(0); PG8_BAR; PG8_MMA(0, 0, At, B0); PG8_MMA(0, 1, At, B1); PG8_BAR; PG8_SCHED;
	s_waitcnt lgkmcnt(0)
	v_mfma_f32_16x16x32_bf16 v[60:63], v[114:117], v[180:183], v[60:63]
	v_mfma_f32_16x16x32_bf16 v[60:63], v[128:131], v[184:187], v[60:63]
	v_mfma_f32_16x16x32_bf16 v[56:59], v[132:135], v[180:183], v[56:59]
	v_mfma_f32_16x16x32_bf16 v[56:59], v[140:143], v[184:187], v[56:59]
	v_mfma_f32_16x16x32_bf16 v[44:47], v[114:117], v[188:191], v[44:47]
	v_mfma_f32_16x16x32_bf16 v[44:47], v[128:131], v[192:195], v[44:47]
	v_mfma_f32_16x16x32_bf16 v[40:43], v[132:135], v[188:191], v[40:43]
	v_mfma_f32_16x16x32_bf16 v[40:43], v[140:143], v[192:195], v[40:43]
	v_mfma_f32_16x16x32_bf16 v[28:31], v[114:117], v[196:199], v[28:31]
	v_mfma_f32_16x16x32_bf16 v[28:31], v[128:131], v[200:203], v[28:31]
	v_mfma_f32_16x16x32_bf16 v[24:27], v[132:135], v[196:199], v[24:27]
	v_mfma_f32_16x16x32_bf16 v[24:27], v[140:143], v[200:203], v[24:27]
	v_mfma_f32_16x16x32_bf16 v[12:15], v[114:117], v[204:207], v[12:15]
	v_mfma_f32_16x16x32_bf16 v[12:15], v[128:131], v[208:211], v[12:15]
	v_mfma_f32_16x16x32_bf16 v[8:11], v[132:135], v[204:207], v[8:11]
	v_mfma_f32_16x16x32_bf16 v[8:11], v[140:143], v[208:211], v[8:11]
	v_mfma_f32_16x16x32_bf16 v[52:55], v[144:147], v[180:183], v[52:55]
	v_mfma_f32_16x16x32_bf16 v[52:55], v[166:169], v[184:187], v[52:55]
	v_mfma_f32_16x16x32_bf16 v[48:51], v[170:173], v[180:183], v[48:51]
	v_mfma_f32_16x16x32_bf16 v[48:51], v[176:179], v[184:187], v[48:51]
	v_mfma_f32_16x16x32_bf16 v[36:39], v[144:147], v[188:191], v[36:39]
	v_mfma_f32_16x16x32_bf16 v[36:39], v[166:169], v[192:195], v[36:39]
	v_mfma_f32_16x16x32_bf16 v[32:35], v[170:173], v[188:191], v[32:35]
	v_mfma_f32_16x16x32_bf16 v[32:35], v[176:179], v[192:195], v[32:35]
	v_mfma_f32_16x16x32_bf16 v[20:23], v[144:147], v[196:199], v[20:23]
	v_mfma_f32_16x16x32_bf16 v[20:23], v[166:169], v[200:203], v[20:23]
	v_mfma_f32_16x16x32_bf16 v[16:19], v[170:173], v[196:199], v[16:19]
	v_mfma_f32_16x16x32_bf16 v[16:19], v[176:179], v[200:203], v[16:19]
	v_mfma_f32_16x16x32_bf16 v[4:7], v[144:147], v[204:207], v[4:7]
	v_mfma_f32_16x16x32_bf16 v[4:7], v[166:169], v[208:211], v[4:7]
	v_mfma_f32_16x16x32_bf16 v[0:3], v[170:173], v[204:207], v[0:3]
	v_mfma_f32_16x16x32_bf16 v[0:3], v[176:179], v[208:211], v[0:3]
	s_barrier
	s_add_i32 s65, 0, 0x18000
	v_add_u32_e32 v122, s65, v110
	s_add_i32 s66, 0, 0x1c000
	ds_read_b128 v[114:117], v122
	ds_read_b128 v[128:131], v122 offset:1024
	ds_read_b128 v[132:135], v122 offset:2048
	ds_read_b128 v[140:143], v122 offset:3072
	v_add_u32_e32 v122, s66, v110
	ds_read_b128 v[144:147], v122
	ds_read_b128 v[166:169], v122 offset:1024
	ds_read_b128 v[170:173], v122 offset:2048
	ds_read_b128 v[176:179], v122 offset:3072
	s_add_u32 s42, s42, 0x2b0000
	s_addc_u32 s43, s43, 0
	s_mov_b32 m0, s29
	v_lshl_add_u64 v[122:123], s[42:43], 0, v[160:161]
	ds_read_b128 v[180:183], v113 offset:32768
	ds_read_b128 v[184:187], v113 offset:33792
	ds_read_b128 v[188:191], v113 offset:34816
	ds_read_b128 v[192:195], v113 offset:35840
	ds_read_b128 v[196:199], v113 offset:36864
	ds_read_b128 v[200:203], v113 offset:37888
	ds_read_b128 v[204:207], v113 offset:38912
	ds_read_b128 v[208:211], v113 offset:39936
	global_load_lds_dwordx4 v[122:123], off
	v_lshl_add_u64 v[122:123], s[42:43], 0, v[106:107]
	s_mov_b32 m0, s33
	s_nop 0
	global_load_lds_dwordx4 v[122:123], off
	s_waitcnt vmcnt(8)
	s_waitcnt lgkmcnt(0)
	s_barrier
	s_waitcnt lgkmcnt(0)
	v_mfma_f32_16x16x32_bf16 v[156:159], v[114:117], v[180:183], v[156:159]
	v_mfma_f32_16x16x32_bf16 v[152:155], v[132:135], v[180:183], v[152:155]
	v_mfma_f32_16x16x32_bf16 v[122:125], v[114:117], v[188:191], v[124:127]
	v_mfma_f32_16x16x32_bf16 v[118:121], v[132:135], v[188:191], v[118:121]
	v_mfma_f32_16x16x32_bf16 v[92:95], v[114:117], v[196:199], v[92:95]
	v_mfma_f32_16x16x32_bf16 v[88:91], v[132:135], v[196:199], v[88:91]
	v_mfma_f32_16x16x32_bf16 v[76:79], v[114:117], v[204:207], v[76:79]
	v_mfma_f32_16x16x32_bf16 v[72:75], v[132:135], v[204:207], v[72:75]
	v_mfma_f32_16x16x32_bf16 v[156:159], v[128:131], v[184:187], v[156:159]
	v_mfma_f32_16x16x32_bf16 v[152:155], v[140:143], v[184:187], v[152:155]
	v_mfma_f32_16x16x32_bf16 v[124:127], v[128:131], v[192:195], v[122:125]
	v_mfma_f32_16x16x32_bf16 v[120:123], v[140:143], v[192:195], v[118:121]
	v_mfma_f32_16x16x32_bf16 v[92:95], v[128:131], v[200:203], v[92:95]
	v_mfma_f32_16x16x32_bf16 v[88:91], v[140:143], v[200:203], v[88:91]
	v_mfma_f32_16x16x32_bf16 v[76:79], v[128:131], v[208:211], v[76:79]
	v_mfma_f32_16x16x32_bf16 v[72:75], v[140:143], v[208:211], v[72:75]
	v_mfma_f32_16x16x32_bf16 v[148:151], v[144:147], v[180:183], v[148:151]
	v_mfma_f32_16x16x32_bf16 v[148:151], v[166:169], v[184:187], v[148:151]
	v_mfma_f32_16x16x32_bf16 v[136:139], v[170:173], v[180:183], v[136:139]
	v_mfma_f32_16x16x32_bf16 v[136:139], v[176:179], v[184:187], v[136:139]
	v_mfma_f32_16x16x32_bf16 v[100:103], v[144:147], v[188:191], v[100:103]
	v_mfma_f32_16x16x32_bf16 v[100:103], v[166:169], v[192:195], v[100:103]
	v_mfma_f32_16x16x32_bf16 v[96:99], v[170:173], v[188:191], v[96:99]
	v_mfma_f32_16x16x32_bf16 v[96:99], v[176:179], v[192:195], v[96:99]
	v_mfma_f32_16x16x32_bf16 v[84:87], v[144:147], v[196:199], v[84:87]
	v_mfma_f32_16x16x32_bf16 v[84:87], v[166:169], v[200:203], v[84:87]
	v_mfma_f32_16x16x32_bf16 v[80:83], v[170:173], v[196:199], v[80:83]
	v_mfma_f32_16x16x32_bf16 v[80:83], v[176:179], v[200:203], v[80:83]
	v_mfma_f32_16x16x32_bf16 v[68:71], v[144:147], v[204:207], v[68:71]
	v_mfma_f32_16x16x32_bf16 v[68:71], v[166:169], v[208:211], v[68:71]
	v_mfma_f32_16x16x32_bf16 v[64:67], v[170:173], v[204:207], v[64:67]
	v_mfma_f32_16x16x32_bf16 v[64:67], v[176:179], v[208:211], v[64:67]
	s_barrier
; #define PG8_STAGE(bufoff, gbase, voff) do { _Pragma("unroll") for (int _i = 0; _i < 2; ++_i) \
;         __builtin_amdgcn_global_load_lds((const unsigned*)((const char*)(gbase) + (voff)[_i]), (LAS unsigned*)(lds + (bufoff) + ldsw + _i * 8192), 16, 0, 0); } while (0)
; #define PG8_LDA(dst, b, h) do { _Pragma("unroll") for (int m = 0; m < 4; ++m) _Pragma("unroll") for (int k = 0; k < 2; ++k) dst[m][k] = *(const LAS bf16x8*)(lds + PG8_SA(b, h) + aoff + m * 2048 + k * 1024); } while (0)
; #define PG8_MMA(ai, bj, At, Bt) do { __builtin_amdgcn_s_setprio(1); _Pragma("unroll") for (int m = 0; m < 4; ++m) _Pragma("unroll") for (int n = 0; n < 2; ++n) _Pragma("unroll") for (int k = 0; k < 2; ++k) \
;         acc[ai][bj][m][n] = __builtin_amdgcn_mfma_f32_16x16x32_bf16(Bt[n][k], At[m][k], acc[ai][bj][m][n], 0, 0, 0); __builtin_amdgcn_s_setprio(0); } while (0)
; #define PG8_WAIT_V(n) asm volatile("s_waitcnt vmcnt(" #n ")" ::: "memory")
; #define PG8_WAIT_L(n) asm volatile("s_waitcnt lgkmcnt(" #n ")" ::: "memory")
; #define PG8_BAR __builtin_amdgcn_s_barrier()
; #define PG8_SCHED __builtin_amdgcn_sched_barrier(0)
; template <class Epi>
; __device__ __forceinline__ void gemm_phase(LAS unsigned char* lds, const Gemm g, const Order& S, const Epi& E, const int wid) {
;     ...
;             PG8_LDA(At, 1, 1); PG8_STAGE(PG8_SB(1, 0), b3, voffB); PG8_STAGE(PG8_SB(1, 1), b3 + hB, voffB); PG8_STAGE(PG8_SA(1, 0), a3, voffA);
;             PG8_WAIT_V(8); PG8_WAIT_L(0); PG8_BAR; PG8_MMA(1, 0, At, B0); PG8_MMA(1, 1, At, B1); PG8_BAR; PG8_SCHED;
;     ...
;         }
;         if (wr == 0) PG8_BAR;
	s_add_i32 s42, s65, s24
	v_lshl_add_u64 v[118:119], v[212:213], 0, s[18:19]
	s_mov_b32 m0, s42
	ds_read_b128 v[180:183], v113 offset:49152
	ds_read_b128 v[184:187], v113 offset:50176
	ds_read_b128 v[188:191], v113 offset:51200
	ds_read_b128 v[192:195], v113 offset:52224
	ds_read_b128 v[196:199], v113 offset:53248
	ds_read_b128 v[200:203], v113 offset:54272
	ds_read_b128 v[204:207], v113 offset:55296
	ds_read_b128 v[208:211], v113 offset:56320
	global_load_lds_dwordx4 v[118:119], off
	s_add_i32 m0, s42, 0x2000
	s_add_u32 s40, s40, 0x2b0080
	v_lshl_add_u64 v[118:119], v[214:215], 0, s[18:19]
	s_addc_u32 s41, s41, 0
	s_add_i32 s42, s66, s24
	global_load_lds_dwordx4 v[118:119], off
	v_lshl_add_u64 v[118:119], s[40:41], 0, v[104:105]
	s_mov_b32 m0, s42
	s_nop 0
	global_load_lds_dwordx4 v[118:119], off
	v_lshl_add_u64 v[118:119], s[40:41], 0, v[108:109]
	s_add_i32 m0, s42, 0x2000
	s_nop 0
	global_load_lds_dwordx4 v[118:119], off
	v_lshl_add_u64 v[118:119], v[216:217], 0, s[18:19]
	s_mov_b32 m0, s51
	s_nop 0
	global_load_lds_dwordx4 v[118:119], off
	v_lshl_add_u64 v[118:119], v[218:219], 0, s[18:19]
	s_mov_b32 m0, s68
	s_nop 0
	global_load_lds_dwordx4 v[118:119], off
	s_waitcnt vmcnt(8)
	s_waitcnt lgkmcnt(0)
	s_barrier
	s_waitcnt lgkmcnt(0)
	v_mfma_f32_16x16x32_bf16 v[60:63], v[114:117], v[180:183], v[60:63]
	v_mfma_f32_16x16x32_bf16 v[60:63], v[128:131], v[184:187], v[60:63]
	v_mfma_f32_16x16x32_bf16 v[56:59], v[132:135], v[180:183], v[56:59]
	v_mfma_f32_16x16x32_bf16 v[56:59], v[140:143], v[184:187], v[56:59]
	v_mfma_f32_16x16x32_bf16 v[44:47], v[114:117], v[188:191], v[44:47]
	v_mfma_f32_16x16x32_bf16 v[44:47], v[128:131], v[192:195], v[44:47]
	v_mfma_f32_16x16x32_bf16 v[40:43], v[132:135], v[188:191], v[40:43]
	v_mfma_f32_16x16x32_bf16 v[40:43], v[140:143], v[192:195], v[40:43]
	v_mfma_f32_16x16x32_bf16 v[28:31], v[114:117], v[196:199], v[28:31]
	v_mfma_f32_16x16x32_bf16 v[28:31], v[128:131], v[200:203], v[28:31]
	v_mfma_f32_16x16x32_bf16 v[24:27], v[132:135], v[196:199], v[24:27]
	v_mfma_f32_16x16x32_bf16 v[24:27], v[140:143], v[200:203], v[24:27]
	v_mfma_f32_16x16x32_bf16 v[12:15], v[114:117], v[204:207], v[12:15]
	v_mfma_f32_16x16x32_bf16 v[12:15], v[128:131], v[208:211], v[12:15]
	v_mfma_f32_16x16x32_bf16 v[8:11], v[132:135], v[204:207], v[8:11]
	v_mfma_f32_16x16x32_bf16 v[8:11], v[140:143], v[208:211], v[8:11]
	v_mfma_f32_16x16x32_bf16 v[52:55], v[144:147], v[180:183], v[52:55]
	v_mfma_f32_16x16x32_bf16 v[52:55], v[166:169], v[184:187], v[52:55]
	v_mfma_f32_16x16x32_bf16 v[48:51], v[170:173], v[180:183], v[48:51]
	v_mfma_f32_16x16x32_bf16 v[48:51], v[176:179], v[184:187], v[48:51]
	v_mfma_f32_16x16x32_bf16 v[36:39], v[144:147], v[188:191], v[36:39]
	v_mfma_f32_16x16x32_bf16 v[36:39], v[166:169], v[192:195], v[36:39]
	v_mfma_f32_16x16x32_bf16 v[32:35], v[170:173], v[188:191], v[32:35]
	v_mfma_f32_16x16x32_bf16 v[32:35], v[176:179], v[192:195], v[32:35]
	v_mfma_f32_16x16x32_bf16 v[20:23], v[144:147], v[196:199], v[20:23]
	v_mfma_f32_16x16x32_bf16 v[20:23], v[166:169], v[200:203], v[20:23]
	v_mfma_f32_16x16x32_bf16 v[16:19], v[170:173], v[196:199], v[16:19]
	v_mfma_f32_16x16x32_bf16 v[16:19], v[176:179], v[200:203], v[16:19]
	v_mfma_f32_16x16x32_bf16 v[4:7], v[144:147], v[204:207], v[4:7]
	v_mfma_f32_16x16x32_bf16 v[4:7], v[166:169], v[208:211], v[4:7]
	v_mfma_f32_16x16x32_bf16 v[0:3], v[170:173], v[204:207], v[0:3]
	v_mfma_f32_16x16x32_bf16 v[0:3], v[176:179], v[208:211], v[0:3]
	s_add_i32 s64, s64, 2
	s_add_u32 s38, s38, 0x100
	s_addc_u32 s39, s39, 0
	s_add_u32 s62, s62, 0x100
	s_addc_u32 s63, s63, 0
	s_cmpk_gt_u32 s64, 0xa9
	s_barrier
	s_cbranch_scc0 .LBB0_1549
	s_and_b64 vcc, exec, s[10:11]
	s_cbranch_vccz .LBB0_1552
	s_barrier
